# v15 + GEMM main loops: s_setprio 1 moved before the pre-MFMA barrier, redundant lgkmcnt(0) after it dropped, mid-block setprio pair removed, s_setprio 0 moved after the post-MFMA barrier
# speedup vs baseline: 1.0041x; 1.0029x over previous
; #define PG8_STAGE(bufoff, gbase, voff) do { _Pragma("unroll") for (int _i = 0; _i < 2; ++_i) \
;         __builtin_amdgcn_global_load_lds((const unsigned*)((const char*)(gbase) + (voff)[_i]), (PG8_LAS unsigned*)(lds + (bufoff) + ldsw + _i * 8192), 16, 0, 0); } while (0)
; #define PG8_LDA(dst, b, h) do { _Pragma("unroll") for (int m = 0; m < 4; ++m) _Pragma("unroll") for (int k = 0; k < 2; ++k) dst[m][k] = *(const PG8_LAS bf16x8*)(lds + PG8_SA(b, h) + aoff + m * 2048 + k * 1024); } while (0)
; #define PG8_LDB(dst, b, h) do { _Pragma("unroll") for (int n = 0; n < 2; ++n) _Pragma("unroll") for (int k = 0; k < 2; ++k) dst[n][k] = *(const PG8_LAS bf16x8*)(lds + PG8_SB(b, h) + boff + n * 2048 + k * 1024); } while (0)
; #define PG8_MMA(ai, bj, At, Bt) do { __builtin_amdgcn_s_setprio(1); _Pragma("unroll") for (int m = 0; m < 4; ++m) _Pragma("unroll") for (int n = 0; n < 2; ++n) _Pragma("unroll") for (int k = 0; k < 2; ++k) \
;         acc[ai][bj][m][n] = __builtin_amdgcn_mfma_f32_16x16x32_bf16(Bt[n][k], At[m][k], acc[ai][bj][m][n], 0, 0, 0); __builtin_amdgcn_s_setprio(0); } while (0)
; #define PG8_WAIT_V(n) asm volatile("s_waitcnt vmcnt(" #n ")" ::: "memory")
; #define PG8_WAIT_L(n) asm volatile("s_waitcnt lgkmcnt(" #n ")" ::: "memory")
; #define PG8_BAR __builtin_amdgcn_s_barrier()
; #define PG8_SCHED __builtin_amdgcn_sched_barrier(0)
; template <class Epi, class Sched, bool ALIGN_EPI = false, bool SP2 = false>
; __device__ __forceinline__ void gemm_phase(PG8_LAS unsigned char* lds, const Gemm g, const Sched& S, const Epi& E) {
;     ...
;             PG8_LDB(B0, 0, 0); PG8_LDB(B1, 0, 1); PG8_SCHED; PG8_LDA(At, 0, 0); PG8_STAGE(PG8_SA(1, 1), a1 + hstepA, voffA);
;             PG8_WAIT_V(8); PG8_WAIT_L(0); PG8_BAR; PG8_MMA(0, 0, At, B0); PG8_MMA(0, 1, At, B1); PG8_BAR; PG8_SCHED;
;             PG8_LDA(At, 0, 1); PG8_STAGE(PG8_SB(0, 0), b2, voffB); PG8_STAGE(PG8_SB(0, 1), b2 + hstepB, voffB); PG8_STAGE(PG8_SA(0, 0), a2, voffA);
;             PG8_WAIT_V(8); PG8_WAIT_L(0); PG8_BAR; PG8_MMA(1, 0, At, B0); PG8_MMA(1, 1, At, B1); PG8_BAR; PG8_SCHED;
.LBB0_185:
	ds_read_b128 v[162:165], v158
	ds_read_b128 v[166:169], v158 offset:1024
	ds_read_b128 v[170:173], v158 offset:2048
	ds_read_b128 v[174:177], v158 offset:3072
	ds_read_b128 v[178:181], v159
	ds_read_b128 v[182:185], v159 offset:1024
	ds_read_b128 v[186:189], v159 offset:2048
	ds_read_b128 v[190:193], v159 offset:3072
	s_add_u32 s36, s34, 0xfff80080
	s_addc_u32 s37, s35, -1
	s_cmp_eq_u32 s42, 28
	s_cselect_b32 s39, s1, s37
	s_cselect_b32 s38, s11, s36
	s_cselect_b32 s37, s25, s41
	s_cselect_b32 s36, s27, s40
	v_lshl_add_u64 v[156:157], s[34:35], 0, v[148:149]
	s_add_i32 m0, s45, 0xc000
	ds_read_b128 v[194:197], v160
	ds_read_b128 v[198:201], v160 offset:1024
	ds_read_b128 v[202:205], v160 offset:2048
	ds_read_b128 v[210:213], v160 offset:3072
	ds_read_b128 v[214:217], v160 offset:4096
	ds_read_b128 v[218:221], v160 offset:5120
	ds_read_b128 v[222:225], v160 offset:6144
	ds_read_b128 v[226:229], v160 offset:7168
	global_load_lds_dwordx4 v[156:157], off
	v_lshl_add_u64 v[156:157], s[34:35], 0, v[150:151]
	s_add_i32 m0, s45, 0xe000
	s_nop 0
	global_load_lds_dwordx4 v[156:157], off
	s_waitcnt vmcnt(8)
	s_waitcnt lgkmcnt(0)
	s_setprio 1
	s_barrier
	v_mfma_f32_16x16x32_bf16 v[126:129], v[162:165], v[194:197], v[126:129]
	v_mfma_f32_16x16x32_bf16 v[122:125], v[170:173], v[194:197], v[122:125]
	v_mfma_f32_16x16x32_bf16 v[110:113], v[162:165], v[202:205], v[110:113]
	v_mfma_f32_16x16x32_bf16 v[106:109], v[170:173], v[202:205], v[106:109]
	v_mfma_f32_16x16x32_bf16 v[94:97], v[162:165], v[214:217], v[94:97]
	v_mfma_f32_16x16x32_bf16 v[90:93], v[170:173], v[214:217], v[90:93]
	v_mfma_f32_16x16x32_bf16 v[78:81], v[162:165], v[222:225], v[78:81]
	v_mfma_f32_16x16x32_bf16 v[74:77], v[170:173], v[222:225], v[74:77]
	v_mfma_f32_16x16x32_bf16 v[126:129], v[166:169], v[198:201], v[126:129]
	v_mfma_f32_16x16x32_bf16 v[122:125], v[174:177], v[198:201], v[122:125]
	v_mfma_f32_16x16x32_bf16 v[110:113], v[166:169], v[210:213], v[110:113]
	v_mfma_f32_16x16x32_bf16 v[106:109], v[174:177], v[210:213], v[106:109]
	v_mfma_f32_16x16x32_bf16 v[94:97], v[166:169], v[218:221], v[94:97]
	v_mfma_f32_16x16x32_bf16 v[90:93], v[174:177], v[218:221], v[90:93]
	v_mfma_f32_16x16x32_bf16 v[78:81], v[166:169], v[226:229], v[78:81]
	v_mfma_f32_16x16x32_bf16 v[74:77], v[174:177], v[226:229], v[74:77]
	v_mfma_f32_16x16x32_bf16 v[118:121], v[178:181], v[194:197], v[118:121]
	v_mfma_f32_16x16x32_bf16 v[114:117], v[186:189], v[194:197], v[114:117]
	v_mfma_f32_16x16x32_bf16 v[102:105], v[178:181], v[202:205], v[102:105]
	v_mfma_f32_16x16x32_bf16 v[98:101], v[186:189], v[202:205], v[98:101]
	v_mfma_f32_16x16x32_bf16 v[86:89], v[178:181], v[214:217], v[86:89]
	v_mfma_f32_16x16x32_bf16 v[82:85], v[186:189], v[214:217], v[82:85]
	v_mfma_f32_16x16x32_bf16 v[70:73], v[178:181], v[222:225], v[70:73]
	v_mfma_f32_16x16x32_bf16 v[66:69], v[186:189], v[222:225], v[66:69]
	v_mfma_f32_16x16x32_bf16 v[118:121], v[182:185], v[198:201], v[118:121]
	v_mfma_f32_16x16x32_bf16 v[114:117], v[190:193], v[198:201], v[114:117]
	v_mfma_f32_16x16x32_bf16 v[102:105], v[182:185], v[210:213], v[102:105]
	v_mfma_f32_16x16x32_bf16 v[98:101], v[190:193], v[210:213], v[98:101]
	v_mfma_f32_16x16x32_bf16 v[86:89], v[182:185], v[218:221], v[86:89]
	v_mfma_f32_16x16x32_bf16 v[82:85], v[190:193], v[218:221], v[82:85]
	v_mfma_f32_16x16x32_bf16 v[70:73], v[182:185], v[226:229], v[70:73]
	v_mfma_f32_16x16x32_bf16 v[66:69], v[190:193], v[226:229], v[66:69]
	s_barrier
	s_setprio 0
	s_add_i32 s43, s56, s44
	v_lshl_add_u64 v[156:157], s[36:37], 0, v[132:133]
	s_mov_b32 m0, s43
	ds_read_b128 v[194:197], v160 offset:16384
	ds_read_b128 v[198:201], v160 offset:17408
	ds_read_b128 v[202:205], v160 offset:18432
	ds_read_b128 v[210:213], v160 offset:19456
	ds_read_b128 v[214:217], v160 offset:20480
	ds_read_b128 v[218:221], v160 offset:21504
	ds_read_b128 v[222:225], v160 offset:22528
	ds_read_b128 v[226:229], v160 offset:23552
	global_load_lds_dwordx4 v[156:157], off
	s_add_i32 m0, s43, 0x2000
	s_add_u32 s62, s36, 0x80000
	v_lshl_add_u64 v[206:207], s[36:37], 0, v[136:137]
	s_addc_u32 s63, s37, 0
	s_add_i32 s43, s57, s44
	global_load_lds_dwordx4 v[206:207], off
	v_lshl_add_u64 v[230:231], s[62:63], 0, v[132:133]
	s_mov_b32 m0, s43
	v_lshl_add_u64 v[232:233], s[38:39], 0, v[134:135]
	global_load_lds_dwordx4 v[230:231], off
	v_lshl_add_u64 v[230:231], s[62:63], 0, v[136:137]
	s_add_i32 m0, s43, 0x2000
	s_nop 0
	global_load_lds_dwordx4 v[230:231], off
	v_lshl_add_u64 v[230:231], s[38:39], 0, v[130:131]
	s_mov_b32 m0, s45
	s_nop 0
	global_load_lds_dwordx4 v[230:231], off
	s_mov_b32 m0, s46
	s_nop 0
	global_load_lds_dwordx4 v[232:233], off
	s_waitcnt vmcnt(8)
	s_waitcnt lgkmcnt(0)
	s_setprio 1
	s_barrier
; #define PG8_STAGE(bufoff, gbase, voff) do { _Pragma("unroll") for (int _i = 0; _i < 2; ++_i) \
;         __builtin_amdgcn_global_load_lds((const unsigned*)((const char*)(gbase) + (voff)[_i]), (PG8_LAS unsigned*)(lds + (bufoff) + ldsw + _i * 8192), 16, 0, 0); } while (0)
; #define PG8_LDA(dst, b, h) do { _Pragma("unroll") for (int m = 0; m < 4; ++m) _Pragma("unroll") for (int k = 0; k < 2; ++k) dst[m][k] = *(const PG8_LAS bf16x8*)(lds + PG8_SA(b, h) + aoff + m * 2048 + k * 1024); } while (0)
; #define PG8_LDB(dst, b, h) do { _Pragma("unroll") for (int n = 0; n < 2; ++n) _Pragma("unroll") for (int k = 0; k < 2; ++k) dst[n][k] = *(const PG8_LAS bf16x8*)(lds + PG8_SB(b, h) + boff + n * 2048 + k * 1024); } while (0)
; #define PG8_MMA(ai, bj, At, Bt) do { __builtin_amdgcn_s_setprio(1); _Pragma("unroll") for (int m = 0; m < 4; ++m) _Pragma("unroll") for (int n = 0; n < 2; ++n) _Pragma("unroll") for (int k = 0; k < 2; ++k) \
;         acc[ai][bj][m][n] = __builtin_amdgcn_mfma_f32_16x16x32_bf16(Bt[n][k], At[m][k], acc[ai][bj][m][n], 0, 0, 0); __builtin_amdgcn_s_setprio(0); } while (0)
; #define PG8_WAIT_V(n) asm volatile("s_waitcnt vmcnt(" #n ")" ::: "memory")
; #define PG8_WAIT_L(n) asm volatile("s_waitcnt lgkmcnt(" #n ")" ::: "memory")
; #define PG8_BAR __builtin_amdgcn_s_barrier()
; #define PG8_SCHED __builtin_amdgcn_sched_barrier(0)
; template <class Epi, class Sched, bool ALIGN_EPI = false, bool SP2 = false>
; __device__ __forceinline__ void gemm_phase(PG8_LAS unsigned char* lds, const Gemm g, const Sched& S, const Epi& E) {
;     ...
;             PG8_WAIT_V(8); PG8_WAIT_L(0); PG8_BAR; PG8_MMA(1, 0, At, B0); PG8_MMA(1, 1, At, B1); PG8_BAR; PG8_SCHED;
;             PG8_LDB(B0, 1, 0); PG8_LDB(B1, 1, 1); PG8_SCHED; PG8_LDA(At, 1, 0); PG8_STAGE(PG8_SA(0, 1), a2 + hstepA, voffA);
;             PG8_WAIT_V(8); PG8_WAIT_L(0); PG8_BAR; PG8_MMA(0, 0, At, B0); PG8_MMA(0, 1, At, B1); PG8_BAR; PG8_SCHED;
	v_mfma_f32_16x16x32_bf16 v[62:65], v[162:165], v[194:197], v[62:65]
	v_mfma_f32_16x16x32_bf16 v[58:61], v[170:173], v[194:197], v[58:61]
	v_mfma_f32_16x16x32_bf16 v[46:49], v[162:165], v[202:205], v[46:49]
	v_mfma_f32_16x16x32_bf16 v[42:45], v[170:173], v[202:205], v[42:45]
	v_mfma_f32_16x16x32_bf16 v[30:33], v[162:165], v[214:217], v[30:33]
	v_mfma_f32_16x16x32_bf16 v[26:29], v[170:173], v[214:217], v[26:29]
	v_mfma_f32_16x16x32_bf16 v[14:17], v[162:165], v[222:225], v[14:17]
	v_mfma_f32_16x16x32_bf16 v[10:13], v[170:173], v[222:225], v[10:13]
	v_mfma_f32_16x16x32_bf16 v[62:65], v[166:169], v[198:201], v[62:65]
	v_mfma_f32_16x16x32_bf16 v[58:61], v[174:177], v[198:201], v[58:61]
	v_mfma_f32_16x16x32_bf16 v[46:49], v[166:169], v[210:213], v[46:49]
	v_mfma_f32_16x16x32_bf16 v[42:45], v[174:177], v[210:213], v[42:45]
	v_mfma_f32_16x16x32_bf16 v[30:33], v[166:169], v[218:221], v[30:33]
	v_mfma_f32_16x16x32_bf16 v[26:29], v[174:177], v[218:221], v[26:29]
	v_mfma_f32_16x16x32_bf16 v[14:17], v[166:169], v[226:229], v[14:17]
	v_mfma_f32_16x16x32_bf16 v[10:13], v[174:177], v[226:229], v[10:13]
	v_mfma_f32_16x16x32_bf16 v[54:57], v[178:181], v[194:197], v[54:57]
	v_mfma_f32_16x16x32_bf16 v[50:53], v[186:189], v[194:197], v[50:53]
	v_mfma_f32_16x16x32_bf16 v[38:41], v[178:181], v[202:205], v[38:41]
	v_mfma_f32_16x16x32_bf16 v[34:37], v[186:189], v[202:205], v[34:37]
	v_mfma_f32_16x16x32_bf16 v[22:25], v[178:181], v[214:217], v[22:25]
	v_mfma_f32_16x16x32_bf16 v[18:21], v[186:189], v[214:217], v[18:21]
	v_mfma_f32_16x16x32_bf16 v[6:9], v[178:181], v[222:225], v[6:9]
	v_mfma_f32_16x16x32_bf16 v[2:5], v[186:189], v[222:225], v[2:5]
	v_mfma_f32_16x16x32_bf16 v[54:57], v[182:185], v[198:201], v[54:57]
	v_mfma_f32_16x16x32_bf16 v[50:53], v[190:193], v[198:201], v[50:53]
	v_mfma_f32_16x16x32_bf16 v[38:41], v[182:185], v[210:213], v[38:41]
	v_mfma_f32_16x16x32_bf16 v[34:37], v[190:193], v[210:213], v[34:37]
	v_mfma_f32_16x16x32_bf16 v[22:25], v[182:185], v[218:221], v[22:25]
	v_mfma_f32_16x16x32_bf16 v[18:21], v[190:193], v[218:221], v[18:21]
	v_mfma_f32_16x16x32_bf16 v[6:9], v[182:185], v[226:229], v[6:9]
	v_mfma_f32_16x16x32_bf16 v[2:5], v[190:193], v[226:229], v[2:5]
	s_barrier
	s_setprio 0
	s_add_i32 s43, 0, 0x18000
	v_add_u32_e32 v138, s43, v143
	s_add_i32 s61, 0, 0x1c000
	ds_read_b128 v[162:165], v138
	ds_read_b128 v[166:169], v138 offset:1024
	ds_read_b128 v[170:173], v138 offset:2048
	ds_read_b128 v[174:177], v138 offset:3072
	v_add_u32_e32 v138, s61, v143
	ds_read_b128 v[178:181], v138
	ds_read_b128 v[182:185], v138 offset:1024
	ds_read_b128 v[186:189], v138 offset:2048
	ds_read_b128 v[190:193], v138 offset:3072
	s_add_u32 s38, s38, 0x80000
	s_addc_u32 s39, s39, 0
	s_mov_b32 m0, s47
	v_lshl_add_u64 v[234:235], s[38:39], 0, v[130:131]
	ds_read_b128 v[194:197], v160 offset:32768
	ds_read_b128 v[198:201], v160 offset:33792
	ds_read_b128 v[202:205], v160 offset:34816
	ds_read_b128 v[210:213], v160 offset:35840
	ds_read_b128 v[214:217], v160 offset:36864
	ds_read_b128 v[218:221], v160 offset:37888
	ds_read_b128 v[222:225], v160 offset:38912
	ds_read_b128 v[226:229], v160 offset:39936
	global_load_lds_dwordx4 v[234:235], off
	v_lshl_add_u64 v[234:235], s[38:39], 0, v[134:135]
	s_mov_b32 m0, s48
	s_nop 0
	global_load_lds_dwordx4 v[234:235], off
	s_waitcnt vmcnt(8)
	s_waitcnt lgkmcnt(0)
	s_setprio 1
	s_barrier
	v_mfma_f32_16x16x32_bf16 v[126:129], v[162:165], v[194:197], v[126:129]
	v_mfma_f32_16x16x32_bf16 v[122:125], v[170:173], v[194:197], v[122:125]
	v_mfma_f32_16x16x32_bf16 v[110:113], v[162:165], v[202:205], v[110:113]
	v_mfma_f32_16x16x32_bf16 v[106:109], v[170:173], v[202:205], v[106:109]
	v_mfma_f32_16x16x32_bf16 v[94:97], v[162:165], v[214:217], v[94:97]
	v_mfma_f32_16x16x32_bf16 v[90:93], v[170:173], v[214:217], v[90:93]
	v_mfma_f32_16x16x32_bf16 v[78:81], v[162:165], v[222:225], v[78:81]
	v_mfma_f32_16x16x32_bf16 v[74:77], v[170:173], v[222:225], v[74:77]
	v_mfma_f32_16x16x32_bf16 v[126:129], v[166:169], v[198:201], v[126:129]
	v_mfma_f32_16x16x32_bf16 v[122:125], v[174:177], v[198:201], v[122:125]
	v_mfma_f32_16x16x32_bf16 v[110:113], v[166:169], v[210:213], v[110:113]
	v_mfma_f32_16x16x32_bf16 v[106:109], v[174:177], v[210:213], v[106:109]
	v_mfma_f32_16x16x32_bf16 v[94:97], v[166:169], v[218:221], v[94:97]
	v_mfma_f32_16x16x32_bf16 v[90:93], v[174:177], v[218:221], v[90:93]
	v_mfma_f32_16x16x32_bf16 v[78:81], v[166:169], v[226:229], v[78:81]
	v_mfma_f32_16x16x32_bf16 v[74:77], v[174:177], v[226:229], v[74:77]
	v_mfma_f32_16x16x32_bf16 v[118:121], v[178:181], v[194:197], v[118:121]
	v_mfma_f32_16x16x32_bf16 v[114:117], v[186:189], v[194:197], v[114:117]
	v_mfma_f32_16x16x32_bf16 v[102:105], v[178:181], v[202:205], v[102:105]
	v_mfma_f32_16x16x32_bf16 v[98:101], v[186:189], v[202:205], v[98:101]
	v_mfma_f32_16x16x32_bf16 v[86:89], v[178:181], v[214:217], v[86:89]
	v_mfma_f32_16x16x32_bf16 v[82:85], v[186:189], v[214:217], v[82:85]
	v_mfma_f32_16x16x32_bf16 v[70:73], v[178:181], v[222:225], v[70:73]
	v_mfma_f32_16x16x32_bf16 v[66:69], v[186:189], v[222:225], v[66:69]
	v_mfma_f32_16x16x32_bf16 v[118:121], v[182:185], v[198:201], v[118:121]
	v_mfma_f32_16x16x32_bf16 v[114:117], v[190:193], v[198:201], v[114:117]
	v_mfma_f32_16x16x32_bf16 v[102:105], v[182:185], v[210:213], v[102:105]
	v_mfma_f32_16x16x32_bf16 v[98:101], v[190:193], v[210:213], v[98:101]
	v_mfma_f32_16x16x32_bf16 v[86:89], v[182:185], v[218:221], v[86:89]
	v_mfma_f32_16x16x32_bf16 v[82:85], v[190:193], v[218:221], v[82:85]
	v_mfma_f32_16x16x32_bf16 v[70:73], v[182:185], v[226:229], v[70:73]
	v_mfma_f32_16x16x32_bf16 v[66:69], v[190:193], v[226:229], v[66:69]
	s_barrier
; #define PG8_STAGE(bufoff, gbase, voff) do { _Pragma("unroll") for (int _i = 0; _i < 2; ++_i) \
;         __builtin_amdgcn_global_load_lds((const unsigned*)((const char*)(gbase) + (voff)[_i]), (PG8_LAS unsigned*)(lds + (bufoff) + ldsw + _i * 8192), 16, 0, 0); } while (0)
; #define PG8_LDA(dst, b, h) do { _Pragma("unroll") for (int m = 0; m < 4; ++m) _Pragma("unroll") for (int k = 0; k < 2; ++k) dst[m][k] = *(const PG8_LAS bf16x8*)(lds + PG8_SA(b, h) + aoff + m * 2048 + k * 1024); } while (0)
; #define PG8_MMA(ai, bj, At, Bt) do { __builtin_amdgcn_s_setprio(1); _Pragma("unroll") for (int m = 0; m < 4; ++m) _Pragma("unroll") for (int n = 0; n < 2; ++n) _Pragma("unroll") for (int k = 0; k < 2; ++k) \
;         acc[ai][bj][m][n] = __builtin_amdgcn_mfma_f32_16x16x32_bf16(Bt[n][k], At[m][k], acc[ai][bj][m][n], 0, 0, 0); __builtin_amdgcn_s_setprio(0); } while (0)
; #define PG8_WAIT_V(n) asm volatile("s_waitcnt vmcnt(" #n ")" ::: "memory")
; #define PG8_WAIT_L(n) asm volatile("s_waitcnt lgkmcnt(" #n ")" ::: "memory")
; #define PG8_BAR __builtin_amdgcn_s_barrier()
; #define PG8_SCHED __builtin_amdgcn_sched_barrier(0)
; template <class Epi, class Sched, bool ALIGN_EPI = false, bool SP2 = false>
; __device__ __forceinline__ void gemm_phase(PG8_LAS unsigned char* lds, const Gemm g, const Sched& S, const Epi& E) {
;     ...
;         for (int t = 0; t < nt; t += 2) {
;     ...
;             PG8_WAIT_V(8); PG8_WAIT_L(0); PG8_BAR; PG8_MMA(0, 0, At, B0); PG8_MMA(0, 1, At, B1); PG8_BAR; PG8_SCHED;
;             PG8_LDA(At, 1, 1); PG8_STAGE(PG8_SB(1, 0), b3, voffB); PG8_STAGE(PG8_SB(1, 1), b3 + hstepB, voffB); PG8_STAGE(PG8_SA(1, 0), a3, voffA);
;             PG8_WAIT_V(8); PG8_WAIT_L(0); PG8_BAR; PG8_MMA(1, 0, At, B0); PG8_MMA(1, 1, At, B1); PG8_BAR; PG8_SCHED;
	s_setprio 0
	s_add_i32 s38, s43, s44
	v_lshl_add_u64 v[156:157], v[156:157], 0, s[20:21]
	s_mov_b32 m0, s38
	ds_read_b128 v[194:197], v160 offset:49152
	ds_read_b128 v[198:201], v160 offset:50176
	ds_read_b128 v[202:205], v160 offset:51200
	ds_read_b128 v[210:213], v160 offset:52224
	ds_read_b128 v[214:217], v160 offset:53248
	ds_read_b128 v[218:221], v160 offset:54272
	ds_read_b128 v[222:225], v160 offset:55296
	ds_read_b128 v[226:229], v160 offset:56320
	global_load_lds_dwordx4 v[156:157], off
	s_add_i32 m0, s38, 0x2000
	s_add_u32 s36, s36, 0x80080
	v_lshl_add_u64 v[156:157], v[206:207], 0, s[20:21]
	s_addc_u32 s37, s37, 0
	s_add_i32 s38, s61, s44
	global_load_lds_dwordx4 v[156:157], off
	v_lshl_add_u64 v[156:157], s[36:37], 0, v[132:133]
	s_mov_b32 m0, s38
	s_nop 0
	global_load_lds_dwordx4 v[156:157], off
	v_lshl_add_u64 v[156:157], s[36:37], 0, v[136:137]
	s_add_i32 m0, s38, 0x2000
	s_nop 0
	global_load_lds_dwordx4 v[156:157], off
	v_lshl_add_u64 v[156:157], v[230:231], 0, s[20:21]
	s_mov_b32 m0, s52
	s_nop 0
	global_load_lds_dwordx4 v[156:157], off
	v_lshl_add_u64 v[156:157], v[232:233], 0, s[20:21]
	s_mov_b32 m0, s53
	s_nop 0
	global_load_lds_dwordx4 v[156:157], off
	s_waitcnt vmcnt(8)
	s_waitcnt lgkmcnt(0)
	s_setprio 1
	s_barrier
	v_mfma_f32_16x16x32_bf16 v[62:65], v[162:165], v[194:197], v[62:65]
	v_mfma_f32_16x16x32_bf16 v[58:61], v[170:173], v[194:197], v[58:61]
	v_mfma_f32_16x16x32_bf16 v[46:49], v[162:165], v[202:205], v[46:49]
	v_mfma_f32_16x16x32_bf16 v[42:45], v[170:173], v[202:205], v[42:45]
	v_mfma_f32_16x16x32_bf16 v[30:33], v[162:165], v[214:217], v[30:33]
	v_mfma_f32_16x16x32_bf16 v[26:29], v[170:173], v[214:217], v[26:29]
	v_mfma_f32_16x16x32_bf16 v[14:17], v[162:165], v[222:225], v[14:17]
	v_mfma_f32_16x16x32_bf16 v[10:13], v[170:173], v[222:225], v[10:13]
	v_mfma_f32_16x16x32_bf16 v[62:65], v[166:169], v[198:201], v[62:65]
	v_mfma_f32_16x16x32_bf16 v[58:61], v[174:177], v[198:201], v[58:61]
	v_mfma_f32_16x16x32_bf16 v[46:49], v[166:169], v[210:213], v[46:49]
	v_mfma_f32_16x16x32_bf16 v[42:45], v[174:177], v[210:213], v[42:45]
	v_mfma_f32_16x16x32_bf16 v[30:33], v[166:169], v[218:221], v[30:33]
	v_mfma_f32_16x16x32_bf16 v[26:29], v[174:177], v[218:221], v[26:29]
	v_mfma_f32_16x16x32_bf16 v[14:17], v[166:169], v[226:229], v[14:17]
	v_mfma_f32_16x16x32_bf16 v[10:13], v[174:177], v[226:229], v[10:13]
	v_mfma_f32_16x16x32_bf16 v[54:57], v[178:181], v[194:197], v[54:57]
	v_mfma_f32_16x16x32_bf16 v[50:53], v[186:189], v[194:197], v[50:53]
	v_mfma_f32_16x16x32_bf16 v[38:41], v[178:181], v[202:205], v[38:41]
	v_mfma_f32_16x16x32_bf16 v[34:37], v[186:189], v[202:205], v[34:37]
	v_mfma_f32_16x16x32_bf16 v[22:25], v[178:181], v[214:217], v[22:25]
	v_mfma_f32_16x16x32_bf16 v[18:21], v[186:189], v[214:217], v[18:21]
	v_mfma_f32_16x16x32_bf16 v[6:9], v[178:181], v[222:225], v[6:9]
	v_mfma_f32_16x16x32_bf16 v[2:5], v[186:189], v[222:225], v[2:5]
	v_mfma_f32_16x16x32_bf16 v[54:57], v[182:185], v[198:201], v[54:57]
	v_mfma_f32_16x16x32_bf16 v[50:53], v[190:193], v[198:201], v[50:53]
	v_mfma_f32_16x16x32_bf16 v[38:41], v[182:185], v[210:213], v[38:41]
	v_mfma_f32_16x16x32_bf16 v[34:37], v[190:193], v[210:213], v[34:37]
	v_mfma_f32_16x16x32_bf16 v[22:25], v[182:185], v[218:221], v[22:25]
	v_mfma_f32_16x16x32_bf16 v[18:21], v[190:193], v[218:221], v[18:21]
	v_mfma_f32_16x16x32_bf16 v[6:9], v[182:185], v[226:229], v[6:9]
	v_mfma_f32_16x16x32_bf16 v[2:5], v[190:193], v[226:229], v[2:5]
	s_barrier
	s_setprio 0
	s_add_i32 s42, s42, 2
	s_add_u32 s34, s34, 0x100
	s_addc_u32 s35, s35, 0
	s_add_u32 s40, s40, 0x100
	s_addc_u32 s41, s41, 0
	s_cmp_gt_u32 s42, 29
	s_cbranch_scc0 .LBB0_185
	s_and_b64 vcc, exec, s[22:23]
	s_cbranch_vccz .LBB0_188
	s_barrier

; #define PG8_STAGE(bufoff, gbase, voff) do { _Pragma("unroll") for (int _i = 0; _i < 2; ++_i) \
;         __builtin_amdgcn_global_load_lds((const unsigned*)((const char*)(gbase) + (voff)[_i]), (PG8_LAS unsigned*)(lds + (bufoff) + ldsw + _i * 8192), 16, 0, 0); } while (0)
; #define PG8_LDA(dst, b, h) do { _Pragma("unroll") for (int m = 0; m < 4; ++m) _Pragma("unroll") for (int k = 0; k < 2; ++k) dst[m][k] = *(const PG8_LAS bf16x8*)(lds + PG8_SA(b, h) + aoff + m * 2048 + k * 1024); } while (0)
; #define PG8_LDB(dst, b, h) do { _Pragma("unroll") for (int n = 0; n < 2; ++n) _Pragma("unroll") for (int k = 0; k < 2; ++k) dst[n][k] = *(const PG8_LAS bf16x8*)(lds + PG8_SB(b, h) + boff + n * 2048 + k * 1024); } while (0)
; #define PG8_MMA(ai, bj, At, Bt) do { __builtin_amdgcn_s_setprio(1); _Pragma("unroll") for (int m = 0; m < 4; ++m) _Pragma("unroll") for (int n = 0; n < 2; ++n) _Pragma("unroll") for (int k = 0; k < 2; ++k) \
;         acc[ai][bj][m][n] = __builtin_amdgcn_mfma_f32_16x16x32_bf16(Bt[n][k], At[m][k], acc[ai][bj][m][n], 0, 0, 0); __builtin_amdgcn_s_setprio(0); } while (0)
; #define PG8_WAIT_V(n) asm volatile("s_waitcnt vmcnt(" #n ")" ::: "memory")
; #define PG8_WAIT_L(n) asm volatile("s_waitcnt lgkmcnt(" #n ")" ::: "memory")
; #define PG8_BAR __builtin_amdgcn_s_barrier()
; #define PG8_SCHED __builtin_amdgcn_sched_barrier(0)
; template <class Epi, class Sched, bool ALIGN_EPI = false, bool SP2 = false>
; __device__ __forceinline__ void gemm_phase(PG8_LAS unsigned char* lds, const Gemm g, const Sched& S, const Epi& E) {
;     ...
;             PG8_LDB(B0, 0, 0); PG8_LDB(B1, 0, 1); PG8_SCHED; PG8_LDA(At, 0, 0); PG8_STAGE(PG8_SA(1, 1), a1 + hstepA, voffA);
;             PG8_WAIT_V(8); PG8_WAIT_L(0); PG8_BAR; PG8_MMA(0, 0, At, B0); PG8_MMA(0, 1, At, B1); PG8_BAR; PG8_SCHED;
;             PG8_LDA(At, 0, 1); PG8_STAGE(PG8_SB(0, 0), b2, voffB); PG8_STAGE(PG8_SB(0, 1), b2 + hstepB, voffB); PG8_STAGE(PG8_SA(0, 0), a2, voffA);
;             PG8_WAIT_V(8); PG8_WAIT_L(0); PG8_BAR; PG8_MMA(1, 0, At, B0); PG8_MMA(1, 1, At, B1); PG8_BAR; PG8_SCHED;
.LBB0_802:
	ds_read_b128 v[152:155], v148
	ds_read_b128 v[156:159], v148 offset:1024
	ds_read_b128 v[160:163], v148 offset:2048
	ds_read_b128 v[164:167], v148 offset:3072
	ds_read_b128 v[168:171], v149
	ds_read_b128 v[172:175], v149 offset:1024
	ds_read_b128 v[176:179], v149 offset:2048
	ds_read_b128 v[180:183], v149 offset:3072
	s_add_u32 s40, s38, 0xfff80080
	s_addc_u32 s41, s39, -1
	s_cmp_eq_u32 s65, 28
	s_cselect_b32 s43, s31, s41
	s_cselect_b32 s42, s61, s40
	s_cselect_b32 s41, s29, s64
	s_cselect_b32 s40, s62, s63
	v_lshl_add_u64 v[218:219], s[38:39], 0, v[138:139]
	s_add_i32 m0, s27, 0xc000
	ds_read_b128 v[184:187], v150
	ds_read_b128 v[188:191], v150 offset:1024
	ds_read_b128 v[192:195], v150 offset:2048
	ds_read_b128 v[196:199], v150 offset:3072
	ds_read_b128 v[200:203], v150 offset:4096
	ds_read_b128 v[204:207], v150 offset:5120
	ds_read_b128 v[210:213], v150 offset:6144
	ds_read_b128 v[214:217], v150 offset:7168
	global_load_lds_dwordx4 v[218:219], off
	v_lshl_add_u64 v[218:219], s[38:39], 0, v[140:141]
	s_add_i32 m0, s27, 0xe000
	s_nop 0
	global_load_lds_dwordx4 v[218:219], off
	s_waitcnt vmcnt(8)
	s_waitcnt lgkmcnt(0)
	s_setprio 1
	s_barrier
	v_mfma_f32_16x16x32_bf16 v[126:129], v[152:155], v[184:187], v[126:129]
	v_mfma_f32_16x16x32_bf16 v[122:125], v[160:163], v[184:187], v[122:125]
	v_mfma_f32_16x16x32_bf16 v[118:121], v[152:155], v[192:195], v[118:121]
	v_mfma_f32_16x16x32_bf16 v[114:117], v[160:163], v[192:195], v[114:117]
	v_mfma_f32_16x16x32_bf16 v[102:105], v[152:155], v[200:203], v[102:105]
	v_mfma_f32_16x16x32_bf16 v[98:101], v[160:163], v[200:203], v[98:101]
	v_mfma_f32_16x16x32_bf16 v[86:89], v[152:155], v[210:213], v[86:89]
	v_mfma_f32_16x16x32_bf16 v[82:85], v[160:163], v[210:213], v[82:85]
	v_mfma_f32_16x16x32_bf16 v[126:129], v[156:159], v[188:191], v[126:129]
	v_mfma_f32_16x16x32_bf16 v[122:125], v[164:167], v[188:191], v[122:125]
	v_mfma_f32_16x16x32_bf16 v[118:121], v[156:159], v[196:199], v[118:121]
	v_mfma_f32_16x16x32_bf16 v[114:117], v[164:167], v[196:199], v[114:117]
	v_mfma_f32_16x16x32_bf16 v[102:105], v[156:159], v[204:207], v[102:105]
	v_mfma_f32_16x16x32_bf16 v[98:101], v[164:167], v[204:207], v[98:101]
	v_mfma_f32_16x16x32_bf16 v[86:89], v[156:159], v[214:217], v[86:89]
	v_mfma_f32_16x16x32_bf16 v[82:85], v[164:167], v[214:217], v[82:85]
	v_mfma_f32_16x16x32_bf16 v[110:113], v[168:171], v[184:187], v[110:113]
	v_mfma_f32_16x16x32_bf16 v[106:109], v[176:179], v[184:187], v[106:109]
	v_mfma_f32_16x16x32_bf16 v[94:97], v[168:171], v[192:195], v[94:97]
	v_mfma_f32_16x16x32_bf16 v[90:93], v[176:179], v[192:195], v[90:93]
	v_mfma_f32_16x16x32_bf16 v[78:81], v[168:171], v[200:203], v[78:81]
	v_mfma_f32_16x16x32_bf16 v[74:77], v[176:179], v[200:203], v[74:77]
	v_mfma_f32_16x16x32_bf16 v[70:73], v[168:171], v[210:213], v[70:73]
	v_mfma_f32_16x16x32_bf16 v[66:69], v[176:179], v[210:213], v[66:69]
	v_mfma_f32_16x16x32_bf16 v[110:113], v[172:175], v[188:191], v[110:113]
	v_mfma_f32_16x16x32_bf16 v[106:109], v[180:183], v[188:191], v[106:109]
	v_mfma_f32_16x16x32_bf16 v[94:97], v[172:175], v[196:199], v[94:97]
	v_mfma_f32_16x16x32_bf16 v[90:93], v[180:183], v[196:199], v[90:93]
	v_mfma_f32_16x16x32_bf16 v[78:81], v[172:175], v[204:207], v[78:81]
	v_mfma_f32_16x16x32_bf16 v[74:77], v[180:183], v[204:207], v[74:77]
	v_mfma_f32_16x16x32_bf16 v[70:73], v[172:175], v[214:217], v[70:73]
	v_mfma_f32_16x16x32_bf16 v[66:69], v[180:183], v[214:217], v[66:69]
	s_barrier
	s_setprio 0
	s_add_i32 s66, s54, s44
	v_lshl_add_u64 v[218:219], s[40:41], 0, v[134:135]
	s_mov_b32 m0, s66
	ds_read_b128 v[184:187], v150 offset:16384
	ds_read_b128 v[188:191], v150 offset:17408
	ds_read_b128 v[192:195], v150 offset:18432
	ds_read_b128 v[196:199], v150 offset:19456
	ds_read_b128 v[200:203], v150 offset:20480
	ds_read_b128 v[204:207], v150 offset:21504
	ds_read_b128 v[210:213], v150 offset:22528
	ds_read_b128 v[214:217], v150 offset:23552
	global_load_lds_dwordx4 v[218:219], off
	s_add_i32 m0, s66, 0x2000
	s_add_u32 s66, s40, 0x80000
	v_lshl_add_u64 v[220:221], s[40:41], 0, v[130:131]
	s_addc_u32 s67, s41, 0
	s_add_i32 s68, s55, s44
	global_load_lds_dwordx4 v[220:221], off
	v_lshl_add_u64 v[222:223], s[66:67], 0, v[134:135]
	s_mov_b32 m0, s68
	v_lshl_add_u64 v[224:225], s[42:43], 0, v[132:133]
	global_load_lds_dwordx4 v[222:223], off
	v_lshl_add_u64 v[222:223], s[66:67], 0, v[130:131]
	s_add_i32 m0, s68, 0x2000
	s_nop 0
	global_load_lds_dwordx4 v[222:223], off
	v_lshl_add_u64 v[222:223], s[42:43], 0, v[136:137]
	s_mov_b32 m0, s27
	s_nop 0
	global_load_lds_dwordx4 v[222:223], off
	s_mov_b32 m0, s47
	s_nop 0
	global_load_lds_dwordx4 v[224:225], off
	s_waitcnt vmcnt(8)
	s_waitcnt lgkmcnt(0)
	s_setprio 1
	s_barrier
; #define PG8_STAGE(bufoff, gbase, voff) do { _Pragma("unroll") for (int _i = 0; _i < 2; ++_i) \
;         __builtin_amdgcn_global_load_lds((const unsigned*)((const char*)(gbase) + (voff)[_i]), (PG8_LAS unsigned*)(lds + (bufoff) + ldsw + _i * 8192), 16, 0, 0); } while (0)
; #define PG8_LDA(dst, b, h) do { _Pragma("unroll") for (int m = 0; m < 4; ++m) _Pragma("unroll") for (int k = 0; k < 2; ++k) dst[m][k] = *(const PG8_LAS bf16x8*)(lds + PG8_SA(b, h) + aoff + m * 2048 + k * 1024); } while (0)
; #define PG8_LDB(dst, b, h) do { _Pragma("unroll") for (int n = 0; n < 2; ++n) _Pragma("unroll") for (int k = 0; k < 2; ++k) dst[n][k] = *(const PG8_LAS bf16x8*)(lds + PG8_SB(b, h) + boff + n * 2048 + k * 1024); } while (0)
; #define PG8_MMA(ai, bj, At, Bt) do { __builtin_amdgcn_s_setprio(1); _Pragma("unroll") for (int m = 0; m < 4; ++m) _Pragma("unroll") for (int n = 0; n < 2; ++n) _Pragma("unroll") for (int k = 0; k < 2; ++k) \
;         acc[ai][bj][m][n] = __builtin_amdgcn_mfma_f32_16x16x32_bf16(Bt[n][k], At[m][k], acc[ai][bj][m][n], 0, 0, 0); __builtin_amdgcn_s_setprio(0); } while (0)
; #define PG8_WAIT_V(n) asm volatile("s_waitcnt vmcnt(" #n ")" ::: "memory")
; #define PG8_WAIT_L(n) asm volatile("s_waitcnt lgkmcnt(" #n ")" ::: "memory")
; #define PG8_BAR __builtin_amdgcn_s_barrier()
; #define PG8_SCHED __builtin_amdgcn_sched_barrier(0)
; template <class Epi, class Sched, bool ALIGN_EPI = false, bool SP2 = false>
; __device__ __forceinline__ void gemm_phase(PG8_LAS unsigned char* lds, const Gemm g, const Sched& S, const Epi& E) {
;     ...
;             PG8_WAIT_V(8); PG8_WAIT_L(0); PG8_BAR; PG8_MMA(1, 0, At, B0); PG8_MMA(1, 1, At, B1); PG8_BAR; PG8_SCHED;
;             PG8_LDB(B0, 1, 0); PG8_LDB(B1, 1, 1); PG8_SCHED; PG8_LDA(At, 1, 0); PG8_STAGE(PG8_SA(0, 1), a2 + hstepA, voffA);
;             PG8_WAIT_V(8); PG8_WAIT_L(0); PG8_BAR; PG8_MMA(0, 0, At, B0); PG8_MMA(0, 1, At, B1); PG8_BAR; PG8_SCHED;
	v_mfma_f32_16x16x32_bf16 v[62:65], v[152:155], v[184:187], v[62:65]
	v_mfma_f32_16x16x32_bf16 v[58:61], v[160:163], v[184:187], v[58:61]
	v_mfma_f32_16x16x32_bf16 v[54:57], v[152:155], v[192:195], v[54:57]
	v_mfma_f32_16x16x32_bf16 v[50:53], v[160:163], v[192:195], v[50:53]
	v_mfma_f32_16x16x32_bf16 v[38:41], v[152:155], v[200:203], v[38:41]
	v_mfma_f32_16x16x32_bf16 v[34:37], v[160:163], v[200:203], v[34:37]
	v_mfma_f32_16x16x32_bf16 v[22:25], v[152:155], v[210:213], v[22:25]
	v_mfma_f32_16x16x32_bf16 v[18:21], v[160:163], v[210:213], v[18:21]
	v_mfma_f32_16x16x32_bf16 v[62:65], v[156:159], v[188:191], v[62:65]
	v_mfma_f32_16x16x32_bf16 v[58:61], v[164:167], v[188:191], v[58:61]
	v_mfma_f32_16x16x32_bf16 v[54:57], v[156:159], v[196:199], v[54:57]
	v_mfma_f32_16x16x32_bf16 v[50:53], v[164:167], v[196:199], v[50:53]
	v_mfma_f32_16x16x32_bf16 v[38:41], v[156:159], v[204:207], v[38:41]
	v_mfma_f32_16x16x32_bf16 v[34:37], v[164:167], v[204:207], v[34:37]
	v_mfma_f32_16x16x32_bf16 v[22:25], v[156:159], v[214:217], v[22:25]
	v_mfma_f32_16x16x32_bf16 v[18:21], v[164:167], v[214:217], v[18:21]
	v_mfma_f32_16x16x32_bf16 v[46:49], v[168:171], v[184:187], v[46:49]
	v_mfma_f32_16x16x32_bf16 v[42:45], v[176:179], v[184:187], v[42:45]
	v_mfma_f32_16x16x32_bf16 v[30:33], v[168:171], v[192:195], v[30:33]
	v_mfma_f32_16x16x32_bf16 v[26:29], v[176:179], v[192:195], v[26:29]
	v_mfma_f32_16x16x32_bf16 v[14:17], v[168:171], v[200:203], v[14:17]
	v_mfma_f32_16x16x32_bf16 v[10:13], v[176:179], v[200:203], v[10:13]
	v_mfma_f32_16x16x32_bf16 v[6:9], v[168:171], v[210:213], v[6:9]
	v_mfma_f32_16x16x32_bf16 v[2:5], v[176:179], v[210:213], v[2:5]
	v_mfma_f32_16x16x32_bf16 v[46:49], v[172:175], v[188:191], v[46:49]
	v_mfma_f32_16x16x32_bf16 v[42:45], v[180:183], v[188:191], v[42:45]
	v_mfma_f32_16x16x32_bf16 v[30:33], v[172:175], v[196:199], v[30:33]
	v_mfma_f32_16x16x32_bf16 v[26:29], v[180:183], v[196:199], v[26:29]
	v_mfma_f32_16x16x32_bf16 v[14:17], v[172:175], v[204:207], v[14:17]
	v_mfma_f32_16x16x32_bf16 v[10:13], v[180:183], v[204:207], v[10:13]
	v_mfma_f32_16x16x32_bf16 v[6:9], v[172:175], v[214:217], v[6:9]
	v_mfma_f32_16x16x32_bf16 v[2:5], v[180:183], v[214:217], v[2:5]
	s_barrier
	s_setprio 0
	s_add_i32 s66, 0, 0x18000
	v_add_u32_e32 v151, s66, v146
	s_add_i32 s67, 0, 0x1c000
	ds_read_b128 v[152:155], v151
	ds_read_b128 v[156:159], v151 offset:1024
	ds_read_b128 v[160:163], v151 offset:2048
	ds_read_b128 v[164:167], v151 offset:3072
	v_add_u32_e32 v151, s67, v146
	ds_read_b128 v[168:171], v151
	ds_read_b128 v[172:175], v151 offset:1024
	ds_read_b128 v[176:179], v151 offset:2048
	ds_read_b128 v[180:183], v151 offset:3072
	s_add_u32 s42, s42, 0x80000
	s_addc_u32 s43, s43, 0
	s_mov_b32 m0, s48
	v_lshl_add_u64 v[226:227], s[42:43], 0, v[136:137]
	ds_read_b128 v[184:187], v150 offset:32768
	ds_read_b128 v[188:191], v150 offset:33792
	ds_read_b128 v[192:195], v150 offset:34816
	ds_read_b128 v[196:199], v150 offset:35840
	ds_read_b128 v[200:203], v150 offset:36864
	ds_read_b128 v[204:207], v150 offset:37888
	ds_read_b128 v[210:213], v150 offset:38912
	ds_read_b128 v[214:217], v150 offset:39936
	global_load_lds_dwordx4 v[226:227], off
	v_lshl_add_u64 v[226:227], s[42:43], 0, v[132:133]
	s_mov_b32 m0, s49
	s_nop 0
	global_load_lds_dwordx4 v[226:227], off
	s_waitcnt vmcnt(8)
	s_waitcnt lgkmcnt(0)
	s_setprio 1
	s_barrier
	v_mfma_f32_16x16x32_bf16 v[126:129], v[152:155], v[184:187], v[126:129]
	v_mfma_f32_16x16x32_bf16 v[122:125], v[160:163], v[184:187], v[122:125]
	v_mfma_f32_16x16x32_bf16 v[118:121], v[152:155], v[192:195], v[118:121]
	v_mfma_f32_16x16x32_bf16 v[114:117], v[160:163], v[192:195], v[114:117]
	v_mfma_f32_16x16x32_bf16 v[102:105], v[152:155], v[200:203], v[102:105]
	v_mfma_f32_16x16x32_bf16 v[98:101], v[160:163], v[200:203], v[98:101]
	v_mfma_f32_16x16x32_bf16 v[86:89], v[152:155], v[210:213], v[86:89]
	v_mfma_f32_16x16x32_bf16 v[82:85], v[160:163], v[210:213], v[82:85]
	v_mfma_f32_16x16x32_bf16 v[126:129], v[156:159], v[188:191], v[126:129]
	v_mfma_f32_16x16x32_bf16 v[122:125], v[164:167], v[188:191], v[122:125]
	v_mfma_f32_16x16x32_bf16 v[118:121], v[156:159], v[196:199], v[118:121]
	v_mfma_f32_16x16x32_bf16 v[114:117], v[164:167], v[196:199], v[114:117]
	v_mfma_f32_16x16x32_bf16 v[102:105], v[156:159], v[204:207], v[102:105]
	v_mfma_f32_16x16x32_bf16 v[98:101], v[164:167], v[204:207], v[98:101]
	v_mfma_f32_16x16x32_bf16 v[86:89], v[156:159], v[214:217], v[86:89]
	v_mfma_f32_16x16x32_bf16 v[82:85], v[164:167], v[214:217], v[82:85]
	v_mfma_f32_16x16x32_bf16 v[110:113], v[168:171], v[184:187], v[110:113]
	v_mfma_f32_16x16x32_bf16 v[106:109], v[176:179], v[184:187], v[106:109]
	v_mfma_f32_16x16x32_bf16 v[94:97], v[168:171], v[192:195], v[94:97]
	v_mfma_f32_16x16x32_bf16 v[90:93], v[176:179], v[192:195], v[90:93]
	v_mfma_f32_16x16x32_bf16 v[78:81], v[168:171], v[200:203], v[78:81]
	v_mfma_f32_16x16x32_bf16 v[74:77], v[176:179], v[200:203], v[74:77]
	v_mfma_f32_16x16x32_bf16 v[70:73], v[168:171], v[210:213], v[70:73]
	v_mfma_f32_16x16x32_bf16 v[66:69], v[176:179], v[210:213], v[66:69]
	v_mfma_f32_16x16x32_bf16 v[110:113], v[172:175], v[188:191], v[110:113]
	v_mfma_f32_16x16x32_bf16 v[106:109], v[180:183], v[188:191], v[106:109]
	v_mfma_f32_16x16x32_bf16 v[94:97], v[172:175], v[196:199], v[94:97]
	v_mfma_f32_16x16x32_bf16 v[90:93], v[180:183], v[196:199], v[90:93]
	v_mfma_f32_16x16x32_bf16 v[78:81], v[172:175], v[204:207], v[78:81]
	v_mfma_f32_16x16x32_bf16 v[74:77], v[180:183], v[204:207], v[74:77]
	v_mfma_f32_16x16x32_bf16 v[70:73], v[172:175], v[214:217], v[70:73]
	v_mfma_f32_16x16x32_bf16 v[66:69], v[180:183], v[214:217], v[66:69]
	s_barrier
; #define PG8_STAGE(bufoff, gbase, voff) do { _Pragma("unroll") for (int _i = 0; _i < 2; ++_i) \
;         __builtin_amdgcn_global_load_lds((const unsigned*)((const char*)(gbase) + (voff)[_i]), (PG8_LAS unsigned*)(lds + (bufoff) + ldsw + _i * 8192), 16, 0, 0); } while (0)
; #define PG8_LDA(dst, b, h) do { _Pragma("unroll") for (int m = 0; m < 4; ++m) _Pragma("unroll") for (int k = 0; k < 2; ++k) dst[m][k] = *(const PG8_LAS bf16x8*)(lds + PG8_SA(b, h) + aoff + m * 2048 + k * 1024); } while (0)
; #define PG8_MMA(ai, bj, At, Bt) do { __builtin_amdgcn_s_setprio(1); _Pragma("unroll") for (int m = 0; m < 4; ++m) _Pragma("unroll") for (int n = 0; n < 2; ++n) _Pragma("unroll") for (int k = 0; k < 2; ++k) \
;         acc[ai][bj][m][n] = __builtin_amdgcn_mfma_f32_16x16x32_bf16(Bt[n][k], At[m][k], acc[ai][bj][m][n], 0, 0, 0); __builtin_amdgcn_s_setprio(0); } while (0)
; #define PG8_WAIT_V(n) asm volatile("s_waitcnt vmcnt(" #n ")" ::: "memory")
; #define PG8_WAIT_L(n) asm volatile("s_waitcnt lgkmcnt(" #n ")" ::: "memory")
; #define PG8_BAR __builtin_amdgcn_s_barrier()
; #define PG8_SCHED __builtin_amdgcn_sched_barrier(0)
; template <class Epi, class Sched, bool ALIGN_EPI = false, bool SP2 = false>
; __device__ __forceinline__ void gemm_phase(PG8_LAS unsigned char* lds, const Gemm g, const Sched& S, const Epi& E) {
;     ...
;         for (int t = 0; t < nt; t += 2) {
;     ...
;             PG8_WAIT_V(8); PG8_WAIT_L(0); PG8_BAR; PG8_MMA(0, 0, At, B0); PG8_MMA(0, 1, At, B1); PG8_BAR; PG8_SCHED;
;             PG8_LDA(At, 1, 1); PG8_STAGE(PG8_SB(1, 0), b3, voffB); PG8_STAGE(PG8_SB(1, 1), b3 + hstepB, voffB); PG8_STAGE(PG8_SA(1, 0), a3, voffA);
;             PG8_WAIT_V(8); PG8_WAIT_L(0); PG8_BAR; PG8_MMA(1, 0, At, B0); PG8_MMA(1, 1, At, B1); PG8_BAR; PG8_SCHED;
	s_setprio 0
	s_add_i32 s42, s66, s44
	v_lshl_add_u64 v[218:219], v[218:219], 0, s[10:11]
	s_mov_b32 m0, s42
	ds_read_b128 v[184:187], v150 offset:49152
	ds_read_b128 v[188:191], v150 offset:50176
	ds_read_b128 v[192:195], v150 offset:51200
	ds_read_b128 v[196:199], v150 offset:52224
	ds_read_b128 v[200:203], v150 offset:53248
	ds_read_b128 v[204:207], v150 offset:54272
	ds_read_b128 v[210:213], v150 offset:55296
	ds_read_b128 v[214:217], v150 offset:56320
	global_load_lds_dwordx4 v[218:219], off
	s_add_i32 m0, s42, 0x2000
	s_add_u32 s40, s40, 0x80080
	v_lshl_add_u64 v[218:219], v[220:221], 0, s[10:11]
	s_addc_u32 s41, s41, 0
	s_add_i32 s42, s67, s44
	global_load_lds_dwordx4 v[218:219], off
	v_lshl_add_u64 v[218:219], s[40:41], 0, v[134:135]
	s_mov_b32 m0, s42
	s_nop 0
	global_load_lds_dwordx4 v[218:219], off
	v_lshl_add_u64 v[218:219], s[40:41], 0, v[130:131]
	s_add_i32 m0, s42, 0x2000
	s_nop 0
	global_load_lds_dwordx4 v[218:219], off
	v_lshl_add_u64 v[218:219], v[222:223], 0, s[10:11]
	s_mov_b32 m0, s51
	s_nop 0
	global_load_lds_dwordx4 v[218:219], off
	v_lshl_add_u64 v[218:219], v[224:225], 0, s[10:11]
	s_mov_b32 m0, s52
	s_nop 0
	global_load_lds_dwordx4 v[218:219], off
	s_waitcnt vmcnt(8)
	s_waitcnt lgkmcnt(0)
	s_setprio 1
	s_barrier
	v_mfma_f32_16x16x32_bf16 v[62:65], v[152:155], v[184:187], v[62:65]
	v_mfma_f32_16x16x32_bf16 v[58:61], v[160:163], v[184:187], v[58:61]
	v_mfma_f32_16x16x32_bf16 v[54:57], v[152:155], v[192:195], v[54:57]
	v_mfma_f32_16x16x32_bf16 v[50:53], v[160:163], v[192:195], v[50:53]
	v_mfma_f32_16x16x32_bf16 v[38:41], v[152:155], v[200:203], v[38:41]
	v_mfma_f32_16x16x32_bf16 v[34:37], v[160:163], v[200:203], v[34:37]
	v_mfma_f32_16x16x32_bf16 v[22:25], v[152:155], v[210:213], v[22:25]
	v_mfma_f32_16x16x32_bf16 v[18:21], v[160:163], v[210:213], v[18:21]
	v_mfma_f32_16x16x32_bf16 v[62:65], v[156:159], v[188:191], v[62:65]
	v_mfma_f32_16x16x32_bf16 v[58:61], v[164:167], v[188:191], v[58:61]
	v_mfma_f32_16x16x32_bf16 v[54:57], v[156:159], v[196:199], v[54:57]
	v_mfma_f32_16x16x32_bf16 v[50:53], v[164:167], v[196:199], v[50:53]
	v_mfma_f32_16x16x32_bf16 v[38:41], v[156:159], v[204:207], v[38:41]
	v_mfma_f32_16x16x32_bf16 v[34:37], v[164:167], v[204:207], v[34:37]
	v_mfma_f32_16x16x32_bf16 v[22:25], v[156:159], v[214:217], v[22:25]
	v_mfma_f32_16x16x32_bf16 v[18:21], v[164:167], v[214:217], v[18:21]
	v_mfma_f32_16x16x32_bf16 v[46:49], v[168:171], v[184:187], v[46:49]
	v_mfma_f32_16x16x32_bf16 v[42:45], v[176:179], v[184:187], v[42:45]
	v_mfma_f32_16x16x32_bf16 v[30:33], v[168:171], v[192:195], v[30:33]
	v_mfma_f32_16x16x32_bf16 v[26:29], v[176:179], v[192:195], v[26:29]
	v_mfma_f32_16x16x32_bf16 v[14:17], v[168:171], v[200:203], v[14:17]
	v_mfma_f32_16x16x32_bf16 v[10:13], v[176:179], v[200:203], v[10:13]
	v_mfma_f32_16x16x32_bf16 v[6:9], v[168:171], v[210:213], v[6:9]
	v_mfma_f32_16x16x32_bf16 v[2:5], v[176:179], v[210:213], v[2:5]
	v_mfma_f32_16x16x32_bf16 v[46:49], v[172:175], v[188:191], v[46:49]
	v_mfma_f32_16x16x32_bf16 v[42:45], v[180:183], v[188:191], v[42:45]
	v_mfma_f32_16x16x32_bf16 v[30:33], v[172:175], v[196:199], v[30:33]
	v_mfma_f32_16x16x32_bf16 v[26:29], v[180:183], v[196:199], v[26:29]
	v_mfma_f32_16x16x32_bf16 v[14:17], v[172:175], v[204:207], v[14:17]
	v_mfma_f32_16x16x32_bf16 v[10:13], v[180:183], v[204:207], v[10:13]
	v_mfma_f32_16x16x32_bf16 v[6:9], v[172:175], v[214:217], v[6:9]
	v_mfma_f32_16x16x32_bf16 v[2:5], v[180:183], v[214:217], v[2:5]
	s_barrier
	s_setprio 0
	s_add_i32 s65, s65, 2
	s_add_u32 s38, s38, 0x100
	s_addc_u32 s39, s39, 0
	s_add_u32 s63, s63, 0x100
	s_addc_u32 s64, s64, 0
	s_cmp_gt_u32 s65, 29
	s_cbranch_scc0 .LBB0_802
	s_and_b64 vcc, exec, s[12:13]
	s_cbranch_vccz .LBB0_805
	s_barrier

; #define PG8_STAGE(bufoff, gbase, voff) do { _Pragma("unroll") for (int _i = 0; _i < 2; ++_i) \
;         __builtin_amdgcn_global_load_lds((const unsigned*)((const char*)(gbase) + (voff)[_i]), (PG8_LAS unsigned*)(lds + (bufoff) + ldsw + _i * 8192), 16, 0, 0); } while (0)
; #define PG8_LDA(dst, b, h) do { _Pragma("unroll") for (int m = 0; m < 4; ++m) _Pragma("unroll") for (int k = 0; k < 2; ++k) dst[m][k] = *(const PG8_LAS bf16x8*)(lds + PG8_SA(b, h) + aoff + m * 2048 + k * 1024); } while (0)
; #define PG8_LDB(dst, b, h) do { _Pragma("unroll") for (int n = 0; n < 2; ++n) _Pragma("unroll") for (int k = 0; k < 2; ++k) dst[n][k] = *(const PG8_LAS bf16x8*)(lds + PG8_SB(b, h) + boff + n * 2048 + k * 1024); } while (0)
; #define PG8_MMA(ai, bj, At, Bt) do { __builtin_amdgcn_s_setprio(1); _Pragma("unroll") for (int m = 0; m < 4; ++m) _Pragma("unroll") for (int n = 0; n < 2; ++n) _Pragma("unroll") for (int k = 0; k < 2; ++k) \
;         acc[ai][bj][m][n] = __builtin_amdgcn_mfma_f32_16x16x32_bf16(Bt[n][k], At[m][k], acc[ai][bj][m][n], 0, 0, 0); __builtin_amdgcn_s_setprio(0); } while (0)
; #define PG8_WAIT_V(n) asm volatile("s_waitcnt vmcnt(" #n ")" ::: "memory")
; #define PG8_WAIT_L(n) asm volatile("s_waitcnt lgkmcnt(" #n ")" ::: "memory")
; #define PG8_BAR __builtin_amdgcn_s_barrier()
; #define PG8_SCHED __builtin_amdgcn_sched_barrier(0)
; template <class Epi, class Sched, bool ALIGN_EPI = false, bool SP2 = false>
; __device__ __forceinline__ void gemm_phase(PG8_LAS unsigned char* lds, const Gemm g, const Sched& S, const Epi& E) {
;     ...
;             PG8_LDB(B0, 0, 0); PG8_LDB(B1, 0, 1); PG8_SCHED; PG8_LDA(At, 0, 0); PG8_STAGE(PG8_SA(1, 1), a1 + hstepA, voffA);
;             PG8_WAIT_V(8); PG8_WAIT_L(0); PG8_BAR; PG8_MMA(0, 0, At, B0); PG8_MMA(0, 1, At, B1); PG8_BAR; PG8_SCHED;
;             PG8_LDA(At, 0, 1); PG8_STAGE(PG8_SB(0, 0), b2, voffB); PG8_STAGE(PG8_SB(0, 1), b2 + hstepB, voffB); PG8_STAGE(PG8_SA(0, 0), a2, voffA);
;             PG8_WAIT_V(8); PG8_WAIT_L(0); PG8_BAR; PG8_MMA(1, 0, At, B0); PG8_MMA(1, 1, At, B1); PG8_BAR; PG8_SCHED;
.LBB0_940:
	ds_read_b128 v[154:157], v150
	ds_read_b128 v[158:161], v150 offset:1024
	ds_read_b128 v[162:165], v150 offset:2048
	ds_read_b128 v[166:169], v150 offset:3072
	ds_read_b128 v[170:173], v151
	ds_read_b128 v[174:177], v151 offset:1024
	ds_read_b128 v[178:181], v151 offset:2048
	ds_read_b128 v[182:185], v151 offset:3072
	s_add_u32 s28, s26, 0xfff80080
	s_addc_u32 s29, s27, -1
	s_cmp_eq_u32 s52, 28
	s_cselect_b32 s31, s13, s29
	s_cselect_b32 s30, s48, s28
	s_cselect_b32 s29, s11, s51
	s_cselect_b32 s28, s49, s50
	v_lshl_add_u64 v[146:147], s[26:27], 0, v[138:139]
	s_add_i32 m0, s25, 0xc000
	ds_read_b128 v[186:189], v152
	ds_read_b128 v[190:193], v152 offset:1024
	ds_read_b128 v[194:197], v152 offset:2048
	ds_read_b128 v[198:201], v152 offset:3072
	ds_read_b128 v[202:205], v152 offset:4096
	ds_read_b128 v[210:213], v152 offset:5120
	ds_read_b128 v[214:217], v152 offset:6144
	ds_read_b128 v[218:221], v152 offset:7168
	global_load_lds_dwordx4 v[146:147], off
	v_lshl_add_u64 v[146:147], s[26:27], 0, v[140:141]
	s_add_i32 m0, s25, 0xe000
	s_nop 0
	global_load_lds_dwordx4 v[146:147], off
	s_waitcnt vmcnt(8)
	s_waitcnt lgkmcnt(0)
	s_setprio 1
	s_barrier
	v_mfma_f32_16x16x32_bf16 v[126:129], v[154:157], v[186:189], v[126:129]
	v_mfma_f32_16x16x32_bf16 v[122:125], v[162:165], v[186:189], v[122:125]
	v_mfma_f32_16x16x32_bf16 v[110:113], v[154:157], v[194:197], v[110:113]
	v_mfma_f32_16x16x32_bf16 v[106:109], v[162:165], v[194:197], v[106:109]
	v_mfma_f32_16x16x32_bf16 v[94:97], v[154:157], v[202:205], v[94:97]
	v_mfma_f32_16x16x32_bf16 v[90:93], v[162:165], v[202:205], v[90:93]
	v_mfma_f32_16x16x32_bf16 v[78:81], v[154:157], v[214:217], v[78:81]
	v_mfma_f32_16x16x32_bf16 v[74:77], v[162:165], v[214:217], v[74:77]
	v_mfma_f32_16x16x32_bf16 v[126:129], v[158:161], v[190:193], v[126:129]
	v_mfma_f32_16x16x32_bf16 v[122:125], v[166:169], v[190:193], v[122:125]
	v_mfma_f32_16x16x32_bf16 v[110:113], v[158:161], v[198:201], v[110:113]
	v_mfma_f32_16x16x32_bf16 v[106:109], v[166:169], v[198:201], v[106:109]
	v_mfma_f32_16x16x32_bf16 v[94:97], v[158:161], v[210:213], v[94:97]
	v_mfma_f32_16x16x32_bf16 v[90:93], v[166:169], v[210:213], v[90:93]
	v_mfma_f32_16x16x32_bf16 v[78:81], v[158:161], v[218:221], v[78:81]
	v_mfma_f32_16x16x32_bf16 v[74:77], v[166:169], v[218:221], v[74:77]
	v_mfma_f32_16x16x32_bf16 v[118:121], v[170:173], v[186:189], v[118:121]
	v_mfma_f32_16x16x32_bf16 v[114:117], v[178:181], v[186:189], v[114:117]
	v_mfma_f32_16x16x32_bf16 v[102:105], v[170:173], v[194:197], v[102:105]
	v_mfma_f32_16x16x32_bf16 v[98:101], v[178:181], v[194:197], v[98:101]
	v_mfma_f32_16x16x32_bf16 v[86:89], v[170:173], v[202:205], v[86:89]
	v_mfma_f32_16x16x32_bf16 v[82:85], v[178:181], v[202:205], v[82:85]
	v_mfma_f32_16x16x32_bf16 v[70:73], v[170:173], v[214:217], v[70:73]
	v_mfma_f32_16x16x32_bf16 v[66:69], v[178:181], v[214:217], v[66:69]
	v_mfma_f32_16x16x32_bf16 v[118:121], v[174:177], v[190:193], v[118:121]
	v_mfma_f32_16x16x32_bf16 v[114:117], v[182:185], v[190:193], v[114:117]
	v_mfma_f32_16x16x32_bf16 v[102:105], v[174:177], v[198:201], v[102:105]
	v_mfma_f32_16x16x32_bf16 v[98:101], v[182:185], v[198:201], v[98:101]
	v_mfma_f32_16x16x32_bf16 v[86:89], v[174:177], v[210:213], v[86:89]
	v_mfma_f32_16x16x32_bf16 v[82:85], v[182:185], v[210:213], v[82:85]
	v_mfma_f32_16x16x32_bf16 v[70:73], v[174:177], v[218:221], v[70:73]
	v_mfma_f32_16x16x32_bf16 v[66:69], v[182:185], v[218:221], v[66:69]
	s_barrier
	s_setprio 0
	s_add_i32 s53, s44, s34
	v_lshl_add_u64 v[146:147], s[28:29], 0, v[134:135]
	s_mov_b32 m0, s53
	ds_read_b128 v[186:189], v152 offset:16384
	ds_read_b128 v[190:193], v152 offset:17408
	ds_read_b128 v[194:197], v152 offset:18432
	ds_read_b128 v[198:201], v152 offset:19456
	ds_read_b128 v[202:205], v152 offset:20480
	ds_read_b128 v[210:213], v152 offset:21504
	ds_read_b128 v[214:217], v152 offset:22528
	ds_read_b128 v[218:221], v152 offset:23552
	global_load_lds_dwordx4 v[146:147], off
	s_add_i32 m0, s53, 0x2000
	s_add_u32 s54, s28, 0x80000
	v_lshl_add_u64 v[206:207], s[28:29], 0, v[130:131]
	s_addc_u32 s55, s29, 0
	s_add_i32 s53, s45, s34
	global_load_lds_dwordx4 v[206:207], off
	v_lshl_add_u64 v[222:223], s[54:55], 0, v[134:135]
	s_mov_b32 m0, s53
	v_lshl_add_u64 v[224:225], s[30:31], 0, v[132:133]
	global_load_lds_dwordx4 v[222:223], off
	v_lshl_add_u64 v[222:223], s[54:55], 0, v[130:131]
	s_add_i32 m0, s53, 0x2000
	s_nop 0
	global_load_lds_dwordx4 v[222:223], off
	v_lshl_add_u64 v[222:223], s[30:31], 0, v[136:137]
	s_mov_b32 m0, s25
	s_nop 0
	global_load_lds_dwordx4 v[222:223], off
	s_mov_b32 m0, s37
	s_nop 0
	global_load_lds_dwordx4 v[224:225], off
	s_waitcnt vmcnt(8)
	s_waitcnt lgkmcnt(0)
	s_setprio 1
	s_barrier
; #define PG8_STAGE(bufoff, gbase, voff) do { _Pragma("unroll") for (int _i = 0; _i < 2; ++_i) \
;         __builtin_amdgcn_global_load_lds((const unsigned*)((const char*)(gbase) + (voff)[_i]), (PG8_LAS unsigned*)(lds + (bufoff) + ldsw + _i * 8192), 16, 0, 0); } while (0)
; #define PG8_LDA(dst, b, h) do { _Pragma("unroll") for (int m = 0; m < 4; ++m) _Pragma("unroll") for (int k = 0; k < 2; ++k) dst[m][k] = *(const PG8_LAS bf16x8*)(lds + PG8_SA(b, h) + aoff + m * 2048 + k * 1024); } while (0)
; #define PG8_LDB(dst, b, h) do { _Pragma("unroll") for (int n = 0; n < 2; ++n) _Pragma("unroll") for (int k = 0; k < 2; ++k) dst[n][k] = *(const PG8_LAS bf16x8*)(lds + PG8_SB(b, h) + boff + n * 2048 + k * 1024); } while (0)
; #define PG8_MMA(ai, bj, At, Bt) do { __builtin_amdgcn_s_setprio(1); _Pragma("unroll") for (int m = 0; m < 4; ++m) _Pragma("unroll") for (int n = 0; n < 2; ++n) _Pragma("unroll") for (int k = 0; k < 2; ++k) \
;         acc[ai][bj][m][n] = __builtin_amdgcn_mfma_f32_16x16x32_bf16(Bt[n][k], At[m][k], acc[ai][bj][m][n], 0, 0, 0); __builtin_amdgcn_s_setprio(0); } while (0)
; #define PG8_WAIT_V(n) asm volatile("s_waitcnt vmcnt(" #n ")" ::: "memory")
; #define PG8_WAIT_L(n) asm volatile("s_waitcnt lgkmcnt(" #n ")" ::: "memory")
; #define PG8_BAR __builtin_amdgcn_s_barrier()
; #define PG8_SCHED __builtin_amdgcn_sched_barrier(0)
; template <class Epi, class Sched, bool ALIGN_EPI = false, bool SP2 = false>
; __device__ __forceinline__ void gemm_phase(PG8_LAS unsigned char* lds, const Gemm g, const Sched& S, const Epi& E) {
;     ...
;             PG8_WAIT_V(8); PG8_WAIT_L(0); PG8_BAR; PG8_MMA(1, 0, At, B0); PG8_MMA(1, 1, At, B1); PG8_BAR; PG8_SCHED;
;             PG8_LDB(B0, 1, 0); PG8_LDB(B1, 1, 1); PG8_SCHED; PG8_LDA(At, 1, 0); PG8_STAGE(PG8_SA(0, 1), a2 + hstepA, voffA);
;             PG8_WAIT_V(8); PG8_WAIT_L(0); PG8_BAR; PG8_MMA(0, 0, At, B0); PG8_MMA(0, 1, At, B1); PG8_BAR; PG8_SCHED;
	v_mfma_f32_16x16x32_bf16 v[62:65], v[154:157], v[186:189], v[62:65]
	v_mfma_f32_16x16x32_bf16 v[58:61], v[162:165], v[186:189], v[58:61]
	v_mfma_f32_16x16x32_bf16 v[46:49], v[154:157], v[194:197], v[46:49]
	v_mfma_f32_16x16x32_bf16 v[42:45], v[162:165], v[194:197], v[42:45]
	v_mfma_f32_16x16x32_bf16 v[30:33], v[154:157], v[202:205], v[30:33]
	v_mfma_f32_16x16x32_bf16 v[26:29], v[162:165], v[202:205], v[26:29]
	v_mfma_f32_16x16x32_bf16 v[14:17], v[154:157], v[214:217], v[14:17]
	v_mfma_f32_16x16x32_bf16 v[10:13], v[162:165], v[214:217], v[10:13]
	v_mfma_f32_16x16x32_bf16 v[62:65], v[158:161], v[190:193], v[62:65]
	v_mfma_f32_16x16x32_bf16 v[58:61], v[166:169], v[190:193], v[58:61]
	v_mfma_f32_16x16x32_bf16 v[46:49], v[158:161], v[198:201], v[46:49]
	v_mfma_f32_16x16x32_bf16 v[42:45], v[166:169], v[198:201], v[42:45]
	v_mfma_f32_16x16x32_bf16 v[30:33], v[158:161], v[210:213], v[30:33]
	v_mfma_f32_16x16x32_bf16 v[26:29], v[166:169], v[210:213], v[26:29]
	v_mfma_f32_16x16x32_bf16 v[14:17], v[158:161], v[218:221], v[14:17]
	v_mfma_f32_16x16x32_bf16 v[10:13], v[166:169], v[218:221], v[10:13]
	v_mfma_f32_16x16x32_bf16 v[54:57], v[170:173], v[186:189], v[54:57]
	v_mfma_f32_16x16x32_bf16 v[50:53], v[178:181], v[186:189], v[50:53]
	v_mfma_f32_16x16x32_bf16 v[38:41], v[170:173], v[194:197], v[38:41]
	v_mfma_f32_16x16x32_bf16 v[34:37], v[178:181], v[194:197], v[34:37]
	v_mfma_f32_16x16x32_bf16 v[22:25], v[170:173], v[202:205], v[22:25]
	v_mfma_f32_16x16x32_bf16 v[18:21], v[178:181], v[202:205], v[18:21]
	v_mfma_f32_16x16x32_bf16 v[6:9], v[170:173], v[214:217], v[6:9]
	v_mfma_f32_16x16x32_bf16 v[2:5], v[178:181], v[214:217], v[2:5]
	v_mfma_f32_16x16x32_bf16 v[54:57], v[174:177], v[190:193], v[54:57]
	v_mfma_f32_16x16x32_bf16 v[50:53], v[182:185], v[190:193], v[50:53]
	v_mfma_f32_16x16x32_bf16 v[38:41], v[174:177], v[198:201], v[38:41]
	v_mfma_f32_16x16x32_bf16 v[34:37], v[182:185], v[198:201], v[34:37]
	v_mfma_f32_16x16x32_bf16 v[22:25], v[174:177], v[210:213], v[22:25]
	v_mfma_f32_16x16x32_bf16 v[18:21], v[182:185], v[210:213], v[18:21]
	v_mfma_f32_16x16x32_bf16 v[6:9], v[174:177], v[218:221], v[6:9]
	v_mfma_f32_16x16x32_bf16 v[2:5], v[182:185], v[218:221], v[2:5]
	s_barrier
	s_setprio 0
	s_add_i32 s53, 0, 0x18000
	v_add_u32_e32 v153, s53, v148
	s_add_i32 s54, 0, 0x1c000
	ds_read_b128 v[154:157], v153
	ds_read_b128 v[158:161], v153 offset:1024
	ds_read_b128 v[162:165], v153 offset:2048
	ds_read_b128 v[166:169], v153 offset:3072
	v_add_u32_e32 v153, s54, v148
	ds_read_b128 v[170:173], v153
	ds_read_b128 v[174:177], v153 offset:1024
	ds_read_b128 v[178:181], v153 offset:2048
	ds_read_b128 v[182:185], v153 offset:3072
	s_add_u32 s30, s30, 0x80000
	s_addc_u32 s31, s31, 0
	s_mov_b32 m0, s38
	v_lshl_add_u64 v[226:227], s[30:31], 0, v[136:137]
	ds_read_b128 v[186:189], v152 offset:32768
	ds_read_b128 v[190:193], v152 offset:33792
	ds_read_b128 v[194:197], v152 offset:34816
	ds_read_b128 v[198:201], v152 offset:35840
	ds_read_b128 v[202:205], v152 offset:36864
	ds_read_b128 v[210:213], v152 offset:37888
	ds_read_b128 v[214:217], v152 offset:38912
	ds_read_b128 v[218:221], v152 offset:39936
	global_load_lds_dwordx4 v[226:227], off
	v_lshl_add_u64 v[226:227], s[30:31], 0, v[132:133]
	s_mov_b32 m0, s39
	s_nop 0
	global_load_lds_dwordx4 v[226:227], off
	s_waitcnt vmcnt(8)
	s_waitcnt lgkmcnt(0)
	s_setprio 1
	s_barrier
	v_mfma_f32_16x16x32_bf16 v[126:129], v[154:157], v[186:189], v[126:129]
	v_mfma_f32_16x16x32_bf16 v[122:125], v[162:165], v[186:189], v[122:125]
	v_mfma_f32_16x16x32_bf16 v[110:113], v[154:157], v[194:197], v[110:113]
	v_mfma_f32_16x16x32_bf16 v[106:109], v[162:165], v[194:197], v[106:109]
	v_mfma_f32_16x16x32_bf16 v[94:97], v[154:157], v[202:205], v[94:97]
	v_mfma_f32_16x16x32_bf16 v[90:93], v[162:165], v[202:205], v[90:93]
	v_mfma_f32_16x16x32_bf16 v[78:81], v[154:157], v[214:217], v[78:81]
	v_mfma_f32_16x16x32_bf16 v[74:77], v[162:165], v[214:217], v[74:77]
	v_mfma_f32_16x16x32_bf16 v[126:129], v[158:161], v[190:193], v[126:129]
	v_mfma_f32_16x16x32_bf16 v[122:125], v[166:169], v[190:193], v[122:125]
	v_mfma_f32_16x16x32_bf16 v[110:113], v[158:161], v[198:201], v[110:113]
	v_mfma_f32_16x16x32_bf16 v[106:109], v[166:169], v[198:201], v[106:109]
	v_mfma_f32_16x16x32_bf16 v[94:97], v[158:161], v[210:213], v[94:97]
	v_mfma_f32_16x16x32_bf16 v[90:93], v[166:169], v[210:213], v[90:93]
	v_mfma_f32_16x16x32_bf16 v[78:81], v[158:161], v[218:221], v[78:81]
	v_mfma_f32_16x16x32_bf16 v[74:77], v[166:169], v[218:221], v[74:77]
	v_mfma_f32_16x16x32_bf16 v[118:121], v[170:173], v[186:189], v[118:121]
	v_mfma_f32_16x16x32_bf16 v[114:117], v[178:181], v[186:189], v[114:117]
	v_mfma_f32_16x16x32_bf16 v[102:105], v[170:173], v[194:197], v[102:105]
	v_mfma_f32_16x16x32_bf16 v[98:101], v[178:181], v[194:197], v[98:101]
	v_mfma_f32_16x16x32_bf16 v[86:89], v[170:173], v[202:205], v[86:89]
	v_mfma_f32_16x16x32_bf16 v[82:85], v[178:181], v[202:205], v[82:85]
	v_mfma_f32_16x16x32_bf16 v[70:73], v[170:173], v[214:217], v[70:73]
	v_mfma_f32_16x16x32_bf16 v[66:69], v[178:181], v[214:217], v[66:69]
	v_mfma_f32_16x16x32_bf16 v[118:121], v[174:177], v[190:193], v[118:121]
	v_mfma_f32_16x16x32_bf16 v[114:117], v[182:185], v[190:193], v[114:117]
	v_mfma_f32_16x16x32_bf16 v[102:105], v[174:177], v[198:201], v[102:105]
	v_mfma_f32_16x16x32_bf16 v[98:101], v[182:185], v[198:201], v[98:101]
	v_mfma_f32_16x16x32_bf16 v[86:89], v[174:177], v[210:213], v[86:89]
	v_mfma_f32_16x16x32_bf16 v[82:85], v[182:185], v[210:213], v[82:85]
	v_mfma_f32_16x16x32_bf16 v[70:73], v[174:177], v[218:221], v[70:73]
	v_mfma_f32_16x16x32_bf16 v[66:69], v[182:185], v[218:221], v[66:69]
	s_barrier
; #define PG8_STAGE(bufoff, gbase, voff) do { _Pragma("unroll") for (int _i = 0; _i < 2; ++_i) \
;         __builtin_amdgcn_global_load_lds((const unsigned*)((const char*)(gbase) + (voff)[_i]), (PG8_LAS unsigned*)(lds + (bufoff) + ldsw + _i * 8192), 16, 0, 0); } while (0)
; #define PG8_LDA(dst, b, h) do { _Pragma("unroll") for (int m = 0; m < 4; ++m) _Pragma("unroll") for (int k = 0; k < 2; ++k) dst[m][k] = *(const PG8_LAS bf16x8*)(lds + PG8_SA(b, h) + aoff + m * 2048 + k * 1024); } while (0)
; #define PG8_MMA(ai, bj, At, Bt) do { __builtin_amdgcn_s_setprio(1); _Pragma("unroll") for (int m = 0; m < 4; ++m) _Pragma("unroll") for (int n = 0; n < 2; ++n) _Pragma("unroll") for (int k = 0; k < 2; ++k) \
;         acc[ai][bj][m][n] = __builtin_amdgcn_mfma_f32_16x16x32_bf16(Bt[n][k], At[m][k], acc[ai][bj][m][n], 0, 0, 0); __builtin_amdgcn_s_setprio(0); } while (0)
; #define PG8_WAIT_V(n) asm volatile("s_waitcnt vmcnt(" #n ")" ::: "memory")
; #define PG8_WAIT_L(n) asm volatile("s_waitcnt lgkmcnt(" #n ")" ::: "memory")
; #define PG8_BAR __builtin_amdgcn_s_barrier()
; #define PG8_SCHED __builtin_amdgcn_sched_barrier(0)
; template <class Epi, class Sched, bool ALIGN_EPI = false, bool SP2 = false>
; __device__ __forceinline__ void gemm_phase(PG8_LAS unsigned char* lds, const Gemm g, const Sched& S, const Epi& E) {
;     ...
;         for (int t = 0; t < nt; t += 2) {
;     ...
;             PG8_WAIT_V(8); PG8_WAIT_L(0); PG8_BAR; PG8_MMA(0, 0, At, B0); PG8_MMA(0, 1, At, B1); PG8_BAR; PG8_SCHED;
;             PG8_LDA(At, 1, 1); PG8_STAGE(PG8_SB(1, 0), b3, voffB); PG8_STAGE(PG8_SB(1, 1), b3 + hstepB, voffB); PG8_STAGE(PG8_SA(1, 0), a3, voffA);
;             PG8_WAIT_V(8); PG8_WAIT_L(0); PG8_BAR; PG8_MMA(1, 0, At, B0); PG8_MMA(1, 1, At, B1); PG8_BAR; PG8_SCHED;
	s_setprio 0
	s_add_i32 s30, s53, s34
	v_lshl_add_u64 v[146:147], v[146:147], 0, s[2:3]
	s_mov_b32 m0, s30
	ds_read_b128 v[186:189], v152 offset:49152
	ds_read_b128 v[190:193], v152 offset:50176
	ds_read_b128 v[194:197], v152 offset:51200
	ds_read_b128 v[198:201], v152 offset:52224
	ds_read_b128 v[202:205], v152 offset:53248
	ds_read_b128 v[210:213], v152 offset:54272
	ds_read_b128 v[214:217], v152 offset:55296
	ds_read_b128 v[218:221], v152 offset:56320
	global_load_lds_dwordx4 v[146:147], off
	s_add_i32 m0, s30, 0x2000
	s_add_u32 s28, s28, 0x80080
	v_lshl_add_u64 v[146:147], v[206:207], 0, s[2:3]
	s_addc_u32 s29, s29, 0
	s_add_i32 s30, s54, s34
	global_load_lds_dwordx4 v[146:147], off
	v_lshl_add_u64 v[146:147], s[28:29], 0, v[134:135]
	s_mov_b32 m0, s30
	s_nop 0
	global_load_lds_dwordx4 v[146:147], off
	v_lshl_add_u64 v[146:147], s[28:29], 0, v[130:131]
	s_add_i32 m0, s30, 0x2000
	s_nop 0
	global_load_lds_dwordx4 v[146:147], off
	v_lshl_add_u64 v[146:147], v[222:223], 0, s[2:3]
	s_mov_b32 m0, s41
	s_nop 0
	global_load_lds_dwordx4 v[146:147], off
	v_lshl_add_u64 v[146:147], v[224:225], 0, s[2:3]
	s_mov_b32 m0, s42
	s_nop 0
	global_load_lds_dwordx4 v[146:147], off
	s_waitcnt vmcnt(8)
	s_waitcnt lgkmcnt(0)
	s_setprio 1
	s_barrier
	v_mfma_f32_16x16x32_bf16 v[62:65], v[154:157], v[186:189], v[62:65]
	v_mfma_f32_16x16x32_bf16 v[58:61], v[162:165], v[186:189], v[58:61]
	v_mfma_f32_16x16x32_bf16 v[46:49], v[154:157], v[194:197], v[46:49]
	v_mfma_f32_16x16x32_bf16 v[42:45], v[162:165], v[194:197], v[42:45]
	v_mfma_f32_16x16x32_bf16 v[30:33], v[154:157], v[202:205], v[30:33]
	v_mfma_f32_16x16x32_bf16 v[26:29], v[162:165], v[202:205], v[26:29]
	v_mfma_f32_16x16x32_bf16 v[14:17], v[154:157], v[214:217], v[14:17]
	v_mfma_f32_16x16x32_bf16 v[10:13], v[162:165], v[214:217], v[10:13]
	v_mfma_f32_16x16x32_bf16 v[62:65], v[158:161], v[190:193], v[62:65]
	v_mfma_f32_16x16x32_bf16 v[58:61], v[166:169], v[190:193], v[58:61]
	v_mfma_f32_16x16x32_bf16 v[46:49], v[158:161], v[198:201], v[46:49]
	v_mfma_f32_16x16x32_bf16 v[42:45], v[166:169], v[198:201], v[42:45]
	v_mfma_f32_16x16x32_bf16 v[30:33], v[158:161], v[210:213], v[30:33]
	v_mfma_f32_16x16x32_bf16 v[26:29], v[166:169], v[210:213], v[26:29]
	v_mfma_f32_16x16x32_bf16 v[14:17], v[158:161], v[218:221], v[14:17]
	v_mfma_f32_16x16x32_bf16 v[10:13], v[166:169], v[218:221], v[10:13]
	v_mfma_f32_16x16x32_bf16 v[54:57], v[170:173], v[186:189], v[54:57]
	v_mfma_f32_16x16x32_bf16 v[50:53], v[178:181], v[186:189], v[50:53]
	v_mfma_f32_16x16x32_bf16 v[38:41], v[170:173], v[194:197], v[38:41]
	v_mfma_f32_16x16x32_bf16 v[34:37], v[178:181], v[194:197], v[34:37]
	v_mfma_f32_16x16x32_bf16 v[22:25], v[170:173], v[202:205], v[22:25]
	v_mfma_f32_16x16x32_bf16 v[18:21], v[178:181], v[202:205], v[18:21]
	v_mfma_f32_16x16x32_bf16 v[6:9], v[170:173], v[214:217], v[6:9]
	v_mfma_f32_16x16x32_bf16 v[2:5], v[178:181], v[214:217], v[2:5]
	v_mfma_f32_16x16x32_bf16 v[54:57], v[174:177], v[190:193], v[54:57]
	v_mfma_f32_16x16x32_bf16 v[50:53], v[182:185], v[190:193], v[50:53]
	v_mfma_f32_16x16x32_bf16 v[38:41], v[174:177], v[198:201], v[38:41]
	v_mfma_f32_16x16x32_bf16 v[34:37], v[182:185], v[198:201], v[34:37]
	v_mfma_f32_16x16x32_bf16 v[22:25], v[174:177], v[210:213], v[22:25]
	v_mfma_f32_16x16x32_bf16 v[18:21], v[182:185], v[210:213], v[18:21]
	v_mfma_f32_16x16x32_bf16 v[6:9], v[174:177], v[218:221], v[6:9]
	v_mfma_f32_16x16x32_bf16 v[2:5], v[182:185], v[218:221], v[2:5]
	s_barrier
	s_setprio 0
	s_add_i32 s52, s52, 2
	s_add_u32 s26, s26, 0x100
	s_addc_u32 s27, s27, 0
	s_add_u32 s50, s50, 0x100
	s_addc_u32 s51, s51, 0
	s_cmp_gt_u32 s52, 29
	s_cbranch_scc0 .LBB0_940
	s_and_b64 vcc, exec, s[8:9]
	s_cbranch_vccz .LBB0_943
	s_barrier

; #define PG8_STAGE(bufoff, gbase, voff) do { _Pragma("unroll") for (int _i = 0; _i < 2; ++_i) \
;         __builtin_amdgcn_global_load_lds((const unsigned*)((const char*)(gbase) + (voff)[_i]), (PG8_LAS unsigned*)(lds + (bufoff) + ldsw + _i * 8192), 16, 0, 0); } while (0)
; #define PG8_LDA(dst, b, h) do { _Pragma("unroll") for (int m = 0; m < 4; ++m) _Pragma("unroll") for (int k = 0; k < 2; ++k) dst[m][k] = *(const PG8_LAS bf16x8*)(lds + PG8_SA(b, h) + aoff + m * 2048 + k * 1024); } while (0)
; #define PG8_LDB(dst, b, h) do { _Pragma("unroll") for (int n = 0; n < 2; ++n) _Pragma("unroll") for (int k = 0; k < 2; ++k) dst[n][k] = *(const PG8_LAS bf16x8*)(lds + PG8_SB(b, h) + boff + n * 2048 + k * 1024); } while (0)
; #define PG8_MMA(ai, bj, At, Bt) do { __builtin_amdgcn_s_setprio(1); _Pragma("unroll") for (int m = 0; m < 4; ++m) _Pragma("unroll") for (int n = 0; n < 2; ++n) _Pragma("unroll") for (int k = 0; k < 2; ++k) \
;         acc[ai][bj][m][n] = __builtin_amdgcn_mfma_f32_16x16x32_bf16(Bt[n][k], At[m][k], acc[ai][bj][m][n], 0, 0, 0); __builtin_amdgcn_s_setprio(0); } while (0)
; #define PG8_WAIT_V(n) asm volatile("s_waitcnt vmcnt(" #n ")" ::: "memory")
; #define PG8_WAIT_L(n) asm volatile("s_waitcnt lgkmcnt(" #n ")" ::: "memory")
; #define PG8_BAR __builtin_amdgcn_s_barrier()
; #define PG8_SCHED __builtin_amdgcn_sched_barrier(0)
; template <class Epi, class Sched, bool ALIGN_EPI = false, bool SP2 = false>
; __device__ __forceinline__ void gemm_phase(PG8_LAS unsigned char* lds, const Gemm g, const Sched& S, const Epi& E) {
;     ...
;             PG8_LDB(B0, 0, 0); PG8_LDB(B1, 0, 1); PG8_SCHED; PG8_LDA(At, 0, 0); PG8_STAGE(PG8_SA(1, 1), a1 + hstepA, voffA);
;             PG8_WAIT_V(8); PG8_WAIT_L(0); PG8_BAR; PG8_MMA(0, 0, At, B0); PG8_MMA(0, 1, At, B1); PG8_BAR; PG8_SCHED;
;             PG8_LDA(At, 0, 1); PG8_STAGE(PG8_SB(0, 0), b2, voffB); PG8_STAGE(PG8_SB(0, 1), b2 + hstepB, voffB); PG8_STAGE(PG8_SA(0, 0), a2, voffA);
;             PG8_WAIT_V(8); PG8_WAIT_L(0); PG8_BAR; PG8_MMA(1, 0, At, B0); PG8_MMA(1, 1, At, B1); PG8_BAR; PG8_SCHED;
.LBB0_1033:
	ds_read_b128 v[152:155], v148
	ds_read_b128 v[156:159], v148 offset:1024
	ds_read_b128 v[160:163], v148 offset:2048
	ds_read_b128 v[164:167], v148 offset:3072
	ds_read_b128 v[168:171], v149
	ds_read_b128 v[172:175], v149 offset:1024
	ds_read_b128 v[176:179], v149 offset:2048
	ds_read_b128 v[180:183], v149 offset:3072
	s_add_u32 s30, s28, 0xffea0080
	s_addc_u32 s31, s29, -1
	s_cmpk_eq_i32 s59, 0x54
	s_cselect_b32 s35, s7, s31
	s_cselect_b32 s34, s6, s30
	s_cselect_b32 s31, s27, s58
	s_cselect_b32 s30, s26, s57
	v_lshl_add_u64 v[218:219], s[28:29], 0, v[138:139]
	s_add_i32 m0, s39, 0xc000
	ds_read_b128 v[184:187], v150
	ds_read_b128 v[188:191], v150 offset:1024
	ds_read_b128 v[192:195], v150 offset:2048
	ds_read_b128 v[196:199], v150 offset:3072
	ds_read_b128 v[200:203], v150 offset:4096
	ds_read_b128 v[204:207], v150 offset:5120
	ds_read_b128 v[210:213], v150 offset:6144
	ds_read_b128 v[214:217], v150 offset:7168
	global_load_lds_dwordx4 v[218:219], off
	v_lshl_add_u64 v[218:219], s[28:29], 0, v[140:141]
	s_add_i32 m0, s39, 0xe000
	s_nop 0
	global_load_lds_dwordx4 v[218:219], off
	s_waitcnt vmcnt(8)
	s_waitcnt lgkmcnt(0)
	s_setprio 1
	s_barrier
	v_mfma_f32_16x16x32_bf16 v[126:129], v[152:155], v[184:187], v[126:129]
	v_mfma_f32_16x16x32_bf16 v[122:125], v[160:163], v[184:187], v[122:125]
	v_mfma_f32_16x16x32_bf16 v[118:121], v[152:155], v[192:195], v[118:121]
	v_mfma_f32_16x16x32_bf16 v[114:117], v[160:163], v[192:195], v[114:117]
	v_mfma_f32_16x16x32_bf16 v[102:105], v[152:155], v[200:203], v[102:105]
	v_mfma_f32_16x16x32_bf16 v[98:101], v[160:163], v[200:203], v[98:101]
	v_mfma_f32_16x16x32_bf16 v[86:89], v[152:155], v[210:213], v[86:89]
	v_mfma_f32_16x16x32_bf16 v[82:85], v[160:163], v[210:213], v[82:85]
	v_mfma_f32_16x16x32_bf16 v[126:129], v[156:159], v[188:191], v[126:129]
	v_mfma_f32_16x16x32_bf16 v[122:125], v[164:167], v[188:191], v[122:125]
	v_mfma_f32_16x16x32_bf16 v[118:121], v[156:159], v[196:199], v[118:121]
	v_mfma_f32_16x16x32_bf16 v[114:117], v[164:167], v[196:199], v[114:117]
	v_mfma_f32_16x16x32_bf16 v[102:105], v[156:159], v[204:207], v[102:105]
	v_mfma_f32_16x16x32_bf16 v[98:101], v[164:167], v[204:207], v[98:101]
	v_mfma_f32_16x16x32_bf16 v[86:89], v[156:159], v[214:217], v[86:89]
	v_mfma_f32_16x16x32_bf16 v[82:85], v[164:167], v[214:217], v[82:85]
	v_mfma_f32_16x16x32_bf16 v[110:113], v[168:171], v[184:187], v[110:113]
	v_mfma_f32_16x16x32_bf16 v[106:109], v[176:179], v[184:187], v[106:109]
	v_mfma_f32_16x16x32_bf16 v[94:97], v[168:171], v[192:195], v[94:97]
	v_mfma_f32_16x16x32_bf16 v[90:93], v[176:179], v[192:195], v[90:93]
	v_mfma_f32_16x16x32_bf16 v[78:81], v[168:171], v[200:203], v[78:81]
	v_mfma_f32_16x16x32_bf16 v[74:77], v[176:179], v[200:203], v[74:77]
	v_mfma_f32_16x16x32_bf16 v[70:73], v[168:171], v[210:213], v[70:73]
	v_mfma_f32_16x16x32_bf16 v[66:69], v[176:179], v[210:213], v[66:69]
	v_mfma_f32_16x16x32_bf16 v[110:113], v[172:175], v[188:191], v[110:113]
	v_mfma_f32_16x16x32_bf16 v[106:109], v[180:183], v[188:191], v[106:109]
	v_mfma_f32_16x16x32_bf16 v[94:97], v[172:175], v[196:199], v[94:97]
	v_mfma_f32_16x16x32_bf16 v[90:93], v[180:183], v[196:199], v[90:93]
	v_mfma_f32_16x16x32_bf16 v[78:81], v[172:175], v[204:207], v[78:81]
	v_mfma_f32_16x16x32_bf16 v[74:77], v[180:183], v[204:207], v[74:77]
	v_mfma_f32_16x16x32_bf16 v[70:73], v[172:175], v[214:217], v[70:73]
	v_mfma_f32_16x16x32_bf16 v[66:69], v[180:183], v[214:217], v[66:69]
	s_barrier
	s_setprio 0
	s_add_i32 s60, s47, s36
	v_lshl_add_u64 v[218:219], s[30:31], 0, v[134:135]
	s_mov_b32 m0, s60
	ds_read_b128 v[184:187], v150 offset:16384
	ds_read_b128 v[188:191], v150 offset:17408
	ds_read_b128 v[192:195], v150 offset:18432
	ds_read_b128 v[196:199], v150 offset:19456
	ds_read_b128 v[200:203], v150 offset:20480
	ds_read_b128 v[204:207], v150 offset:21504
	ds_read_b128 v[210:213], v150 offset:22528
	ds_read_b128 v[214:217], v150 offset:23552
	global_load_lds_dwordx4 v[218:219], off
	s_add_i32 m0, s60, 0x2000
	s_add_u32 s60, s30, 0x160000
	v_lshl_add_u64 v[220:221], s[30:31], 0, v[130:131]
	s_addc_u32 s61, s31, 0
	s_add_i32 s62, s48, s36
	global_load_lds_dwordx4 v[220:221], off
	v_lshl_add_u64 v[222:223], s[60:61], 0, v[134:135]
	s_mov_b32 m0, s62
	v_lshl_add_u64 v[224:225], s[34:35], 0, v[132:133]
	global_load_lds_dwordx4 v[222:223], off
	v_lshl_add_u64 v[222:223], s[60:61], 0, v[130:131]
	s_add_i32 m0, s62, 0x2000
	s_nop 0
	global_load_lds_dwordx4 v[222:223], off
	v_lshl_add_u64 v[222:223], s[34:35], 0, v[136:137]
	s_mov_b32 m0, s39
	s_nop 0
	global_load_lds_dwordx4 v[222:223], off
	s_mov_b32 m0, s40
	s_nop 0
	global_load_lds_dwordx4 v[224:225], off
	s_waitcnt vmcnt(8)
	s_waitcnt lgkmcnt(0)
	s_setprio 1
	s_barrier
; #define PG8_STAGE(bufoff, gbase, voff) do { _Pragma("unroll") for (int _i = 0; _i < 2; ++_i) \
;         __builtin_amdgcn_global_load_lds((const unsigned*)((const char*)(gbase) + (voff)[_i]), (PG8_LAS unsigned*)(lds + (bufoff) + ldsw + _i * 8192), 16, 0, 0); } while (0)
; #define PG8_LDA(dst, b, h) do { _Pragma("unroll") for (int m = 0; m < 4; ++m) _Pragma("unroll") for (int k = 0; k < 2; ++k) dst[m][k] = *(const PG8_LAS bf16x8*)(lds + PG8_SA(b, h) + aoff + m * 2048 + k * 1024); } while (0)
; #define PG8_LDB(dst, b, h) do { _Pragma("unroll") for (int n = 0; n < 2; ++n) _Pragma("unroll") for (int k = 0; k < 2; ++k) dst[n][k] = *(const PG8_LAS bf16x8*)(lds + PG8_SB(b, h) + boff + n * 2048 + k * 1024); } while (0)
; #define PG8_MMA(ai, bj, At, Bt) do { __builtin_amdgcn_s_setprio(1); _Pragma("unroll") for (int m = 0; m < 4; ++m) _Pragma("unroll") for (int n = 0; n < 2; ++n) _Pragma("unroll") for (int k = 0; k < 2; ++k) \
;         acc[ai][bj][m][n] = __builtin_amdgcn_mfma_f32_16x16x32_bf16(Bt[n][k], At[m][k], acc[ai][bj][m][n], 0, 0, 0); __builtin_amdgcn_s_setprio(0); } while (0)
; #define PG8_WAIT_V(n) asm volatile("s_waitcnt vmcnt(" #n ")" ::: "memory")
; #define PG8_WAIT_L(n) asm volatile("s_waitcnt lgkmcnt(" #n ")" ::: "memory")
; #define PG8_BAR __builtin_amdgcn_s_barrier()
; #define PG8_SCHED __builtin_amdgcn_sched_barrier(0)
; template <class Epi, class Sched, bool ALIGN_EPI = false, bool SP2 = false>
; __device__ __forceinline__ void gemm_phase(PG8_LAS unsigned char* lds, const Gemm g, const Sched& S, const Epi& E) {
;     ...
;             PG8_WAIT_V(8); PG8_WAIT_L(0); PG8_BAR; PG8_MMA(1, 0, At, B0); PG8_MMA(1, 1, At, B1); PG8_BAR; PG8_SCHED;
;             PG8_LDB(B0, 1, 0); PG8_LDB(B1, 1, 1); PG8_SCHED; PG8_LDA(At, 1, 0); PG8_STAGE(PG8_SA(0, 1), a2 + hstepA, voffA);
;             PG8_WAIT_V(8); PG8_WAIT_L(0); PG8_BAR; PG8_MMA(0, 0, At, B0); PG8_MMA(0, 1, At, B1); PG8_BAR; PG8_SCHED;
	v_mfma_f32_16x16x32_bf16 v[62:65], v[152:155], v[184:187], v[62:65]
	v_mfma_f32_16x16x32_bf16 v[58:61], v[160:163], v[184:187], v[58:61]
	v_mfma_f32_16x16x32_bf16 v[54:57], v[152:155], v[192:195], v[54:57]
	v_mfma_f32_16x16x32_bf16 v[50:53], v[160:163], v[192:195], v[50:53]
	v_mfma_f32_16x16x32_bf16 v[38:41], v[152:155], v[200:203], v[38:41]
	v_mfma_f32_16x16x32_bf16 v[34:37], v[160:163], v[200:203], v[34:37]
	v_mfma_f32_16x16x32_bf16 v[22:25], v[152:155], v[210:213], v[22:25]
	v_mfma_f32_16x16x32_bf16 v[18:21], v[160:163], v[210:213], v[18:21]
	v_mfma_f32_16x16x32_bf16 v[62:65], v[156:159], v[188:191], v[62:65]
	v_mfma_f32_16x16x32_bf16 v[58:61], v[164:167], v[188:191], v[58:61]
	v_mfma_f32_16x16x32_bf16 v[54:57], v[156:159], v[196:199], v[54:57]
	v_mfma_f32_16x16x32_bf16 v[50:53], v[164:167], v[196:199], v[50:53]
	v_mfma_f32_16x16x32_bf16 v[38:41], v[156:159], v[204:207], v[38:41]
	v_mfma_f32_16x16x32_bf16 v[34:37], v[164:167], v[204:207], v[34:37]
	v_mfma_f32_16x16x32_bf16 v[22:25], v[156:159], v[214:217], v[22:25]
	v_mfma_f32_16x16x32_bf16 v[18:21], v[164:167], v[214:217], v[18:21]
	v_mfma_f32_16x16x32_bf16 v[46:49], v[168:171], v[184:187], v[46:49]
	v_mfma_f32_16x16x32_bf16 v[42:45], v[176:179], v[184:187], v[42:45]
	v_mfma_f32_16x16x32_bf16 v[30:33], v[168:171], v[192:195], v[30:33]
	v_mfma_f32_16x16x32_bf16 v[26:29], v[176:179], v[192:195], v[26:29]
	v_mfma_f32_16x16x32_bf16 v[14:17], v[168:171], v[200:203], v[14:17]
	v_mfma_f32_16x16x32_bf16 v[10:13], v[176:179], v[200:203], v[10:13]
	v_mfma_f32_16x16x32_bf16 v[6:9], v[168:171], v[210:213], v[6:9]
	v_mfma_f32_16x16x32_bf16 v[2:5], v[176:179], v[210:213], v[2:5]
	v_mfma_f32_16x16x32_bf16 v[46:49], v[172:175], v[188:191], v[46:49]
	v_mfma_f32_16x16x32_bf16 v[42:45], v[180:183], v[188:191], v[42:45]
	v_mfma_f32_16x16x32_bf16 v[30:33], v[172:175], v[196:199], v[30:33]
	v_mfma_f32_16x16x32_bf16 v[26:29], v[180:183], v[196:199], v[26:29]
	v_mfma_f32_16x16x32_bf16 v[14:17], v[172:175], v[204:207], v[14:17]
	v_mfma_f32_16x16x32_bf16 v[10:13], v[180:183], v[204:207], v[10:13]
	v_mfma_f32_16x16x32_bf16 v[6:9], v[172:175], v[214:217], v[6:9]
	v_mfma_f32_16x16x32_bf16 v[2:5], v[180:183], v[214:217], v[2:5]
	s_barrier
	s_setprio 0
	s_add_i32 s60, 0, 0x18000
	v_add_u32_e32 v151, s60, v146
	s_add_i32 s61, 0, 0x1c000
	ds_read_b128 v[152:155], v151
	ds_read_b128 v[156:159], v151 offset:1024
	ds_read_b128 v[160:163], v151 offset:2048
	ds_read_b128 v[164:167], v151 offset:3072
	v_add_u32_e32 v151, s61, v146
	ds_read_b128 v[168:171], v151
	ds_read_b128 v[172:175], v151 offset:1024
	ds_read_b128 v[176:179], v151 offset:2048
	ds_read_b128 v[180:183], v151 offset:3072
	s_add_u32 s34, s34, 0x160000
	s_addc_u32 s35, s35, 0
	s_mov_b32 m0, s41
	v_lshl_add_u64 v[226:227], s[34:35], 0, v[136:137]
	ds_read_b128 v[184:187], v150 offset:32768
	ds_read_b128 v[188:191], v150 offset:33792
	ds_read_b128 v[192:195], v150 offset:34816
	ds_read_b128 v[196:199], v150 offset:35840
	ds_read_b128 v[200:203], v150 offset:36864
	ds_read_b128 v[204:207], v150 offset:37888
	ds_read_b128 v[210:213], v150 offset:38912
	ds_read_b128 v[214:217], v150 offset:39936
	global_load_lds_dwordx4 v[226:227], off
	v_lshl_add_u64 v[226:227], s[34:35], 0, v[132:133]
	s_mov_b32 m0, s42
	s_nop 0
	global_load_lds_dwordx4 v[226:227], off
	s_waitcnt vmcnt(8)
	s_waitcnt lgkmcnt(0)
	s_setprio 1
	s_barrier
	v_mfma_f32_16x16x32_bf16 v[126:129], v[152:155], v[184:187], v[126:129]
	v_mfma_f32_16x16x32_bf16 v[122:125], v[160:163], v[184:187], v[122:125]
	v_mfma_f32_16x16x32_bf16 v[118:121], v[152:155], v[192:195], v[118:121]
	v_mfma_f32_16x16x32_bf16 v[114:117], v[160:163], v[192:195], v[114:117]
	v_mfma_f32_16x16x32_bf16 v[102:105], v[152:155], v[200:203], v[102:105]
	v_mfma_f32_16x16x32_bf16 v[98:101], v[160:163], v[200:203], v[98:101]
	v_mfma_f32_16x16x32_bf16 v[86:89], v[152:155], v[210:213], v[86:89]
	v_mfma_f32_16x16x32_bf16 v[82:85], v[160:163], v[210:213], v[82:85]
	v_mfma_f32_16x16x32_bf16 v[126:129], v[156:159], v[188:191], v[126:129]
	v_mfma_f32_16x16x32_bf16 v[122:125], v[164:167], v[188:191], v[122:125]
	v_mfma_f32_16x16x32_bf16 v[118:121], v[156:159], v[196:199], v[118:121]
	v_mfma_f32_16x16x32_bf16 v[114:117], v[164:167], v[196:199], v[114:117]
	v_mfma_f32_16x16x32_bf16 v[102:105], v[156:159], v[204:207], v[102:105]
	v_mfma_f32_16x16x32_bf16 v[98:101], v[164:167], v[204:207], v[98:101]
	v_mfma_f32_16x16x32_bf16 v[86:89], v[156:159], v[214:217], v[86:89]
	v_mfma_f32_16x16x32_bf16 v[82:85], v[164:167], v[214:217], v[82:85]
	v_mfma_f32_16x16x32_bf16 v[110:113], v[168:171], v[184:187], v[110:113]
	v_mfma_f32_16x16x32_bf16 v[106:109], v[176:179], v[184:187], v[106:109]
	v_mfma_f32_16x16x32_bf16 v[94:97], v[168:171], v[192:195], v[94:97]
	v_mfma_f32_16x16x32_bf16 v[90:93], v[176:179], v[192:195], v[90:93]
	v_mfma_f32_16x16x32_bf16 v[78:81], v[168:171], v[200:203], v[78:81]
	v_mfma_f32_16x16x32_bf16 v[74:77], v[176:179], v[200:203], v[74:77]
	v_mfma_f32_16x16x32_bf16 v[70:73], v[168:171], v[210:213], v[70:73]
	v_mfma_f32_16x16x32_bf16 v[66:69], v[176:179], v[210:213], v[66:69]
	v_mfma_f32_16x16x32_bf16 v[110:113], v[172:175], v[188:191], v[110:113]
	v_mfma_f32_16x16x32_bf16 v[106:109], v[180:183], v[188:191], v[106:109]
	v_mfma_f32_16x16x32_bf16 v[94:97], v[172:175], v[196:199], v[94:97]
	v_mfma_f32_16x16x32_bf16 v[90:93], v[180:183], v[196:199], v[90:93]
	v_mfma_f32_16x16x32_bf16 v[78:81], v[172:175], v[204:207], v[78:81]
	v_mfma_f32_16x16x32_bf16 v[74:77], v[180:183], v[204:207], v[74:77]
	v_mfma_f32_16x16x32_bf16 v[70:73], v[172:175], v[214:217], v[70:73]
	v_mfma_f32_16x16x32_bf16 v[66:69], v[180:183], v[214:217], v[66:69]
	s_barrier
; #define PG8_STAGE(bufoff, gbase, voff) do { _Pragma("unroll") for (int _i = 0; _i < 2; ++_i) \
;         __builtin_amdgcn_global_load_lds((const unsigned*)((const char*)(gbase) + (voff)[_i]), (PG8_LAS unsigned*)(lds + (bufoff) + ldsw + _i * 8192), 16, 0, 0); } while (0)
; #define PG8_LDA(dst, b, h) do { _Pragma("unroll") for (int m = 0; m < 4; ++m) _Pragma("unroll") for (int k = 0; k < 2; ++k) dst[m][k] = *(const PG8_LAS bf16x8*)(lds + PG8_SA(b, h) + aoff + m * 2048 + k * 1024); } while (0)
; #define PG8_MMA(ai, bj, At, Bt) do { __builtin_amdgcn_s_setprio(1); _Pragma("unroll") for (int m = 0; m < 4; ++m) _Pragma("unroll") for (int n = 0; n < 2; ++n) _Pragma("unroll") for (int k = 0; k < 2; ++k) \
;         acc[ai][bj][m][n] = __builtin_amdgcn_mfma_f32_16x16x32_bf16(Bt[n][k], At[m][k], acc[ai][bj][m][n], 0, 0, 0); __builtin_amdgcn_s_setprio(0); } while (0)
; #define PG8_WAIT_V(n) asm volatile("s_waitcnt vmcnt(" #n ")" ::: "memory")
; #define PG8_WAIT_L(n) asm volatile("s_waitcnt lgkmcnt(" #n ")" ::: "memory")
; #define PG8_BAR __builtin_amdgcn_s_barrier()
; #define PG8_SCHED __builtin_amdgcn_sched_barrier(0)
; template <class Epi, class Sched, bool ALIGN_EPI = false, bool SP2 = false>
; __device__ __forceinline__ void gemm_phase(PG8_LAS unsigned char* lds, const Gemm g, const Sched& S, const Epi& E) {
;     ...
;         for (int t = 0; t < nt; t += 2) {
;     ...
;             PG8_WAIT_V(8); PG8_WAIT_L(0); PG8_BAR; PG8_MMA(0, 0, At, B0); PG8_MMA(0, 1, At, B1); PG8_BAR; PG8_SCHED;
;             PG8_LDA(At, 1, 1); PG8_STAGE(PG8_SB(1, 0), b3, voffB); PG8_STAGE(PG8_SB(1, 1), b3 + hstepB, voffB); PG8_STAGE(PG8_SA(1, 0), a3, voffA);
;             PG8_WAIT_V(8); PG8_WAIT_L(0); PG8_BAR; PG8_MMA(1, 0, At, B0); PG8_MMA(1, 1, At, B1); PG8_BAR; PG8_SCHED;
	s_setprio 0
	s_add_i32 s34, s60, s36
	v_lshl_add_u64 v[218:219], v[218:219], 0, s[8:9]
	s_mov_b32 m0, s34
	ds_read_b128 v[184:187], v150 offset:49152
	ds_read_b128 v[188:191], v150 offset:50176
	ds_read_b128 v[192:195], v150 offset:51200
	ds_read_b128 v[196:199], v150 offset:52224
	ds_read_b128 v[200:203], v150 offset:53248
	ds_read_b128 v[204:207], v150 offset:54272
	ds_read_b128 v[210:213], v150 offset:55296
	ds_read_b128 v[214:217], v150 offset:56320
	global_load_lds_dwordx4 v[218:219], off
	s_add_i32 m0, s34, 0x2000
	s_add_u32 s30, s30, 0x160080
	v_lshl_add_u64 v[218:219], v[220:221], 0, s[8:9]
	s_addc_u32 s31, s31, 0
	s_add_i32 s34, s61, s36
	global_load_lds_dwordx4 v[218:219], off
	v_lshl_add_u64 v[218:219], s[30:31], 0, v[134:135]
	s_mov_b32 m0, s34
	s_nop 0
	global_load_lds_dwordx4 v[218:219], off
	v_lshl_add_u64 v[218:219], s[30:31], 0, v[130:131]
	s_add_i32 m0, s34, 0x2000
	s_nop 0
	global_load_lds_dwordx4 v[218:219], off
	v_lshl_add_u64 v[218:219], v[222:223], 0, s[8:9]
	s_mov_b32 m0, s44
	s_nop 0
	global_load_lds_dwordx4 v[218:219], off
	v_lshl_add_u64 v[218:219], v[224:225], 0, s[8:9]
	s_mov_b32 m0, s45
	s_nop 0
	global_load_lds_dwordx4 v[218:219], off
	s_waitcnt vmcnt(8)
	s_waitcnt lgkmcnt(0)
	s_setprio 1
	s_barrier
	v_mfma_f32_16x16x32_bf16 v[62:65], v[152:155], v[184:187], v[62:65]
	v_mfma_f32_16x16x32_bf16 v[58:61], v[160:163], v[184:187], v[58:61]
	v_mfma_f32_16x16x32_bf16 v[54:57], v[152:155], v[192:195], v[54:57]
	v_mfma_f32_16x16x32_bf16 v[50:53], v[160:163], v[192:195], v[50:53]
	v_mfma_f32_16x16x32_bf16 v[38:41], v[152:155], v[200:203], v[38:41]
	v_mfma_f32_16x16x32_bf16 v[34:37], v[160:163], v[200:203], v[34:37]
	v_mfma_f32_16x16x32_bf16 v[22:25], v[152:155], v[210:213], v[22:25]
	v_mfma_f32_16x16x32_bf16 v[18:21], v[160:163], v[210:213], v[18:21]
	v_mfma_f32_16x16x32_bf16 v[62:65], v[156:159], v[188:191], v[62:65]
	v_mfma_f32_16x16x32_bf16 v[58:61], v[164:167], v[188:191], v[58:61]
	v_mfma_f32_16x16x32_bf16 v[54:57], v[156:159], v[196:199], v[54:57]
	v_mfma_f32_16x16x32_bf16 v[50:53], v[164:167], v[196:199], v[50:53]
	v_mfma_f32_16x16x32_bf16 v[38:41], v[156:159], v[204:207], v[38:41]
	v_mfma_f32_16x16x32_bf16 v[34:37], v[164:167], v[204:207], v[34:37]
	v_mfma_f32_16x16x32_bf16 v[22:25], v[156:159], v[214:217], v[22:25]
	v_mfma_f32_16x16x32_bf16 v[18:21], v[164:167], v[214:217], v[18:21]
	v_mfma_f32_16x16x32_bf16 v[46:49], v[168:171], v[184:187], v[46:49]
	v_mfma_f32_16x16x32_bf16 v[42:45], v[176:179], v[184:187], v[42:45]
	v_mfma_f32_16x16x32_bf16 v[30:33], v[168:171], v[192:195], v[30:33]
	v_mfma_f32_16x16x32_bf16 v[26:29], v[176:179], v[192:195], v[26:29]
	v_mfma_f32_16x16x32_bf16 v[14:17], v[168:171], v[200:203], v[14:17]
	v_mfma_f32_16x16x32_bf16 v[10:13], v[176:179], v[200:203], v[10:13]
	v_mfma_f32_16x16x32_bf16 v[6:9], v[168:171], v[210:213], v[6:9]
	v_mfma_f32_16x16x32_bf16 v[2:5], v[176:179], v[210:213], v[2:5]
	v_mfma_f32_16x16x32_bf16 v[46:49], v[172:175], v[188:191], v[46:49]
	v_mfma_f32_16x16x32_bf16 v[42:45], v[180:183], v[188:191], v[42:45]
	v_mfma_f32_16x16x32_bf16 v[30:33], v[172:175], v[196:199], v[30:33]
	v_mfma_f32_16x16x32_bf16 v[26:29], v[180:183], v[196:199], v[26:29]
	v_mfma_f32_16x16x32_bf16 v[14:17], v[172:175], v[204:207], v[14:17]
	v_mfma_f32_16x16x32_bf16 v[10:13], v[180:183], v[204:207], v[10:13]
	v_mfma_f32_16x16x32_bf16 v[6:9], v[172:175], v[214:217], v[6:9]
	v_mfma_f32_16x16x32_bf16 v[2:5], v[180:183], v[214:217], v[2:5]
	s_barrier
	s_setprio 0
	s_add_i32 s59, s59, 2
	s_add_u32 s28, s28, 0x100
	s_addc_u32 s29, s29, 0
	s_add_u32 s57, s57, 0x100
	s_addc_u32 s58, s58, 0
	s_cmpk_gt_u32 s59, 0x55
	s_cbranch_scc0 .LBB0_1033
	s_and_b64 vcc, exec, s[10:11]
	s_cbranch_vccz .LBB0_1036
	s_barrier

; #define PG8_STAGE(bufoff, gbase, voff) do { _Pragma("unroll") for (int _i = 0; _i < 2; ++_i) \
;         __builtin_amdgcn_global_load_lds((const unsigned*)((const char*)(gbase) + (voff)[_i]), (PG8_LAS unsigned*)(lds + (bufoff) + ldsw + _i * 8192), 16, 0, 0); } while (0)
; #define PG8_LDA(dst, b, h) do { _Pragma("unroll") for (int m = 0; m < 4; ++m) _Pragma("unroll") for (int k = 0; k < 2; ++k) dst[m][k] = *(const PG8_LAS bf16x8*)(lds + PG8_SA(b, h) + aoff + m * 2048 + k * 1024); } while (0)
; #define PG8_LDB(dst, b, h) do { _Pragma("unroll") for (int n = 0; n < 2; ++n) _Pragma("unroll") for (int k = 0; k < 2; ++k) dst[n][k] = *(const PG8_LAS bf16x8*)(lds + PG8_SB(b, h) + boff + n * 2048 + k * 1024); } while (0)
; #define PG8_MMA(ai, bj, At, Bt) do { __builtin_amdgcn_s_setprio(1); _Pragma("unroll") for (int m = 0; m < 4; ++m) _Pragma("unroll") for (int n = 0; n < 2; ++n) _Pragma("unroll") for (int k = 0; k < 2; ++k) \
;         acc[ai][bj][m][n] = __builtin_amdgcn_mfma_f32_16x16x32_bf16(Bt[n][k], At[m][k], acc[ai][bj][m][n], 0, 0, 0); __builtin_amdgcn_s_setprio(0); } while (0)
; #define PG8_WAIT_V(n) asm volatile("s_waitcnt vmcnt(" #n ")" ::: "memory")
; #define PG8_WAIT_L(n) asm volatile("s_waitcnt lgkmcnt(" #n ")" ::: "memory")
; #define PG8_BAR __builtin_amdgcn_s_barrier()
; #define PG8_SCHED __builtin_amdgcn_sched_barrier(0)
; template <class Epi, class Sched, bool ALIGN_EPI = false, bool SP2 = false>
; __device__ __forceinline__ void gemm_phase(PG8_LAS unsigned char* lds, const Gemm g, const Sched& S, const Epi& E) {
;     ...
;             PG8_LDB(B0, 0, 0); PG8_LDB(B1, 0, 1); PG8_SCHED; PG8_LDA(At, 0, 0); PG8_STAGE(PG8_SA(1, 1), a1 + hstepA, voffA);
;             PG8_WAIT_V(8); PG8_WAIT_L(0); PG8_BAR; PG8_MMA(0, 0, At, B0); PG8_MMA(0, 1, At, B1); PG8_BAR; PG8_SCHED;
;             PG8_LDA(At, 0, 1); PG8_STAGE(PG8_SB(0, 0), b2, voffB); PG8_STAGE(PG8_SB(0, 1), b2 + hstepB, voffB); PG8_STAGE(PG8_SA(0, 0), a2, voffA);
;             PG8_WAIT_V(8); PG8_WAIT_L(0); PG8_BAR; PG8_MMA(1, 0, At, B0); PG8_MMA(1, 1, At, B1); PG8_BAR; PG8_SCHED;
.LBB0_1163:
	ds_read_b128 v[152:155], v149
	ds_read_b128 v[156:159], v149 offset:1024
	ds_read_b128 v[160:163], v149 offset:2048
	ds_read_b128 v[164:167], v149 offset:3072
	ds_read_b128 v[168:171], v150
	ds_read_b128 v[172:175], v150 offset:1024
	ds_read_b128 v[176:179], v150 offset:2048
	ds_read_b128 v[180:183], v150 offset:3072
	s_add_u32 s36, s6, 0xfffd0080
	s_addc_u32 s37, s7, -1
	s_cmp_eq_u32 s60, 4
	s_cselect_b32 s39, s31, s37
	s_cselect_b32 s38, s30, s36
	s_cselect_b32 s37, s29, s59
	s_cselect_b32 s36, s57, s58
	v_lshl_add_u64 v[218:219], s[6:7], 0, v[140:141]
	s_add_i32 m0, s42, 0xc000
	ds_read_b128 v[184:187], v151
	ds_read_b128 v[188:191], v151 offset:1024
	ds_read_b128 v[192:195], v151 offset:2048
	ds_read_b128 v[196:199], v151 offset:3072
	ds_read_b128 v[200:203], v151 offset:4096
	ds_read_b128 v[204:207], v151 offset:5120
	ds_read_b128 v[210:213], v151 offset:6144
	ds_read_b128 v[214:217], v151 offset:7168
	global_load_lds_dwordx4 v[218:219], off
	v_lshl_add_u64 v[218:219], s[6:7], 0, v[142:143]
	s_add_i32 m0, s42, 0xe000
	s_nop 0
	global_load_lds_dwordx4 v[218:219], off
	s_waitcnt vmcnt(8)
	s_waitcnt lgkmcnt(0)
	s_setprio 1
	s_barrier
	v_mfma_f32_16x16x32_bf16 v[126:129], v[152:155], v[184:187], v[126:129]
	v_mfma_f32_16x16x32_bf16 v[122:125], v[160:163], v[184:187], v[122:125]
	v_mfma_f32_16x16x32_bf16 v[118:121], v[152:155], v[192:195], v[118:121]
	v_mfma_f32_16x16x32_bf16 v[114:117], v[160:163], v[192:195], v[114:117]
	v_mfma_f32_16x16x32_bf16 v[106:109], v[152:155], v[200:203], v[106:109]
	v_mfma_f32_16x16x32_bf16 v[98:101], v[160:163], v[200:203], v[98:101]
	v_mfma_f32_16x16x32_bf16 v[90:93], v[152:155], v[210:213], v[90:93]
	v_mfma_f32_16x16x32_bf16 v[82:85], v[160:163], v[210:213], v[82:85]
	v_mfma_f32_16x16x32_bf16 v[126:129], v[156:159], v[188:191], v[126:129]
	v_mfma_f32_16x16x32_bf16 v[122:125], v[164:167], v[188:191], v[122:125]
	v_mfma_f32_16x16x32_bf16 v[118:121], v[156:159], v[196:199], v[118:121]
	v_mfma_f32_16x16x32_bf16 v[114:117], v[164:167], v[196:199], v[114:117]
	v_mfma_f32_16x16x32_bf16 v[106:109], v[156:159], v[204:207], v[106:109]
	v_mfma_f32_16x16x32_bf16 v[98:101], v[164:167], v[204:207], v[98:101]
	v_mfma_f32_16x16x32_bf16 v[90:93], v[156:159], v[214:217], v[90:93]
	v_mfma_f32_16x16x32_bf16 v[82:85], v[164:167], v[214:217], v[82:85]
	v_mfma_f32_16x16x32_bf16 v[110:113], v[168:171], v[184:187], v[110:113]
	v_mfma_f32_16x16x32_bf16 v[102:105], v[176:179], v[184:187], v[102:105]
	v_mfma_f32_16x16x32_bf16 v[94:97], v[168:171], v[192:195], v[94:97]
	v_mfma_f32_16x16x32_bf16 v[86:89], v[176:179], v[192:195], v[86:89]
	v_mfma_f32_16x16x32_bf16 v[78:81], v[168:171], v[200:203], v[78:81]
	v_mfma_f32_16x16x32_bf16 v[74:77], v[176:179], v[200:203], v[74:77]
	v_mfma_f32_16x16x32_bf16 v[70:73], v[168:171], v[210:213], v[70:73]
	v_mfma_f32_16x16x32_bf16 v[66:69], v[176:179], v[210:213], v[66:69]
	v_mfma_f32_16x16x32_bf16 v[110:113], v[172:175], v[188:191], v[110:113]
	v_mfma_f32_16x16x32_bf16 v[102:105], v[180:183], v[188:191], v[102:105]
	v_mfma_f32_16x16x32_bf16 v[94:97], v[172:175], v[196:199], v[94:97]
	v_mfma_f32_16x16x32_bf16 v[86:89], v[180:183], v[196:199], v[86:89]
	v_mfma_f32_16x16x32_bf16 v[78:81], v[172:175], v[204:207], v[78:81]
	v_mfma_f32_16x16x32_bf16 v[74:77], v[180:183], v[204:207], v[74:77]
	v_mfma_f32_16x16x32_bf16 v[70:73], v[172:175], v[214:217], v[70:73]
	v_mfma_f32_16x16x32_bf16 v[66:69], v[180:183], v[214:217], v[66:69]
	s_barrier
	s_setprio 0
	s_add_i32 s61, s51, s40
	v_lshl_add_u64 v[218:219], s[36:37], 0, v[134:135]
	s_mov_b32 m0, s61
	ds_read_b128 v[184:187], v151 offset:16384
	ds_read_b128 v[188:191], v151 offset:17408
	ds_read_b128 v[192:195], v151 offset:18432
	ds_read_b128 v[196:199], v151 offset:19456
	ds_read_b128 v[200:203], v151 offset:20480
	ds_read_b128 v[204:207], v151 offset:21504
	ds_read_b128 v[210:213], v151 offset:22528
	ds_read_b128 v[214:217], v151 offset:23552
	global_load_lds_dwordx4 v[218:219], off
	s_add_i32 m0, s61, 0x2000
	s_add_u32 s62, s36, 0x20000
	v_lshl_add_u64 v[220:221], s[36:37], 0, v[130:131]
	s_addc_u32 s63, s37, 0
	s_add_i32 s61, s52, s40
	global_load_lds_dwordx4 v[220:221], off
	v_lshl_add_u64 v[222:223], s[62:63], 0, v[134:135]
	s_mov_b32 m0, s61
	v_lshl_add_u64 v[224:225], s[38:39], 0, v[132:133]
	global_load_lds_dwordx4 v[222:223], off
	v_lshl_add_u64 v[222:223], s[62:63], 0, v[130:131]
	s_add_i32 m0, s61, 0x2000
	s_nop 0
	global_load_lds_dwordx4 v[222:223], off
	v_lshl_add_u64 v[222:223], s[38:39], 0, v[136:137]
	s_mov_b32 m0, s42
	s_nop 0
	global_load_lds_dwordx4 v[222:223], off
	s_mov_b32 m0, s43
	s_nop 0
	global_load_lds_dwordx4 v[224:225], off
	s_waitcnt vmcnt(8)
	s_waitcnt lgkmcnt(0)
	s_setprio 1
	s_barrier
; #define PG8_STAGE(bufoff, gbase, voff) do { _Pragma("unroll") for (int _i = 0; _i < 2; ++_i) \
;         __builtin_amdgcn_global_load_lds((const unsigned*)((const char*)(gbase) + (voff)[_i]), (PG8_LAS unsigned*)(lds + (bufoff) + ldsw + _i * 8192), 16, 0, 0); } while (0)
; #define PG8_LDA(dst, b, h) do { _Pragma("unroll") for (int m = 0; m < 4; ++m) _Pragma("unroll") for (int k = 0; k < 2; ++k) dst[m][k] = *(const PG8_LAS bf16x8*)(lds + PG8_SA(b, h) + aoff + m * 2048 + k * 1024); } while (0)
; #define PG8_LDB(dst, b, h) do { _Pragma("unroll") for (int n = 0; n < 2; ++n) _Pragma("unroll") for (int k = 0; k < 2; ++k) dst[n][k] = *(const PG8_LAS bf16x8*)(lds + PG8_SB(b, h) + boff + n * 2048 + k * 1024); } while (0)
; #define PG8_MMA(ai, bj, At, Bt) do { __builtin_amdgcn_s_setprio(1); _Pragma("unroll") for (int m = 0; m < 4; ++m) _Pragma("unroll") for (int n = 0; n < 2; ++n) _Pragma("unroll") for (int k = 0; k < 2; ++k) \
;         acc[ai][bj][m][n] = __builtin_amdgcn_mfma_f32_16x16x32_bf16(Bt[n][k], At[m][k], acc[ai][bj][m][n], 0, 0, 0); __builtin_amdgcn_s_setprio(0); } while (0)
; #define PG8_WAIT_V(n) asm volatile("s_waitcnt vmcnt(" #n ")" ::: "memory")
; #define PG8_WAIT_L(n) asm volatile("s_waitcnt lgkmcnt(" #n ")" ::: "memory")
; #define PG8_BAR __builtin_amdgcn_s_barrier()
; #define PG8_SCHED __builtin_amdgcn_sched_barrier(0)
; template <class Epi, class Sched, bool ALIGN_EPI = false, bool SP2 = false>
; __device__ __forceinline__ void gemm_phase(PG8_LAS unsigned char* lds, const Gemm g, const Sched& S, const Epi& E) {
;     ...
;             PG8_WAIT_V(8); PG8_WAIT_L(0); PG8_BAR; PG8_MMA(1, 0, At, B0); PG8_MMA(1, 1, At, B1); PG8_BAR; PG8_SCHED;
;             PG8_LDB(B0, 1, 0); PG8_LDB(B1, 1, 1); PG8_SCHED; PG8_LDA(At, 1, 0); PG8_STAGE(PG8_SA(0, 1), a2 + hstepA, voffA);
;             PG8_WAIT_V(8); PG8_WAIT_L(0); PG8_BAR; PG8_MMA(0, 0, At, B0); PG8_MMA(0, 1, At, B1); PG8_BAR; PG8_SCHED;
	v_mfma_f32_16x16x32_bf16 v[62:65], v[152:155], v[184:187], v[62:65]
	v_mfma_f32_16x16x32_bf16 v[58:61], v[160:163], v[184:187], v[58:61]
	v_mfma_f32_16x16x32_bf16 v[54:57], v[152:155], v[192:195], v[54:57]
	v_mfma_f32_16x16x32_bf16 v[50:53], v[160:163], v[192:195], v[50:53]
	v_mfma_f32_16x16x32_bf16 v[42:45], v[152:155], v[200:203], v[42:45]
	v_mfma_f32_16x16x32_bf16 v[34:37], v[160:163], v[200:203], v[34:37]
	v_mfma_f32_16x16x32_bf16 v[26:29], v[152:155], v[210:213], v[26:29]
	v_mfma_f32_16x16x32_bf16 v[18:21], v[160:163], v[210:213], v[18:21]
	v_mfma_f32_16x16x32_bf16 v[62:65], v[156:159], v[188:191], v[62:65]
	v_mfma_f32_16x16x32_bf16 v[58:61], v[164:167], v[188:191], v[58:61]
	v_mfma_f32_16x16x32_bf16 v[54:57], v[156:159], v[196:199], v[54:57]
	v_mfma_f32_16x16x32_bf16 v[50:53], v[164:167], v[196:199], v[50:53]
	v_mfma_f32_16x16x32_bf16 v[42:45], v[156:159], v[204:207], v[42:45]
	v_mfma_f32_16x16x32_bf16 v[34:37], v[164:167], v[204:207], v[34:37]
	v_mfma_f32_16x16x32_bf16 v[26:29], v[156:159], v[214:217], v[26:29]
	v_mfma_f32_16x16x32_bf16 v[18:21], v[164:167], v[214:217], v[18:21]
	v_mfma_f32_16x16x32_bf16 v[46:49], v[168:171], v[184:187], v[46:49]
	v_mfma_f32_16x16x32_bf16 v[38:41], v[176:179], v[184:187], v[38:41]
	v_mfma_f32_16x16x32_bf16 v[30:33], v[168:171], v[192:195], v[30:33]
	v_mfma_f32_16x16x32_bf16 v[22:25], v[176:179], v[192:195], v[22:25]
	v_mfma_f32_16x16x32_bf16 v[14:17], v[168:171], v[200:203], v[14:17]
	v_mfma_f32_16x16x32_bf16 v[10:13], v[176:179], v[200:203], v[10:13]
	v_mfma_f32_16x16x32_bf16 v[6:9], v[168:171], v[210:213], v[6:9]
	v_mfma_f32_16x16x32_bf16 v[2:5], v[176:179], v[210:213], v[2:5]
	v_mfma_f32_16x16x32_bf16 v[46:49], v[172:175], v[188:191], v[46:49]
	v_mfma_f32_16x16x32_bf16 v[38:41], v[180:183], v[188:191], v[38:41]
	v_mfma_f32_16x16x32_bf16 v[30:33], v[172:175], v[196:199], v[30:33]
	v_mfma_f32_16x16x32_bf16 v[22:25], v[180:183], v[196:199], v[22:25]
	v_mfma_f32_16x16x32_bf16 v[14:17], v[172:175], v[204:207], v[14:17]
	v_mfma_f32_16x16x32_bf16 v[10:13], v[180:183], v[204:207], v[10:13]
	v_mfma_f32_16x16x32_bf16 v[6:9], v[172:175], v[214:217], v[6:9]
	v_mfma_f32_16x16x32_bf16 v[2:5], v[180:183], v[214:217], v[2:5]
	s_barrier
	s_setprio 0
	s_add_i32 s61, 0, 0x18000
	s_add_i32 s62, 0, 0x1c000
	v_add_u32_e32 v164, s61, v148
	v_add_u32_e32 v180, s62, v148
	ds_read_b128 v[152:155], v164
	ds_read_b128 v[156:159], v164 offset:1024
	ds_read_b128 v[160:163], v164 offset:2048
	ds_read_b128 v[164:167], v164 offset:3072
	ds_read_b128 v[168:171], v180
	ds_read_b128 v[172:175], v180 offset:1024
	ds_read_b128 v[176:179], v180 offset:2048
	ds_read_b128 v[180:183], v180 offset:3072
	s_add_u32 s38, s38, 0x30000
	s_addc_u32 s39, s39, 0
	s_mov_b32 m0, s44
	v_lshl_add_u64 v[226:227], s[38:39], 0, v[136:137]
	ds_read_b128 v[184:187], v151 offset:32768
	ds_read_b128 v[188:191], v151 offset:33792
	ds_read_b128 v[192:195], v151 offset:34816
	ds_read_b128 v[196:199], v151 offset:35840
	ds_read_b128 v[200:203], v151 offset:36864
	ds_read_b128 v[204:207], v151 offset:37888
	ds_read_b128 v[210:213], v151 offset:38912
	ds_read_b128 v[214:217], v151 offset:39936
	global_load_lds_dwordx4 v[226:227], off
	v_lshl_add_u64 v[226:227], s[38:39], 0, v[132:133]
	s_mov_b32 m0, s45
	s_nop 0
	global_load_lds_dwordx4 v[226:227], off
	s_waitcnt vmcnt(8)
	s_waitcnt lgkmcnt(0)
	s_setprio 1
	s_barrier
	v_mfma_f32_16x16x32_bf16 v[126:129], v[152:155], v[184:187], v[126:129]
	v_mfma_f32_16x16x32_bf16 v[122:125], v[160:163], v[184:187], v[122:125]
	v_mfma_f32_16x16x32_bf16 v[118:121], v[152:155], v[192:195], v[118:121]
	v_mfma_f32_16x16x32_bf16 v[114:117], v[160:163], v[192:195], v[114:117]
	v_mfma_f32_16x16x32_bf16 v[106:109], v[152:155], v[200:203], v[106:109]
	v_mfma_f32_16x16x32_bf16 v[98:101], v[160:163], v[200:203], v[98:101]
	v_mfma_f32_16x16x32_bf16 v[90:93], v[152:155], v[210:213], v[90:93]
	v_mfma_f32_16x16x32_bf16 v[82:85], v[160:163], v[210:213], v[82:85]
	v_mfma_f32_16x16x32_bf16 v[126:129], v[156:159], v[188:191], v[126:129]
	v_mfma_f32_16x16x32_bf16 v[122:125], v[164:167], v[188:191], v[122:125]
	v_mfma_f32_16x16x32_bf16 v[118:121], v[156:159], v[196:199], v[118:121]
	v_mfma_f32_16x16x32_bf16 v[114:117], v[164:167], v[196:199], v[114:117]
	v_mfma_f32_16x16x32_bf16 v[106:109], v[156:159], v[204:207], v[106:109]
	v_mfma_f32_16x16x32_bf16 v[98:101], v[164:167], v[204:207], v[98:101]
	v_mfma_f32_16x16x32_bf16 v[90:93], v[156:159], v[214:217], v[90:93]
	v_mfma_f32_16x16x32_bf16 v[82:85], v[164:167], v[214:217], v[82:85]
	v_mfma_f32_16x16x32_bf16 v[110:113], v[168:171], v[184:187], v[110:113]
	v_mfma_f32_16x16x32_bf16 v[102:105], v[176:179], v[184:187], v[102:105]
	v_mfma_f32_16x16x32_bf16 v[94:97], v[168:171], v[192:195], v[94:97]
	v_mfma_f32_16x16x32_bf16 v[86:89], v[176:179], v[192:195], v[86:89]
	v_mfma_f32_16x16x32_bf16 v[78:81], v[168:171], v[200:203], v[78:81]
	v_mfma_f32_16x16x32_bf16 v[74:77], v[176:179], v[200:203], v[74:77]
	v_mfma_f32_16x16x32_bf16 v[70:73], v[168:171], v[210:213], v[70:73]
	v_mfma_f32_16x16x32_bf16 v[66:69], v[176:179], v[210:213], v[66:69]
	v_mfma_f32_16x16x32_bf16 v[110:113], v[172:175], v[188:191], v[110:113]
	v_mfma_f32_16x16x32_bf16 v[102:105], v[180:183], v[188:191], v[102:105]
	v_mfma_f32_16x16x32_bf16 v[94:97], v[172:175], v[196:199], v[94:97]
	v_mfma_f32_16x16x32_bf16 v[86:89], v[180:183], v[196:199], v[86:89]
	v_mfma_f32_16x16x32_bf16 v[78:81], v[172:175], v[204:207], v[78:81]
	v_mfma_f32_16x16x32_bf16 v[74:77], v[180:183], v[204:207], v[74:77]
	v_mfma_f32_16x16x32_bf16 v[70:73], v[172:175], v[214:217], v[70:73]
	v_mfma_f32_16x16x32_bf16 v[66:69], v[180:183], v[214:217], v[66:69]
	s_barrier
; #define PG8_STAGE(bufoff, gbase, voff) do { _Pragma("unroll") for (int _i = 0; _i < 2; ++_i) \
;         __builtin_amdgcn_global_load_lds((const unsigned*)((const char*)(gbase) + (voff)[_i]), (PG8_LAS unsigned*)(lds + (bufoff) + ldsw + _i * 8192), 16, 0, 0); } while (0)
; #define PG8_LDA(dst, b, h) do { _Pragma("unroll") for (int m = 0; m < 4; ++m) _Pragma("unroll") for (int k = 0; k < 2; ++k) dst[m][k] = *(const PG8_LAS bf16x8*)(lds + PG8_SA(b, h) + aoff + m * 2048 + k * 1024); } while (0)
; #define PG8_MMA(ai, bj, At, Bt) do { __builtin_amdgcn_s_setprio(1); _Pragma("unroll") for (int m = 0; m < 4; ++m) _Pragma("unroll") for (int n = 0; n < 2; ++n) _Pragma("unroll") for (int k = 0; k < 2; ++k) \
;         acc[ai][bj][m][n] = __builtin_amdgcn_mfma_f32_16x16x32_bf16(Bt[n][k], At[m][k], acc[ai][bj][m][n], 0, 0, 0); __builtin_amdgcn_s_setprio(0); } while (0)
; #define PG8_WAIT_V(n) asm volatile("s_waitcnt vmcnt(" #n ")" ::: "memory")
; #define PG8_WAIT_L(n) asm volatile("s_waitcnt lgkmcnt(" #n ")" ::: "memory")
; #define PG8_BAR __builtin_amdgcn_s_barrier()
; #define PG8_SCHED __builtin_amdgcn_sched_barrier(0)
; template <class Epi, class Sched, bool ALIGN_EPI = false, bool SP2 = false>
; __device__ __forceinline__ void gemm_phase(PG8_LAS unsigned char* lds, const Gemm g, const Sched& S, const Epi& E) {
;     ...
;         for (int t = 0; t < nt; t += 2) {
;     ...
;             PG8_WAIT_V(8); PG8_WAIT_L(0); PG8_BAR; PG8_MMA(0, 0, At, B0); PG8_MMA(0, 1, At, B1); PG8_BAR; PG8_SCHED;
;             PG8_LDA(At, 1, 1); PG8_STAGE(PG8_SB(1, 0), b3, voffB); PG8_STAGE(PG8_SB(1, 1), b3 + hstepB, voffB); PG8_STAGE(PG8_SA(1, 0), a3, voffA);
;             PG8_WAIT_V(8); PG8_WAIT_L(0); PG8_BAR; PG8_MMA(1, 0, At, B0); PG8_MMA(1, 1, At, B1); PG8_BAR; PG8_SCHED;
	s_setprio 0
	s_add_i32 s38, s61, s40
	v_lshl_add_u64 v[218:219], v[218:219], 0, s[12:13]
	s_mov_b32 m0, s38
	ds_read_b128 v[184:187], v151 offset:49152
	ds_read_b128 v[188:191], v151 offset:50176
	ds_read_b128 v[192:195], v151 offset:51200
	ds_read_b128 v[196:199], v151 offset:52224
	ds_read_b128 v[200:203], v151 offset:53248
	ds_read_b128 v[204:207], v151 offset:54272
	ds_read_b128 v[210:213], v151 offset:55296
	ds_read_b128 v[214:217], v151 offset:56320
	global_load_lds_dwordx4 v[218:219], off
	s_add_i32 m0, s38, 0x2000
	s_add_u32 s36, s36, 0x20080
	v_lshl_add_u64 v[218:219], v[220:221], 0, s[12:13]
	s_addc_u32 s37, s37, 0
	s_add_i32 s38, s62, s40
	global_load_lds_dwordx4 v[218:219], off
	v_lshl_add_u64 v[218:219], s[36:37], 0, v[134:135]
	s_mov_b32 m0, s38
	s_nop 0
	global_load_lds_dwordx4 v[218:219], off
	v_lshl_add_u64 v[218:219], s[36:37], 0, v[130:131]
	s_add_i32 m0, s38, 0x2000
	s_nop 0
	global_load_lds_dwordx4 v[218:219], off
	v_lshl_add_u64 v[218:219], v[222:223], 0, s[12:13]
	s_mov_b32 m0, s48
	s_nop 0
	global_load_lds_dwordx4 v[218:219], off
	v_lshl_add_u64 v[218:219], v[224:225], 0, s[12:13]
	s_mov_b32 m0, s49
	s_nop 0
	global_load_lds_dwordx4 v[218:219], off
	s_waitcnt vmcnt(8)
	s_waitcnt lgkmcnt(0)
	s_setprio 1
	s_barrier
	v_mfma_f32_16x16x32_bf16 v[62:65], v[152:155], v[184:187], v[62:65]
	v_mfma_f32_16x16x32_bf16 v[58:61], v[160:163], v[184:187], v[58:61]
	v_mfma_f32_16x16x32_bf16 v[54:57], v[152:155], v[192:195], v[54:57]
	v_mfma_f32_16x16x32_bf16 v[50:53], v[160:163], v[192:195], v[50:53]
	v_mfma_f32_16x16x32_bf16 v[42:45], v[152:155], v[200:203], v[42:45]
	v_mfma_f32_16x16x32_bf16 v[34:37], v[160:163], v[200:203], v[34:37]
	v_mfma_f32_16x16x32_bf16 v[26:29], v[152:155], v[210:213], v[26:29]
	v_mfma_f32_16x16x32_bf16 v[18:21], v[160:163], v[210:213], v[18:21]
	v_mfma_f32_16x16x32_bf16 v[62:65], v[156:159], v[188:191], v[62:65]
	v_mfma_f32_16x16x32_bf16 v[58:61], v[164:167], v[188:191], v[58:61]
	v_mfma_f32_16x16x32_bf16 v[54:57], v[156:159], v[196:199], v[54:57]
	v_mfma_f32_16x16x32_bf16 v[50:53], v[164:167], v[196:199], v[50:53]
	v_mfma_f32_16x16x32_bf16 v[42:45], v[156:159], v[204:207], v[42:45]
	v_mfma_f32_16x16x32_bf16 v[34:37], v[164:167], v[204:207], v[34:37]
	v_mfma_f32_16x16x32_bf16 v[26:29], v[156:159], v[214:217], v[26:29]
	v_mfma_f32_16x16x32_bf16 v[18:21], v[164:167], v[214:217], v[18:21]
	v_mfma_f32_16x16x32_bf16 v[46:49], v[168:171], v[184:187], v[46:49]
	v_mfma_f32_16x16x32_bf16 v[38:41], v[176:179], v[184:187], v[38:41]
	v_mfma_f32_16x16x32_bf16 v[30:33], v[168:171], v[192:195], v[30:33]
	v_mfma_f32_16x16x32_bf16 v[22:25], v[176:179], v[192:195], v[22:25]
	v_mfma_f32_16x16x32_bf16 v[14:17], v[168:171], v[200:203], v[14:17]
	v_mfma_f32_16x16x32_bf16 v[10:13], v[176:179], v[200:203], v[10:13]
	v_mfma_f32_16x16x32_bf16 v[6:9], v[168:171], v[210:213], v[6:9]
	v_mfma_f32_16x16x32_bf16 v[2:5], v[176:179], v[210:213], v[2:5]
	v_mfma_f32_16x16x32_bf16 v[46:49], v[172:175], v[188:191], v[46:49]
	v_mfma_f32_16x16x32_bf16 v[38:41], v[180:183], v[188:191], v[38:41]
	v_mfma_f32_16x16x32_bf16 v[30:33], v[172:175], v[196:199], v[30:33]
	v_mfma_f32_16x16x32_bf16 v[22:25], v[180:183], v[196:199], v[22:25]
	v_mfma_f32_16x16x32_bf16 v[14:17], v[172:175], v[204:207], v[14:17]
	v_mfma_f32_16x16x32_bf16 v[10:13], v[180:183], v[204:207], v[10:13]
	v_mfma_f32_16x16x32_bf16 v[6:9], v[172:175], v[214:217], v[6:9]
	v_mfma_f32_16x16x32_bf16 v[2:5], v[180:183], v[214:217], v[2:5]
	s_barrier
	s_setprio 0
	s_add_i32 s60, s60, 2
	s_add_u32 s6, s6, 0x100
	s_addc_u32 s7, s7, 0
	s_add_u32 s58, s58, 0x100
	s_addc_u32 s59, s59, 0
	s_cmp_gt_u32 s60, 5
	s_cbranch_scc0 .LBB0_1163
	s_and_b64 vcc, exec, s[14:15]
	s_cbranch_vccz .LBB0_1166
	s_barrier

; #define PG8_STAGE(bufoff, gbase, voff) do { _Pragma("unroll") for (int _i = 0; _i < 2; ++_i) \
;         __builtin_amdgcn_global_load_lds((const unsigned*)((const char*)(gbase) + (voff)[_i]), (PG8_LAS unsigned*)(lds + (bufoff) + ldsw + _i * 8192), 16, 0, 0); } while (0)
; #define PG8_LDA(dst, b, h) do { _Pragma("unroll") for (int m = 0; m < 4; ++m) _Pragma("unroll") for (int k = 0; k < 2; ++k) dst[m][k] = *(const PG8_LAS bf16x8*)(lds + PG8_SA(b, h) + aoff + m * 2048 + k * 1024); } while (0)
; #define PG8_LDB(dst, b, h) do { _Pragma("unroll") for (int n = 0; n < 2; ++n) _Pragma("unroll") for (int k = 0; k < 2; ++k) dst[n][k] = *(const PG8_LAS bf16x8*)(lds + PG8_SB(b, h) + boff + n * 2048 + k * 1024); } while (0)
; #define PG8_MMA(ai, bj, At, Bt) do { __builtin_amdgcn_s_setprio(1); _Pragma("unroll") for (int m = 0; m < 4; ++m) _Pragma("unroll") for (int n = 0; n < 2; ++n) _Pragma("unroll") for (int k = 0; k < 2; ++k) \
;         acc[ai][bj][m][n] = __builtin_amdgcn_mfma_f32_16x16x32_bf16(Bt[n][k], At[m][k], acc[ai][bj][m][n], 0, 0, 0); __builtin_amdgcn_s_setprio(0); } while (0)
; #define PG8_WAIT_V(n) asm volatile("s_waitcnt vmcnt(" #n ")" ::: "memory")
; #define PG8_WAIT_L(n) asm volatile("s_waitcnt lgkmcnt(" #n ")" ::: "memory")
; #define PG8_BAR __builtin_amdgcn_s_barrier()
; #define PG8_SCHED __builtin_amdgcn_sched_barrier(0)
; template <class Epi, class Sched, bool ALIGN_EPI = false, bool SP2 = false>
; __device__ __forceinline__ void gemm_phase(PG8_LAS unsigned char* lds, const Gemm g, const Sched& S, const Epi& E) {
;     ...
;             PG8_LDB(B0, 0, 0); PG8_LDB(B1, 0, 1); PG8_SCHED; PG8_LDA(At, 0, 0); PG8_STAGE(PG8_SA(1, 1), a1 + hstepA, voffA);
;             PG8_WAIT_V(8); PG8_WAIT_L(0); PG8_BAR; PG8_MMA(0, 0, At, B0); PG8_MMA(0, 1, At, B1); PG8_BAR; PG8_SCHED;
;             PG8_LDA(At, 0, 1); PG8_STAGE(PG8_SB(0, 0), b2, voffB); PG8_STAGE(PG8_SB(0, 1), b2 + hstepB, voffB); PG8_STAGE(PG8_SA(0, 0), a2, voffA);
;             PG8_WAIT_V(8); PG8_WAIT_L(0); PG8_BAR; PG8_MMA(1, 0, At, B0); PG8_MMA(1, 1, At, B1); PG8_BAR; PG8_SCHED;
.LBB0_1290:
	ds_read_b128 v[154:157], v150
	ds_read_b128 v[158:161], v150 offset:1024
	ds_read_b128 v[162:165], v150 offset:2048
	ds_read_b128 v[166:169], v150 offset:3072
	ds_read_b128 v[170:173], v151
	ds_read_b128 v[174:177], v151 offset:1024
	ds_read_b128 v[178:181], v151 offset:2048
	ds_read_b128 v[182:185], v151 offset:3072
	s_add_u32 s2, s0, 0xfffd0080
	s_addc_u32 s3, s1, -1
	s_cmp_eq_u32 s42, 8
	s_cselect_b32 s21, s7, s3
	s_cselect_b32 s20, s6, s2
	s_cselect_b32 s3, s17, s41
	s_cselect_b32 s2, s16, s40
	v_lshl_add_u64 v[206:207], s[0:1], 0, v[140:141]
	s_add_i32 m0, s25, 0xc000
	ds_read_b128 v[186:189], v152
	ds_read_b128 v[190:193], v152 offset:1024
	ds_read_b128 v[194:197], v152 offset:2048
	ds_read_b128 v[198:201], v152 offset:3072
	ds_read_b128 v[202:205], v152 offset:4096
	ds_read_b128 v[210:213], v152 offset:5120
	ds_read_b128 v[214:217], v152 offset:6144
	ds_read_b128 v[218:221], v152 offset:7168
	global_load_lds_dwordx4 v[206:207], off
	v_lshl_add_u64 v[206:207], s[0:1], 0, v[142:143]
	s_add_i32 m0, s25, 0xe000
	s_nop 0
	global_load_lds_dwordx4 v[206:207], off
	s_waitcnt vmcnt(8)
	s_waitcnt lgkmcnt(0)
	s_setprio 1
	s_barrier
	v_mfma_f32_16x16x32_bf16 v[126:129], v[154:157], v[186:189], v[126:129]
	v_mfma_f32_16x16x32_bf16 v[122:125], v[162:165], v[186:189], v[122:125]
	v_mfma_f32_16x16x32_bf16 v[110:113], v[154:157], v[194:197], v[110:113]
	v_mfma_f32_16x16x32_bf16 v[106:109], v[162:165], v[194:197], v[106:109]
	v_mfma_f32_16x16x32_bf16 v[94:97], v[154:157], v[202:205], v[94:97]
	v_mfma_f32_16x16x32_bf16 v[90:93], v[162:165], v[202:205], v[90:93]
	v_mfma_f32_16x16x32_bf16 v[78:81], v[154:157], v[214:217], v[78:81]
	v_mfma_f32_16x16x32_bf16 v[74:77], v[162:165], v[214:217], v[74:77]
	v_mfma_f32_16x16x32_bf16 v[126:129], v[158:161], v[190:193], v[126:129]
	v_mfma_f32_16x16x32_bf16 v[122:125], v[166:169], v[190:193], v[122:125]
	v_mfma_f32_16x16x32_bf16 v[110:113], v[158:161], v[198:201], v[110:113]
	v_mfma_f32_16x16x32_bf16 v[106:109], v[166:169], v[198:201], v[106:109]
	v_mfma_f32_16x16x32_bf16 v[94:97], v[158:161], v[210:213], v[94:97]
	v_mfma_f32_16x16x32_bf16 v[90:93], v[166:169], v[210:213], v[90:93]
	v_mfma_f32_16x16x32_bf16 v[78:81], v[158:161], v[218:221], v[78:81]
	v_mfma_f32_16x16x32_bf16 v[74:77], v[166:169], v[218:221], v[74:77]
	v_mfma_f32_16x16x32_bf16 v[118:121], v[170:173], v[186:189], v[118:121]
	v_mfma_f32_16x16x32_bf16 v[114:117], v[178:181], v[186:189], v[114:117]
	v_mfma_f32_16x16x32_bf16 v[102:105], v[170:173], v[194:197], v[102:105]
	v_mfma_f32_16x16x32_bf16 v[98:101], v[178:181], v[194:197], v[98:101]
	v_mfma_f32_16x16x32_bf16 v[86:89], v[170:173], v[202:205], v[86:89]
	v_mfma_f32_16x16x32_bf16 v[82:85], v[178:181], v[202:205], v[82:85]
	v_mfma_f32_16x16x32_bf16 v[70:73], v[170:173], v[214:217], v[70:73]
	v_mfma_f32_16x16x32_bf16 v[66:69], v[178:181], v[214:217], v[66:69]
	v_mfma_f32_16x16x32_bf16 v[118:121], v[174:177], v[190:193], v[118:121]
	v_mfma_f32_16x16x32_bf16 v[114:117], v[182:185], v[190:193], v[114:117]
	v_mfma_f32_16x16x32_bf16 v[102:105], v[174:177], v[198:201], v[102:105]
	v_mfma_f32_16x16x32_bf16 v[98:101], v[182:185], v[198:201], v[98:101]
	v_mfma_f32_16x16x32_bf16 v[86:89], v[174:177], v[210:213], v[86:89]
	v_mfma_f32_16x16x32_bf16 v[82:85], v[182:185], v[210:213], v[82:85]
	v_mfma_f32_16x16x32_bf16 v[70:73], v[174:177], v[218:221], v[70:73]
	v_mfma_f32_16x16x32_bf16 v[66:69], v[182:185], v[218:221], v[66:69]
	s_barrier
	s_setprio 0
	s_add_i32 s43, s34, s23
	v_lshl_add_u64 v[206:207], s[2:3], 0, v[134:135]
	s_mov_b32 m0, s43
	ds_read_b128 v[186:189], v152 offset:16384
	ds_read_b128 v[190:193], v152 offset:17408
	ds_read_b128 v[194:197], v152 offset:18432
	ds_read_b128 v[198:201], v152 offset:19456
	ds_read_b128 v[202:205], v152 offset:20480
	ds_read_b128 v[210:213], v152 offset:21504
	ds_read_b128 v[214:217], v152 offset:22528
	ds_read_b128 v[218:221], v152 offset:23552
	global_load_lds_dwordx4 v[206:207], off
	s_add_i32 m0, s43, 0x2000
	s_add_u32 s44, s2, 0x30000
	v_lshl_add_u64 v[222:223], s[2:3], 0, v[130:131]
	s_addc_u32 s45, s3, 0
	s_add_i32 s43, s35, s23
	global_load_lds_dwordx4 v[222:223], off
	v_lshl_add_u64 v[224:225], s[44:45], 0, v[134:135]
	s_mov_b32 m0, s43
	v_lshl_add_u64 v[226:227], s[20:21], 0, v[132:133]
	global_load_lds_dwordx4 v[224:225], off
	v_lshl_add_u64 v[224:225], s[44:45], 0, v[130:131]
	s_add_i32 m0, s43, 0x2000
	s_nop 0
	global_load_lds_dwordx4 v[224:225], off
	v_lshl_add_u64 v[224:225], s[20:21], 0, v[136:137]
	s_mov_b32 m0, s25
	s_nop 0
	global_load_lds_dwordx4 v[224:225], off
	s_mov_b32 m0, s26
	s_nop 0
	global_load_lds_dwordx4 v[226:227], off
	s_waitcnt vmcnt(8)
	s_waitcnt lgkmcnt(0)
	s_setprio 1
	s_barrier
; #define PG8_STAGE(bufoff, gbase, voff) do { _Pragma("unroll") for (int _i = 0; _i < 2; ++_i) \
;         __builtin_amdgcn_global_load_lds((const unsigned*)((const char*)(gbase) + (voff)[_i]), (PG8_LAS unsigned*)(lds + (bufoff) + ldsw + _i * 8192), 16, 0, 0); } while (0)
; #define PG8_LDA(dst, b, h) do { _Pragma("unroll") for (int m = 0; m < 4; ++m) _Pragma("unroll") for (int k = 0; k < 2; ++k) dst[m][k] = *(const PG8_LAS bf16x8*)(lds + PG8_SA(b, h) + aoff + m * 2048 + k * 1024); } while (0)
; #define PG8_LDB(dst, b, h) do { _Pragma("unroll") for (int n = 0; n < 2; ++n) _Pragma("unroll") for (int k = 0; k < 2; ++k) dst[n][k] = *(const PG8_LAS bf16x8*)(lds + PG8_SB(b, h) + boff + n * 2048 + k * 1024); } while (0)
; #define PG8_MMA(ai, bj, At, Bt) do { __builtin_amdgcn_s_setprio(1); _Pragma("unroll") for (int m = 0; m < 4; ++m) _Pragma("unroll") for (int n = 0; n < 2; ++n) _Pragma("unroll") for (int k = 0; k < 2; ++k) \
;         acc[ai][bj][m][n] = __builtin_amdgcn_mfma_f32_16x16x32_bf16(Bt[n][k], At[m][k], acc[ai][bj][m][n], 0, 0, 0); __builtin_amdgcn_s_setprio(0); } while (0)
; #define PG8_WAIT_V(n) asm volatile("s_waitcnt vmcnt(" #n ")" ::: "memory")
; #define PG8_WAIT_L(n) asm volatile("s_waitcnt lgkmcnt(" #n ")" ::: "memory")
; #define PG8_BAR __builtin_amdgcn_s_barrier()
; #define PG8_SCHED __builtin_amdgcn_sched_barrier(0)
; template <class Epi, class Sched, bool ALIGN_EPI = false, bool SP2 = false>
; __device__ __forceinline__ void gemm_phase(PG8_LAS unsigned char* lds, const Gemm g, const Sched& S, const Epi& E) {
;     ...
;             PG8_WAIT_V(8); PG8_WAIT_L(0); PG8_BAR; PG8_MMA(1, 0, At, B0); PG8_MMA(1, 1, At, B1); PG8_BAR; PG8_SCHED;
;             PG8_LDB(B0, 1, 0); PG8_LDB(B1, 1, 1); PG8_SCHED; PG8_LDA(At, 1, 0); PG8_STAGE(PG8_SA(0, 1), a2 + hstepA, voffA);
;             PG8_WAIT_V(8); PG8_WAIT_L(0); PG8_BAR; PG8_MMA(0, 0, At, B0); PG8_MMA(0, 1, At, B1); PG8_BAR; PG8_SCHED;
	v_mfma_f32_16x16x32_bf16 v[62:65], v[154:157], v[186:189], v[62:65]
	v_mfma_f32_16x16x32_bf16 v[58:61], v[162:165], v[186:189], v[58:61]
	v_mfma_f32_16x16x32_bf16 v[46:49], v[154:157], v[194:197], v[46:49]
	v_mfma_f32_16x16x32_bf16 v[42:45], v[162:165], v[194:197], v[42:45]
	v_mfma_f32_16x16x32_bf16 v[30:33], v[154:157], v[202:205], v[30:33]
	v_mfma_f32_16x16x32_bf16 v[26:29], v[162:165], v[202:205], v[26:29]
	v_mfma_f32_16x16x32_bf16 v[14:17], v[154:157], v[214:217], v[14:17]
	v_mfma_f32_16x16x32_bf16 v[10:13], v[162:165], v[214:217], v[10:13]
	v_mfma_f32_16x16x32_bf16 v[62:65], v[158:161], v[190:193], v[62:65]
	v_mfma_f32_16x16x32_bf16 v[58:61], v[166:169], v[190:193], v[58:61]
	v_mfma_f32_16x16x32_bf16 v[46:49], v[158:161], v[198:201], v[46:49]
	v_mfma_f32_16x16x32_bf16 v[42:45], v[166:169], v[198:201], v[42:45]
	v_mfma_f32_16x16x32_bf16 v[30:33], v[158:161], v[210:213], v[30:33]
	v_mfma_f32_16x16x32_bf16 v[26:29], v[166:169], v[210:213], v[26:29]
	v_mfma_f32_16x16x32_bf16 v[14:17], v[158:161], v[218:221], v[14:17]
	v_mfma_f32_16x16x32_bf16 v[10:13], v[166:169], v[218:221], v[10:13]
	v_mfma_f32_16x16x32_bf16 v[54:57], v[170:173], v[186:189], v[54:57]
	v_mfma_f32_16x16x32_bf16 v[50:53], v[178:181], v[186:189], v[50:53]
	v_mfma_f32_16x16x32_bf16 v[38:41], v[170:173], v[194:197], v[38:41]
	v_mfma_f32_16x16x32_bf16 v[34:37], v[178:181], v[194:197], v[34:37]
	v_mfma_f32_16x16x32_bf16 v[22:25], v[170:173], v[202:205], v[22:25]
	v_mfma_f32_16x16x32_bf16 v[18:21], v[178:181], v[202:205], v[18:21]
	v_mfma_f32_16x16x32_bf16 v[6:9], v[170:173], v[214:217], v[6:9]
	v_mfma_f32_16x16x32_bf16 v[2:5], v[178:181], v[214:217], v[2:5]
	v_mfma_f32_16x16x32_bf16 v[54:57], v[174:177], v[190:193], v[54:57]
	v_mfma_f32_16x16x32_bf16 v[50:53], v[182:185], v[190:193], v[50:53]
	v_mfma_f32_16x16x32_bf16 v[38:41], v[174:177], v[198:201], v[38:41]
	v_mfma_f32_16x16x32_bf16 v[34:37], v[182:185], v[198:201], v[34:37]
	v_mfma_f32_16x16x32_bf16 v[22:25], v[174:177], v[210:213], v[22:25]
	v_mfma_f32_16x16x32_bf16 v[18:21], v[182:185], v[210:213], v[18:21]
	v_mfma_f32_16x16x32_bf16 v[6:9], v[174:177], v[218:221], v[6:9]
	v_mfma_f32_16x16x32_bf16 v[2:5], v[182:185], v[218:221], v[2:5]
	s_barrier
	s_setprio 0
	s_add_i32 s43, 0, 0x18000
	v_add_u32_e32 v153, s43, v1
	s_add_i32 s44, 0, 0x1c000
	ds_read_b128 v[154:157], v153
	ds_read_b128 v[158:161], v153 offset:1024
	ds_read_b128 v[162:165], v153 offset:2048
	ds_read_b128 v[166:169], v153 offset:3072
	v_add_u32_e32 v153, s44, v1
	ds_read_b128 v[170:173], v153
	ds_read_b128 v[174:177], v153 offset:1024
	ds_read_b128 v[178:181], v153 offset:2048
	ds_read_b128 v[182:185], v153 offset:3072
	s_add_u32 s20, s20, 0x30000
	s_addc_u32 s21, s21, 0
	s_mov_b32 m0, s27
	v_lshl_add_u64 v[228:229], s[20:21], 0, v[136:137]
	ds_read_b128 v[186:189], v152 offset:32768
	ds_read_b128 v[190:193], v152 offset:33792
	ds_read_b128 v[194:197], v152 offset:34816
	ds_read_b128 v[198:201], v152 offset:35840
	ds_read_b128 v[202:205], v152 offset:36864
	ds_read_b128 v[210:213], v152 offset:37888
	ds_read_b128 v[214:217], v152 offset:38912
	ds_read_b128 v[218:221], v152 offset:39936
	global_load_lds_dwordx4 v[228:229], off
	v_lshl_add_u64 v[228:229], s[20:21], 0, v[132:133]
	s_mov_b32 m0, s28
	s_nop 0
	global_load_lds_dwordx4 v[228:229], off
	s_waitcnt vmcnt(8)
	s_waitcnt lgkmcnt(0)
	s_setprio 1
	s_barrier
	v_mfma_f32_16x16x32_bf16 v[126:129], v[154:157], v[186:189], v[126:129]
	v_mfma_f32_16x16x32_bf16 v[122:125], v[162:165], v[186:189], v[122:125]
	v_mfma_f32_16x16x32_bf16 v[110:113], v[154:157], v[194:197], v[110:113]
	v_mfma_f32_16x16x32_bf16 v[106:109], v[162:165], v[194:197], v[106:109]
	v_mfma_f32_16x16x32_bf16 v[94:97], v[154:157], v[202:205], v[94:97]
	v_mfma_f32_16x16x32_bf16 v[90:93], v[162:165], v[202:205], v[90:93]
	v_mfma_f32_16x16x32_bf16 v[78:81], v[154:157], v[214:217], v[78:81]
	v_mfma_f32_16x16x32_bf16 v[74:77], v[162:165], v[214:217], v[74:77]
	v_mfma_f32_16x16x32_bf16 v[126:129], v[158:161], v[190:193], v[126:129]
	v_mfma_f32_16x16x32_bf16 v[122:125], v[166:169], v[190:193], v[122:125]
	v_mfma_f32_16x16x32_bf16 v[110:113], v[158:161], v[198:201], v[110:113]
	v_mfma_f32_16x16x32_bf16 v[106:109], v[166:169], v[198:201], v[106:109]
	v_mfma_f32_16x16x32_bf16 v[94:97], v[158:161], v[210:213], v[94:97]
	v_mfma_f32_16x16x32_bf16 v[90:93], v[166:169], v[210:213], v[90:93]
	v_mfma_f32_16x16x32_bf16 v[78:81], v[158:161], v[218:221], v[78:81]
	v_mfma_f32_16x16x32_bf16 v[74:77], v[166:169], v[218:221], v[74:77]
	v_mfma_f32_16x16x32_bf16 v[118:121], v[170:173], v[186:189], v[118:121]
	v_mfma_f32_16x16x32_bf16 v[114:117], v[178:181], v[186:189], v[114:117]
	v_mfma_f32_16x16x32_bf16 v[102:105], v[170:173], v[194:197], v[102:105]
	v_mfma_f32_16x16x32_bf16 v[98:101], v[178:181], v[194:197], v[98:101]
	v_mfma_f32_16x16x32_bf16 v[86:89], v[170:173], v[202:205], v[86:89]
	v_mfma_f32_16x16x32_bf16 v[82:85], v[178:181], v[202:205], v[82:85]
	v_mfma_f32_16x16x32_bf16 v[70:73], v[170:173], v[214:217], v[70:73]
	v_mfma_f32_16x16x32_bf16 v[66:69], v[178:181], v[214:217], v[66:69]
	v_mfma_f32_16x16x32_bf16 v[118:121], v[174:177], v[190:193], v[118:121]
	v_mfma_f32_16x16x32_bf16 v[114:117], v[182:185], v[190:193], v[114:117]
	v_mfma_f32_16x16x32_bf16 v[102:105], v[174:177], v[198:201], v[102:105]
	v_mfma_f32_16x16x32_bf16 v[98:101], v[182:185], v[198:201], v[98:101]
	v_mfma_f32_16x16x32_bf16 v[86:89], v[174:177], v[210:213], v[86:89]
	v_mfma_f32_16x16x32_bf16 v[82:85], v[182:185], v[210:213], v[82:85]
	v_mfma_f32_16x16x32_bf16 v[70:73], v[174:177], v[218:221], v[70:73]
	v_mfma_f32_16x16x32_bf16 v[66:69], v[182:185], v[218:221], v[66:69]
	s_barrier
; #define PG8_STAGE(bufoff, gbase, voff) do { _Pragma("unroll") for (int _i = 0; _i < 2; ++_i) \
;         __builtin_amdgcn_global_load_lds((const unsigned*)((const char*)(gbase) + (voff)[_i]), (PG8_LAS unsigned*)(lds + (bufoff) + ldsw + _i * 8192), 16, 0, 0); } while (0)
; #define PG8_LDA(dst, b, h) do { _Pragma("unroll") for (int m = 0; m < 4; ++m) _Pragma("unroll") for (int k = 0; k < 2; ++k) dst[m][k] = *(const PG8_LAS bf16x8*)(lds + PG8_SA(b, h) + aoff + m * 2048 + k * 1024); } while (0)
; #define PG8_MMA(ai, bj, At, Bt) do { __builtin_amdgcn_s_setprio(1); _Pragma("unroll") for (int m = 0; m < 4; ++m) _Pragma("unroll") for (int n = 0; n < 2; ++n) _Pragma("unroll") for (int k = 0; k < 2; ++k) \
;         acc[ai][bj][m][n] = __builtin_amdgcn_mfma_f32_16x16x32_bf16(Bt[n][k], At[m][k], acc[ai][bj][m][n], 0, 0, 0); __builtin_amdgcn_s_setprio(0); } while (0)
; #define PG8_WAIT_V(n) asm volatile("s_waitcnt vmcnt(" #n ")" ::: "memory")
; #define PG8_WAIT_L(n) asm volatile("s_waitcnt lgkmcnt(" #n ")" ::: "memory")
; #define PG8_BAR __builtin_amdgcn_s_barrier()
; #define PG8_SCHED __builtin_amdgcn_sched_barrier(0)
; template <class Epi, class Sched, bool ALIGN_EPI = false, bool SP2 = false>
; __device__ __forceinline__ void gemm_phase(PG8_LAS unsigned char* lds, const Gemm g, const Sched& S, const Epi& E) {
;     ...
;             PG8_LDA(At, 1, 1); PG8_STAGE(PG8_SB(1, 0), b3, voffB); PG8_STAGE(PG8_SB(1, 1), b3 + hstepB, voffB); PG8_STAGE(PG8_SA(1, 0), a3, voffA);
;             PG8_WAIT_V(8); PG8_WAIT_L(0); PG8_BAR; PG8_MMA(1, 0, At, B0); PG8_MMA(1, 1, At, B1); PG8_BAR; PG8_SCHED;
	s_setprio 0
	s_add_i32 s20, s43, s23
	v_lshl_add_u64 v[206:207], v[206:207], 0, s[12:13]
	s_mov_b32 m0, s20
	ds_read_b128 v[186:189], v152 offset:49152
	ds_read_b128 v[190:193], v152 offset:50176
	ds_read_b128 v[194:197], v152 offset:51200
	ds_read_b128 v[198:201], v152 offset:52224
	ds_read_b128 v[202:205], v152 offset:53248
	ds_read_b128 v[210:213], v152 offset:54272
	ds_read_b128 v[214:217], v152 offset:55296
	ds_read_b128 v[218:221], v152 offset:56320
	global_load_lds_dwordx4 v[206:207], off
	s_add_i32 m0, s20, 0x2000
	s_add_u32 s2, s2, 0x30080
	v_lshl_add_u64 v[206:207], v[222:223], 0, s[12:13]
	s_addc_u32 s3, s3, 0
	s_add_i32 s20, s44, s23
	global_load_lds_dwordx4 v[206:207], off
	v_lshl_add_u64 v[206:207], s[2:3], 0, v[134:135]
	s_mov_b32 m0, s20
	s_nop 0
	global_load_lds_dwordx4 v[206:207], off
	v_lshl_add_u64 v[206:207], s[2:3], 0, v[130:131]
	s_add_i32 m0, s20, 0x2000
	s_nop 0
	global_load_lds_dwordx4 v[206:207], off
	v_lshl_add_u64 v[206:207], v[224:225], 0, s[12:13]
	s_mov_b32 m0, s30
	s_nop 0
	global_load_lds_dwordx4 v[206:207], off
	v_lshl_add_u64 v[206:207], v[226:227], 0, s[12:13]
	s_mov_b32 m0, s31
	s_nop 0
	global_load_lds_dwordx4 v[206:207], off
	s_waitcnt vmcnt(8)
	s_waitcnt lgkmcnt(0)
	s_setprio 1
	s_barrier
	v_mfma_f32_16x16x32_bf16 v[62:65], v[154:157], v[186:189], v[62:65]
	v_mfma_f32_16x16x32_bf16 v[58:61], v[162:165], v[186:189], v[58:61]
	v_mfma_f32_16x16x32_bf16 v[46:49], v[154:157], v[194:197], v[46:49]
	v_mfma_f32_16x16x32_bf16 v[42:45], v[162:165], v[194:197], v[42:45]
	v_mfma_f32_16x16x32_bf16 v[30:33], v[154:157], v[202:205], v[30:33]
	v_mfma_f32_16x16x32_bf16 v[26:29], v[162:165], v[202:205], v[26:29]
	v_mfma_f32_16x16x32_bf16 v[14:17], v[154:157], v[214:217], v[14:17]
	v_mfma_f32_16x16x32_bf16 v[10:13], v[162:165], v[214:217], v[10:13]
	v_mfma_f32_16x16x32_bf16 v[62:65], v[158:161], v[190:193], v[62:65]
	v_mfma_f32_16x16x32_bf16 v[58:61], v[166:169], v[190:193], v[58:61]
	v_mfma_f32_16x16x32_bf16 v[46:49], v[158:161], v[198:201], v[46:49]
	v_mfma_f32_16x16x32_bf16 v[42:45], v[166:169], v[198:201], v[42:45]
	v_mfma_f32_16x16x32_bf16 v[30:33], v[158:161], v[210:213], v[30:33]
	v_mfma_f32_16x16x32_bf16 v[26:29], v[166:169], v[210:213], v[26:29]
	v_mfma_f32_16x16x32_bf16 v[14:17], v[158:161], v[218:221], v[14:17]
	v_mfma_f32_16x16x32_bf16 v[10:13], v[166:169], v[218:221], v[10:13]
	v_mfma_f32_16x16x32_bf16 v[54:57], v[170:173], v[186:189], v[54:57]
	v_mfma_f32_16x16x32_bf16 v[50:53], v[178:181], v[186:189], v[50:53]
	v_mfma_f32_16x16x32_bf16 v[38:41], v[170:173], v[194:197], v[38:41]
	v_mfma_f32_16x16x32_bf16 v[34:37], v[178:181], v[194:197], v[34:37]
	v_mfma_f32_16x16x32_bf16 v[22:25], v[170:173], v[202:205], v[22:25]
	v_mfma_f32_16x16x32_bf16 v[18:21], v[178:181], v[202:205], v[18:21]
	v_mfma_f32_16x16x32_bf16 v[6:9], v[170:173], v[214:217], v[6:9]
	v_mfma_f32_16x16x32_bf16 v[2:5], v[178:181], v[214:217], v[2:5]
	v_mfma_f32_16x16x32_bf16 v[54:57], v[174:177], v[190:193], v[54:57]
	v_mfma_f32_16x16x32_bf16 v[50:53], v[182:185], v[190:193], v[50:53]
	v_mfma_f32_16x16x32_bf16 v[38:41], v[174:177], v[198:201], v[38:41]
	v_mfma_f32_16x16x32_bf16 v[34:37], v[182:185], v[198:201], v[34:37]
	v_mfma_f32_16x16x32_bf16 v[22:25], v[174:177], v[210:213], v[22:25]
	v_mfma_f32_16x16x32_bf16 v[18:21], v[182:185], v[210:213], v[18:21]
	v_mfma_f32_16x16x32_bf16 v[6:9], v[174:177], v[218:221], v[6:9]
	v_mfma_f32_16x16x32_bf16 v[2:5], v[182:185], v[218:221], v[2:5]
	s_barrier
	s_setprio 0
	s_add_i32 s42, s42, 2
	s_add_u32 s0, s0, 0x100
	s_addc_u32 s1, s1, 0
	s_add_u32 s40, s40, 0x100
	s_addc_u32 s41, s41, 0
	s_cmp_gt_u32 s42, 9
	s_cbranch_scc0 .LBB0_1290
	s_and_b64 vcc, exec, s[14:15]
	s_cbranch_vccz .LBB0_1293
	s_barrier

; #define PG8_STAGE(bufoff, gbase, voff) do { _Pragma("unroll") for (int _i = 0; _i < 2; ++_i) \
;         __builtin_amdgcn_global_load_lds((const unsigned*)((const char*)(gbase) + (voff)[_i]), (PG8_LAS unsigned*)(lds + (bufoff) + ldsw + _i * 8192), 16, 0, 0); } while (0)
; #define PG8_LDA(dst, b, h) do { _Pragma("unroll") for (int m = 0; m < 4; ++m) _Pragma("unroll") for (int k = 0; k < 2; ++k) dst[m][k] = *(const PG8_LAS bf16x8*)(lds + PG8_SA(b, h) + aoff + m * 2048 + k * 1024); } while (0)
; #define PG8_LDB(dst, b, h) do { _Pragma("unroll") for (int n = 0; n < 2; ++n) _Pragma("unroll") for (int k = 0; k < 2; ++k) dst[n][k] = *(const PG8_LAS bf16x8*)(lds + PG8_SB(b, h) + boff + n * 2048 + k * 1024); } while (0)
; #define PG8_MMA(ai, bj, At, Bt) do { __builtin_amdgcn_s_setprio(1); _Pragma("unroll") for (int m = 0; m < 4; ++m) _Pragma("unroll") for (int n = 0; n < 2; ++n) _Pragma("unroll") for (int k = 0; k < 2; ++k) \
;         acc[ai][bj][m][n] = __builtin_amdgcn_mfma_f32_16x16x32_bf16(Bt[n][k], At[m][k], acc[ai][bj][m][n], 0, 0, 0); __builtin_amdgcn_s_setprio(0); } while (0)
; #define PG8_WAIT_V(n) asm volatile("s_waitcnt vmcnt(" #n ")" ::: "memory")
; #define PG8_WAIT_L(n) asm volatile("s_waitcnt lgkmcnt(" #n ")" ::: "memory")
; #define PG8_BAR __builtin_amdgcn_s_barrier()
; #define PG8_SCHED __builtin_amdgcn_sched_barrier(0)
; template <class Epi, class Sched, bool ALIGN_EPI = false, bool SP2 = false>
; __device__ __forceinline__ void gemm_phase(PG8_LAS unsigned char* lds, const Gemm g, const Sched& S, const Epi& E) {
;     ...
;             PG8_LDB(B0, 0, 0); PG8_LDB(B1, 0, 1); PG8_SCHED; PG8_LDA(At, 0, 0); PG8_STAGE(PG8_SA(1, 1), a1 + hstepA, voffA);
;             PG8_WAIT_V(8); PG8_WAIT_L(0); PG8_BAR; PG8_MMA(0, 0, At, B0); PG8_MMA(0, 1, At, B1); PG8_BAR; PG8_SCHED;
;             PG8_LDA(At, 0, 1); PG8_STAGE(PG8_SB(0, 0), b2, voffB); PG8_STAGE(PG8_SB(0, 1), b2 + hstepB, voffB); PG8_STAGE(PG8_SA(0, 0), a2, voffA);
;             PG8_WAIT_V(8); PG8_WAIT_L(0); PG8_BAR; PG8_MMA(1, 0, At, B0); PG8_MMA(1, 1, At, B1); PG8_BAR; PG8_SCHED;
.LBB0_1357:
	ds_read_b128 v[66:69], v170
	ds_read_b128 v[70:73], v170 offset:1024
	ds_read_b128 v[74:77], v170 offset:2048
	ds_read_b128 v[78:81], v170 offset:3072
	ds_read_b128 v[162:165], v171
	ds_read_b128 v[174:177], v171 offset:1024
	ds_read_b128 v[178:181], v171 offset:2048
	ds_read_b128 v[182:185], v171 offset:3072
	s_add_u32 s36, s2, 0xfff80080
	s_addc_u32 s37, s3, -1
	s_cmp_eq_u32 s57, 28
	s_cselect_b32 s39, s29, s37
	s_cselect_b32 s38, s53, s36
	s_cselect_b32 s37, s27, s56
	s_cselect_b32 s36, s54, s55
	v_lshl_add_u64 v[166:167], s[2:3], 0, v[154:155]
	s_add_i32 m0, s43, 0xc000
	ds_read_b128 v[186:189], v172
	ds_read_b128 v[190:193], v172 offset:1024
	ds_read_b128 v[194:197], v172 offset:2048
	ds_read_b128 v[198:201], v172 offset:3072
	ds_read_b128 v[202:205], v172 offset:4096
	ds_read_b128 v[210:213], v172 offset:5120
	ds_read_b128 v[214:217], v172 offset:6144
	ds_read_b128 v[218:221], v172 offset:7168
	global_load_lds_dwordx4 v[166:167], off
	v_lshl_add_u64 v[166:167], s[2:3], 0, v[156:157]
	s_add_i32 m0, s43, 0xe000
	s_nop 0
	global_load_lds_dwordx4 v[166:167], off
	s_waitcnt vmcnt(8)
	s_waitcnt lgkmcnt(0)
	s_setprio 1
	s_barrier
	v_mfma_f32_16x16x32_bf16 v[142:145], v[66:69], v[186:189], v[142:145]
	v_mfma_f32_16x16x32_bf16 v[138:141], v[74:77], v[186:189], v[138:141]
	v_mfma_f32_16x16x32_bf16 v[126:129], v[66:69], v[194:197], v[126:129]
	v_mfma_f32_16x16x32_bf16 v[122:125], v[74:77], v[194:197], v[122:125]
	v_mfma_f32_16x16x32_bf16 v[110:113], v[66:69], v[202:205], v[110:113]
	v_mfma_f32_16x16x32_bf16 v[106:109], v[74:77], v[202:205], v[106:109]
	v_mfma_f32_16x16x32_bf16 v[94:97], v[66:69], v[214:217], v[94:97]
	v_mfma_f32_16x16x32_bf16 v[90:93], v[74:77], v[214:217], v[90:93]
	v_mfma_f32_16x16x32_bf16 v[142:145], v[70:73], v[190:193], v[142:145]
	v_mfma_f32_16x16x32_bf16 v[138:141], v[78:81], v[190:193], v[138:141]
	v_mfma_f32_16x16x32_bf16 v[126:129], v[70:73], v[198:201], v[126:129]
	v_mfma_f32_16x16x32_bf16 v[122:125], v[78:81], v[198:201], v[122:125]
	v_mfma_f32_16x16x32_bf16 v[110:113], v[70:73], v[210:213], v[110:113]
	v_mfma_f32_16x16x32_bf16 v[106:109], v[78:81], v[210:213], v[106:109]
	v_mfma_f32_16x16x32_bf16 v[94:97], v[70:73], v[218:221], v[94:97]
	v_mfma_f32_16x16x32_bf16 v[90:93], v[78:81], v[218:221], v[90:93]
	v_mfma_f32_16x16x32_bf16 v[134:137], v[162:165], v[186:189], v[134:137]
	v_mfma_f32_16x16x32_bf16 v[130:133], v[178:181], v[186:189], v[130:133]
	v_mfma_f32_16x16x32_bf16 v[118:121], v[162:165], v[194:197], v[118:121]
	v_mfma_f32_16x16x32_bf16 v[114:117], v[178:181], v[194:197], v[114:117]
	v_mfma_f32_16x16x32_bf16 v[102:105], v[162:165], v[202:205], v[102:105]
	v_mfma_f32_16x16x32_bf16 v[98:101], v[178:181], v[202:205], v[98:101]
	v_mfma_f32_16x16x32_bf16 v[86:89], v[162:165], v[214:217], v[86:89]
	v_mfma_f32_16x16x32_bf16 v[82:85], v[178:181], v[214:217], v[82:85]
	v_mfma_f32_16x16x32_bf16 v[134:137], v[174:177], v[190:193], v[134:137]
	v_mfma_f32_16x16x32_bf16 v[130:133], v[182:185], v[190:193], v[130:133]
	v_mfma_f32_16x16x32_bf16 v[118:121], v[174:177], v[198:201], v[118:121]
	v_mfma_f32_16x16x32_bf16 v[114:117], v[182:185], v[198:201], v[114:117]
	v_mfma_f32_16x16x32_bf16 v[102:105], v[174:177], v[210:213], v[102:105]
	v_mfma_f32_16x16x32_bf16 v[98:101], v[182:185], v[210:213], v[98:101]
	v_mfma_f32_16x16x32_bf16 v[86:89], v[174:177], v[218:221], v[86:89]
	v_mfma_f32_16x16x32_bf16 v[82:85], v[182:185], v[218:221], v[82:85]
	s_barrier
	s_setprio 0
	s_add_i32 s58, s51, s40
	v_lshl_add_u64 v[166:167], s[36:37], 0, v[150:151]
	s_mov_b32 m0, s58
	ds_read_b128 v[186:189], v172 offset:16384
	ds_read_b128 v[190:193], v172 offset:17408
	ds_read_b128 v[194:197], v172 offset:18432
	ds_read_b128 v[198:201], v172 offset:19456
	ds_read_b128 v[202:205], v172 offset:20480
	ds_read_b128 v[210:213], v172 offset:21504
	ds_read_b128 v[214:217], v172 offset:22528
	ds_read_b128 v[218:221], v172 offset:23552
	global_load_lds_dwordx4 v[166:167], off
	s_add_i32 m0, s58, 0x2000
	s_add_u32 s58, s36, 0x80000
	v_lshl_add_u64 v[206:207], s[36:37], 0, v[146:147]
	s_addc_u32 s59, s37, 0
	s_add_i32 s60, s52, s40
	global_load_lds_dwordx4 v[206:207], off
	v_lshl_add_u64 v[222:223], s[58:59], 0, v[150:151]
	s_mov_b32 m0, s60
	v_lshl_add_u64 v[224:225], s[38:39], 0, v[148:149]
	global_load_lds_dwordx4 v[222:223], off
	v_lshl_add_u64 v[222:223], s[58:59], 0, v[146:147]
	s_add_i32 m0, s60, 0x2000
	s_nop 0
	global_load_lds_dwordx4 v[222:223], off
	v_lshl_add_u64 v[222:223], s[38:39], 0, v[152:153]
	s_mov_b32 m0, s43
	s_nop 0
	global_load_lds_dwordx4 v[222:223], off
	s_mov_b32 m0, s44
	s_nop 0
	global_load_lds_dwordx4 v[224:225], off
	s_waitcnt vmcnt(8)
	s_waitcnt lgkmcnt(0)
	s_setprio 1
	s_barrier
; #define PG8_STAGE(bufoff, gbase, voff) do { _Pragma("unroll") for (int _i = 0; _i < 2; ++_i) \
;         __builtin_amdgcn_global_load_lds((const unsigned*)((const char*)(gbase) + (voff)[_i]), (PG8_LAS unsigned*)(lds + (bufoff) + ldsw + _i * 8192), 16, 0, 0); } while (0)
; #define PG8_LDA(dst, b, h) do { _Pragma("unroll") for (int m = 0; m < 4; ++m) _Pragma("unroll") for (int k = 0; k < 2; ++k) dst[m][k] = *(const PG8_LAS bf16x8*)(lds + PG8_SA(b, h) + aoff + m * 2048 + k * 1024); } while (0)
; #define PG8_LDB(dst, b, h) do { _Pragma("unroll") for (int n = 0; n < 2; ++n) _Pragma("unroll") for (int k = 0; k < 2; ++k) dst[n][k] = *(const PG8_LAS bf16x8*)(lds + PG8_SB(b, h) + boff + n * 2048 + k * 1024); } while (0)
; #define PG8_MMA(ai, bj, At, Bt) do { __builtin_amdgcn_s_setprio(1); _Pragma("unroll") for (int m = 0; m < 4; ++m) _Pragma("unroll") for (int n = 0; n < 2; ++n) _Pragma("unroll") for (int k = 0; k < 2; ++k) \
;         acc[ai][bj][m][n] = __builtin_amdgcn_mfma_f32_16x16x32_bf16(Bt[n][k], At[m][k], acc[ai][bj][m][n], 0, 0, 0); __builtin_amdgcn_s_setprio(0); } while (0)
; #define PG8_WAIT_V(n) asm volatile("s_waitcnt vmcnt(" #n ")" ::: "memory")
; #define PG8_WAIT_L(n) asm volatile("s_waitcnt lgkmcnt(" #n ")" ::: "memory")
; #define PG8_BAR __builtin_amdgcn_s_barrier()
; #define PG8_SCHED __builtin_amdgcn_sched_barrier(0)
; template <class Epi, class Sched, bool ALIGN_EPI = false, bool SP2 = false>
; __device__ __forceinline__ void gemm_phase(PG8_LAS unsigned char* lds, const Gemm g, const Sched& S, const Epi& E) {
;     ...
;             PG8_WAIT_V(8); PG8_WAIT_L(0); PG8_BAR; PG8_MMA(1, 0, At, B0); PG8_MMA(1, 1, At, B1); PG8_BAR; PG8_SCHED;
;             PG8_LDB(B0, 1, 0); PG8_LDB(B1, 1, 1); PG8_SCHED; PG8_LDA(At, 1, 0); PG8_STAGE(PG8_SA(0, 1), a2 + hstepA, voffA);
;             PG8_WAIT_V(8); PG8_WAIT_L(0); PG8_BAR; PG8_MMA(0, 0, At, B0); PG8_MMA(0, 1, At, B1); PG8_BAR; PG8_SCHED;
	v_mfma_f32_16x16x32_bf16 v[62:65], v[66:69], v[186:189], v[62:65]
	v_mfma_f32_16x16x32_bf16 v[58:61], v[74:77], v[186:189], v[58:61]
	v_mfma_f32_16x16x32_bf16 v[46:49], v[66:69], v[194:197], v[46:49]
	v_mfma_f32_16x16x32_bf16 v[42:45], v[74:77], v[194:197], v[42:45]
	v_mfma_f32_16x16x32_bf16 v[30:33], v[66:69], v[202:205], v[30:33]
	v_mfma_f32_16x16x32_bf16 v[26:29], v[74:77], v[202:205], v[26:29]
	v_mfma_f32_16x16x32_bf16 v[14:17], v[66:69], v[214:217], v[14:17]
	v_mfma_f32_16x16x32_bf16 v[10:13], v[74:77], v[214:217], v[10:13]
	v_mfma_f32_16x16x32_bf16 v[62:65], v[70:73], v[190:193], v[62:65]
	v_mfma_f32_16x16x32_bf16 v[58:61], v[78:81], v[190:193], v[58:61]
	v_mfma_f32_16x16x32_bf16 v[46:49], v[70:73], v[198:201], v[46:49]
	v_mfma_f32_16x16x32_bf16 v[42:45], v[78:81], v[198:201], v[42:45]
	v_mfma_f32_16x16x32_bf16 v[30:33], v[70:73], v[210:213], v[30:33]
	v_mfma_f32_16x16x32_bf16 v[26:29], v[78:81], v[210:213], v[26:29]
	v_mfma_f32_16x16x32_bf16 v[14:17], v[70:73], v[218:221], v[14:17]
	v_mfma_f32_16x16x32_bf16 v[10:13], v[78:81], v[218:221], v[10:13]
	v_mfma_f32_16x16x32_bf16 v[54:57], v[162:165], v[186:189], v[54:57]
	v_mfma_f32_16x16x32_bf16 v[50:53], v[178:181], v[186:189], v[50:53]
	v_mfma_f32_16x16x32_bf16 v[38:41], v[162:165], v[194:197], v[38:41]
	v_mfma_f32_16x16x32_bf16 v[34:37], v[178:181], v[194:197], v[34:37]
	v_mfma_f32_16x16x32_bf16 v[22:25], v[162:165], v[202:205], v[22:25]
	v_mfma_f32_16x16x32_bf16 v[18:21], v[178:181], v[202:205], v[18:21]
	v_mfma_f32_16x16x32_bf16 v[6:9], v[162:165], v[214:217], v[6:9]
	v_mfma_f32_16x16x32_bf16 v[2:5], v[178:181], v[214:217], v[2:5]
	v_mfma_f32_16x16x32_bf16 v[54:57], v[174:177], v[190:193], v[54:57]
	v_mfma_f32_16x16x32_bf16 v[50:53], v[182:185], v[190:193], v[50:53]
	v_mfma_f32_16x16x32_bf16 v[38:41], v[174:177], v[198:201], v[38:41]
	v_mfma_f32_16x16x32_bf16 v[34:37], v[182:185], v[198:201], v[34:37]
	v_mfma_f32_16x16x32_bf16 v[22:25], v[174:177], v[210:213], v[22:25]
	v_mfma_f32_16x16x32_bf16 v[18:21], v[182:185], v[210:213], v[18:21]
	v_mfma_f32_16x16x32_bf16 v[6:9], v[174:177], v[218:221], v[6:9]
	v_mfma_f32_16x16x32_bf16 v[2:5], v[182:185], v[218:221], v[2:5]
	s_barrier
	s_setprio 0
	s_add_i32 s58, 0, 0x18000
	s_add_i32 s59, 0, 0x1c000
	v_add_u32_e32 v78, s58, v168
	v_add_u32_e32 v173, s59, v168
	ds_read_b128 v[66:69], v78
	ds_read_b128 v[70:73], v78 offset:1024
	ds_read_b128 v[74:77], v78 offset:2048
	ds_read_b128 v[78:81], v78 offset:3072
	ds_read_b128 v[162:165], v173
	ds_read_b128 v[174:177], v173 offset:1024
	ds_read_b128 v[178:181], v173 offset:2048
	ds_read_b128 v[182:185], v173 offset:3072
	s_add_u32 s38, s38, 0x80000
	s_addc_u32 s39, s39, 0
	s_mov_b32 m0, s45
	v_lshl_add_u64 v[226:227], s[38:39], 0, v[152:153]
	ds_read_b128 v[186:189], v172 offset:32768
	ds_read_b128 v[190:193], v172 offset:33792
	ds_read_b128 v[194:197], v172 offset:34816
	ds_read_b128 v[198:201], v172 offset:35840
	ds_read_b128 v[202:205], v172 offset:36864
	ds_read_b128 v[210:213], v172 offset:37888
	ds_read_b128 v[214:217], v172 offset:38912
	ds_read_b128 v[218:221], v172 offset:39936
	global_load_lds_dwordx4 v[226:227], off
	v_lshl_add_u64 v[226:227], s[38:39], 0, v[148:149]
	s_mov_b32 m0, s46
	s_nop 0
	global_load_lds_dwordx4 v[226:227], off
	s_waitcnt vmcnt(8)
	s_waitcnt lgkmcnt(0)
	s_setprio 1
	s_barrier
	v_mfma_f32_16x16x32_bf16 v[142:145], v[66:69], v[186:189], v[142:145]
	v_mfma_f32_16x16x32_bf16 v[138:141], v[74:77], v[186:189], v[138:141]
	v_mfma_f32_16x16x32_bf16 v[126:129], v[66:69], v[194:197], v[126:129]
	v_mfma_f32_16x16x32_bf16 v[122:125], v[74:77], v[194:197], v[122:125]
	v_mfma_f32_16x16x32_bf16 v[110:113], v[66:69], v[202:205], v[110:113]
	v_mfma_f32_16x16x32_bf16 v[106:109], v[74:77], v[202:205], v[106:109]
	v_mfma_f32_16x16x32_bf16 v[94:97], v[66:69], v[214:217], v[94:97]
	v_mfma_f32_16x16x32_bf16 v[90:93], v[74:77], v[214:217], v[90:93]
	v_mfma_f32_16x16x32_bf16 v[142:145], v[70:73], v[190:193], v[142:145]
	v_mfma_f32_16x16x32_bf16 v[138:141], v[78:81], v[190:193], v[138:141]
	v_mfma_f32_16x16x32_bf16 v[126:129], v[70:73], v[198:201], v[126:129]
	v_mfma_f32_16x16x32_bf16 v[122:125], v[78:81], v[198:201], v[122:125]
	v_mfma_f32_16x16x32_bf16 v[110:113], v[70:73], v[210:213], v[110:113]
	v_mfma_f32_16x16x32_bf16 v[106:109], v[78:81], v[210:213], v[106:109]
	v_mfma_f32_16x16x32_bf16 v[94:97], v[70:73], v[218:221], v[94:97]
	v_mfma_f32_16x16x32_bf16 v[90:93], v[78:81], v[218:221], v[90:93]
	v_mfma_f32_16x16x32_bf16 v[134:137], v[162:165], v[186:189], v[134:137]
	v_mfma_f32_16x16x32_bf16 v[130:133], v[178:181], v[186:189], v[130:133]
	v_mfma_f32_16x16x32_bf16 v[118:121], v[162:165], v[194:197], v[118:121]
	v_mfma_f32_16x16x32_bf16 v[114:117], v[178:181], v[194:197], v[114:117]
	v_mfma_f32_16x16x32_bf16 v[102:105], v[162:165], v[202:205], v[102:105]
	v_mfma_f32_16x16x32_bf16 v[98:101], v[178:181], v[202:205], v[98:101]
	v_mfma_f32_16x16x32_bf16 v[86:89], v[162:165], v[214:217], v[86:89]
	v_mfma_f32_16x16x32_bf16 v[82:85], v[178:181], v[214:217], v[82:85]
	v_mfma_f32_16x16x32_bf16 v[134:137], v[174:177], v[190:193], v[134:137]
	v_mfma_f32_16x16x32_bf16 v[130:133], v[182:185], v[190:193], v[130:133]
	v_mfma_f32_16x16x32_bf16 v[118:121], v[174:177], v[198:201], v[118:121]
	v_mfma_f32_16x16x32_bf16 v[114:117], v[182:185], v[198:201], v[114:117]
	v_mfma_f32_16x16x32_bf16 v[102:105], v[174:177], v[210:213], v[102:105]
	v_mfma_f32_16x16x32_bf16 v[98:101], v[182:185], v[210:213], v[98:101]
	v_mfma_f32_16x16x32_bf16 v[86:89], v[174:177], v[218:221], v[86:89]
	v_mfma_f32_16x16x32_bf16 v[82:85], v[182:185], v[218:221], v[82:85]
	s_barrier
; #define PG8_STAGE(bufoff, gbase, voff) do { _Pragma("unroll") for (int _i = 0; _i < 2; ++_i) \
;         __builtin_amdgcn_global_load_lds((const unsigned*)((const char*)(gbase) + (voff)[_i]), (PG8_LAS unsigned*)(lds + (bufoff) + ldsw + _i * 8192), 16, 0, 0); } while (0)
; #define PG8_LDA(dst, b, h) do { _Pragma("unroll") for (int m = 0; m < 4; ++m) _Pragma("unroll") for (int k = 0; k < 2; ++k) dst[m][k] = *(const PG8_LAS bf16x8*)(lds + PG8_SA(b, h) + aoff + m * 2048 + k * 1024); } while (0)
; #define PG8_MMA(ai, bj, At, Bt) do { __builtin_amdgcn_s_setprio(1); _Pragma("unroll") for (int m = 0; m < 4; ++m) _Pragma("unroll") for (int n = 0; n < 2; ++n) _Pragma("unroll") for (int k = 0; k < 2; ++k) \
;         acc[ai][bj][m][n] = __builtin_amdgcn_mfma_f32_16x16x32_bf16(Bt[n][k], At[m][k], acc[ai][bj][m][n], 0, 0, 0); __builtin_amdgcn_s_setprio(0); } while (0)
; #define PG8_WAIT_V(n) asm volatile("s_waitcnt vmcnt(" #n ")" ::: "memory")
; #define PG8_WAIT_L(n) asm volatile("s_waitcnt lgkmcnt(" #n ")" ::: "memory")
; #define PG8_BAR __builtin_amdgcn_s_barrier()
; #define PG8_SCHED __builtin_amdgcn_sched_barrier(0)
; template <class Epi, class Sched, bool ALIGN_EPI = false, bool SP2 = false>
; __device__ __forceinline__ void gemm_phase(PG8_LAS unsigned char* lds, const Gemm g, const Sched& S, const Epi& E) {
;     ...
;             PG8_LDA(At, 1, 1); PG8_STAGE(PG8_SB(1, 0), b3, voffB); PG8_STAGE(PG8_SB(1, 1), b3 + hstepB, voffB); PG8_STAGE(PG8_SA(1, 0), a3, voffA);
;             PG8_WAIT_V(8); PG8_WAIT_L(0); PG8_BAR; PG8_MMA(1, 0, At, B0); PG8_MMA(1, 1, At, B1); PG8_BAR; PG8_SCHED;
	s_setprio 0
	s_add_i32 s38, s58, s40
	v_lshl_add_u64 v[166:167], v[166:167], 0, s[14:15]
	s_mov_b32 m0, s38
	ds_read_b128 v[186:189], v172 offset:49152
	ds_read_b128 v[190:193], v172 offset:50176
	ds_read_b128 v[194:197], v172 offset:51200
	ds_read_b128 v[198:201], v172 offset:52224
	ds_read_b128 v[202:205], v172 offset:53248
	ds_read_b128 v[210:213], v172 offset:54272
	ds_read_b128 v[214:217], v172 offset:55296
	ds_read_b128 v[218:221], v172 offset:56320
	global_load_lds_dwordx4 v[166:167], off
	s_add_i32 m0, s38, 0x2000
	s_add_u32 s36, s36, 0x80080
	v_lshl_add_u64 v[166:167], v[206:207], 0, s[14:15]
	s_addc_u32 s37, s37, 0
	s_add_i32 s38, s59, s40
	global_load_lds_dwordx4 v[166:167], off
	v_lshl_add_u64 v[166:167], s[36:37], 0, v[150:151]
	s_mov_b32 m0, s38
	s_nop 0
	global_load_lds_dwordx4 v[166:167], off
	v_lshl_add_u64 v[166:167], s[36:37], 0, v[146:147]
	s_add_i32 m0, s38, 0x2000
	s_nop 0
	global_load_lds_dwordx4 v[166:167], off
	v_lshl_add_u64 v[166:167], v[222:223], 0, s[14:15]
	s_mov_b32 m0, s48
	s_nop 0
	global_load_lds_dwordx4 v[166:167], off
	v_lshl_add_u64 v[166:167], v[224:225], 0, s[14:15]
	s_mov_b32 m0, s49
	s_nop 0
	global_load_lds_dwordx4 v[166:167], off
	s_waitcnt vmcnt(8)
	s_waitcnt lgkmcnt(0)
	s_setprio 1
	s_barrier
	v_mfma_f32_16x16x32_bf16 v[62:65], v[66:69], v[186:189], v[62:65]
	v_mfma_f32_16x16x32_bf16 v[58:61], v[74:77], v[186:189], v[58:61]
	v_mfma_f32_16x16x32_bf16 v[46:49], v[66:69], v[194:197], v[46:49]
	v_mfma_f32_16x16x32_bf16 v[42:45], v[74:77], v[194:197], v[42:45]
	v_mfma_f32_16x16x32_bf16 v[30:33], v[66:69], v[202:205], v[30:33]
	v_mfma_f32_16x16x32_bf16 v[26:29], v[74:77], v[202:205], v[26:29]
	v_mfma_f32_16x16x32_bf16 v[14:17], v[66:69], v[214:217], v[14:17]
	v_mfma_f32_16x16x32_bf16 v[10:13], v[74:77], v[214:217], v[10:13]
	v_mfma_f32_16x16x32_bf16 v[62:65], v[70:73], v[190:193], v[62:65]
	v_mfma_f32_16x16x32_bf16 v[58:61], v[78:81], v[190:193], v[58:61]
	v_mfma_f32_16x16x32_bf16 v[46:49], v[70:73], v[198:201], v[46:49]
	v_mfma_f32_16x16x32_bf16 v[42:45], v[78:81], v[198:201], v[42:45]
	v_mfma_f32_16x16x32_bf16 v[30:33], v[70:73], v[210:213], v[30:33]
	v_mfma_f32_16x16x32_bf16 v[26:29], v[78:81], v[210:213], v[26:29]
	v_mfma_f32_16x16x32_bf16 v[14:17], v[70:73], v[218:221], v[14:17]
	v_mfma_f32_16x16x32_bf16 v[10:13], v[78:81], v[218:221], v[10:13]
	v_mfma_f32_16x16x32_bf16 v[54:57], v[162:165], v[186:189], v[54:57]
	v_mfma_f32_16x16x32_bf16 v[50:53], v[178:181], v[186:189], v[50:53]
	v_mfma_f32_16x16x32_bf16 v[38:41], v[162:165], v[194:197], v[38:41]
	v_mfma_f32_16x16x32_bf16 v[34:37], v[178:181], v[194:197], v[34:37]
	v_mfma_f32_16x16x32_bf16 v[22:25], v[162:165], v[202:205], v[22:25]
	v_mfma_f32_16x16x32_bf16 v[18:21], v[178:181], v[202:205], v[18:21]
	v_mfma_f32_16x16x32_bf16 v[6:9], v[162:165], v[214:217], v[6:9]
	v_mfma_f32_16x16x32_bf16 v[2:5], v[178:181], v[214:217], v[2:5]
	v_mfma_f32_16x16x32_bf16 v[54:57], v[174:177], v[190:193], v[54:57]
	v_mfma_f32_16x16x32_bf16 v[50:53], v[182:185], v[190:193], v[50:53]
	v_mfma_f32_16x16x32_bf16 v[38:41], v[174:177], v[198:201], v[38:41]
	v_mfma_f32_16x16x32_bf16 v[34:37], v[182:185], v[198:201], v[34:37]
	v_mfma_f32_16x16x32_bf16 v[22:25], v[174:177], v[210:213], v[22:25]
	v_mfma_f32_16x16x32_bf16 v[18:21], v[182:185], v[210:213], v[18:21]
	v_mfma_f32_16x16x32_bf16 v[6:9], v[174:177], v[218:221], v[6:9]
	v_mfma_f32_16x16x32_bf16 v[2:5], v[182:185], v[218:221], v[2:5]
	s_barrier
	s_setprio 0
	s_add_i32 s57, s57, 2
	s_add_u32 s2, s2, 0x100
	s_addc_u32 s3, s3, 0
	s_add_u32 s55, s55, 0x100
	s_addc_u32 s56, s56, 0
	s_cmp_gt_u32 s57, 29
	s_cbranch_scc0 .LBB0_1357
	s_and_b64 vcc, exec, s[16:17]
	s_cbranch_vccz .LBB0_1360
	s_barrier

; #define PG8_STAGE(bufoff, gbase, voff) do { _Pragma("unroll") for (int _i = 0; _i < 2; ++_i) \
;         __builtin_amdgcn_global_load_lds((const unsigned*)((const char*)(gbase) + (voff)[_i]), (PG8_LAS unsigned*)(lds + (bufoff) + ldsw + _i * 8192), 16, 0, 0); } while (0)
; #define PG8_LDA(dst, b, h) do { _Pragma("unroll") for (int m = 0; m < 4; ++m) _Pragma("unroll") for (int k = 0; k < 2; ++k) dst[m][k] = *(const PG8_LAS bf16x8*)(lds + PG8_SA(b, h) + aoff + m * 2048 + k * 1024); } while (0)
; #define PG8_LDB(dst, b, h) do { _Pragma("unroll") for (int n = 0; n < 2; ++n) _Pragma("unroll") for (int k = 0; k < 2; ++k) dst[n][k] = *(const PG8_LAS bf16x8*)(lds + PG8_SB(b, h) + boff + n * 2048 + k * 1024); } while (0)
; #define PG8_MMA(ai, bj, At, Bt) do { __builtin_amdgcn_s_setprio(1); _Pragma("unroll") for (int m = 0; m < 4; ++m) _Pragma("unroll") for (int n = 0; n < 2; ++n) _Pragma("unroll") for (int k = 0; k < 2; ++k) \
;         acc[ai][bj][m][n] = __builtin_amdgcn_mfma_f32_16x16x32_bf16(Bt[n][k], At[m][k], acc[ai][bj][m][n], 0, 0, 0); __builtin_amdgcn_s_setprio(0); } while (0)
; #define PG8_WAIT_V(n) asm volatile("s_waitcnt vmcnt(" #n ")" ::: "memory")
; #define PG8_WAIT_L(n) asm volatile("s_waitcnt lgkmcnt(" #n ")" ::: "memory")
; #define PG8_BAR __builtin_amdgcn_s_barrier()
; #define PG8_SCHED __builtin_amdgcn_sched_barrier(0)
; template <class Epi, class Sched, bool ALIGN_EPI = false, bool SP2 = false>
; __device__ __forceinline__ void gemm_phase(PG8_LAS unsigned char* lds, const Gemm g, const Sched& S, const Epi& E) {
;     ...
;             PG8_LDB(B0, 0, 0); PG8_LDB(B1, 0, 1); PG8_SCHED; PG8_LDA(At, 0, 0); PG8_STAGE(PG8_SA(1, 1), a1 + hstepA, voffA);
;             PG8_WAIT_V(8); PG8_WAIT_L(0); PG8_BAR; PG8_MMA(0, 0, At, B0); PG8_MMA(0, 1, At, B1); PG8_BAR; PG8_SCHED;
;             PG8_LDA(At, 0, 1); PG8_STAGE(PG8_SB(0, 0), b2, voffB); PG8_STAGE(PG8_SB(0, 1), b2 + hstepB, voffB); PG8_STAGE(PG8_SA(0, 0), a2, voffA);
;             PG8_WAIT_V(8); PG8_WAIT_L(0); PG8_BAR; PG8_MMA(1, 0, At, B0); PG8_MMA(1, 1, At, B1); PG8_BAR; PG8_SCHED;
.LBB0_1487:
	ds_read_b128 v[154:157], v150
	ds_read_b128 v[158:161], v150 offset:1024
	ds_read_b128 v[162:165], v150 offset:2048
	ds_read_b128 v[166:169], v150 offset:3072
	ds_read_b128 v[170:173], v151
	ds_read_b128 v[174:177], v151 offset:1024
	ds_read_b128 v[178:181], v151 offset:2048
	ds_read_b128 v[182:185], v151 offset:3072
	s_add_u32 s24, s22, 0xfff80080
	s_addc_u32 s25, s23, -1
	s_cmp_eq_u32 s50, 28
	s_cselect_b32 s27, s13, s25
	s_cselect_b32 s26, s46, s24
	s_cselect_b32 s25, s11, s49
	s_cselect_b32 s24, s47, s48
	v_lshl_add_u64 v[146:147], s[22:23], 0, v[138:139]
	s_add_i32 m0, s21, 0xc000
	ds_read_b128 v[186:189], v152
	ds_read_b128 v[190:193], v152 offset:1024
	ds_read_b128 v[194:197], v152 offset:2048
	ds_read_b128 v[198:201], v152 offset:3072
	ds_read_b128 v[202:205], v152 offset:4096
	ds_read_b128 v[210:213], v152 offset:5120
	ds_read_b128 v[214:217], v152 offset:6144
	ds_read_b128 v[218:221], v152 offset:7168
	global_load_lds_dwordx4 v[146:147], off
	v_lshl_add_u64 v[146:147], s[22:23], 0, v[140:141]
	s_add_i32 m0, s21, 0xe000
	s_nop 0
	global_load_lds_dwordx4 v[146:147], off
	s_waitcnt vmcnt(8)
	s_waitcnt lgkmcnt(0)
	s_setprio 1
	s_barrier
	v_mfma_f32_16x16x32_bf16 v[126:129], v[154:157], v[186:189], v[126:129]
	v_mfma_f32_16x16x32_bf16 v[122:125], v[162:165], v[186:189], v[122:125]
	v_mfma_f32_16x16x32_bf16 v[110:113], v[154:157], v[194:197], v[110:113]
	v_mfma_f32_16x16x32_bf16 v[106:109], v[162:165], v[194:197], v[106:109]
	v_mfma_f32_16x16x32_bf16 v[94:97], v[154:157], v[202:205], v[94:97]
	v_mfma_f32_16x16x32_bf16 v[90:93], v[162:165], v[202:205], v[90:93]
	v_mfma_f32_16x16x32_bf16 v[78:81], v[154:157], v[214:217], v[78:81]
	v_mfma_f32_16x16x32_bf16 v[74:77], v[162:165], v[214:217], v[74:77]
	v_mfma_f32_16x16x32_bf16 v[126:129], v[158:161], v[190:193], v[126:129]
	v_mfma_f32_16x16x32_bf16 v[122:125], v[166:169], v[190:193], v[122:125]
	v_mfma_f32_16x16x32_bf16 v[110:113], v[158:161], v[198:201], v[110:113]
	v_mfma_f32_16x16x32_bf16 v[106:109], v[166:169], v[198:201], v[106:109]
	v_mfma_f32_16x16x32_bf16 v[94:97], v[158:161], v[210:213], v[94:97]
	v_mfma_f32_16x16x32_bf16 v[90:93], v[166:169], v[210:213], v[90:93]
	v_mfma_f32_16x16x32_bf16 v[78:81], v[158:161], v[218:221], v[78:81]
	v_mfma_f32_16x16x32_bf16 v[74:77], v[166:169], v[218:221], v[74:77]
	v_mfma_f32_16x16x32_bf16 v[118:121], v[170:173], v[186:189], v[118:121]
	v_mfma_f32_16x16x32_bf16 v[114:117], v[178:181], v[186:189], v[114:117]
	v_mfma_f32_16x16x32_bf16 v[102:105], v[170:173], v[194:197], v[102:105]
	v_mfma_f32_16x16x32_bf16 v[98:101], v[178:181], v[194:197], v[98:101]
	v_mfma_f32_16x16x32_bf16 v[86:89], v[170:173], v[202:205], v[86:89]
	v_mfma_f32_16x16x32_bf16 v[82:85], v[178:181], v[202:205], v[82:85]
	v_mfma_f32_16x16x32_bf16 v[70:73], v[170:173], v[214:217], v[70:73]
	v_mfma_f32_16x16x32_bf16 v[66:69], v[178:181], v[214:217], v[66:69]
	v_mfma_f32_16x16x32_bf16 v[118:121], v[174:177], v[190:193], v[118:121]
	v_mfma_f32_16x16x32_bf16 v[114:117], v[182:185], v[190:193], v[114:117]
	v_mfma_f32_16x16x32_bf16 v[102:105], v[174:177], v[198:201], v[102:105]
	v_mfma_f32_16x16x32_bf16 v[98:101], v[182:185], v[198:201], v[98:101]
	v_mfma_f32_16x16x32_bf16 v[86:89], v[174:177], v[210:213], v[86:89]
	v_mfma_f32_16x16x32_bf16 v[82:85], v[182:185], v[210:213], v[82:85]
	v_mfma_f32_16x16x32_bf16 v[70:73], v[174:177], v[218:221], v[70:73]
	v_mfma_f32_16x16x32_bf16 v[66:69], v[182:185], v[218:221], v[66:69]
	s_barrier
	s_setprio 0
	s_add_i32 s51, s42, s31
	v_lshl_add_u64 v[146:147], s[24:25], 0, v[134:135]
	s_mov_b32 m0, s51
	ds_read_b128 v[186:189], v152 offset:16384
	ds_read_b128 v[190:193], v152 offset:17408
	ds_read_b128 v[194:197], v152 offset:18432
	ds_read_b128 v[198:201], v152 offset:19456
	ds_read_b128 v[202:205], v152 offset:20480
	ds_read_b128 v[210:213], v152 offset:21504
	ds_read_b128 v[214:217], v152 offset:22528
	ds_read_b128 v[218:221], v152 offset:23552
	global_load_lds_dwordx4 v[146:147], off
	s_add_i32 m0, s51, 0x2000
	s_add_u32 s52, s24, 0x80000
	v_lshl_add_u64 v[206:207], s[24:25], 0, v[130:131]
	s_addc_u32 s53, s25, 0
	s_add_i32 s51, s43, s31
	global_load_lds_dwordx4 v[206:207], off
	v_lshl_add_u64 v[222:223], s[52:53], 0, v[134:135]
	s_mov_b32 m0, s51
	v_lshl_add_u64 v[224:225], s[26:27], 0, v[132:133]
	global_load_lds_dwordx4 v[222:223], off
	v_lshl_add_u64 v[222:223], s[52:53], 0, v[130:131]
	s_add_i32 m0, s51, 0x2000
	s_nop 0
	global_load_lds_dwordx4 v[222:223], off
	v_lshl_add_u64 v[222:223], s[26:27], 0, v[136:137]
	s_mov_b32 m0, s21
	s_nop 0
	global_load_lds_dwordx4 v[222:223], off
	s_mov_b32 m0, s35
	s_nop 0
	global_load_lds_dwordx4 v[224:225], off
	s_waitcnt vmcnt(8)
	s_waitcnt lgkmcnt(0)
	s_setprio 1
	s_barrier
; #define PG8_STAGE(bufoff, gbase, voff) do { _Pragma("unroll") for (int _i = 0; _i < 2; ++_i) \
;         __builtin_amdgcn_global_load_lds((const unsigned*)((const char*)(gbase) + (voff)[_i]), (PG8_LAS unsigned*)(lds + (bufoff) + ldsw + _i * 8192), 16, 0, 0); } while (0)
; #define PG8_LDA(dst, b, h) do { _Pragma("unroll") for (int m = 0; m < 4; ++m) _Pragma("unroll") for (int k = 0; k < 2; ++k) dst[m][k] = *(const PG8_LAS bf16x8*)(lds + PG8_SA(b, h) + aoff + m * 2048 + k * 1024); } while (0)
; #define PG8_LDB(dst, b, h) do { _Pragma("unroll") for (int n = 0; n < 2; ++n) _Pragma("unroll") for (int k = 0; k < 2; ++k) dst[n][k] = *(const PG8_LAS bf16x8*)(lds + PG8_SB(b, h) + boff + n * 2048 + k * 1024); } while (0)
; #define PG8_MMA(ai, bj, At, Bt) do { __builtin_amdgcn_s_setprio(1); _Pragma("unroll") for (int m = 0; m < 4; ++m) _Pragma("unroll") for (int n = 0; n < 2; ++n) _Pragma("unroll") for (int k = 0; k < 2; ++k) \
;         acc[ai][bj][m][n] = __builtin_amdgcn_mfma_f32_16x16x32_bf16(Bt[n][k], At[m][k], acc[ai][bj][m][n], 0, 0, 0); __builtin_amdgcn_s_setprio(0); } while (0)
; #define PG8_WAIT_V(n) asm volatile("s_waitcnt vmcnt(" #n ")" ::: "memory")
; #define PG8_WAIT_L(n) asm volatile("s_waitcnt lgkmcnt(" #n ")" ::: "memory")
; #define PG8_BAR __builtin_amdgcn_s_barrier()
; #define PG8_SCHED __builtin_amdgcn_sched_barrier(0)
; template <class Epi, class Sched, bool ALIGN_EPI = false, bool SP2 = false>
; __device__ __forceinline__ void gemm_phase(PG8_LAS unsigned char* lds, const Gemm g, const Sched& S, const Epi& E) {
;     ...
;             PG8_WAIT_V(8); PG8_WAIT_L(0); PG8_BAR; PG8_MMA(1, 0, At, B0); PG8_MMA(1, 1, At, B1); PG8_BAR; PG8_SCHED;
;             PG8_LDB(B0, 1, 0); PG8_LDB(B1, 1, 1); PG8_SCHED; PG8_LDA(At, 1, 0); PG8_STAGE(PG8_SA(0, 1), a2 + hstepA, voffA);
;             PG8_WAIT_V(8); PG8_WAIT_L(0); PG8_BAR; PG8_MMA(0, 0, At, B0); PG8_MMA(0, 1, At, B1); PG8_BAR; PG8_SCHED;
	v_mfma_f32_16x16x32_bf16 v[62:65], v[154:157], v[186:189], v[62:65]
	v_mfma_f32_16x16x32_bf16 v[58:61], v[162:165], v[186:189], v[58:61]
	v_mfma_f32_16x16x32_bf16 v[46:49], v[154:157], v[194:197], v[46:49]
	v_mfma_f32_16x16x32_bf16 v[42:45], v[162:165], v[194:197], v[42:45]
	v_mfma_f32_16x16x32_bf16 v[30:33], v[154:157], v[202:205], v[30:33]
	v_mfma_f32_16x16x32_bf16 v[26:29], v[162:165], v[202:205], v[26:29]
	v_mfma_f32_16x16x32_bf16 v[14:17], v[154:157], v[214:217], v[14:17]
	v_mfma_f32_16x16x32_bf16 v[10:13], v[162:165], v[214:217], v[10:13]
	v_mfma_f32_16x16x32_bf16 v[62:65], v[158:161], v[190:193], v[62:65]
	v_mfma_f32_16x16x32_bf16 v[58:61], v[166:169], v[190:193], v[58:61]
	v_mfma_f32_16x16x32_bf16 v[46:49], v[158:161], v[198:201], v[46:49]
	v_mfma_f32_16x16x32_bf16 v[42:45], v[166:169], v[198:201], v[42:45]
	v_mfma_f32_16x16x32_bf16 v[30:33], v[158:161], v[210:213], v[30:33]
	v_mfma_f32_16x16x32_bf16 v[26:29], v[166:169], v[210:213], v[26:29]
	v_mfma_f32_16x16x32_bf16 v[14:17], v[158:161], v[218:221], v[14:17]
	v_mfma_f32_16x16x32_bf16 v[10:13], v[166:169], v[218:221], v[10:13]
	v_mfma_f32_16x16x32_bf16 v[54:57], v[170:173], v[186:189], v[54:57]
	v_mfma_f32_16x16x32_bf16 v[50:53], v[178:181], v[186:189], v[50:53]
	v_mfma_f32_16x16x32_bf16 v[38:41], v[170:173], v[194:197], v[38:41]
	v_mfma_f32_16x16x32_bf16 v[34:37], v[178:181], v[194:197], v[34:37]
	v_mfma_f32_16x16x32_bf16 v[22:25], v[170:173], v[202:205], v[22:25]
	v_mfma_f32_16x16x32_bf16 v[18:21], v[178:181], v[202:205], v[18:21]
	v_mfma_f32_16x16x32_bf16 v[6:9], v[170:173], v[214:217], v[6:9]
	v_mfma_f32_16x16x32_bf16 v[2:5], v[178:181], v[214:217], v[2:5]
	v_mfma_f32_16x16x32_bf16 v[54:57], v[174:177], v[190:193], v[54:57]
	v_mfma_f32_16x16x32_bf16 v[50:53], v[182:185], v[190:193], v[50:53]
	v_mfma_f32_16x16x32_bf16 v[38:41], v[174:177], v[198:201], v[38:41]
	v_mfma_f32_16x16x32_bf16 v[34:37], v[182:185], v[198:201], v[34:37]
	v_mfma_f32_16x16x32_bf16 v[22:25], v[174:177], v[210:213], v[22:25]
	v_mfma_f32_16x16x32_bf16 v[18:21], v[182:185], v[210:213], v[18:21]
	v_mfma_f32_16x16x32_bf16 v[6:9], v[174:177], v[218:221], v[6:9]
	v_mfma_f32_16x16x32_bf16 v[2:5], v[182:185], v[218:221], v[2:5]
	s_barrier
	s_setprio 0
	s_add_i32 s51, 0, 0x18000
	v_add_u32_e32 v153, s51, v148
	s_add_i32 s52, 0, 0x1c000
	ds_read_b128 v[154:157], v153
	ds_read_b128 v[158:161], v153 offset:1024
	ds_read_b128 v[162:165], v153 offset:2048
	ds_read_b128 v[166:169], v153 offset:3072
	v_add_u32_e32 v153, s52, v148
	ds_read_b128 v[170:173], v153
	ds_read_b128 v[174:177], v153 offset:1024
	ds_read_b128 v[178:181], v153 offset:2048
	ds_read_b128 v[182:185], v153 offset:3072
	s_add_u32 s26, s26, 0x80000
	s_addc_u32 s27, s27, 0
	s_mov_b32 m0, s36
	v_lshl_add_u64 v[226:227], s[26:27], 0, v[136:137]
	ds_read_b128 v[186:189], v152 offset:32768
	ds_read_b128 v[190:193], v152 offset:33792
	ds_read_b128 v[194:197], v152 offset:34816
	ds_read_b128 v[198:201], v152 offset:35840
	ds_read_b128 v[202:205], v152 offset:36864
	ds_read_b128 v[210:213], v152 offset:37888
	ds_read_b128 v[214:217], v152 offset:38912
	ds_read_b128 v[218:221], v152 offset:39936
	global_load_lds_dwordx4 v[226:227], off
	v_lshl_add_u64 v[226:227], s[26:27], 0, v[132:133]
	s_mov_b32 m0, s37
	s_nop 0
	global_load_lds_dwordx4 v[226:227], off
	s_waitcnt vmcnt(8)
	s_waitcnt lgkmcnt(0)
	s_setprio 1
	s_barrier
	v_mfma_f32_16x16x32_bf16 v[126:129], v[154:157], v[186:189], v[126:129]
	v_mfma_f32_16x16x32_bf16 v[122:125], v[162:165], v[186:189], v[122:125]
	v_mfma_f32_16x16x32_bf16 v[110:113], v[154:157], v[194:197], v[110:113]
	v_mfma_f32_16x16x32_bf16 v[106:109], v[162:165], v[194:197], v[106:109]
	v_mfma_f32_16x16x32_bf16 v[94:97], v[154:157], v[202:205], v[94:97]
	v_mfma_f32_16x16x32_bf16 v[90:93], v[162:165], v[202:205], v[90:93]
	v_mfma_f32_16x16x32_bf16 v[78:81], v[154:157], v[214:217], v[78:81]
	v_mfma_f32_16x16x32_bf16 v[74:77], v[162:165], v[214:217], v[74:77]
	v_mfma_f32_16x16x32_bf16 v[126:129], v[158:161], v[190:193], v[126:129]
	v_mfma_f32_16x16x32_bf16 v[122:125], v[166:169], v[190:193], v[122:125]
	v_mfma_f32_16x16x32_bf16 v[110:113], v[158:161], v[198:201], v[110:113]
	v_mfma_f32_16x16x32_bf16 v[106:109], v[166:169], v[198:201], v[106:109]
	v_mfma_f32_16x16x32_bf16 v[94:97], v[158:161], v[210:213], v[94:97]
	v_mfma_f32_16x16x32_bf16 v[90:93], v[166:169], v[210:213], v[90:93]
	v_mfma_f32_16x16x32_bf16 v[78:81], v[158:161], v[218:221], v[78:81]
	v_mfma_f32_16x16x32_bf16 v[74:77], v[166:169], v[218:221], v[74:77]
	v_mfma_f32_16x16x32_bf16 v[118:121], v[170:173], v[186:189], v[118:121]
	v_mfma_f32_16x16x32_bf16 v[114:117], v[178:181], v[186:189], v[114:117]
	v_mfma_f32_16x16x32_bf16 v[102:105], v[170:173], v[194:197], v[102:105]
	v_mfma_f32_16x16x32_bf16 v[98:101], v[178:181], v[194:197], v[98:101]
	v_mfma_f32_16x16x32_bf16 v[86:89], v[170:173], v[202:205], v[86:89]
	v_mfma_f32_16x16x32_bf16 v[82:85], v[178:181], v[202:205], v[82:85]
	v_mfma_f32_16x16x32_bf16 v[70:73], v[170:173], v[214:217], v[70:73]
	v_mfma_f32_16x16x32_bf16 v[66:69], v[178:181], v[214:217], v[66:69]
	v_mfma_f32_16x16x32_bf16 v[118:121], v[174:177], v[190:193], v[118:121]
	v_mfma_f32_16x16x32_bf16 v[114:117], v[182:185], v[190:193], v[114:117]
	v_mfma_f32_16x16x32_bf16 v[102:105], v[174:177], v[198:201], v[102:105]
	v_mfma_f32_16x16x32_bf16 v[98:101], v[182:185], v[198:201], v[98:101]
	v_mfma_f32_16x16x32_bf16 v[86:89], v[174:177], v[210:213], v[86:89]
	v_mfma_f32_16x16x32_bf16 v[82:85], v[182:185], v[210:213], v[82:85]
	v_mfma_f32_16x16x32_bf16 v[70:73], v[174:177], v[218:221], v[70:73]
	v_mfma_f32_16x16x32_bf16 v[66:69], v[182:185], v[218:221], v[66:69]
	s_barrier
; #define PG8_STAGE(bufoff, gbase, voff) do { _Pragma("unroll") for (int _i = 0; _i < 2; ++_i) \
;         __builtin_amdgcn_global_load_lds((const unsigned*)((const char*)(gbase) + (voff)[_i]), (PG8_LAS unsigned*)(lds + (bufoff) + ldsw + _i * 8192), 16, 0, 0); } while (0)
; #define PG8_LDA(dst, b, h) do { _Pragma("unroll") for (int m = 0; m < 4; ++m) _Pragma("unroll") for (int k = 0; k < 2; ++k) dst[m][k] = *(const PG8_LAS bf16x8*)(lds + PG8_SA(b, h) + aoff + m * 2048 + k * 1024); } while (0)
; #define PG8_MMA(ai, bj, At, Bt) do { __builtin_amdgcn_s_setprio(1); _Pragma("unroll") for (int m = 0; m < 4; ++m) _Pragma("unroll") for (int n = 0; n < 2; ++n) _Pragma("unroll") for (int k = 0; k < 2; ++k) \
;         acc[ai][bj][m][n] = __builtin_amdgcn_mfma_f32_16x16x32_bf16(Bt[n][k], At[m][k], acc[ai][bj][m][n], 0, 0, 0); __builtin_amdgcn_s_setprio(0); } while (0)
; #define PG8_WAIT_V(n) asm volatile("s_waitcnt vmcnt(" #n ")" ::: "memory")
; #define PG8_WAIT_L(n) asm volatile("s_waitcnt lgkmcnt(" #n ")" ::: "memory")
; #define PG8_BAR __builtin_amdgcn_s_barrier()
; #define PG8_SCHED __builtin_amdgcn_sched_barrier(0)
; template <class Epi, class Sched, bool ALIGN_EPI = false, bool SP2 = false>
; __device__ __forceinline__ void gemm_phase(PG8_LAS unsigned char* lds, const Gemm g, const Sched& S, const Epi& E) {
;     ...
;             PG8_LDA(At, 1, 1); PG8_STAGE(PG8_SB(1, 0), b3, voffB); PG8_STAGE(PG8_SB(1, 1), b3 + hstepB, voffB); PG8_STAGE(PG8_SA(1, 0), a3, voffA);
;             PG8_WAIT_V(8); PG8_WAIT_L(0); PG8_BAR; PG8_MMA(1, 0, At, B0); PG8_MMA(1, 1, At, B1); PG8_BAR; PG8_SCHED;
	s_setprio 0
	s_add_i32 s26, s51, s31
	v_lshl_add_u64 v[146:147], v[146:147], 0, s[2:3]
	s_mov_b32 m0, s26
	ds_read_b128 v[186:189], v152 offset:49152
	ds_read_b128 v[190:193], v152 offset:50176
	ds_read_b128 v[194:197], v152 offset:51200
	ds_read_b128 v[198:201], v152 offset:52224
	ds_read_b128 v[202:205], v152 offset:53248
	ds_read_b128 v[210:213], v152 offset:54272
	ds_read_b128 v[214:217], v152 offset:55296
	ds_read_b128 v[218:221], v152 offset:56320
	global_load_lds_dwordx4 v[146:147], off
	s_add_i32 m0, s26, 0x2000
	s_add_u32 s24, s24, 0x80080
	v_lshl_add_u64 v[146:147], v[206:207], 0, s[2:3]
	s_addc_u32 s25, s25, 0
	s_add_i32 s26, s52, s31
	global_load_lds_dwordx4 v[146:147], off
	v_lshl_add_u64 v[146:147], s[24:25], 0, v[134:135]
	s_mov_b32 m0, s26
	s_nop 0
	global_load_lds_dwordx4 v[146:147], off
	v_lshl_add_u64 v[146:147], s[24:25], 0, v[130:131]
	s_add_i32 m0, s26, 0x2000
	s_nop 0
	global_load_lds_dwordx4 v[146:147], off
	v_lshl_add_u64 v[146:147], v[222:223], 0, s[2:3]
	s_mov_b32 m0, s39
	s_nop 0
	global_load_lds_dwordx4 v[146:147], off
	v_lshl_add_u64 v[146:147], v[224:225], 0, s[2:3]
	s_mov_b32 m0, s40
	s_nop 0
	global_load_lds_dwordx4 v[146:147], off
	s_waitcnt vmcnt(8)
	s_waitcnt lgkmcnt(0)
	s_setprio 1
	s_barrier
	v_mfma_f32_16x16x32_bf16 v[62:65], v[154:157], v[186:189], v[62:65]
	v_mfma_f32_16x16x32_bf16 v[58:61], v[162:165], v[186:189], v[58:61]
	v_mfma_f32_16x16x32_bf16 v[46:49], v[154:157], v[194:197], v[46:49]
	v_mfma_f32_16x16x32_bf16 v[42:45], v[162:165], v[194:197], v[42:45]
	v_mfma_f32_16x16x32_bf16 v[30:33], v[154:157], v[202:205], v[30:33]
	v_mfma_f32_16x16x32_bf16 v[26:29], v[162:165], v[202:205], v[26:29]
	v_mfma_f32_16x16x32_bf16 v[14:17], v[154:157], v[214:217], v[14:17]
	v_mfma_f32_16x16x32_bf16 v[10:13], v[162:165], v[214:217], v[10:13]
	v_mfma_f32_16x16x32_bf16 v[62:65], v[158:161], v[190:193], v[62:65]
	v_mfma_f32_16x16x32_bf16 v[58:61], v[166:169], v[190:193], v[58:61]
	v_mfma_f32_16x16x32_bf16 v[46:49], v[158:161], v[198:201], v[46:49]
	v_mfma_f32_16x16x32_bf16 v[42:45], v[166:169], v[198:201], v[42:45]
	v_mfma_f32_16x16x32_bf16 v[30:33], v[158:161], v[210:213], v[30:33]
	v_mfma_f32_16x16x32_bf16 v[26:29], v[166:169], v[210:213], v[26:29]
	v_mfma_f32_16x16x32_bf16 v[14:17], v[158:161], v[218:221], v[14:17]
	v_mfma_f32_16x16x32_bf16 v[10:13], v[166:169], v[218:221], v[10:13]
	v_mfma_f32_16x16x32_bf16 v[54:57], v[170:173], v[186:189], v[54:57]
	v_mfma_f32_16x16x32_bf16 v[50:53], v[178:181], v[186:189], v[50:53]
	v_mfma_f32_16x16x32_bf16 v[38:41], v[170:173], v[194:197], v[38:41]
	v_mfma_f32_16x16x32_bf16 v[34:37], v[178:181], v[194:197], v[34:37]
	v_mfma_f32_16x16x32_bf16 v[22:25], v[170:173], v[202:205], v[22:25]
	v_mfma_f32_16x16x32_bf16 v[18:21], v[178:181], v[202:205], v[18:21]
	v_mfma_f32_16x16x32_bf16 v[6:9], v[170:173], v[214:217], v[6:9]
	v_mfma_f32_16x16x32_bf16 v[2:5], v[178:181], v[214:217], v[2:5]
	v_mfma_f32_16x16x32_bf16 v[54:57], v[174:177], v[190:193], v[54:57]
	v_mfma_f32_16x16x32_bf16 v[50:53], v[182:185], v[190:193], v[50:53]
	v_mfma_f32_16x16x32_bf16 v[38:41], v[174:177], v[198:201], v[38:41]
	v_mfma_f32_16x16x32_bf16 v[34:37], v[182:185], v[198:201], v[34:37]
	v_mfma_f32_16x16x32_bf16 v[22:25], v[174:177], v[210:213], v[22:25]
	v_mfma_f32_16x16x32_bf16 v[18:21], v[182:185], v[210:213], v[18:21]
	v_mfma_f32_16x16x32_bf16 v[6:9], v[174:177], v[218:221], v[6:9]
	v_mfma_f32_16x16x32_bf16 v[2:5], v[182:185], v[218:221], v[2:5]
	s_barrier
	s_setprio 0
	s_add_i32 s50, s50, 2
	s_add_u32 s22, s22, 0x100
	s_addc_u32 s23, s23, 0
	s_add_u32 s48, s48, 0x100
	s_addc_u32 s49, s49, 0
	s_cmp_gt_u32 s50, 29
	s_cbranch_scc0 .LBB0_1487
	s_and_b64 vcc, exec, s[8:9]
	s_cbranch_vccz .LBB0_1490
	s_barrier

; #define PG8_STAGE(bufoff, gbase, voff) do { _Pragma("unroll") for (int _i = 0; _i < 2; ++_i) \
;         __builtin_amdgcn_global_load_lds((const unsigned*)((const char*)(gbase) + (voff)[_i]), (PG8_LAS unsigned*)(lds + (bufoff) + ldsw + _i * 8192), 16, 0, 0); } while (0)
; #define PG8_LDA(dst, b, h) do { _Pragma("unroll") for (int m = 0; m < 4; ++m) _Pragma("unroll") for (int k = 0; k < 2; ++k) dst[m][k] = *(const PG8_LAS bf16x8*)(lds + PG8_SA(b, h) + aoff + m * 2048 + k * 1024); } while (0)
; #define PG8_LDB(dst, b, h) do { _Pragma("unroll") for (int n = 0; n < 2; ++n) _Pragma("unroll") for (int k = 0; k < 2; ++k) dst[n][k] = *(const PG8_LAS bf16x8*)(lds + PG8_SB(b, h) + boff + n * 2048 + k * 1024); } while (0)
; #define PG8_MMA(ai, bj, At, Bt) do { __builtin_amdgcn_s_setprio(1); _Pragma("unroll") for (int m = 0; m < 4; ++m) _Pragma("unroll") for (int n = 0; n < 2; ++n) _Pragma("unroll") for (int k = 0; k < 2; ++k) \
;         acc[ai][bj][m][n] = __builtin_amdgcn_mfma_f32_16x16x32_bf16(Bt[n][k], At[m][k], acc[ai][bj][m][n], 0, 0, 0); __builtin_amdgcn_s_setprio(0); } while (0)
; #define PG8_WAIT_V(n) asm volatile("s_waitcnt vmcnt(" #n ")" ::: "memory")
; #define PG8_WAIT_L(n) asm volatile("s_waitcnt lgkmcnt(" #n ")" ::: "memory")
; #define PG8_BAR __builtin_amdgcn_s_barrier()
; #define PG8_SCHED __builtin_amdgcn_sched_barrier(0)
; template <class Epi, class Sched, bool ALIGN_EPI = false, bool SP2 = false>
; __device__ __forceinline__ void gemm_phase(PG8_LAS unsigned char* lds, const Gemm g, const Sched& S, const Epi& E) {
;     ...
;             PG8_LDB(B0, 0, 0); PG8_LDB(B1, 0, 1); PG8_SCHED; PG8_LDA(At, 0, 0); PG8_STAGE(PG8_SA(1, 1), a1 + hstepA, voffA);
;             PG8_WAIT_V(8); PG8_WAIT_L(0); PG8_BAR; PG8_MMA(0, 0, At, B0); PG8_MMA(0, 1, At, B1); PG8_BAR; PG8_SCHED;
;             PG8_LDA(At, 0, 1); PG8_STAGE(PG8_SB(0, 0), b2, voffB); PG8_STAGE(PG8_SB(0, 1), b2 + hstepB, voffB); PG8_STAGE(PG8_SA(0, 0), a2, voffA);
;             PG8_WAIT_V(8); PG8_WAIT_L(0); PG8_BAR; PG8_MMA(1, 0, At, B0); PG8_MMA(1, 1, At, B1); PG8_BAR; PG8_SCHED;
.LBB0_1708:
	ds_read_b128 v[152:155], v148
	ds_read_b128 v[156:159], v148 offset:1024
	ds_read_b128 v[160:163], v148 offset:2048
	ds_read_b128 v[164:167], v148 offset:3072
	ds_read_b128 v[168:171], v149
	ds_read_b128 v[172:175], v149 offset:1024
	ds_read_b128 v[176:179], v149 offset:2048
	ds_read_b128 v[180:183], v149 offset:3072
	s_add_u32 s26, s24, 0xffea0080
	s_addc_u32 s27, s25, -1
	s_cmpk_eq_i32 s57, 0x54
	s_cselect_b32 s29, s7, s27
	s_cselect_b32 s28, s6, s26
	s_cselect_b32 s27, s23, s56
	s_cselect_b32 s26, s22, s55
	v_lshl_add_u64 v[218:219], s[24:25], 0, v[138:139]
	s_add_i32 m0, s37, 0xc000
	ds_read_b128 v[184:187], v150
	ds_read_b128 v[188:191], v150 offset:1024
	ds_read_b128 v[192:195], v150 offset:2048
	ds_read_b128 v[196:199], v150 offset:3072
	ds_read_b128 v[200:203], v150 offset:4096
	ds_read_b128 v[204:207], v150 offset:5120
	ds_read_b128 v[210:213], v150 offset:6144
	ds_read_b128 v[214:217], v150 offset:7168
	global_load_lds_dwordx4 v[218:219], off
	v_lshl_add_u64 v[218:219], s[24:25], 0, v[140:141]
	s_add_i32 m0, s37, 0xe000
	s_nop 0
	global_load_lds_dwordx4 v[218:219], off
	s_waitcnt vmcnt(8)
	s_waitcnt lgkmcnt(0)
	s_setprio 1
	s_barrier
	v_mfma_f32_16x16x32_bf16 v[126:129], v[152:155], v[184:187], v[126:129]
	v_mfma_f32_16x16x32_bf16 v[122:125], v[160:163], v[184:187], v[122:125]
	v_mfma_f32_16x16x32_bf16 v[118:121], v[152:155], v[192:195], v[118:121]
	v_mfma_f32_16x16x32_bf16 v[114:117], v[160:163], v[192:195], v[114:117]
	v_mfma_f32_16x16x32_bf16 v[102:105], v[152:155], v[200:203], v[102:105]
	v_mfma_f32_16x16x32_bf16 v[98:101], v[160:163], v[200:203], v[98:101]
	v_mfma_f32_16x16x32_bf16 v[86:89], v[152:155], v[210:213], v[86:89]
	v_mfma_f32_16x16x32_bf16 v[82:85], v[160:163], v[210:213], v[82:85]
	v_mfma_f32_16x16x32_bf16 v[126:129], v[156:159], v[188:191], v[126:129]
	v_mfma_f32_16x16x32_bf16 v[122:125], v[164:167], v[188:191], v[122:125]
	v_mfma_f32_16x16x32_bf16 v[118:121], v[156:159], v[196:199], v[118:121]
	v_mfma_f32_16x16x32_bf16 v[114:117], v[164:167], v[196:199], v[114:117]
	v_mfma_f32_16x16x32_bf16 v[102:105], v[156:159], v[204:207], v[102:105]
	v_mfma_f32_16x16x32_bf16 v[98:101], v[164:167], v[204:207], v[98:101]
	v_mfma_f32_16x16x32_bf16 v[86:89], v[156:159], v[214:217], v[86:89]
	v_mfma_f32_16x16x32_bf16 v[82:85], v[164:167], v[214:217], v[82:85]
	v_mfma_f32_16x16x32_bf16 v[110:113], v[168:171], v[184:187], v[110:113]
	v_mfma_f32_16x16x32_bf16 v[106:109], v[176:179], v[184:187], v[106:109]
	v_mfma_f32_16x16x32_bf16 v[94:97], v[168:171], v[192:195], v[94:97]
	v_mfma_f32_16x16x32_bf16 v[90:93], v[176:179], v[192:195], v[90:93]
	v_mfma_f32_16x16x32_bf16 v[78:81], v[168:171], v[200:203], v[78:81]
	v_mfma_f32_16x16x32_bf16 v[74:77], v[176:179], v[200:203], v[74:77]
	v_mfma_f32_16x16x32_bf16 v[70:73], v[168:171], v[210:213], v[70:73]
	v_mfma_f32_16x16x32_bf16 v[66:69], v[176:179], v[210:213], v[66:69]
	v_mfma_f32_16x16x32_bf16 v[110:113], v[172:175], v[188:191], v[110:113]
	v_mfma_f32_16x16x32_bf16 v[106:109], v[180:183], v[188:191], v[106:109]
	v_mfma_f32_16x16x32_bf16 v[94:97], v[172:175], v[196:199], v[94:97]
	v_mfma_f32_16x16x32_bf16 v[90:93], v[180:183], v[196:199], v[90:93]
	v_mfma_f32_16x16x32_bf16 v[78:81], v[172:175], v[204:207], v[78:81]
	v_mfma_f32_16x16x32_bf16 v[74:77], v[180:183], v[204:207], v[74:77]
	v_mfma_f32_16x16x32_bf16 v[70:73], v[172:175], v[214:217], v[70:73]
	v_mfma_f32_16x16x32_bf16 v[66:69], v[180:183], v[214:217], v[66:69]
	s_barrier
	s_setprio 0
	s_add_i32 s58, s45, s34
	v_lshl_add_u64 v[218:219], s[26:27], 0, v[134:135]
	s_mov_b32 m0, s58
	ds_read_b128 v[184:187], v150 offset:16384
	ds_read_b128 v[188:191], v150 offset:17408
	ds_read_b128 v[192:195], v150 offset:18432
	ds_read_b128 v[196:199], v150 offset:19456
	ds_read_b128 v[200:203], v150 offset:20480
	ds_read_b128 v[204:207], v150 offset:21504
	ds_read_b128 v[210:213], v150 offset:22528
	ds_read_b128 v[214:217], v150 offset:23552
	global_load_lds_dwordx4 v[218:219], off
	s_add_i32 m0, s58, 0x2000
	s_add_u32 s58, s26, 0x160000
	v_lshl_add_u64 v[220:221], s[26:27], 0, v[130:131]
	s_addc_u32 s59, s27, 0
	s_add_i32 s60, s46, s34
	global_load_lds_dwordx4 v[220:221], off
	v_lshl_add_u64 v[222:223], s[58:59], 0, v[134:135]
	s_mov_b32 m0, s60
	v_lshl_add_u64 v[224:225], s[28:29], 0, v[132:133]
	global_load_lds_dwordx4 v[222:223], off
	v_lshl_add_u64 v[222:223], s[58:59], 0, v[130:131]
	s_add_i32 m0, s60, 0x2000
	s_nop 0
	global_load_lds_dwordx4 v[222:223], off
	v_lshl_add_u64 v[222:223], s[28:29], 0, v[136:137]
	s_mov_b32 m0, s37
	s_nop 0
	global_load_lds_dwordx4 v[222:223], off
	s_mov_b32 m0, s38
	s_nop 0
	global_load_lds_dwordx4 v[224:225], off
	s_waitcnt vmcnt(8)
	s_waitcnt lgkmcnt(0)
	s_setprio 1
	s_barrier
; #define PG8_STAGE(bufoff, gbase, voff) do { _Pragma("unroll") for (int _i = 0; _i < 2; ++_i) \
;         __builtin_amdgcn_global_load_lds((const unsigned*)((const char*)(gbase) + (voff)[_i]), (PG8_LAS unsigned*)(lds + (bufoff) + ldsw + _i * 8192), 16, 0, 0); } while (0)
; #define PG8_LDA(dst, b, h) do { _Pragma("unroll") for (int m = 0; m < 4; ++m) _Pragma("unroll") for (int k = 0; k < 2; ++k) dst[m][k] = *(const PG8_LAS bf16x8*)(lds + PG8_SA(b, h) + aoff + m * 2048 + k * 1024); } while (0)
; #define PG8_LDB(dst, b, h) do { _Pragma("unroll") for (int n = 0; n < 2; ++n) _Pragma("unroll") for (int k = 0; k < 2; ++k) dst[n][k] = *(const PG8_LAS bf16x8*)(lds + PG8_SB(b, h) + boff + n * 2048 + k * 1024); } while (0)
; #define PG8_MMA(ai, bj, At, Bt) do { __builtin_amdgcn_s_setprio(1); _Pragma("unroll") for (int m = 0; m < 4; ++m) _Pragma("unroll") for (int n = 0; n < 2; ++n) _Pragma("unroll") for (int k = 0; k < 2; ++k) \
;         acc[ai][bj][m][n] = __builtin_amdgcn_mfma_f32_16x16x32_bf16(Bt[n][k], At[m][k], acc[ai][bj][m][n], 0, 0, 0); __builtin_amdgcn_s_setprio(0); } while (0)
; #define PG8_WAIT_V(n) asm volatile("s_waitcnt vmcnt(" #n ")" ::: "memory")
; #define PG8_WAIT_L(n) asm volatile("s_waitcnt lgkmcnt(" #n ")" ::: "memory")
; #define PG8_BAR __builtin_amdgcn_s_barrier()
; #define PG8_SCHED __builtin_amdgcn_sched_barrier(0)
; template <class Epi, class Sched, bool ALIGN_EPI = false, bool SP2 = false>
; __device__ __forceinline__ void gemm_phase(PG8_LAS unsigned char* lds, const Gemm g, const Sched& S, const Epi& E) {
;     ...
;             PG8_WAIT_V(8); PG8_WAIT_L(0); PG8_BAR; PG8_MMA(1, 0, At, B0); PG8_MMA(1, 1, At, B1); PG8_BAR; PG8_SCHED;
;             PG8_LDB(B0, 1, 0); PG8_LDB(B1, 1, 1); PG8_SCHED; PG8_LDA(At, 1, 0); PG8_STAGE(PG8_SA(0, 1), a2 + hstepA, voffA);
;             PG8_WAIT_V(8); PG8_WAIT_L(0); PG8_BAR; PG8_MMA(0, 0, At, B0); PG8_MMA(0, 1, At, B1); PG8_BAR; PG8_SCHED;
	v_mfma_f32_16x16x32_bf16 v[62:65], v[152:155], v[184:187], v[62:65]
	v_mfma_f32_16x16x32_bf16 v[58:61], v[160:163], v[184:187], v[58:61]
	v_mfma_f32_16x16x32_bf16 v[54:57], v[152:155], v[192:195], v[54:57]
	v_mfma_f32_16x16x32_bf16 v[50:53], v[160:163], v[192:195], v[50:53]
	v_mfma_f32_16x16x32_bf16 v[38:41], v[152:155], v[200:203], v[38:41]
	v_mfma_f32_16x16x32_bf16 v[34:37], v[160:163], v[200:203], v[34:37]
	v_mfma_f32_16x16x32_bf16 v[22:25], v[152:155], v[210:213], v[22:25]
	v_mfma_f32_16x16x32_bf16 v[18:21], v[160:163], v[210:213], v[18:21]
	v_mfma_f32_16x16x32_bf16 v[62:65], v[156:159], v[188:191], v[62:65]
	v_mfma_f32_16x16x32_bf16 v[58:61], v[164:167], v[188:191], v[58:61]
	v_mfma_f32_16x16x32_bf16 v[54:57], v[156:159], v[196:199], v[54:57]
	v_mfma_f32_16x16x32_bf16 v[50:53], v[164:167], v[196:199], v[50:53]
	v_mfma_f32_16x16x32_bf16 v[38:41], v[156:159], v[204:207], v[38:41]
	v_mfma_f32_16x16x32_bf16 v[34:37], v[164:167], v[204:207], v[34:37]
	v_mfma_f32_16x16x32_bf16 v[22:25], v[156:159], v[214:217], v[22:25]
	v_mfma_f32_16x16x32_bf16 v[18:21], v[164:167], v[214:217], v[18:21]
	v_mfma_f32_16x16x32_bf16 v[46:49], v[168:171], v[184:187], v[46:49]
	v_mfma_f32_16x16x32_bf16 v[42:45], v[176:179], v[184:187], v[42:45]
	v_mfma_f32_16x16x32_bf16 v[30:33], v[168:171], v[192:195], v[30:33]
	v_mfma_f32_16x16x32_bf16 v[26:29], v[176:179], v[192:195], v[26:29]
	v_mfma_f32_16x16x32_bf16 v[14:17], v[168:171], v[200:203], v[14:17]
	v_mfma_f32_16x16x32_bf16 v[10:13], v[176:179], v[200:203], v[10:13]
	v_mfma_f32_16x16x32_bf16 v[6:9], v[168:171], v[210:213], v[6:9]
	v_mfma_f32_16x16x32_bf16 v[2:5], v[176:179], v[210:213], v[2:5]
	v_mfma_f32_16x16x32_bf16 v[46:49], v[172:175], v[188:191], v[46:49]
	v_mfma_f32_16x16x32_bf16 v[42:45], v[180:183], v[188:191], v[42:45]
	v_mfma_f32_16x16x32_bf16 v[30:33], v[172:175], v[196:199], v[30:33]
	v_mfma_f32_16x16x32_bf16 v[26:29], v[180:183], v[196:199], v[26:29]
	v_mfma_f32_16x16x32_bf16 v[14:17], v[172:175], v[204:207], v[14:17]
	v_mfma_f32_16x16x32_bf16 v[10:13], v[180:183], v[204:207], v[10:13]
	v_mfma_f32_16x16x32_bf16 v[6:9], v[172:175], v[214:217], v[6:9]
	v_mfma_f32_16x16x32_bf16 v[2:5], v[180:183], v[214:217], v[2:5]
	s_barrier
	s_setprio 0
	s_add_i32 s58, 0, 0x18000
	v_add_u32_e32 v151, s58, v146
	s_add_i32 s59, 0, 0x1c000
	ds_read_b128 v[152:155], v151
	ds_read_b128 v[156:159], v151 offset:1024
	ds_read_b128 v[160:163], v151 offset:2048
	ds_read_b128 v[164:167], v151 offset:3072
	v_add_u32_e32 v151, s59, v146
	ds_read_b128 v[168:171], v151
	ds_read_b128 v[172:175], v151 offset:1024
	ds_read_b128 v[176:179], v151 offset:2048
	ds_read_b128 v[180:183], v151 offset:3072
	s_add_u32 s28, s28, 0x160000
	s_addc_u32 s29, s29, 0
	s_mov_b32 m0, s39
	v_lshl_add_u64 v[226:227], s[28:29], 0, v[136:137]
	ds_read_b128 v[184:187], v150 offset:32768
	ds_read_b128 v[188:191], v150 offset:33792
	ds_read_b128 v[192:195], v150 offset:34816
	ds_read_b128 v[196:199], v150 offset:35840
	ds_read_b128 v[200:203], v150 offset:36864
	ds_read_b128 v[204:207], v150 offset:37888
	ds_read_b128 v[210:213], v150 offset:38912
	ds_read_b128 v[214:217], v150 offset:39936
	global_load_lds_dwordx4 v[226:227], off
	v_lshl_add_u64 v[226:227], s[28:29], 0, v[132:133]
	s_mov_b32 m0, s40
	s_nop 0
	global_load_lds_dwordx4 v[226:227], off
	s_waitcnt vmcnt(8)
	s_waitcnt lgkmcnt(0)
	s_setprio 1
	s_barrier
	v_mfma_f32_16x16x32_bf16 v[126:129], v[152:155], v[184:187], v[126:129]
	v_mfma_f32_16x16x32_bf16 v[122:125], v[160:163], v[184:187], v[122:125]
	v_mfma_f32_16x16x32_bf16 v[118:121], v[152:155], v[192:195], v[118:121]
	v_mfma_f32_16x16x32_bf16 v[114:117], v[160:163], v[192:195], v[114:117]
	v_mfma_f32_16x16x32_bf16 v[102:105], v[152:155], v[200:203], v[102:105]
	v_mfma_f32_16x16x32_bf16 v[98:101], v[160:163], v[200:203], v[98:101]
	v_mfma_f32_16x16x32_bf16 v[86:89], v[152:155], v[210:213], v[86:89]
	v_mfma_f32_16x16x32_bf16 v[82:85], v[160:163], v[210:213], v[82:85]
	v_mfma_f32_16x16x32_bf16 v[126:129], v[156:159], v[188:191], v[126:129]
	v_mfma_f32_16x16x32_bf16 v[122:125], v[164:167], v[188:191], v[122:125]
	v_mfma_f32_16x16x32_bf16 v[118:121], v[156:159], v[196:199], v[118:121]
	v_mfma_f32_16x16x32_bf16 v[114:117], v[164:167], v[196:199], v[114:117]
	v_mfma_f32_16x16x32_bf16 v[102:105], v[156:159], v[204:207], v[102:105]
	v_mfma_f32_16x16x32_bf16 v[98:101], v[164:167], v[204:207], v[98:101]
	v_mfma_f32_16x16x32_bf16 v[86:89], v[156:159], v[214:217], v[86:89]
	v_mfma_f32_16x16x32_bf16 v[82:85], v[164:167], v[214:217], v[82:85]
	v_mfma_f32_16x16x32_bf16 v[110:113], v[168:171], v[184:187], v[110:113]
	v_mfma_f32_16x16x32_bf16 v[106:109], v[176:179], v[184:187], v[106:109]
	v_mfma_f32_16x16x32_bf16 v[94:97], v[168:171], v[192:195], v[94:97]
	v_mfma_f32_16x16x32_bf16 v[90:93], v[176:179], v[192:195], v[90:93]
	v_mfma_f32_16x16x32_bf16 v[78:81], v[168:171], v[200:203], v[78:81]
	v_mfma_f32_16x16x32_bf16 v[74:77], v[176:179], v[200:203], v[74:77]
	v_mfma_f32_16x16x32_bf16 v[70:73], v[168:171], v[210:213], v[70:73]
	v_mfma_f32_16x16x32_bf16 v[66:69], v[176:179], v[210:213], v[66:69]
	v_mfma_f32_16x16x32_bf16 v[110:113], v[172:175], v[188:191], v[110:113]
	v_mfma_f32_16x16x32_bf16 v[106:109], v[180:183], v[188:191], v[106:109]
	v_mfma_f32_16x16x32_bf16 v[94:97], v[172:175], v[196:199], v[94:97]
	v_mfma_f32_16x16x32_bf16 v[90:93], v[180:183], v[196:199], v[90:93]
	v_mfma_f32_16x16x32_bf16 v[78:81], v[172:175], v[204:207], v[78:81]
	v_mfma_f32_16x16x32_bf16 v[74:77], v[180:183], v[204:207], v[74:77]
	v_mfma_f32_16x16x32_bf16 v[70:73], v[172:175], v[214:217], v[70:73]
	v_mfma_f32_16x16x32_bf16 v[66:69], v[180:183], v[214:217], v[66:69]
	s_barrier
; #define PG8_STAGE(bufoff, gbase, voff) do { _Pragma("unroll") for (int _i = 0; _i < 2; ++_i) \
;         __builtin_amdgcn_global_load_lds((const unsigned*)((const char*)(gbase) + (voff)[_i]), (PG8_LAS unsigned*)(lds + (bufoff) + ldsw + _i * 8192), 16, 0, 0); } while (0)
; #define PG8_LDA(dst, b, h) do { _Pragma("unroll") for (int m = 0; m < 4; ++m) _Pragma("unroll") for (int k = 0; k < 2; ++k) dst[m][k] = *(const PG8_LAS bf16x8*)(lds + PG8_SA(b, h) + aoff + m * 2048 + k * 1024); } while (0)
; #define PG8_MMA(ai, bj, At, Bt) do { __builtin_amdgcn_s_setprio(1); _Pragma("unroll") for (int m = 0; m < 4; ++m) _Pragma("unroll") for (int n = 0; n < 2; ++n) _Pragma("unroll") for (int k = 0; k < 2; ++k) \
;         acc[ai][bj][m][n] = __builtin_amdgcn_mfma_f32_16x16x32_bf16(Bt[n][k], At[m][k], acc[ai][bj][m][n], 0, 0, 0); __builtin_amdgcn_s_setprio(0); } while (0)
; #define PG8_WAIT_V(n) asm volatile("s_waitcnt vmcnt(" #n ")" ::: "memory")
; #define PG8_WAIT_L(n) asm volatile("s_waitcnt lgkmcnt(" #n ")" ::: "memory")
; #define PG8_BAR __builtin_amdgcn_s_barrier()
; #define PG8_SCHED __builtin_amdgcn_sched_barrier(0)
; template <class Epi, class Sched, bool ALIGN_EPI = false, bool SP2 = false>
; __device__ __forceinline__ void gemm_phase(PG8_LAS unsigned char* lds, const Gemm g, const Sched& S, const Epi& E) {
;     ...
;             PG8_LDA(At, 1, 1); PG8_STAGE(PG8_SB(1, 0), b3, voffB); PG8_STAGE(PG8_SB(1, 1), b3 + hstepB, voffB); PG8_STAGE(PG8_SA(1, 0), a3, voffA);
;             PG8_WAIT_V(8); PG8_WAIT_L(0); PG8_BAR; PG8_MMA(1, 0, At, B0); PG8_MMA(1, 1, At, B1); PG8_BAR; PG8_SCHED;
	s_setprio 0
	s_add_i32 s28, s58, s34
	v_lshl_add_u64 v[218:219], v[218:219], 0, s[8:9]
	s_mov_b32 m0, s28
	ds_read_b128 v[184:187], v150 offset:49152
	ds_read_b128 v[188:191], v150 offset:50176
	ds_read_b128 v[192:195], v150 offset:51200
	ds_read_b128 v[196:199], v150 offset:52224
	ds_read_b128 v[200:203], v150 offset:53248
	ds_read_b128 v[204:207], v150 offset:54272
	ds_read_b128 v[210:213], v150 offset:55296
	ds_read_b128 v[214:217], v150 offset:56320
	global_load_lds_dwordx4 v[218:219], off
	s_add_i32 m0, s28, 0x2000
	s_add_u32 s26, s26, 0x160080
	v_lshl_add_u64 v[218:219], v[220:221], 0, s[8:9]
	s_addc_u32 s27, s27, 0
	s_add_i32 s28, s59, s34
	global_load_lds_dwordx4 v[218:219], off
	v_lshl_add_u64 v[218:219], s[26:27], 0, v[134:135]
	s_mov_b32 m0, s28
	s_nop 0
	global_load_lds_dwordx4 v[218:219], off
	v_lshl_add_u64 v[218:219], s[26:27], 0, v[130:131]
	s_add_i32 m0, s28, 0x2000
	s_nop 0
	global_load_lds_dwordx4 v[218:219], off
	v_lshl_add_u64 v[218:219], v[222:223], 0, s[8:9]
	s_mov_b32 m0, s42
	s_nop 0
	global_load_lds_dwordx4 v[218:219], off
	v_lshl_add_u64 v[218:219], v[224:225], 0, s[8:9]
	s_mov_b32 m0, s43
	s_nop 0
	global_load_lds_dwordx4 v[218:219], off
	s_waitcnt vmcnt(8)
	s_waitcnt lgkmcnt(0)
	s_setprio 1
	s_barrier
	v_mfma_f32_16x16x32_bf16 v[62:65], v[152:155], v[184:187], v[62:65]
	v_mfma_f32_16x16x32_bf16 v[58:61], v[160:163], v[184:187], v[58:61]
	v_mfma_f32_16x16x32_bf16 v[54:57], v[152:155], v[192:195], v[54:57]
	v_mfma_f32_16x16x32_bf16 v[50:53], v[160:163], v[192:195], v[50:53]
	v_mfma_f32_16x16x32_bf16 v[38:41], v[152:155], v[200:203], v[38:41]
	v_mfma_f32_16x16x32_bf16 v[34:37], v[160:163], v[200:203], v[34:37]
	v_mfma_f32_16x16x32_bf16 v[22:25], v[152:155], v[210:213], v[22:25]
	v_mfma_f32_16x16x32_bf16 v[18:21], v[160:163], v[210:213], v[18:21]
	v_mfma_f32_16x16x32_bf16 v[62:65], v[156:159], v[188:191], v[62:65]
	v_mfma_f32_16x16x32_bf16 v[58:61], v[164:167], v[188:191], v[58:61]
	v_mfma_f32_16x16x32_bf16 v[54:57], v[156:159], v[196:199], v[54:57]
	v_mfma_f32_16x16x32_bf16 v[50:53], v[164:167], v[196:199], v[50:53]
	v_mfma_f32_16x16x32_bf16 v[38:41], v[156:159], v[204:207], v[38:41]
	v_mfma_f32_16x16x32_bf16 v[34:37], v[164:167], v[204:207], v[34:37]
	v_mfma_f32_16x16x32_bf16 v[22:25], v[156:159], v[214:217], v[22:25]
	v_mfma_f32_16x16x32_bf16 v[18:21], v[164:167], v[214:217], v[18:21]
	v_mfma_f32_16x16x32_bf16 v[46:49], v[168:171], v[184:187], v[46:49]
	v_mfma_f32_16x16x32_bf16 v[42:45], v[176:179], v[184:187], v[42:45]
	v_mfma_f32_16x16x32_bf16 v[30:33], v[168:171], v[192:195], v[30:33]
	v_mfma_f32_16x16x32_bf16 v[26:29], v[176:179], v[192:195], v[26:29]
	v_mfma_f32_16x16x32_bf16 v[14:17], v[168:171], v[200:203], v[14:17]
	v_mfma_f32_16x16x32_bf16 v[10:13], v[176:179], v[200:203], v[10:13]
	v_mfma_f32_16x16x32_bf16 v[6:9], v[168:171], v[210:213], v[6:9]
	v_mfma_f32_16x16x32_bf16 v[2:5], v[176:179], v[210:213], v[2:5]
	v_mfma_f32_16x16x32_bf16 v[46:49], v[172:175], v[188:191], v[46:49]
	v_mfma_f32_16x16x32_bf16 v[42:45], v[180:183], v[188:191], v[42:45]
	v_mfma_f32_16x16x32_bf16 v[30:33], v[172:175], v[196:199], v[30:33]
	v_mfma_f32_16x16x32_bf16 v[26:29], v[180:183], v[196:199], v[26:29]
	v_mfma_f32_16x16x32_bf16 v[14:17], v[172:175], v[204:207], v[14:17]
	v_mfma_f32_16x16x32_bf16 v[10:13], v[180:183], v[204:207], v[10:13]
	v_mfma_f32_16x16x32_bf16 v[6:9], v[172:175], v[214:217], v[6:9]
	v_mfma_f32_16x16x32_bf16 v[2:5], v[180:183], v[214:217], v[2:5]
	s_barrier
	s_setprio 0
	s_add_i32 s57, s57, 2
	s_add_u32 s24, s24, 0x100
	s_addc_u32 s25, s25, 0
	s_add_u32 s55, s55, 0x100
	s_addc_u32 s56, s56, 0
	s_cmpk_gt_u32 s57, 0x55
	s_cbranch_scc0 .LBB0_1708
	s_and_b64 vcc, exec, s[10:11]
	s_cbranch_vccz .LBB0_1711
	s_barrier

; #define PG8_STAGE(bufoff, gbase, voff) do { _Pragma("unroll") for (int _i = 0; _i < 2; ++_i) \
;         __builtin_amdgcn_global_load_lds((const unsigned*)((const char*)(gbase) + (voff)[_i]), (PG8_LAS unsigned*)(lds + (bufoff) + ldsw + _i * 8192), 16, 0, 0); } while (0)
; #define PG8_LDA(dst, b, h) do { _Pragma("unroll") for (int m = 0; m < 4; ++m) _Pragma("unroll") for (int k = 0; k < 2; ++k) dst[m][k] = *(const PG8_LAS bf16x8*)(lds + PG8_SA(b, h) + aoff + m * 2048 + k * 1024); } while (0)
; #define PG8_LDB(dst, b, h) do { _Pragma("unroll") for (int n = 0; n < 2; ++n) _Pragma("unroll") for (int k = 0; k < 2; ++k) dst[n][k] = *(const PG8_LAS bf16x8*)(lds + PG8_SB(b, h) + boff + n * 2048 + k * 1024); } while (0)
; #define PG8_MMA(ai, bj, At, Bt) do { __builtin_amdgcn_s_setprio(1); _Pragma("unroll") for (int m = 0; m < 4; ++m) _Pragma("unroll") for (int n = 0; n < 2; ++n) _Pragma("unroll") for (int k = 0; k < 2; ++k) \
;         acc[ai][bj][m][n] = __builtin_amdgcn_mfma_f32_16x16x32_bf16(Bt[n][k], At[m][k], acc[ai][bj][m][n], 0, 0, 0); __builtin_amdgcn_s_setprio(0); } while (0)
; #define PG8_WAIT_V(n) asm volatile("s_waitcnt vmcnt(" #n ")" ::: "memory")
; #define PG8_WAIT_L(n) asm volatile("s_waitcnt lgkmcnt(" #n ")" ::: "memory")
; #define PG8_BAR __builtin_amdgcn_s_barrier()
; #define PG8_SCHED __builtin_amdgcn_sched_barrier(0)
; template <class Epi, class Sched, bool ALIGN_EPI = false, bool SP2 = false>
; __device__ __forceinline__ void gemm_phase(PG8_LAS unsigned char* lds, const Gemm g, const Sched& S, const Epi& E) {
;     ...
;             PG8_LDB(B0, 0, 0); PG8_LDB(B1, 0, 1); PG8_SCHED; PG8_LDA(At, 0, 0); PG8_STAGE(PG8_SA(1, 1), a1 + hstepA, voffA);
;             PG8_WAIT_V(8); PG8_WAIT_L(0); PG8_BAR; PG8_MMA(0, 0, At, B0); PG8_MMA(0, 1, At, B1); PG8_BAR; PG8_SCHED;
;             PG8_LDA(At, 0, 1); PG8_STAGE(PG8_SB(0, 0), b2, voffB); PG8_STAGE(PG8_SB(0, 1), b2 + hstepB, voffB); PG8_STAGE(PG8_SA(0, 0), a2, voffA);
;             PG8_WAIT_V(8); PG8_WAIT_L(0); PG8_BAR; PG8_MMA(1, 0, At, B0); PG8_MMA(1, 1, At, B1); PG8_BAR; PG8_SCHED;
.LBB0_1839:
	ds_read_b128 v[160:163], v143
	ds_read_b128 v[164:167], v143 offset:1024
	ds_read_b128 v[168:171], v143 offset:2048
	ds_read_b128 v[172:175], v143 offset:3072
	ds_read_b128 v[176:179], v156
	ds_read_b128 v[180:183], v156 offset:1024
	ds_read_b128 v[184:187], v156 offset:2048
	ds_read_b128 v[188:191], v156 offset:3072
	s_add_u32 s30, s12, 0xfff80080
	s_addc_u32 s31, s13, -1
	s_cmp_eq_u32 s39, 28
	s_cselect_b32 s35, s11, s31
	s_cselect_b32 s34, s25, s30
	s_cselect_b32 s31, s23, s38
	s_cselect_b32 s30, s36, s37
	v_lshl_add_u64 v[226:227], s[12:13], 0, v[148:149]
	s_add_i32 m0, s17, 0xc000
	ds_read_b128 v[192:195], v157
	ds_read_b128 v[196:199], v157 offset:1024
	ds_read_b128 v[200:203], v157 offset:2048
	ds_read_b128 v[204:207], v157 offset:3072
	ds_read_b128 v[210:213], v157 offset:4096
	ds_read_b128 v[214:217], v157 offset:5120
	ds_read_b128 v[218:221], v157 offset:6144
	ds_read_b128 v[222:225], v157 offset:7168
	global_load_lds_dwordx4 v[226:227], off
	v_lshl_add_u64 v[226:227], s[12:13], 0, v[150:151]
	s_add_i32 m0, s17, 0xe000
	s_nop 0
	global_load_lds_dwordx4 v[226:227], off
	s_waitcnt vmcnt(8)
	s_waitcnt lgkmcnt(0)
	s_setprio 1
	s_barrier
	v_mfma_f32_16x16x32_bf16 v[126:129], v[160:163], v[192:195], v[126:129]
	v_mfma_f32_16x16x32_bf16 v[122:125], v[168:171], v[192:195], v[122:125]
	v_mfma_f32_16x16x32_bf16 v[110:113], v[160:163], v[200:203], v[110:113]
	v_mfma_f32_16x16x32_bf16 v[106:109], v[168:171], v[200:203], v[106:109]
	v_mfma_f32_16x16x32_bf16 v[94:97], v[160:163], v[210:213], v[94:97]
	v_mfma_f32_16x16x32_bf16 v[90:93], v[168:171], v[210:213], v[90:93]
	v_mfma_f32_16x16x32_bf16 v[78:81], v[160:163], v[218:221], v[78:81]
	v_mfma_f32_16x16x32_bf16 v[74:77], v[168:171], v[218:221], v[74:77]
	v_mfma_f32_16x16x32_bf16 v[126:129], v[164:167], v[196:199], v[126:129]
	v_mfma_f32_16x16x32_bf16 v[122:125], v[172:175], v[196:199], v[122:125]
	v_mfma_f32_16x16x32_bf16 v[110:113], v[164:167], v[204:207], v[110:113]
	v_mfma_f32_16x16x32_bf16 v[106:109], v[172:175], v[204:207], v[106:109]
	v_mfma_f32_16x16x32_bf16 v[94:97], v[164:167], v[214:217], v[94:97]
	v_mfma_f32_16x16x32_bf16 v[90:93], v[172:175], v[214:217], v[90:93]
	v_mfma_f32_16x16x32_bf16 v[78:81], v[164:167], v[222:225], v[78:81]
	v_mfma_f32_16x16x32_bf16 v[74:77], v[172:175], v[222:225], v[74:77]
	v_mfma_f32_16x16x32_bf16 v[118:121], v[176:179], v[192:195], v[118:121]
	v_mfma_f32_16x16x32_bf16 v[114:117], v[184:187], v[192:195], v[114:117]
	v_mfma_f32_16x16x32_bf16 v[102:105], v[176:179], v[200:203], v[102:105]
	v_mfma_f32_16x16x32_bf16 v[98:101], v[184:187], v[200:203], v[98:101]
	v_mfma_f32_16x16x32_bf16 v[86:89], v[176:179], v[210:213], v[86:89]
	v_mfma_f32_16x16x32_bf16 v[82:85], v[184:187], v[210:213], v[82:85]
	v_mfma_f32_16x16x32_bf16 v[70:73], v[176:179], v[218:221], v[70:73]
	v_mfma_f32_16x16x32_bf16 v[66:69], v[184:187], v[218:221], v[66:69]
	v_mfma_f32_16x16x32_bf16 v[118:121], v[180:183], v[196:199], v[118:121]
	v_mfma_f32_16x16x32_bf16 v[114:117], v[188:191], v[196:199], v[114:117]
	v_mfma_f32_16x16x32_bf16 v[102:105], v[180:183], v[204:207], v[102:105]
	v_mfma_f32_16x16x32_bf16 v[98:101], v[188:191], v[204:207], v[98:101]
	v_mfma_f32_16x16x32_bf16 v[86:89], v[180:183], v[214:217], v[86:89]
	v_mfma_f32_16x16x32_bf16 v[82:85], v[188:191], v[214:217], v[82:85]
	v_mfma_f32_16x16x32_bf16 v[70:73], v[180:183], v[222:225], v[70:73]
	v_mfma_f32_16x16x32_bf16 v[66:69], v[188:191], v[222:225], v[66:69]
	s_barrier
	s_setprio 0
	s_add_i32 s58, s50, s40
	v_lshl_add_u64 v[226:227], s[30:31], 0, v[132:133]
	s_mov_b32 m0, s58
	ds_read_b128 v[192:195], v157 offset:16384
	ds_read_b128 v[196:199], v157 offset:17408
	ds_read_b128 v[200:203], v157 offset:18432
	ds_read_b128 v[204:207], v157 offset:19456
	ds_read_b128 v[210:213], v157 offset:20480
	ds_read_b128 v[214:217], v157 offset:21504
	ds_read_b128 v[218:221], v157 offset:22528
	ds_read_b128 v[222:225], v157 offset:23552
	global_load_lds_dwordx4 v[226:227], off
	s_add_i32 m0, s58, 0x2000
	s_add_u32 s58, s30, 0x80000
	v_lshl_add_u64 v[228:229], s[30:31], 0, v[136:137]
	s_addc_u32 s59, s31, 0
	s_add_i32 s60, s51, s40
	global_load_lds_dwordx4 v[228:229], off
	v_lshl_add_u64 v[230:231], s[58:59], 0, v[132:133]
	s_mov_b32 m0, s60
	v_lshl_add_u64 v[232:233], s[34:35], 0, v[134:135]
	global_load_lds_dwordx4 v[230:231], off
	v_lshl_add_u64 v[230:231], s[58:59], 0, v[136:137]
	s_add_i32 m0, s60, 0x2000
	s_nop 0
	global_load_lds_dwordx4 v[230:231], off
	v_lshl_add_u64 v[230:231], s[34:35], 0, v[130:131]
	s_mov_b32 m0, s17
	s_nop 0
	global_load_lds_dwordx4 v[230:231], off
	s_mov_b32 m0, s41
	s_nop 0
	global_load_lds_dwordx4 v[232:233], off
	s_waitcnt vmcnt(8)
	s_waitcnt lgkmcnt(0)
	s_setprio 1
	s_barrier
; #define PG8_STAGE(bufoff, gbase, voff) do { _Pragma("unroll") for (int _i = 0; _i < 2; ++_i) \
;         __builtin_amdgcn_global_load_lds((const unsigned*)((const char*)(gbase) + (voff)[_i]), (PG8_LAS unsigned*)(lds + (bufoff) + ldsw + _i * 8192), 16, 0, 0); } while (0)
; #define PG8_LDA(dst, b, h) do { _Pragma("unroll") for (int m = 0; m < 4; ++m) _Pragma("unroll") for (int k = 0; k < 2; ++k) dst[m][k] = *(const PG8_LAS bf16x8*)(lds + PG8_SA(b, h) + aoff + m * 2048 + k * 1024); } while (0)
; #define PG8_LDB(dst, b, h) do { _Pragma("unroll") for (int n = 0; n < 2; ++n) _Pragma("unroll") for (int k = 0; k < 2; ++k) dst[n][k] = *(const PG8_LAS bf16x8*)(lds + PG8_SB(b, h) + boff + n * 2048 + k * 1024); } while (0)
; #define PG8_MMA(ai, bj, At, Bt) do { __builtin_amdgcn_s_setprio(1); _Pragma("unroll") for (int m = 0; m < 4; ++m) _Pragma("unroll") for (int n = 0; n < 2; ++n) _Pragma("unroll") for (int k = 0; k < 2; ++k) \
;         acc[ai][bj][m][n] = __builtin_amdgcn_mfma_f32_16x16x32_bf16(Bt[n][k], At[m][k], acc[ai][bj][m][n], 0, 0, 0); __builtin_amdgcn_s_setprio(0); } while (0)
; #define PG8_WAIT_V(n) asm volatile("s_waitcnt vmcnt(" #n ")" ::: "memory")
; #define PG8_WAIT_L(n) asm volatile("s_waitcnt lgkmcnt(" #n ")" ::: "memory")
; #define PG8_BAR __builtin_amdgcn_s_barrier()
; #define PG8_SCHED __builtin_amdgcn_sched_barrier(0)
; template <class Epi, class Sched, bool ALIGN_EPI = false, bool SP2 = false>
; __device__ __forceinline__ void gemm_phase(PG8_LAS unsigned char* lds, const Gemm g, const Sched& S, const Epi& E) {
;     ...
;             PG8_WAIT_V(8); PG8_WAIT_L(0); PG8_BAR; PG8_MMA(1, 0, At, B0); PG8_MMA(1, 1, At, B1); PG8_BAR; PG8_SCHED;
;             PG8_LDB(B0, 1, 0); PG8_LDB(B1, 1, 1); PG8_SCHED; PG8_LDA(At, 1, 0); PG8_STAGE(PG8_SA(0, 1), a2 + hstepA, voffA);
;             PG8_WAIT_V(8); PG8_WAIT_L(0); PG8_BAR; PG8_MMA(0, 0, At, B0); PG8_MMA(0, 1, At, B1); PG8_BAR; PG8_SCHED;
	v_mfma_f32_16x16x32_bf16 v[62:65], v[160:163], v[192:195], v[62:65]
	v_mfma_f32_16x16x32_bf16 v[58:61], v[168:171], v[192:195], v[58:61]
	v_mfma_f32_16x16x32_bf16 v[46:49], v[160:163], v[200:203], v[46:49]
	v_mfma_f32_16x16x32_bf16 v[42:45], v[168:171], v[200:203], v[42:45]
	v_mfma_f32_16x16x32_bf16 v[30:33], v[160:163], v[210:213], v[30:33]
	v_mfma_f32_16x16x32_bf16 v[26:29], v[168:171], v[210:213], v[26:29]
	v_mfma_f32_16x16x32_bf16 v[14:17], v[160:163], v[218:221], v[14:17]
	v_mfma_f32_16x16x32_bf16 v[10:13], v[168:171], v[218:221], v[10:13]
	v_mfma_f32_16x16x32_bf16 v[62:65], v[164:167], v[196:199], v[62:65]
	v_mfma_f32_16x16x32_bf16 v[58:61], v[172:175], v[196:199], v[58:61]
	v_mfma_f32_16x16x32_bf16 v[46:49], v[164:167], v[204:207], v[46:49]
	v_mfma_f32_16x16x32_bf16 v[42:45], v[172:175], v[204:207], v[42:45]
	v_mfma_f32_16x16x32_bf16 v[30:33], v[164:167], v[214:217], v[30:33]
	v_mfma_f32_16x16x32_bf16 v[26:29], v[172:175], v[214:217], v[26:29]
	v_mfma_f32_16x16x32_bf16 v[14:17], v[164:167], v[222:225], v[14:17]
	v_mfma_f32_16x16x32_bf16 v[10:13], v[172:175], v[222:225], v[10:13]
	v_mfma_f32_16x16x32_bf16 v[54:57], v[176:179], v[192:195], v[54:57]
	v_mfma_f32_16x16x32_bf16 v[50:53], v[184:187], v[192:195], v[50:53]
	v_mfma_f32_16x16x32_bf16 v[38:41], v[176:179], v[200:203], v[38:41]
	v_mfma_f32_16x16x32_bf16 v[34:37], v[184:187], v[200:203], v[34:37]
	v_mfma_f32_16x16x32_bf16 v[22:25], v[176:179], v[210:213], v[22:25]
	v_mfma_f32_16x16x32_bf16 v[18:21], v[184:187], v[210:213], v[18:21]
	v_mfma_f32_16x16x32_bf16 v[6:9], v[176:179], v[218:221], v[6:9]
	v_mfma_f32_16x16x32_bf16 v[2:5], v[184:187], v[218:221], v[2:5]
	v_mfma_f32_16x16x32_bf16 v[54:57], v[180:183], v[196:199], v[54:57]
	v_mfma_f32_16x16x32_bf16 v[50:53], v[188:191], v[196:199], v[50:53]
	v_mfma_f32_16x16x32_bf16 v[38:41], v[180:183], v[204:207], v[38:41]
	v_mfma_f32_16x16x32_bf16 v[34:37], v[188:191], v[204:207], v[34:37]
	v_mfma_f32_16x16x32_bf16 v[22:25], v[180:183], v[214:217], v[22:25]
	v_mfma_f32_16x16x32_bf16 v[18:21], v[188:191], v[214:217], v[18:21]
	v_mfma_f32_16x16x32_bf16 v[6:9], v[180:183], v[222:225], v[6:9]
	v_mfma_f32_16x16x32_bf16 v[2:5], v[188:191], v[222:225], v[2:5]
	s_barrier
	s_setprio 0
	s_add_i32 s58, 0, 0x18000
	v_add_u32_e32 v138, s58, v1
	s_add_i32 s59, 0, 0x1c000
	ds_read_b128 v[160:163], v138
	ds_read_b128 v[164:167], v138 offset:1024
	ds_read_b128 v[168:171], v138 offset:2048
	ds_read_b128 v[172:175], v138 offset:3072
	v_add_u32_e32 v138, s59, v1
	ds_read_b128 v[176:179], v138
	ds_read_b128 v[180:183], v138 offset:1024
	ds_read_b128 v[184:187], v138 offset:2048
	ds_read_b128 v[188:191], v138 offset:3072
	s_add_u32 s34, s34, 0x80000
	s_addc_u32 s35, s35, 0
	s_mov_b32 m0, s42
	v_lshl_add_u64 v[234:235], s[34:35], 0, v[130:131]
	ds_read_b128 v[192:195], v157 offset:32768
	ds_read_b128 v[196:199], v157 offset:33792
	ds_read_b128 v[200:203], v157 offset:34816
	ds_read_b128 v[204:207], v157 offset:35840
	ds_read_b128 v[210:213], v157 offset:36864
	ds_read_b128 v[214:217], v157 offset:37888
	ds_read_b128 v[218:221], v157 offset:38912
	ds_read_b128 v[222:225], v157 offset:39936
	global_load_lds_dwordx4 v[234:235], off
	v_lshl_add_u64 v[234:235], s[34:35], 0, v[134:135]
	s_mov_b32 m0, s43
	s_nop 0
	global_load_lds_dwordx4 v[234:235], off
	s_waitcnt vmcnt(8)
	s_waitcnt lgkmcnt(0)
	s_setprio 1
	s_barrier
	v_mfma_f32_16x16x32_bf16 v[126:129], v[160:163], v[192:195], v[126:129]
	v_mfma_f32_16x16x32_bf16 v[122:125], v[168:171], v[192:195], v[122:125]
	v_mfma_f32_16x16x32_bf16 v[110:113], v[160:163], v[200:203], v[110:113]
	v_mfma_f32_16x16x32_bf16 v[106:109], v[168:171], v[200:203], v[106:109]
	v_mfma_f32_16x16x32_bf16 v[94:97], v[160:163], v[210:213], v[94:97]
	v_mfma_f32_16x16x32_bf16 v[90:93], v[168:171], v[210:213], v[90:93]
	v_mfma_f32_16x16x32_bf16 v[78:81], v[160:163], v[218:221], v[78:81]
	v_mfma_f32_16x16x32_bf16 v[74:77], v[168:171], v[218:221], v[74:77]
	v_mfma_f32_16x16x32_bf16 v[126:129], v[164:167], v[196:199], v[126:129]
	v_mfma_f32_16x16x32_bf16 v[122:125], v[172:175], v[196:199], v[122:125]
	v_mfma_f32_16x16x32_bf16 v[110:113], v[164:167], v[204:207], v[110:113]
	v_mfma_f32_16x16x32_bf16 v[106:109], v[172:175], v[204:207], v[106:109]
	v_mfma_f32_16x16x32_bf16 v[94:97], v[164:167], v[214:217], v[94:97]
	v_mfma_f32_16x16x32_bf16 v[90:93], v[172:175], v[214:217], v[90:93]
	v_mfma_f32_16x16x32_bf16 v[78:81], v[164:167], v[222:225], v[78:81]
	v_mfma_f32_16x16x32_bf16 v[74:77], v[172:175], v[222:225], v[74:77]
	v_mfma_f32_16x16x32_bf16 v[118:121], v[176:179], v[192:195], v[118:121]
	v_mfma_f32_16x16x32_bf16 v[114:117], v[184:187], v[192:195], v[114:117]
	v_mfma_f32_16x16x32_bf16 v[102:105], v[176:179], v[200:203], v[102:105]
	v_mfma_f32_16x16x32_bf16 v[98:101], v[184:187], v[200:203], v[98:101]
	v_mfma_f32_16x16x32_bf16 v[86:89], v[176:179], v[210:213], v[86:89]
	v_mfma_f32_16x16x32_bf16 v[82:85], v[184:187], v[210:213], v[82:85]
	v_mfma_f32_16x16x32_bf16 v[70:73], v[176:179], v[218:221], v[70:73]
	v_mfma_f32_16x16x32_bf16 v[66:69], v[184:187], v[218:221], v[66:69]
	v_mfma_f32_16x16x32_bf16 v[118:121], v[180:183], v[196:199], v[118:121]
	v_mfma_f32_16x16x32_bf16 v[114:117], v[188:191], v[196:199], v[114:117]
	v_mfma_f32_16x16x32_bf16 v[102:105], v[180:183], v[204:207], v[102:105]
	v_mfma_f32_16x16x32_bf16 v[98:101], v[188:191], v[204:207], v[98:101]
	v_mfma_f32_16x16x32_bf16 v[86:89], v[180:183], v[214:217], v[86:89]
	v_mfma_f32_16x16x32_bf16 v[82:85], v[188:191], v[214:217], v[82:85]
	v_mfma_f32_16x16x32_bf16 v[70:73], v[180:183], v[222:225], v[70:73]
	v_mfma_f32_16x16x32_bf16 v[66:69], v[188:191], v[222:225], v[66:69]
	s_barrier
; #define PG8_STAGE(bufoff, gbase, voff) do { _Pragma("unroll") for (int _i = 0; _i < 2; ++_i) \
;         __builtin_amdgcn_global_load_lds((const unsigned*)((const char*)(gbase) + (voff)[_i]), (PG8_LAS unsigned*)(lds + (bufoff) + ldsw + _i * 8192), 16, 0, 0); } while (0)
; #define PG8_LDA(dst, b, h) do { _Pragma("unroll") for (int m = 0; m < 4; ++m) _Pragma("unroll") for (int k = 0; k < 2; ++k) dst[m][k] = *(const PG8_LAS bf16x8*)(lds + PG8_SA(b, h) + aoff + m * 2048 + k * 1024); } while (0)
; #define PG8_MMA(ai, bj, At, Bt) do { __builtin_amdgcn_s_setprio(1); _Pragma("unroll") for (int m = 0; m < 4; ++m) _Pragma("unroll") for (int n = 0; n < 2; ++n) _Pragma("unroll") for (int k = 0; k < 2; ++k) \
;         acc[ai][bj][m][n] = __builtin_amdgcn_mfma_f32_16x16x32_bf16(Bt[n][k], At[m][k], acc[ai][bj][m][n], 0, 0, 0); __builtin_amdgcn_s_setprio(0); } while (0)
; #define PG8_WAIT_V(n) asm volatile("s_waitcnt vmcnt(" #n ")" ::: "memory")
; #define PG8_WAIT_L(n) asm volatile("s_waitcnt lgkmcnt(" #n ")" ::: "memory")
; #define PG8_BAR __builtin_amdgcn_s_barrier()
; #define PG8_SCHED __builtin_amdgcn_sched_barrier(0)
; template <class Epi, class Sched, bool ALIGN_EPI = false, bool SP2 = false>
; __device__ __forceinline__ void gemm_phase(PG8_LAS unsigned char* lds, const Gemm g, const Sched& S, const Epi& E) {
;     ...
;             PG8_LDA(At, 1, 1); PG8_STAGE(PG8_SB(1, 0), b3, voffB); PG8_STAGE(PG8_SB(1, 1), b3 + hstepB, voffB); PG8_STAGE(PG8_SA(1, 0), a3, voffA);
;             PG8_WAIT_V(8); PG8_WAIT_L(0); PG8_BAR; PG8_MMA(1, 0, At, B0); PG8_MMA(1, 1, At, B1); PG8_BAR; PG8_SCHED;
	s_setprio 0
	s_add_i32 s34, s58, s40
	v_lshl_add_u64 v[226:227], v[226:227], 0, s[14:15]
	s_mov_b32 m0, s34
	ds_read_b128 v[192:195], v157 offset:49152
	ds_read_b128 v[196:199], v157 offset:50176
	ds_read_b128 v[200:203], v157 offset:51200
	ds_read_b128 v[204:207], v157 offset:52224
	ds_read_b128 v[210:213], v157 offset:53248
	ds_read_b128 v[214:217], v157 offset:54272
	ds_read_b128 v[218:221], v157 offset:55296
	ds_read_b128 v[222:225], v157 offset:56320
	global_load_lds_dwordx4 v[226:227], off
	s_add_i32 m0, s34, 0x2000
	s_add_u32 s30, s30, 0x80080
	v_lshl_add_u64 v[226:227], v[228:229], 0, s[14:15]
	s_addc_u32 s31, s31, 0
	s_add_i32 s34, s59, s40
	global_load_lds_dwordx4 v[226:227], off
	v_lshl_add_u64 v[226:227], s[30:31], 0, v[132:133]
	s_mov_b32 m0, s34
	s_nop 0
	global_load_lds_dwordx4 v[226:227], off
	v_lshl_add_u64 v[226:227], s[30:31], 0, v[136:137]
	s_add_i32 m0, s34, 0x2000
	s_nop 0
	global_load_lds_dwordx4 v[226:227], off
	v_lshl_add_u64 v[226:227], v[230:231], 0, s[14:15]
	s_mov_b32 m0, s46
	s_nop 0
	global_load_lds_dwordx4 v[226:227], off
	v_lshl_add_u64 v[226:227], v[232:233], 0, s[14:15]
	s_mov_b32 m0, s47
	s_nop 0
	global_load_lds_dwordx4 v[226:227], off
	s_waitcnt vmcnt(8)
	s_waitcnt lgkmcnt(0)
	s_setprio 1
	s_barrier
	v_mfma_f32_16x16x32_bf16 v[62:65], v[160:163], v[192:195], v[62:65]
	v_mfma_f32_16x16x32_bf16 v[58:61], v[168:171], v[192:195], v[58:61]
	v_mfma_f32_16x16x32_bf16 v[46:49], v[160:163], v[200:203], v[46:49]
	v_mfma_f32_16x16x32_bf16 v[42:45], v[168:171], v[200:203], v[42:45]
	v_mfma_f32_16x16x32_bf16 v[30:33], v[160:163], v[210:213], v[30:33]
	v_mfma_f32_16x16x32_bf16 v[26:29], v[168:171], v[210:213], v[26:29]
	v_mfma_f32_16x16x32_bf16 v[14:17], v[160:163], v[218:221], v[14:17]
	v_mfma_f32_16x16x32_bf16 v[10:13], v[168:171], v[218:221], v[10:13]
	v_mfma_f32_16x16x32_bf16 v[62:65], v[164:167], v[196:199], v[62:65]
	v_mfma_f32_16x16x32_bf16 v[58:61], v[172:175], v[196:199], v[58:61]
	v_mfma_f32_16x16x32_bf16 v[46:49], v[164:167], v[204:207], v[46:49]
	v_mfma_f32_16x16x32_bf16 v[42:45], v[172:175], v[204:207], v[42:45]
	v_mfma_f32_16x16x32_bf16 v[30:33], v[164:167], v[214:217], v[30:33]
	v_mfma_f32_16x16x32_bf16 v[26:29], v[172:175], v[214:217], v[26:29]
	v_mfma_f32_16x16x32_bf16 v[14:17], v[164:167], v[222:225], v[14:17]
	v_mfma_f32_16x16x32_bf16 v[10:13], v[172:175], v[222:225], v[10:13]
	v_mfma_f32_16x16x32_bf16 v[54:57], v[176:179], v[192:195], v[54:57]
	v_mfma_f32_16x16x32_bf16 v[50:53], v[184:187], v[192:195], v[50:53]
	v_mfma_f32_16x16x32_bf16 v[38:41], v[176:179], v[200:203], v[38:41]
	v_mfma_f32_16x16x32_bf16 v[34:37], v[184:187], v[200:203], v[34:37]
	v_mfma_f32_16x16x32_bf16 v[22:25], v[176:179], v[210:213], v[22:25]
	v_mfma_f32_16x16x32_bf16 v[18:21], v[184:187], v[210:213], v[18:21]
	v_mfma_f32_16x16x32_bf16 v[6:9], v[176:179], v[218:221], v[6:9]
	v_mfma_f32_16x16x32_bf16 v[2:5], v[184:187], v[218:221], v[2:5]
	v_mfma_f32_16x16x32_bf16 v[54:57], v[180:183], v[196:199], v[54:57]
	v_mfma_f32_16x16x32_bf16 v[50:53], v[188:191], v[196:199], v[50:53]
	v_mfma_f32_16x16x32_bf16 v[38:41], v[180:183], v[204:207], v[38:41]
	v_mfma_f32_16x16x32_bf16 v[34:37], v[188:191], v[204:207], v[34:37]
	v_mfma_f32_16x16x32_bf16 v[22:25], v[180:183], v[214:217], v[22:25]
	v_mfma_f32_16x16x32_bf16 v[18:21], v[188:191], v[214:217], v[18:21]
	v_mfma_f32_16x16x32_bf16 v[6:9], v[180:183], v[222:225], v[6:9]
	v_mfma_f32_16x16x32_bf16 v[2:5], v[188:191], v[222:225], v[2:5]
	s_barrier
	s_setprio 0
	s_add_i32 s39, s39, 2
	s_add_u32 s12, s12, 0x100
	s_addc_u32 s13, s13, 0
	s_add_u32 s37, s37, 0x100
	s_addc_u32 s38, s38, 0
	s_cmp_gt_u32 s39, 29
	s_cbranch_scc0 .LBB0_1839
	s_and_b64 vcc, exec, s[20:21]
	s_cbranch_vccz .LBB0_1842
	s_barrier

; #define PG8_STAGE(bufoff, gbase, voff) do { _Pragma("unroll") for (int _i = 0; _i < 2; ++_i) \
;         __builtin_amdgcn_global_load_lds((const unsigned*)((const char*)(gbase) + (voff)[_i]), (PG8_LAS unsigned*)(lds + (bufoff) + ldsw + _i * 8192), 16, 0, 0); } while (0)
; #define PG8_LDA(dst, b, h) do { _Pragma("unroll") for (int m = 0; m < 4; ++m) _Pragma("unroll") for (int k = 0; k < 2; ++k) dst[m][k] = *(const PG8_LAS bf16x8*)(lds + PG8_SA(b, h) + aoff + m * 2048 + k * 1024); } while (0)
; #define PG8_LDB(dst, b, h) do { _Pragma("unroll") for (int n = 0; n < 2; ++n) _Pragma("unroll") for (int k = 0; k < 2; ++k) dst[n][k] = *(const PG8_LAS bf16x8*)(lds + PG8_SB(b, h) + boff + n * 2048 + k * 1024); } while (0)
; #define PG8_MMA(ai, bj, At, Bt) do { __builtin_amdgcn_s_setprio(1); _Pragma("unroll") for (int m = 0; m < 4; ++m) _Pragma("unroll") for (int n = 0; n < 2; ++n) _Pragma("unroll") for (int k = 0; k < 2; ++k) \
;         acc[ai][bj][m][n] = __builtin_amdgcn_mfma_f32_16x16x32_bf16(Bt[n][k], At[m][k], acc[ai][bj][m][n], 0, 0, 0); __builtin_amdgcn_s_setprio(0); } while (0)
; #define PG8_WAIT_V(n) asm volatile("s_waitcnt vmcnt(" #n ")" ::: "memory")
; #define PG8_WAIT_L(n) asm volatile("s_waitcnt lgkmcnt(" #n ")" ::: "memory")
; #define PG8_BAR __builtin_amdgcn_s_barrier()
; #define PG8_SCHED __builtin_amdgcn_sched_barrier(0)
; template <class Epi, class Sched, bool ALIGN_EPI = false, bool SP2 = false>
; __device__ __forceinline__ void gemm_phase(PG8_LAS unsigned char* lds, const Gemm g, const Sched& S, const Epi& E) {
;     ...
;             PG8_LDB(B0, 0, 0); PG8_LDB(B1, 0, 1); PG8_SCHED; PG8_LDA(At, 0, 0); PG8_STAGE(PG8_SA(1, 1), a1 + hstepA, voffA);
;             PG8_WAIT_V(8); PG8_WAIT_L(0); PG8_BAR; PG8_MMA(0, 0, At, B0); PG8_MMA(0, 1, At, B1); PG8_BAR; PG8_SCHED;
;             PG8_LDA(At, 0, 1); PG8_STAGE(PG8_SB(0, 0), b2, voffB); PG8_STAGE(PG8_SB(0, 1), b2 + hstepB, voffB); PG8_STAGE(PG8_SA(0, 0), a2, voffA);
;             PG8_WAIT_V(8); PG8_WAIT_L(0); PG8_BAR; PG8_MMA(1, 0, At, B0); PG8_MMA(1, 1, At, B1); PG8_BAR; PG8_SCHED;
.LBB0_2259:
	ds_read_b128 v[152:155], v148
	ds_read_b128 v[156:159], v148 offset:1024
	ds_read_b128 v[160:163], v148 offset:2048
	ds_read_b128 v[164:167], v148 offset:3072
	ds_read_b128 v[168:171], v149
	ds_read_b128 v[172:175], v149 offset:1024
	ds_read_b128 v[176:179], v149 offset:2048
	ds_read_b128 v[180:183], v149 offset:3072
	s_add_u32 s30, s28, 0xfff00080
	s_addc_u32 s31, s29, -1
	s_cmp_eq_u32 s57, 60
	s_cselect_b32 s35, s23, s31
	s_cselect_b32 s34, s53, s30
	s_cselect_b32 s31, s21, s56
	s_cselect_b32 s30, s54, s55
	v_lshl_add_u64 v[218:219], s[28:29], 0, v[138:139]
	s_add_i32 m0, s19, 0xc000
	ds_read_b128 v[184:187], v150
	ds_read_b128 v[188:191], v150 offset:1024
	ds_read_b128 v[192:195], v150 offset:2048
	ds_read_b128 v[196:199], v150 offset:3072
	ds_read_b128 v[200:203], v150 offset:4096
	ds_read_b128 v[204:207], v150 offset:5120
	ds_read_b128 v[210:213], v150 offset:6144
	ds_read_b128 v[214:217], v150 offset:7168
	global_load_lds_dwordx4 v[218:219], off
	v_lshl_add_u64 v[218:219], s[28:29], 0, v[140:141]
	s_add_i32 m0, s19, 0xe000
	s_nop 0
	global_load_lds_dwordx4 v[218:219], off
	s_waitcnt vmcnt(8)
	s_waitcnt lgkmcnt(0)
	s_setprio 1
	s_barrier
	v_mfma_f32_16x16x32_bf16 v[126:129], v[152:155], v[184:187], v[126:129]
	v_mfma_f32_16x16x32_bf16 v[122:125], v[160:163], v[184:187], v[122:125]
	v_mfma_f32_16x16x32_bf16 v[118:121], v[152:155], v[192:195], v[118:121]
	v_mfma_f32_16x16x32_bf16 v[114:117], v[160:163], v[192:195], v[114:117]
	v_mfma_f32_16x16x32_bf16 v[102:105], v[152:155], v[200:203], v[102:105]
	v_mfma_f32_16x16x32_bf16 v[98:101], v[160:163], v[200:203], v[98:101]
	v_mfma_f32_16x16x32_bf16 v[86:89], v[152:155], v[210:213], v[86:89]
	v_mfma_f32_16x16x32_bf16 v[82:85], v[160:163], v[210:213], v[82:85]
	v_mfma_f32_16x16x32_bf16 v[126:129], v[156:159], v[188:191], v[126:129]
	v_mfma_f32_16x16x32_bf16 v[122:125], v[164:167], v[188:191], v[122:125]
	v_mfma_f32_16x16x32_bf16 v[118:121], v[156:159], v[196:199], v[118:121]
	v_mfma_f32_16x16x32_bf16 v[114:117], v[164:167], v[196:199], v[114:117]
	v_mfma_f32_16x16x32_bf16 v[102:105], v[156:159], v[204:207], v[102:105]
	v_mfma_f32_16x16x32_bf16 v[98:101], v[164:167], v[204:207], v[98:101]
	v_mfma_f32_16x16x32_bf16 v[86:89], v[156:159], v[214:217], v[86:89]
	v_mfma_f32_16x16x32_bf16 v[82:85], v[164:167], v[214:217], v[82:85]
	v_mfma_f32_16x16x32_bf16 v[110:113], v[168:171], v[184:187], v[110:113]
	v_mfma_f32_16x16x32_bf16 v[106:109], v[176:179], v[184:187], v[106:109]
	v_mfma_f32_16x16x32_bf16 v[94:97], v[168:171], v[192:195], v[94:97]
	v_mfma_f32_16x16x32_bf16 v[90:93], v[176:179], v[192:195], v[90:93]
	v_mfma_f32_16x16x32_bf16 v[78:81], v[168:171], v[200:203], v[78:81]
	v_mfma_f32_16x16x32_bf16 v[74:77], v[176:179], v[200:203], v[74:77]
	v_mfma_f32_16x16x32_bf16 v[70:73], v[168:171], v[210:213], v[70:73]
	v_mfma_f32_16x16x32_bf16 v[66:69], v[176:179], v[210:213], v[66:69]
	v_mfma_f32_16x16x32_bf16 v[110:113], v[172:175], v[188:191], v[110:113]
	v_mfma_f32_16x16x32_bf16 v[106:109], v[180:183], v[188:191], v[106:109]
	v_mfma_f32_16x16x32_bf16 v[94:97], v[172:175], v[196:199], v[94:97]
	v_mfma_f32_16x16x32_bf16 v[90:93], v[180:183], v[196:199], v[90:93]
	v_mfma_f32_16x16x32_bf16 v[78:81], v[172:175], v[204:207], v[78:81]
	v_mfma_f32_16x16x32_bf16 v[74:77], v[180:183], v[204:207], v[74:77]
	v_mfma_f32_16x16x32_bf16 v[70:73], v[172:175], v[214:217], v[70:73]
	v_mfma_f32_16x16x32_bf16 v[66:69], v[180:183], v[214:217], v[66:69]
	s_barrier
	s_setprio 0
	s_add_i32 s58, s46, s36
	v_lshl_add_u64 v[218:219], s[30:31], 0, v[134:135]
	s_mov_b32 m0, s58
	ds_read_b128 v[184:187], v150 offset:16384
	ds_read_b128 v[188:191], v150 offset:17408
	ds_read_b128 v[192:195], v150 offset:18432
	ds_read_b128 v[196:199], v150 offset:19456
	ds_read_b128 v[200:203], v150 offset:20480
	ds_read_b128 v[204:207], v150 offset:21504
	ds_read_b128 v[210:213], v150 offset:22528
	ds_read_b128 v[214:217], v150 offset:23552
	global_load_lds_dwordx4 v[218:219], off
	s_add_i32 m0, s58, 0x2000
	s_add_u32 s58, s30, 0x100000
	v_lshl_add_u64 v[220:221], s[30:31], 0, v[130:131]
	s_addc_u32 s59, s31, 0
	s_add_i32 s60, s47, s36
	global_load_lds_dwordx4 v[220:221], off
	v_lshl_add_u64 v[222:223], s[58:59], 0, v[134:135]
	s_mov_b32 m0, s60
	v_lshl_add_u64 v[224:225], s[34:35], 0, v[132:133]
	global_load_lds_dwordx4 v[222:223], off
	v_lshl_add_u64 v[222:223], s[58:59], 0, v[130:131]
	s_add_i32 m0, s60, 0x2000
	s_nop 0
	global_load_lds_dwordx4 v[222:223], off
	v_lshl_add_u64 v[222:223], s[34:35], 0, v[136:137]
	s_mov_b32 m0, s19
	s_nop 0
	global_load_lds_dwordx4 v[222:223], off
	s_mov_b32 m0, s39
	s_nop 0
	global_load_lds_dwordx4 v[224:225], off
	s_waitcnt vmcnt(8)
	s_waitcnt lgkmcnt(0)
	s_setprio 1
	s_barrier
; #define PG8_STAGE(bufoff, gbase, voff) do { _Pragma("unroll") for (int _i = 0; _i < 2; ++_i) \
;         __builtin_amdgcn_global_load_lds((const unsigned*)((const char*)(gbase) + (voff)[_i]), (PG8_LAS unsigned*)(lds + (bufoff) + ldsw + _i * 8192), 16, 0, 0); } while (0)
; #define PG8_LDA(dst, b, h) do { _Pragma("unroll") for (int m = 0; m < 4; ++m) _Pragma("unroll") for (int k = 0; k < 2; ++k) dst[m][k] = *(const PG8_LAS bf16x8*)(lds + PG8_SA(b, h) + aoff + m * 2048 + k * 1024); } while (0)
; #define PG8_LDB(dst, b, h) do { _Pragma("unroll") for (int n = 0; n < 2; ++n) _Pragma("unroll") for (int k = 0; k < 2; ++k) dst[n][k] = *(const PG8_LAS bf16x8*)(lds + PG8_SB(b, h) + boff + n * 2048 + k * 1024); } while (0)
; #define PG8_MMA(ai, bj, At, Bt) do { __builtin_amdgcn_s_setprio(1); _Pragma("unroll") for (int m = 0; m < 4; ++m) _Pragma("unroll") for (int n = 0; n < 2; ++n) _Pragma("unroll") for (int k = 0; k < 2; ++k) \
;         acc[ai][bj][m][n] = __builtin_amdgcn_mfma_f32_16x16x32_bf16(Bt[n][k], At[m][k], acc[ai][bj][m][n], 0, 0, 0); __builtin_amdgcn_s_setprio(0); } while (0)
; #define PG8_WAIT_V(n) asm volatile("s_waitcnt vmcnt(" #n ")" ::: "memory")
; #define PG8_WAIT_L(n) asm volatile("s_waitcnt lgkmcnt(" #n ")" ::: "memory")
; #define PG8_BAR __builtin_amdgcn_s_barrier()
; #define PG8_SCHED __builtin_amdgcn_sched_barrier(0)
; template <class Epi, class Sched, bool ALIGN_EPI = false, bool SP2 = false>
; __device__ __forceinline__ void gemm_phase(PG8_LAS unsigned char* lds, const Gemm g, const Sched& S, const Epi& E) {
;     ...
;             PG8_WAIT_V(8); PG8_WAIT_L(0); PG8_BAR; PG8_MMA(1, 0, At, B0); PG8_MMA(1, 1, At, B1); PG8_BAR; PG8_SCHED;
;             PG8_LDB(B0, 1, 0); PG8_LDB(B1, 1, 1); PG8_SCHED; PG8_LDA(At, 1, 0); PG8_STAGE(PG8_SA(0, 1), a2 + hstepA, voffA);
;             PG8_WAIT_V(8); PG8_WAIT_L(0); PG8_BAR; PG8_MMA(0, 0, At, B0); PG8_MMA(0, 1, At, B1); PG8_BAR; PG8_SCHED;
	v_mfma_f32_16x16x32_bf16 v[62:65], v[152:155], v[184:187], v[62:65]
	v_mfma_f32_16x16x32_bf16 v[58:61], v[160:163], v[184:187], v[58:61]
	v_mfma_f32_16x16x32_bf16 v[54:57], v[152:155], v[192:195], v[54:57]
	v_mfma_f32_16x16x32_bf16 v[50:53], v[160:163], v[192:195], v[50:53]
	v_mfma_f32_16x16x32_bf16 v[38:41], v[152:155], v[200:203], v[38:41]
	v_mfma_f32_16x16x32_bf16 v[34:37], v[160:163], v[200:203], v[34:37]
	v_mfma_f32_16x16x32_bf16 v[22:25], v[152:155], v[210:213], v[22:25]
	v_mfma_f32_16x16x32_bf16 v[18:21], v[160:163], v[210:213], v[18:21]
	v_mfma_f32_16x16x32_bf16 v[62:65], v[156:159], v[188:191], v[62:65]
	v_mfma_f32_16x16x32_bf16 v[58:61], v[164:167], v[188:191], v[58:61]
	v_mfma_f32_16x16x32_bf16 v[54:57], v[156:159], v[196:199], v[54:57]
	v_mfma_f32_16x16x32_bf16 v[50:53], v[164:167], v[196:199], v[50:53]
	v_mfma_f32_16x16x32_bf16 v[38:41], v[156:159], v[204:207], v[38:41]
	v_mfma_f32_16x16x32_bf16 v[34:37], v[164:167], v[204:207], v[34:37]
	v_mfma_f32_16x16x32_bf16 v[22:25], v[156:159], v[214:217], v[22:25]
	v_mfma_f32_16x16x32_bf16 v[18:21], v[164:167], v[214:217], v[18:21]
	v_mfma_f32_16x16x32_bf16 v[46:49], v[168:171], v[184:187], v[46:49]
	v_mfma_f32_16x16x32_bf16 v[42:45], v[176:179], v[184:187], v[42:45]
	v_mfma_f32_16x16x32_bf16 v[30:33], v[168:171], v[192:195], v[30:33]
	v_mfma_f32_16x16x32_bf16 v[26:29], v[176:179], v[192:195], v[26:29]
	v_mfma_f32_16x16x32_bf16 v[14:17], v[168:171], v[200:203], v[14:17]
	v_mfma_f32_16x16x32_bf16 v[10:13], v[176:179], v[200:203], v[10:13]
	v_mfma_f32_16x16x32_bf16 v[6:9], v[168:171], v[210:213], v[6:9]
	v_mfma_f32_16x16x32_bf16 v[2:5], v[176:179], v[210:213], v[2:5]
	v_mfma_f32_16x16x32_bf16 v[46:49], v[172:175], v[188:191], v[46:49]
	v_mfma_f32_16x16x32_bf16 v[42:45], v[180:183], v[188:191], v[42:45]
	v_mfma_f32_16x16x32_bf16 v[30:33], v[172:175], v[196:199], v[30:33]
	v_mfma_f32_16x16x32_bf16 v[26:29], v[180:183], v[196:199], v[26:29]
	v_mfma_f32_16x16x32_bf16 v[14:17], v[172:175], v[204:207], v[14:17]
	v_mfma_f32_16x16x32_bf16 v[10:13], v[180:183], v[204:207], v[10:13]
	v_mfma_f32_16x16x32_bf16 v[6:9], v[172:175], v[214:217], v[6:9]
	v_mfma_f32_16x16x32_bf16 v[2:5], v[180:183], v[214:217], v[2:5]
	s_barrier
	s_setprio 0
	s_add_i32 s58, 0, 0x18000
	v_add_u32_e32 v151, s58, v146
	s_add_i32 s59, 0, 0x1c000
	ds_read_b128 v[152:155], v151
	ds_read_b128 v[156:159], v151 offset:1024
	ds_read_b128 v[160:163], v151 offset:2048
	ds_read_b128 v[164:167], v151 offset:3072
	v_add_u32_e32 v151, s59, v146
	ds_read_b128 v[168:171], v151
	ds_read_b128 v[172:175], v151 offset:1024
	ds_read_b128 v[176:179], v151 offset:2048
	ds_read_b128 v[180:183], v151 offset:3072
	s_add_u32 s34, s34, 0x100000
	s_addc_u32 s35, s35, 0
	s_mov_b32 m0, s40
	v_lshl_add_u64 v[226:227], s[34:35], 0, v[136:137]
	ds_read_b128 v[184:187], v150 offset:32768
	ds_read_b128 v[188:191], v150 offset:33792
	ds_read_b128 v[192:195], v150 offset:34816
	ds_read_b128 v[196:199], v150 offset:35840
	ds_read_b128 v[200:203], v150 offset:36864
	ds_read_b128 v[204:207], v150 offset:37888
	ds_read_b128 v[210:213], v150 offset:38912
	ds_read_b128 v[214:217], v150 offset:39936
	global_load_lds_dwordx4 v[226:227], off
	v_lshl_add_u64 v[226:227], s[34:35], 0, v[132:133]
	s_mov_b32 m0, s41
	s_nop 0
	global_load_lds_dwordx4 v[226:227], off
	s_waitcnt vmcnt(8)
	s_waitcnt lgkmcnt(0)
	s_setprio 1
	s_barrier
	v_mfma_f32_16x16x32_bf16 v[126:129], v[152:155], v[184:187], v[126:129]
	v_mfma_f32_16x16x32_bf16 v[122:125], v[160:163], v[184:187], v[122:125]
	v_mfma_f32_16x16x32_bf16 v[118:121], v[152:155], v[192:195], v[118:121]
	v_mfma_f32_16x16x32_bf16 v[114:117], v[160:163], v[192:195], v[114:117]
	v_mfma_f32_16x16x32_bf16 v[102:105], v[152:155], v[200:203], v[102:105]
	v_mfma_f32_16x16x32_bf16 v[98:101], v[160:163], v[200:203], v[98:101]
	v_mfma_f32_16x16x32_bf16 v[86:89], v[152:155], v[210:213], v[86:89]
	v_mfma_f32_16x16x32_bf16 v[82:85], v[160:163], v[210:213], v[82:85]
	v_mfma_f32_16x16x32_bf16 v[126:129], v[156:159], v[188:191], v[126:129]
	v_mfma_f32_16x16x32_bf16 v[122:125], v[164:167], v[188:191], v[122:125]
	v_mfma_f32_16x16x32_bf16 v[118:121], v[156:159], v[196:199], v[118:121]
	v_mfma_f32_16x16x32_bf16 v[114:117], v[164:167], v[196:199], v[114:117]
	v_mfma_f32_16x16x32_bf16 v[102:105], v[156:159], v[204:207], v[102:105]
	v_mfma_f32_16x16x32_bf16 v[98:101], v[164:167], v[204:207], v[98:101]
	v_mfma_f32_16x16x32_bf16 v[86:89], v[156:159], v[214:217], v[86:89]
	v_mfma_f32_16x16x32_bf16 v[82:85], v[164:167], v[214:217], v[82:85]
	v_mfma_f32_16x16x32_bf16 v[110:113], v[168:171], v[184:187], v[110:113]
	v_mfma_f32_16x16x32_bf16 v[106:109], v[176:179], v[184:187], v[106:109]
	v_mfma_f32_16x16x32_bf16 v[94:97], v[168:171], v[192:195], v[94:97]
	v_mfma_f32_16x16x32_bf16 v[90:93], v[176:179], v[192:195], v[90:93]
	v_mfma_f32_16x16x32_bf16 v[78:81], v[168:171], v[200:203], v[78:81]
	v_mfma_f32_16x16x32_bf16 v[74:77], v[176:179], v[200:203], v[74:77]
	v_mfma_f32_16x16x32_bf16 v[70:73], v[168:171], v[210:213], v[70:73]
	v_mfma_f32_16x16x32_bf16 v[66:69], v[176:179], v[210:213], v[66:69]
	v_mfma_f32_16x16x32_bf16 v[110:113], v[172:175], v[188:191], v[110:113]
	v_mfma_f32_16x16x32_bf16 v[106:109], v[180:183], v[188:191], v[106:109]
	v_mfma_f32_16x16x32_bf16 v[94:97], v[172:175], v[196:199], v[94:97]
	v_mfma_f32_16x16x32_bf16 v[90:93], v[180:183], v[196:199], v[90:93]
	v_mfma_f32_16x16x32_bf16 v[78:81], v[172:175], v[204:207], v[78:81]
	v_mfma_f32_16x16x32_bf16 v[74:77], v[180:183], v[204:207], v[74:77]
	v_mfma_f32_16x16x32_bf16 v[70:73], v[172:175], v[214:217], v[70:73]
	v_mfma_f32_16x16x32_bf16 v[66:69], v[180:183], v[214:217], v[66:69]
	s_barrier
; #define PG8_STAGE(bufoff, gbase, voff) do { _Pragma("unroll") for (int _i = 0; _i < 2; ++_i) \
;         __builtin_amdgcn_global_load_lds((const unsigned*)((const char*)(gbase) + (voff)[_i]), (PG8_LAS unsigned*)(lds + (bufoff) + ldsw + _i * 8192), 16, 0, 0); } while (0)
; #define PG8_LDA(dst, b, h) do { _Pragma("unroll") for (int m = 0; m < 4; ++m) _Pragma("unroll") for (int k = 0; k < 2; ++k) dst[m][k] = *(const PG8_LAS bf16x8*)(lds + PG8_SA(b, h) + aoff + m * 2048 + k * 1024); } while (0)
; #define PG8_MMA(ai, bj, At, Bt) do { __builtin_amdgcn_s_setprio(1); _Pragma("unroll") for (int m = 0; m < 4; ++m) _Pragma("unroll") for (int n = 0; n < 2; ++n) _Pragma("unroll") for (int k = 0; k < 2; ++k) \
;         acc[ai][bj][m][n] = __builtin_amdgcn_mfma_f32_16x16x32_bf16(Bt[n][k], At[m][k], acc[ai][bj][m][n], 0, 0, 0); __builtin_amdgcn_s_setprio(0); } while (0)
; #define PG8_WAIT_V(n) asm volatile("s_waitcnt vmcnt(" #n ")" ::: "memory")
; #define PG8_WAIT_L(n) asm volatile("s_waitcnt lgkmcnt(" #n ")" ::: "memory")
; #define PG8_BAR __builtin_amdgcn_s_barrier()
; #define PG8_SCHED __builtin_amdgcn_sched_barrier(0)
; template <class Epi, class Sched, bool ALIGN_EPI = false, bool SP2 = false>
; __device__ __forceinline__ void gemm_phase(PG8_LAS unsigned char* lds, const Gemm g, const Sched& S, const Epi& E) {
;     ...
;             PG8_LDA(At, 1, 1); PG8_STAGE(PG8_SB(1, 0), b3, voffB); PG8_STAGE(PG8_SB(1, 1), b3 + hstepB, voffB); PG8_STAGE(PG8_SA(1, 0), a3, voffA);
;             PG8_WAIT_V(8); PG8_WAIT_L(0); PG8_BAR; PG8_MMA(1, 0, At, B0); PG8_MMA(1, 1, At, B1); PG8_BAR; PG8_SCHED;
	s_setprio 0
	s_add_i32 s34, s58, s36
	v_lshl_add_u64 v[218:219], v[218:219], 0, s[6:7]
	s_mov_b32 m0, s34
	ds_read_b128 v[184:187], v150 offset:49152
	ds_read_b128 v[188:191], v150 offset:50176
	ds_read_b128 v[192:195], v150 offset:51200
	ds_read_b128 v[196:199], v150 offset:52224
	ds_read_b128 v[200:203], v150 offset:53248
	ds_read_b128 v[204:207], v150 offset:54272
	ds_read_b128 v[210:213], v150 offset:55296
	ds_read_b128 v[214:217], v150 offset:56320
	global_load_lds_dwordx4 v[218:219], off
	s_add_i32 m0, s34, 0x2000
	s_add_u32 s30, s30, 0x100080
	v_lshl_add_u64 v[218:219], v[220:221], 0, s[6:7]
	s_addc_u32 s31, s31, 0
	s_add_i32 s34, s59, s36
	global_load_lds_dwordx4 v[218:219], off
	v_lshl_add_u64 v[218:219], s[30:31], 0, v[134:135]
	s_mov_b32 m0, s34
	s_nop 0
	global_load_lds_dwordx4 v[218:219], off
	v_lshl_add_u64 v[218:219], s[30:31], 0, v[130:131]
	s_add_i32 m0, s34, 0x2000
	s_nop 0
	global_load_lds_dwordx4 v[218:219], off
	v_lshl_add_u64 v[218:219], v[222:223], 0, s[6:7]
	s_mov_b32 m0, s43
	s_nop 0
	global_load_lds_dwordx4 v[218:219], off
	v_lshl_add_u64 v[218:219], v[224:225], 0, s[6:7]
	s_mov_b32 m0, s44
	s_nop 0
	global_load_lds_dwordx4 v[218:219], off
	s_waitcnt vmcnt(8)
	s_waitcnt lgkmcnt(0)
	s_setprio 1
	s_barrier
	v_mfma_f32_16x16x32_bf16 v[62:65], v[152:155], v[184:187], v[62:65]
	v_mfma_f32_16x16x32_bf16 v[58:61], v[160:163], v[184:187], v[58:61]
	v_mfma_f32_16x16x32_bf16 v[54:57], v[152:155], v[192:195], v[54:57]
	v_mfma_f32_16x16x32_bf16 v[50:53], v[160:163], v[192:195], v[50:53]
	v_mfma_f32_16x16x32_bf16 v[38:41], v[152:155], v[200:203], v[38:41]
	v_mfma_f32_16x16x32_bf16 v[34:37], v[160:163], v[200:203], v[34:37]
	v_mfma_f32_16x16x32_bf16 v[22:25], v[152:155], v[210:213], v[22:25]
	v_mfma_f32_16x16x32_bf16 v[18:21], v[160:163], v[210:213], v[18:21]
	v_mfma_f32_16x16x32_bf16 v[62:65], v[156:159], v[188:191], v[62:65]
	v_mfma_f32_16x16x32_bf16 v[58:61], v[164:167], v[188:191], v[58:61]
	v_mfma_f32_16x16x32_bf16 v[54:57], v[156:159], v[196:199], v[54:57]
	v_mfma_f32_16x16x32_bf16 v[50:53], v[164:167], v[196:199], v[50:53]
	v_mfma_f32_16x16x32_bf16 v[38:41], v[156:159], v[204:207], v[38:41]
	v_mfma_f32_16x16x32_bf16 v[34:37], v[164:167], v[204:207], v[34:37]
	v_mfma_f32_16x16x32_bf16 v[22:25], v[156:159], v[214:217], v[22:25]
	v_mfma_f32_16x16x32_bf16 v[18:21], v[164:167], v[214:217], v[18:21]
	v_mfma_f32_16x16x32_bf16 v[46:49], v[168:171], v[184:187], v[46:49]
	v_mfma_f32_16x16x32_bf16 v[42:45], v[176:179], v[184:187], v[42:45]
	v_mfma_f32_16x16x32_bf16 v[30:33], v[168:171], v[192:195], v[30:33]
	v_mfma_f32_16x16x32_bf16 v[26:29], v[176:179], v[192:195], v[26:29]
	v_mfma_f32_16x16x32_bf16 v[14:17], v[168:171], v[200:203], v[14:17]
	v_mfma_f32_16x16x32_bf16 v[10:13], v[176:179], v[200:203], v[10:13]
	v_mfma_f32_16x16x32_bf16 v[6:9], v[168:171], v[210:213], v[6:9]
	v_mfma_f32_16x16x32_bf16 v[2:5], v[176:179], v[210:213], v[2:5]
	v_mfma_f32_16x16x32_bf16 v[46:49], v[172:175], v[188:191], v[46:49]
	v_mfma_f32_16x16x32_bf16 v[42:45], v[180:183], v[188:191], v[42:45]
	v_mfma_f32_16x16x32_bf16 v[30:33], v[172:175], v[196:199], v[30:33]
	v_mfma_f32_16x16x32_bf16 v[26:29], v[180:183], v[196:199], v[26:29]
	v_mfma_f32_16x16x32_bf16 v[14:17], v[172:175], v[204:207], v[14:17]
	v_mfma_f32_16x16x32_bf16 v[10:13], v[180:183], v[204:207], v[10:13]
	v_mfma_f32_16x16x32_bf16 v[6:9], v[172:175], v[214:217], v[6:9]
	v_mfma_f32_16x16x32_bf16 v[2:5], v[180:183], v[214:217], v[2:5]
	s_barrier
	s_setprio 0
	s_add_i32 s57, s57, 2
	s_add_u32 s28, s28, 0x100
	s_addc_u32 s29, s29, 0
	s_add_u32 s55, s55, 0x100
	s_addc_u32 s56, s56, 0
	s_cmp_gt_u32 s57, 61
	s_cbranch_scc0 .LBB0_2259
	s_and_b64 vcc, exec, s[8:9]
	s_cbranch_vccz .LBB0_2262
	s_barrier

; #define PG8_STAGE(bufoff, gbase, voff) do { _Pragma("unroll") for (int _i = 0; _i < 2; ++_i) \
;         __builtin_amdgcn_global_load_lds((const unsigned*)((const char*)(gbase) + (voff)[_i]), (PG8_LAS unsigned*)(lds + (bufoff) + ldsw + _i * 8192), 16, 0, 0); } while (0)
; #define PG8_LDA(dst, b, h) do { _Pragma("unroll") for (int m = 0; m < 4; ++m) _Pragma("unroll") for (int k = 0; k < 2; ++k) dst[m][k] = *(const PG8_LAS bf16x8*)(lds + PG8_SA(b, h) + aoff + m * 2048 + k * 1024); } while (0)
; #define PG8_LDB(dst, b, h) do { _Pragma("unroll") for (int n = 0; n < 2; ++n) _Pragma("unroll") for (int k = 0; k < 2; ++k) dst[n][k] = *(const PG8_LAS bf16x8*)(lds + PG8_SB(b, h) + boff + n * 2048 + k * 1024); } while (0)
; #define PG8_MMA(ai, bj, At, Bt) do { __builtin_amdgcn_s_setprio(1); _Pragma("unroll") for (int m = 0; m < 4; ++m) _Pragma("unroll") for (int n = 0; n < 2; ++n) _Pragma("unroll") for (int k = 0; k < 2; ++k) \
;         acc[ai][bj][m][n] = __builtin_amdgcn_mfma_f32_16x16x32_bf16(Bt[n][k], At[m][k], acc[ai][bj][m][n], 0, 0, 0); __builtin_amdgcn_s_setprio(0); } while (0)
; #define PG8_WAIT_V(n) asm volatile("s_waitcnt vmcnt(" #n ")" ::: "memory")
; #define PG8_WAIT_L(n) asm volatile("s_waitcnt lgkmcnt(" #n ")" ::: "memory")
; #define PG8_BAR __builtin_amdgcn_s_barrier()
; #define PG8_SCHED __builtin_amdgcn_sched_barrier(0)
; template <class Epi, class Sched, bool ALIGN_EPI = false, bool SP2 = false>
; __device__ __forceinline__ void gemm_phase(PG8_LAS unsigned char* lds, const Gemm g, const Sched& S, const Epi& E) {
;     ...
;             PG8_LDB(B0, 0, 0); PG8_LDB(B1, 0, 1); PG8_SCHED; PG8_LDA(At, 0, 0); PG8_STAGE(PG8_SA(1, 1), a1 + hstepA, voffA);
;             PG8_WAIT_V(8); PG8_WAIT_L(0); PG8_BAR; PG8_MMA(0, 0, At, B0); PG8_MMA(0, 1, At, B1); PG8_BAR; PG8_SCHED;
;             PG8_LDA(At, 0, 1); PG8_STAGE(PG8_SB(0, 0), b2, voffB); PG8_STAGE(PG8_SB(0, 1), b2 + hstepB, voffB); PG8_STAGE(PG8_SA(0, 0), a2, voffA);
;             PG8_WAIT_V(8); PG8_WAIT_L(0); PG8_BAR; PG8_MMA(1, 0, At, B0); PG8_MMA(1, 1, At, B1); PG8_BAR; PG8_SCHED;
.LBB0_2387:
	ds_read_b128 v[154:157], v150
	ds_read_b128 v[158:161], v150 offset:1024
	ds_read_b128 v[162:165], v150 offset:2048
	ds_read_b128 v[166:169], v150 offset:3072
	ds_read_b128 v[170:173], v151
	ds_read_b128 v[174:177], v151 offset:1024
	ds_read_b128 v[178:181], v151 offset:2048
	ds_read_b128 v[182:185], v151 offset:3072
	s_add_u32 s22, s20, 0xfff80080
	s_addc_u32 s23, s21, -1
	s_cmp_eq_u32 s46, 28
	s_cselect_b32 s25, s13, s23
	s_cselect_b32 s24, s42, s22
	s_cselect_b32 s23, s11, s45
	s_cselect_b32 s22, s43, s44
	v_lshl_add_u64 v[146:147], s[20:21], 0, v[138:139]
	s_add_i32 m0, s19, 0xc000
	ds_read_b128 v[186:189], v152
	ds_read_b128 v[190:193], v152 offset:1024
	ds_read_b128 v[194:197], v152 offset:2048
	ds_read_b128 v[198:201], v152 offset:3072
	ds_read_b128 v[202:205], v152 offset:4096
	ds_read_b128 v[210:213], v152 offset:5120
	ds_read_b128 v[214:217], v152 offset:6144
	ds_read_b128 v[218:221], v152 offset:7168
	global_load_lds_dwordx4 v[146:147], off
	v_lshl_add_u64 v[146:147], s[20:21], 0, v[140:141]
	s_add_i32 m0, s19, 0xe000
	s_nop 0
	global_load_lds_dwordx4 v[146:147], off
	s_waitcnt vmcnt(8)
	s_waitcnt lgkmcnt(0)
	s_setprio 1
	s_barrier
	v_mfma_f32_16x16x32_bf16 v[126:129], v[154:157], v[186:189], v[126:129]
	v_mfma_f32_16x16x32_bf16 v[122:125], v[162:165], v[186:189], v[122:125]
	v_mfma_f32_16x16x32_bf16 v[110:113], v[154:157], v[194:197], v[110:113]
	v_mfma_f32_16x16x32_bf16 v[106:109], v[162:165], v[194:197], v[106:109]
	v_mfma_f32_16x16x32_bf16 v[94:97], v[154:157], v[202:205], v[94:97]
	v_mfma_f32_16x16x32_bf16 v[90:93], v[162:165], v[202:205], v[90:93]
	v_mfma_f32_16x16x32_bf16 v[78:81], v[154:157], v[214:217], v[78:81]
	v_mfma_f32_16x16x32_bf16 v[74:77], v[162:165], v[214:217], v[74:77]
	v_mfma_f32_16x16x32_bf16 v[126:129], v[158:161], v[190:193], v[126:129]
	v_mfma_f32_16x16x32_bf16 v[122:125], v[166:169], v[190:193], v[122:125]
	v_mfma_f32_16x16x32_bf16 v[110:113], v[158:161], v[198:201], v[110:113]
	v_mfma_f32_16x16x32_bf16 v[106:109], v[166:169], v[198:201], v[106:109]
	v_mfma_f32_16x16x32_bf16 v[94:97], v[158:161], v[210:213], v[94:97]
	v_mfma_f32_16x16x32_bf16 v[90:93], v[166:169], v[210:213], v[90:93]
	v_mfma_f32_16x16x32_bf16 v[78:81], v[158:161], v[218:221], v[78:81]
	v_mfma_f32_16x16x32_bf16 v[74:77], v[166:169], v[218:221], v[74:77]
	v_mfma_f32_16x16x32_bf16 v[118:121], v[170:173], v[186:189], v[118:121]
	v_mfma_f32_16x16x32_bf16 v[114:117], v[178:181], v[186:189], v[114:117]
	v_mfma_f32_16x16x32_bf16 v[102:105], v[170:173], v[194:197], v[102:105]
	v_mfma_f32_16x16x32_bf16 v[98:101], v[178:181], v[194:197], v[98:101]
	v_mfma_f32_16x16x32_bf16 v[86:89], v[170:173], v[202:205], v[86:89]
	v_mfma_f32_16x16x32_bf16 v[82:85], v[178:181], v[202:205], v[82:85]
	v_mfma_f32_16x16x32_bf16 v[70:73], v[170:173], v[214:217], v[70:73]
	v_mfma_f32_16x16x32_bf16 v[66:69], v[178:181], v[214:217], v[66:69]
	v_mfma_f32_16x16x32_bf16 v[118:121], v[174:177], v[190:193], v[118:121]
	v_mfma_f32_16x16x32_bf16 v[114:117], v[182:185], v[190:193], v[114:117]
	v_mfma_f32_16x16x32_bf16 v[102:105], v[174:177], v[198:201], v[102:105]
	v_mfma_f32_16x16x32_bf16 v[98:101], v[182:185], v[198:201], v[98:101]
	v_mfma_f32_16x16x32_bf16 v[86:89], v[174:177], v[210:213], v[86:89]
	v_mfma_f32_16x16x32_bf16 v[82:85], v[182:185], v[210:213], v[82:85]
	v_mfma_f32_16x16x32_bf16 v[70:73], v[174:177], v[218:221], v[70:73]
	v_mfma_f32_16x16x32_bf16 v[66:69], v[182:185], v[218:221], v[66:69]
	s_barrier
	s_setprio 0
	s_add_i32 s47, s38, s27
	v_lshl_add_u64 v[146:147], s[22:23], 0, v[134:135]
	s_mov_b32 m0, s47
	ds_read_b128 v[186:189], v152 offset:16384
	ds_read_b128 v[190:193], v152 offset:17408
	ds_read_b128 v[194:197], v152 offset:18432
	ds_read_b128 v[198:201], v152 offset:19456
	ds_read_b128 v[202:205], v152 offset:20480
	ds_read_b128 v[210:213], v152 offset:21504
	ds_read_b128 v[214:217], v152 offset:22528
	ds_read_b128 v[218:221], v152 offset:23552
	global_load_lds_dwordx4 v[146:147], off
	s_add_i32 m0, s47, 0x2000
	s_add_u32 s48, s22, 0x80000
	v_lshl_add_u64 v[206:207], s[22:23], 0, v[130:131]
	s_addc_u32 s49, s23, 0
	s_add_i32 s47, s39, s27
	global_load_lds_dwordx4 v[206:207], off
	v_lshl_add_u64 v[222:223], s[48:49], 0, v[134:135]
	s_mov_b32 m0, s47
	v_lshl_add_u64 v[224:225], s[24:25], 0, v[132:133]
	global_load_lds_dwordx4 v[222:223], off
	v_lshl_add_u64 v[222:223], s[48:49], 0, v[130:131]
	s_add_i32 m0, s47, 0x2000
	s_nop 0
	global_load_lds_dwordx4 v[222:223], off
	v_lshl_add_u64 v[222:223], s[24:25], 0, v[136:137]
	s_mov_b32 m0, s19
	s_nop 0
	global_load_lds_dwordx4 v[222:223], off
	s_mov_b32 m0, s30
	s_nop 0
	global_load_lds_dwordx4 v[224:225], off
	s_waitcnt vmcnt(8)
	s_waitcnt lgkmcnt(0)
	s_setprio 1
	s_barrier
; #define PG8_STAGE(bufoff, gbase, voff) do { _Pragma("unroll") for (int _i = 0; _i < 2; ++_i) \
;         __builtin_amdgcn_global_load_lds((const unsigned*)((const char*)(gbase) + (voff)[_i]), (PG8_LAS unsigned*)(lds + (bufoff) + ldsw + _i * 8192), 16, 0, 0); } while (0)
; #define PG8_LDA(dst, b, h) do { _Pragma("unroll") for (int m = 0; m < 4; ++m) _Pragma("unroll") for (int k = 0; k < 2; ++k) dst[m][k] = *(const PG8_LAS bf16x8*)(lds + PG8_SA(b, h) + aoff + m * 2048 + k * 1024); } while (0)
; #define PG8_LDB(dst, b, h) do { _Pragma("unroll") for (int n = 0; n < 2; ++n) _Pragma("unroll") for (int k = 0; k < 2; ++k) dst[n][k] = *(const PG8_LAS bf16x8*)(lds + PG8_SB(b, h) + boff + n * 2048 + k * 1024); } while (0)
; #define PG8_MMA(ai, bj, At, Bt) do { __builtin_amdgcn_s_setprio(1); _Pragma("unroll") for (int m = 0; m < 4; ++m) _Pragma("unroll") for (int n = 0; n < 2; ++n) _Pragma("unroll") for (int k = 0; k < 2; ++k) \
;         acc[ai][bj][m][n] = __builtin_amdgcn_mfma_f32_16x16x32_bf16(Bt[n][k], At[m][k], acc[ai][bj][m][n], 0, 0, 0); __builtin_amdgcn_s_setprio(0); } while (0)
; #define PG8_WAIT_V(n) asm volatile("s_waitcnt vmcnt(" #n ")" ::: "memory")
; #define PG8_WAIT_L(n) asm volatile("s_waitcnt lgkmcnt(" #n ")" ::: "memory")
; #define PG8_BAR __builtin_amdgcn_s_barrier()
; #define PG8_SCHED __builtin_amdgcn_sched_barrier(0)
; template <class Epi, class Sched, bool ALIGN_EPI = false, bool SP2 = false>
; __device__ __forceinline__ void gemm_phase(PG8_LAS unsigned char* lds, const Gemm g, const Sched& S, const Epi& E) {
;     ...
;             PG8_WAIT_V(8); PG8_WAIT_L(0); PG8_BAR; PG8_MMA(1, 0, At, B0); PG8_MMA(1, 1, At, B1); PG8_BAR; PG8_SCHED;
;             PG8_LDB(B0, 1, 0); PG8_LDB(B1, 1, 1); PG8_SCHED; PG8_LDA(At, 1, 0); PG8_STAGE(PG8_SA(0, 1), a2 + hstepA, voffA);
;             PG8_WAIT_V(8); PG8_WAIT_L(0); PG8_BAR; PG8_MMA(0, 0, At, B0); PG8_MMA(0, 1, At, B1); PG8_BAR; PG8_SCHED;
	v_mfma_f32_16x16x32_bf16 v[62:65], v[154:157], v[186:189], v[62:65]
	v_mfma_f32_16x16x32_bf16 v[58:61], v[162:165], v[186:189], v[58:61]
	v_mfma_f32_16x16x32_bf16 v[46:49], v[154:157], v[194:197], v[46:49]
	v_mfma_f32_16x16x32_bf16 v[42:45], v[162:165], v[194:197], v[42:45]
	v_mfma_f32_16x16x32_bf16 v[30:33], v[154:157], v[202:205], v[30:33]
	v_mfma_f32_16x16x32_bf16 v[26:29], v[162:165], v[202:205], v[26:29]
	v_mfma_f32_16x16x32_bf16 v[14:17], v[154:157], v[214:217], v[14:17]
	v_mfma_f32_16x16x32_bf16 v[10:13], v[162:165], v[214:217], v[10:13]
	v_mfma_f32_16x16x32_bf16 v[62:65], v[158:161], v[190:193], v[62:65]
	v_mfma_f32_16x16x32_bf16 v[58:61], v[166:169], v[190:193], v[58:61]
	v_mfma_f32_16x16x32_bf16 v[46:49], v[158:161], v[198:201], v[46:49]
	v_mfma_f32_16x16x32_bf16 v[42:45], v[166:169], v[198:201], v[42:45]
	v_mfma_f32_16x16x32_bf16 v[30:33], v[158:161], v[210:213], v[30:33]
	v_mfma_f32_16x16x32_bf16 v[26:29], v[166:169], v[210:213], v[26:29]
	v_mfma_f32_16x16x32_bf16 v[14:17], v[158:161], v[218:221], v[14:17]
	v_mfma_f32_16x16x32_bf16 v[10:13], v[166:169], v[218:221], v[10:13]
	v_mfma_f32_16x16x32_bf16 v[54:57], v[170:173], v[186:189], v[54:57]
	v_mfma_f32_16x16x32_bf16 v[50:53], v[178:181], v[186:189], v[50:53]
	v_mfma_f32_16x16x32_bf16 v[38:41], v[170:173], v[194:197], v[38:41]
	v_mfma_f32_16x16x32_bf16 v[34:37], v[178:181], v[194:197], v[34:37]
	v_mfma_f32_16x16x32_bf16 v[22:25], v[170:173], v[202:205], v[22:25]
	v_mfma_f32_16x16x32_bf16 v[18:21], v[178:181], v[202:205], v[18:21]
	v_mfma_f32_16x16x32_bf16 v[6:9], v[170:173], v[214:217], v[6:9]
	v_mfma_f32_16x16x32_bf16 v[2:5], v[178:181], v[214:217], v[2:5]
	v_mfma_f32_16x16x32_bf16 v[54:57], v[174:177], v[190:193], v[54:57]
	v_mfma_f32_16x16x32_bf16 v[50:53], v[182:185], v[190:193], v[50:53]
	v_mfma_f32_16x16x32_bf16 v[38:41], v[174:177], v[198:201], v[38:41]
	v_mfma_f32_16x16x32_bf16 v[34:37], v[182:185], v[198:201], v[34:37]
	v_mfma_f32_16x16x32_bf16 v[22:25], v[174:177], v[210:213], v[22:25]
	v_mfma_f32_16x16x32_bf16 v[18:21], v[182:185], v[210:213], v[18:21]
	v_mfma_f32_16x16x32_bf16 v[6:9], v[174:177], v[218:221], v[6:9]
	v_mfma_f32_16x16x32_bf16 v[2:5], v[182:185], v[218:221], v[2:5]
	s_barrier
	s_setprio 0
	s_add_i32 s47, 0, 0x18000
	v_add_u32_e32 v153, s47, v148
	s_add_i32 s48, 0, 0x1c000
	ds_read_b128 v[154:157], v153
	ds_read_b128 v[158:161], v153 offset:1024
	ds_read_b128 v[162:165], v153 offset:2048
	ds_read_b128 v[166:169], v153 offset:3072
	v_add_u32_e32 v153, s48, v148
	ds_read_b128 v[170:173], v153
	ds_read_b128 v[174:177], v153 offset:1024
	ds_read_b128 v[178:181], v153 offset:2048
	ds_read_b128 v[182:185], v153 offset:3072
	s_add_u32 s24, s24, 0x80000
	s_addc_u32 s25, s25, 0
	s_mov_b32 m0, s31
	v_lshl_add_u64 v[226:227], s[24:25], 0, v[136:137]
	ds_read_b128 v[186:189], v152 offset:32768
	ds_read_b128 v[190:193], v152 offset:33792
	ds_read_b128 v[194:197], v152 offset:34816
	ds_read_b128 v[198:201], v152 offset:35840
	ds_read_b128 v[202:205], v152 offset:36864
	ds_read_b128 v[210:213], v152 offset:37888
	ds_read_b128 v[214:217], v152 offset:38912
	ds_read_b128 v[218:221], v152 offset:39936
	global_load_lds_dwordx4 v[226:227], off
	v_lshl_add_u64 v[226:227], s[24:25], 0, v[132:133]
	s_mov_b32 m0, s33
	s_nop 0
	global_load_lds_dwordx4 v[226:227], off
	s_waitcnt vmcnt(8)
	s_waitcnt lgkmcnt(0)
	s_setprio 1
	s_barrier
	v_mfma_f32_16x16x32_bf16 v[126:129], v[154:157], v[186:189], v[126:129]
	v_mfma_f32_16x16x32_bf16 v[122:125], v[162:165], v[186:189], v[122:125]
	v_mfma_f32_16x16x32_bf16 v[110:113], v[154:157], v[194:197], v[110:113]
	v_mfma_f32_16x16x32_bf16 v[106:109], v[162:165], v[194:197], v[106:109]
	v_mfma_f32_16x16x32_bf16 v[94:97], v[154:157], v[202:205], v[94:97]
	v_mfma_f32_16x16x32_bf16 v[90:93], v[162:165], v[202:205], v[90:93]
	v_mfma_f32_16x16x32_bf16 v[78:81], v[154:157], v[214:217], v[78:81]
	v_mfma_f32_16x16x32_bf16 v[74:77], v[162:165], v[214:217], v[74:77]
	v_mfma_f32_16x16x32_bf16 v[126:129], v[158:161], v[190:193], v[126:129]
	v_mfma_f32_16x16x32_bf16 v[122:125], v[166:169], v[190:193], v[122:125]
	v_mfma_f32_16x16x32_bf16 v[110:113], v[158:161], v[198:201], v[110:113]
	v_mfma_f32_16x16x32_bf16 v[106:109], v[166:169], v[198:201], v[106:109]
	v_mfma_f32_16x16x32_bf16 v[94:97], v[158:161], v[210:213], v[94:97]
	v_mfma_f32_16x16x32_bf16 v[90:93], v[166:169], v[210:213], v[90:93]
	v_mfma_f32_16x16x32_bf16 v[78:81], v[158:161], v[218:221], v[78:81]
	v_mfma_f32_16x16x32_bf16 v[74:77], v[166:169], v[218:221], v[74:77]
	v_mfma_f32_16x16x32_bf16 v[118:121], v[170:173], v[186:189], v[118:121]
	v_mfma_f32_16x16x32_bf16 v[114:117], v[178:181], v[186:189], v[114:117]
	v_mfma_f32_16x16x32_bf16 v[102:105], v[170:173], v[194:197], v[102:105]
	v_mfma_f32_16x16x32_bf16 v[98:101], v[178:181], v[194:197], v[98:101]
	v_mfma_f32_16x16x32_bf16 v[86:89], v[170:173], v[202:205], v[86:89]
	v_mfma_f32_16x16x32_bf16 v[82:85], v[178:181], v[202:205], v[82:85]
	v_mfma_f32_16x16x32_bf16 v[70:73], v[170:173], v[214:217], v[70:73]
	v_mfma_f32_16x16x32_bf16 v[66:69], v[178:181], v[214:217], v[66:69]
	v_mfma_f32_16x16x32_bf16 v[118:121], v[174:177], v[190:193], v[118:121]
	v_mfma_f32_16x16x32_bf16 v[114:117], v[182:185], v[190:193], v[114:117]
	v_mfma_f32_16x16x32_bf16 v[102:105], v[174:177], v[198:201], v[102:105]
	v_mfma_f32_16x16x32_bf16 v[98:101], v[182:185], v[198:201], v[98:101]
	v_mfma_f32_16x16x32_bf16 v[86:89], v[174:177], v[210:213], v[86:89]
	v_mfma_f32_16x16x32_bf16 v[82:85], v[182:185], v[210:213], v[82:85]
	v_mfma_f32_16x16x32_bf16 v[70:73], v[174:177], v[218:221], v[70:73]
	v_mfma_f32_16x16x32_bf16 v[66:69], v[182:185], v[218:221], v[66:69]
	s_barrier
; #define PG8_STAGE(bufoff, gbase, voff) do { _Pragma("unroll") for (int _i = 0; _i < 2; ++_i) \
;         __builtin_amdgcn_global_load_lds((const unsigned*)((const char*)(gbase) + (voff)[_i]), (PG8_LAS unsigned*)(lds + (bufoff) + ldsw + _i * 8192), 16, 0, 0); } while (0)
; #define PG8_LDA(dst, b, h) do { _Pragma("unroll") for (int m = 0; m < 4; ++m) _Pragma("unroll") for (int k = 0; k < 2; ++k) dst[m][k] = *(const PG8_LAS bf16x8*)(lds + PG8_SA(b, h) + aoff + m * 2048 + k * 1024); } while (0)
; #define PG8_MMA(ai, bj, At, Bt) do { __builtin_amdgcn_s_setprio(1); _Pragma("unroll") for (int m = 0; m < 4; ++m) _Pragma("unroll") for (int n = 0; n < 2; ++n) _Pragma("unroll") for (int k = 0; k < 2; ++k) \
;         acc[ai][bj][m][n] = __builtin_amdgcn_mfma_f32_16x16x32_bf16(Bt[n][k], At[m][k], acc[ai][bj][m][n], 0, 0, 0); __builtin_amdgcn_s_setprio(0); } while (0)
; #define PG8_WAIT_V(n) asm volatile("s_waitcnt vmcnt(" #n ")" ::: "memory")
; #define PG8_WAIT_L(n) asm volatile("s_waitcnt lgkmcnt(" #n ")" ::: "memory")
; #define PG8_BAR __builtin_amdgcn_s_barrier()
; #define PG8_SCHED __builtin_amdgcn_sched_barrier(0)
; template <class Epi, class Sched, bool ALIGN_EPI = false, bool SP2 = false>
; __device__ __forceinline__ void gemm_phase(PG8_LAS unsigned char* lds, const Gemm g, const Sched& S, const Epi& E) {
;     ...
;             PG8_LDA(At, 1, 1); PG8_STAGE(PG8_SB(1, 0), b3, voffB); PG8_STAGE(PG8_SB(1, 1), b3 + hstepB, voffB); PG8_STAGE(PG8_SA(1, 0), a3, voffA);
;             PG8_WAIT_V(8); PG8_WAIT_L(0); PG8_BAR; PG8_MMA(1, 0, At, B0); PG8_MMA(1, 1, At, B1); PG8_BAR; PG8_SCHED;
	s_setprio 0
	s_add_i32 s24, s47, s27
	v_lshl_add_u64 v[146:147], v[146:147], 0, s[2:3]
	s_mov_b32 m0, s24
	ds_read_b128 v[186:189], v152 offset:49152
	ds_read_b128 v[190:193], v152 offset:50176
	ds_read_b128 v[194:197], v152 offset:51200
	ds_read_b128 v[198:201], v152 offset:52224
	ds_read_b128 v[202:205], v152 offset:53248
	ds_read_b128 v[210:213], v152 offset:54272
	ds_read_b128 v[214:217], v152 offset:55296
	ds_read_b128 v[218:221], v152 offset:56320
	global_load_lds_dwordx4 v[146:147], off
	s_add_i32 m0, s24, 0x2000
	s_add_u32 s22, s22, 0x80080
	v_lshl_add_u64 v[146:147], v[206:207], 0, s[2:3]
	s_addc_u32 s23, s23, 0
	s_add_i32 s24, s48, s27
	global_load_lds_dwordx4 v[146:147], off
	v_lshl_add_u64 v[146:147], s[22:23], 0, v[134:135]
	s_mov_b32 m0, s24
	s_nop 0
	global_load_lds_dwordx4 v[146:147], off
	v_lshl_add_u64 v[146:147], s[22:23], 0, v[130:131]
	s_add_i32 m0, s24, 0x2000
	s_nop 0
	global_load_lds_dwordx4 v[146:147], off
	v_lshl_add_u64 v[146:147], v[222:223], 0, s[2:3]
	s_mov_b32 m0, s35
	s_nop 0
	global_load_lds_dwordx4 v[146:147], off
	v_lshl_add_u64 v[146:147], v[224:225], 0, s[2:3]
	s_mov_b32 m0, s36
	s_nop 0
	global_load_lds_dwordx4 v[146:147], off
	s_waitcnt vmcnt(8)
	s_waitcnt lgkmcnt(0)
	s_setprio 1
	s_barrier
	v_mfma_f32_16x16x32_bf16 v[62:65], v[154:157], v[186:189], v[62:65]
	v_mfma_f32_16x16x32_bf16 v[58:61], v[162:165], v[186:189], v[58:61]
	v_mfma_f32_16x16x32_bf16 v[46:49], v[154:157], v[194:197], v[46:49]
	v_mfma_f32_16x16x32_bf16 v[42:45], v[162:165], v[194:197], v[42:45]
	v_mfma_f32_16x16x32_bf16 v[30:33], v[154:157], v[202:205], v[30:33]
	v_mfma_f32_16x16x32_bf16 v[26:29], v[162:165], v[202:205], v[26:29]
	v_mfma_f32_16x16x32_bf16 v[14:17], v[154:157], v[214:217], v[14:17]
	v_mfma_f32_16x16x32_bf16 v[10:13], v[162:165], v[214:217], v[10:13]
	v_mfma_f32_16x16x32_bf16 v[62:65], v[158:161], v[190:193], v[62:65]
	v_mfma_f32_16x16x32_bf16 v[58:61], v[166:169], v[190:193], v[58:61]
	v_mfma_f32_16x16x32_bf16 v[46:49], v[158:161], v[198:201], v[46:49]
	v_mfma_f32_16x16x32_bf16 v[42:45], v[166:169], v[198:201], v[42:45]
	v_mfma_f32_16x16x32_bf16 v[30:33], v[158:161], v[210:213], v[30:33]
	v_mfma_f32_16x16x32_bf16 v[26:29], v[166:169], v[210:213], v[26:29]
	v_mfma_f32_16x16x32_bf16 v[14:17], v[158:161], v[218:221], v[14:17]
	v_mfma_f32_16x16x32_bf16 v[10:13], v[166:169], v[218:221], v[10:13]
	v_mfma_f32_16x16x32_bf16 v[54:57], v[170:173], v[186:189], v[54:57]
	v_mfma_f32_16x16x32_bf16 v[50:53], v[178:181], v[186:189], v[50:53]
	v_mfma_f32_16x16x32_bf16 v[38:41], v[170:173], v[194:197], v[38:41]
	v_mfma_f32_16x16x32_bf16 v[34:37], v[178:181], v[194:197], v[34:37]
	v_mfma_f32_16x16x32_bf16 v[22:25], v[170:173], v[202:205], v[22:25]
	v_mfma_f32_16x16x32_bf16 v[18:21], v[178:181], v[202:205], v[18:21]
	v_mfma_f32_16x16x32_bf16 v[6:9], v[170:173], v[214:217], v[6:9]
	v_mfma_f32_16x16x32_bf16 v[2:5], v[178:181], v[214:217], v[2:5]
	v_mfma_f32_16x16x32_bf16 v[54:57], v[174:177], v[190:193], v[54:57]
	v_mfma_f32_16x16x32_bf16 v[50:53], v[182:185], v[190:193], v[50:53]
	v_mfma_f32_16x16x32_bf16 v[38:41], v[174:177], v[198:201], v[38:41]
	v_mfma_f32_16x16x32_bf16 v[34:37], v[182:185], v[198:201], v[34:37]
	v_mfma_f32_16x16x32_bf16 v[22:25], v[174:177], v[210:213], v[22:25]
	v_mfma_f32_16x16x32_bf16 v[18:21], v[182:185], v[210:213], v[18:21]
	v_mfma_f32_16x16x32_bf16 v[6:9], v[174:177], v[218:221], v[6:9]
	v_mfma_f32_16x16x32_bf16 v[2:5], v[182:185], v[218:221], v[2:5]
	s_barrier
	s_setprio 0
	s_add_i32 s46, s46, 2
	s_add_u32 s20, s20, 0x100
	s_addc_u32 s21, s21, 0
	s_add_u32 s44, s44, 0x100
	s_addc_u32 s45, s45, 0
	s_cmp_gt_u32 s46, 29
	s_cbranch_scc0 .LBB0_2387
	s_and_b64 vcc, exec, s[8:9]
	s_cbranch_vccz .LBB0_2390
	s_barrier

; #define PG8_STAGE(bufoff, gbase, voff) do { _Pragma("unroll") for (int _i = 0; _i < 2; ++_i) \
;         __builtin_amdgcn_global_load_lds((const unsigned*)((const char*)(gbase) + (voff)[_i]), (PG8_LAS unsigned*)(lds + (bufoff) + ldsw + _i * 8192), 16, 0, 0); } while (0)
; #define PG8_LDA(dst, b, h) do { _Pragma("unroll") for (int m = 0; m < 4; ++m) _Pragma("unroll") for (int k = 0; k < 2; ++k) dst[m][k] = *(const PG8_LAS bf16x8*)(lds + PG8_SA(b, h) + aoff + m * 2048 + k * 1024); } while (0)
; #define PG8_LDB(dst, b, h) do { _Pragma("unroll") for (int n = 0; n < 2; ++n) _Pragma("unroll") for (int k = 0; k < 2; ++k) dst[n][k] = *(const PG8_LAS bf16x8*)(lds + PG8_SB(b, h) + boff + n * 2048 + k * 1024); } while (0)
; #define PG8_MMA(ai, bj, At, Bt) do { __builtin_amdgcn_s_setprio(1); _Pragma("unroll") for (int m = 0; m < 4; ++m) _Pragma("unroll") for (int n = 0; n < 2; ++n) _Pragma("unroll") for (int k = 0; k < 2; ++k) \
;         acc[ai][bj][m][n] = __builtin_amdgcn_mfma_f32_16x16x32_bf16(Bt[n][k], At[m][k], acc[ai][bj][m][n], 0, 0, 0); __builtin_amdgcn_s_setprio(0); } while (0)
; #define PG8_WAIT_V(n) asm volatile("s_waitcnt vmcnt(" #n ")" ::: "memory")
; #define PG8_WAIT_L(n) asm volatile("s_waitcnt lgkmcnt(" #n ")" ::: "memory")
; #define PG8_BAR __builtin_amdgcn_s_barrier()
; #define PG8_SCHED __builtin_amdgcn_sched_barrier(0)
; template <class Epi, class Sched, bool ALIGN_EPI = false, bool SP2 = false>
; __device__ __forceinline__ void gemm_phase(PG8_LAS unsigned char* lds, const Gemm g, const Sched& S, const Epi& E) {
;     ...
;             PG8_LDB(B0, 0, 0); PG8_LDB(B1, 0, 1); PG8_SCHED; PG8_LDA(At, 0, 0); PG8_STAGE(PG8_SA(1, 1), a1 + hstepA, voffA);
;             PG8_WAIT_V(8); PG8_WAIT_L(0); PG8_BAR; PG8_MMA(0, 0, At, B0); PG8_MMA(0, 1, At, B1); PG8_BAR; PG8_SCHED;
;             PG8_LDA(At, 0, 1); PG8_STAGE(PG8_SB(0, 0), b2, voffB); PG8_STAGE(PG8_SB(0, 1), b2 + hstepB, voffB); PG8_STAGE(PG8_SA(0, 0), a2, voffA);
;             PG8_WAIT_V(8); PG8_WAIT_L(0); PG8_BAR; PG8_MMA(1, 0, At, B0); PG8_MMA(1, 1, At, B1); PG8_BAR; PG8_SCHED;
.LBB0_2487:
	ds_read_b128 v[152:155], v148
	ds_read_b128 v[156:159], v148 offset:1024
	ds_read_b128 v[160:163], v148 offset:2048
	ds_read_b128 v[164:167], v148 offset:3072
	ds_read_b128 v[168:171], v149
	ds_read_b128 v[172:175], v149 offset:1024
	ds_read_b128 v[176:179], v149 offset:2048
	ds_read_b128 v[180:183], v149 offset:3072
	s_add_u32 s24, s22, 0xffea0080
	s_addc_u32 s25, s23, -1
	s_cmpk_eq_i32 s53, 0x54
	s_cselect_b32 s27, s7, s25
	s_cselect_b32 s26, s6, s24
	s_cselect_b32 s25, s21, s52
	s_cselect_b32 s24, s20, s51
	v_lshl_add_u64 v[218:219], s[22:23], 0, v[138:139]
	s_add_i32 m0, s33, 0xc000
	ds_read_b128 v[184:187], v150
	ds_read_b128 v[188:191], v150 offset:1024
	ds_read_b128 v[192:195], v150 offset:2048
	ds_read_b128 v[196:199], v150 offset:3072
	ds_read_b128 v[200:203], v150 offset:4096
	ds_read_b128 v[204:207], v150 offset:5120
	ds_read_b128 v[210:213], v150 offset:6144
	ds_read_b128 v[214:217], v150 offset:7168
	global_load_lds_dwordx4 v[218:219], off
	v_lshl_add_u64 v[218:219], s[22:23], 0, v[140:141]
	s_add_i32 m0, s33, 0xe000
	s_nop 0
	global_load_lds_dwordx4 v[218:219], off
	s_waitcnt vmcnt(8)
	s_waitcnt lgkmcnt(0)
	s_setprio 1
	s_barrier
	v_mfma_f32_16x16x32_bf16 v[126:129], v[152:155], v[184:187], v[126:129]
	v_mfma_f32_16x16x32_bf16 v[122:125], v[160:163], v[184:187], v[122:125]
	v_mfma_f32_16x16x32_bf16 v[118:121], v[152:155], v[192:195], v[118:121]
	v_mfma_f32_16x16x32_bf16 v[114:117], v[160:163], v[192:195], v[114:117]
	v_mfma_f32_16x16x32_bf16 v[102:105], v[152:155], v[200:203], v[102:105]
	v_mfma_f32_16x16x32_bf16 v[98:101], v[160:163], v[200:203], v[98:101]
	v_mfma_f32_16x16x32_bf16 v[86:89], v[152:155], v[210:213], v[86:89]
	v_mfma_f32_16x16x32_bf16 v[82:85], v[160:163], v[210:213], v[82:85]
	v_mfma_f32_16x16x32_bf16 v[126:129], v[156:159], v[188:191], v[126:129]
	v_mfma_f32_16x16x32_bf16 v[122:125], v[164:167], v[188:191], v[122:125]
	v_mfma_f32_16x16x32_bf16 v[118:121], v[156:159], v[196:199], v[118:121]
	v_mfma_f32_16x16x32_bf16 v[114:117], v[164:167], v[196:199], v[114:117]
	v_mfma_f32_16x16x32_bf16 v[102:105], v[156:159], v[204:207], v[102:105]
	v_mfma_f32_16x16x32_bf16 v[98:101], v[164:167], v[204:207], v[98:101]
	v_mfma_f32_16x16x32_bf16 v[86:89], v[156:159], v[214:217], v[86:89]
	v_mfma_f32_16x16x32_bf16 v[82:85], v[164:167], v[214:217], v[82:85]
	v_mfma_f32_16x16x32_bf16 v[110:113], v[168:171], v[184:187], v[110:113]
	v_mfma_f32_16x16x32_bf16 v[106:109], v[176:179], v[184:187], v[106:109]
	v_mfma_f32_16x16x32_bf16 v[94:97], v[168:171], v[192:195], v[94:97]
	v_mfma_f32_16x16x32_bf16 v[90:93], v[176:179], v[192:195], v[90:93]
	v_mfma_f32_16x16x32_bf16 v[78:81], v[168:171], v[200:203], v[78:81]
	v_mfma_f32_16x16x32_bf16 v[74:77], v[176:179], v[200:203], v[74:77]
	v_mfma_f32_16x16x32_bf16 v[70:73], v[168:171], v[210:213], v[70:73]
	v_mfma_f32_16x16x32_bf16 v[66:69], v[176:179], v[210:213], v[66:69]
	v_mfma_f32_16x16x32_bf16 v[110:113], v[172:175], v[188:191], v[110:113]
	v_mfma_f32_16x16x32_bf16 v[106:109], v[180:183], v[188:191], v[106:109]
	v_mfma_f32_16x16x32_bf16 v[94:97], v[172:175], v[196:199], v[94:97]
	v_mfma_f32_16x16x32_bf16 v[90:93], v[180:183], v[196:199], v[90:93]
	v_mfma_f32_16x16x32_bf16 v[78:81], v[172:175], v[204:207], v[78:81]
	v_mfma_f32_16x16x32_bf16 v[74:77], v[180:183], v[204:207], v[74:77]
	v_mfma_f32_16x16x32_bf16 v[70:73], v[172:175], v[214:217], v[70:73]
	v_mfma_f32_16x16x32_bf16 v[66:69], v[180:183], v[214:217], v[66:69]
	s_barrier
	s_setprio 0
	s_add_i32 s54, s41, s29
	v_lshl_add_u64 v[218:219], s[24:25], 0, v[134:135]
	s_mov_b32 m0, s54
	ds_read_b128 v[184:187], v150 offset:16384
	ds_read_b128 v[188:191], v150 offset:17408
	ds_read_b128 v[192:195], v150 offset:18432
	ds_read_b128 v[196:199], v150 offset:19456
	ds_read_b128 v[200:203], v150 offset:20480
	ds_read_b128 v[204:207], v150 offset:21504
	ds_read_b128 v[210:213], v150 offset:22528
	ds_read_b128 v[214:217], v150 offset:23552
	global_load_lds_dwordx4 v[218:219], off
	s_add_i32 m0, s54, 0x2000
	s_add_u32 s54, s24, 0x160000
	v_lshl_add_u64 v[220:221], s[24:25], 0, v[130:131]
	s_addc_u32 s55, s25, 0
	s_add_i32 s56, s42, s29
	global_load_lds_dwordx4 v[220:221], off
	v_lshl_add_u64 v[222:223], s[54:55], 0, v[134:135]
	s_mov_b32 m0, s56
	v_lshl_add_u64 v[224:225], s[26:27], 0, v[132:133]
	global_load_lds_dwordx4 v[222:223], off
	v_lshl_add_u64 v[222:223], s[54:55], 0, v[130:131]
	s_add_i32 m0, s56, 0x2000
	s_nop 0
	global_load_lds_dwordx4 v[222:223], off
	v_lshl_add_u64 v[222:223], s[26:27], 0, v[136:137]
	s_mov_b32 m0, s33
	s_nop 0
	global_load_lds_dwordx4 v[222:223], off
	s_mov_b32 m0, s34
	s_nop 0
	global_load_lds_dwordx4 v[224:225], off
	s_waitcnt vmcnt(8)
	s_waitcnt lgkmcnt(0)
	s_setprio 1
	s_barrier
; #define PG8_STAGE(bufoff, gbase, voff) do { _Pragma("unroll") for (int _i = 0; _i < 2; ++_i) \
;         __builtin_amdgcn_global_load_lds((const unsigned*)((const char*)(gbase) + (voff)[_i]), (PG8_LAS unsigned*)(lds + (bufoff) + ldsw + _i * 8192), 16, 0, 0); } while (0)
; #define PG8_LDA(dst, b, h) do { _Pragma("unroll") for (int m = 0; m < 4; ++m) _Pragma("unroll") for (int k = 0; k < 2; ++k) dst[m][k] = *(const PG8_LAS bf16x8*)(lds + PG8_SA(b, h) + aoff + m * 2048 + k * 1024); } while (0)
; #define PG8_LDB(dst, b, h) do { _Pragma("unroll") for (int n = 0; n < 2; ++n) _Pragma("unroll") for (int k = 0; k < 2; ++k) dst[n][k] = *(const PG8_LAS bf16x8*)(lds + PG8_SB(b, h) + boff + n * 2048 + k * 1024); } while (0)
; #define PG8_MMA(ai, bj, At, Bt) do { __builtin_amdgcn_s_setprio(1); _Pragma("unroll") for (int m = 0; m < 4; ++m) _Pragma("unroll") for (int n = 0; n < 2; ++n) _Pragma("unroll") for (int k = 0; k < 2; ++k) \
;         acc[ai][bj][m][n] = __builtin_amdgcn_mfma_f32_16x16x32_bf16(Bt[n][k], At[m][k], acc[ai][bj][m][n], 0, 0, 0); __builtin_amdgcn_s_setprio(0); } while (0)
; #define PG8_WAIT_V(n) asm volatile("s_waitcnt vmcnt(" #n ")" ::: "memory")
; #define PG8_WAIT_L(n) asm volatile("s_waitcnt lgkmcnt(" #n ")" ::: "memory")
; #define PG8_BAR __builtin_amdgcn_s_barrier()
; #define PG8_SCHED __builtin_amdgcn_sched_barrier(0)
; template <class Epi, class Sched, bool ALIGN_EPI = false, bool SP2 = false>
; __device__ __forceinline__ void gemm_phase(PG8_LAS unsigned char* lds, const Gemm g, const Sched& S, const Epi& E) {
;     ...
;             PG8_WAIT_V(8); PG8_WAIT_L(0); PG8_BAR; PG8_MMA(1, 0, At, B0); PG8_MMA(1, 1, At, B1); PG8_BAR; PG8_SCHED;
;             PG8_LDB(B0, 1, 0); PG8_LDB(B1, 1, 1); PG8_SCHED; PG8_LDA(At, 1, 0); PG8_STAGE(PG8_SA(0, 1), a2 + hstepA, voffA);
;             PG8_WAIT_V(8); PG8_WAIT_L(0); PG8_BAR; PG8_MMA(0, 0, At, B0); PG8_MMA(0, 1, At, B1); PG8_BAR; PG8_SCHED;
	v_mfma_f32_16x16x32_bf16 v[62:65], v[152:155], v[184:187], v[62:65]
	v_mfma_f32_16x16x32_bf16 v[58:61], v[160:163], v[184:187], v[58:61]
	v_mfma_f32_16x16x32_bf16 v[54:57], v[152:155], v[192:195], v[54:57]
	v_mfma_f32_16x16x32_bf16 v[50:53], v[160:163], v[192:195], v[50:53]
	v_mfma_f32_16x16x32_bf16 v[38:41], v[152:155], v[200:203], v[38:41]
	v_mfma_f32_16x16x32_bf16 v[34:37], v[160:163], v[200:203], v[34:37]
	v_mfma_f32_16x16x32_bf16 v[22:25], v[152:155], v[210:213], v[22:25]
	v_mfma_f32_16x16x32_bf16 v[18:21], v[160:163], v[210:213], v[18:21]
	v_mfma_f32_16x16x32_bf16 v[62:65], v[156:159], v[188:191], v[62:65]
	v_mfma_f32_16x16x32_bf16 v[58:61], v[164:167], v[188:191], v[58:61]
	v_mfma_f32_16x16x32_bf16 v[54:57], v[156:159], v[196:199], v[54:57]
	v_mfma_f32_16x16x32_bf16 v[50:53], v[164:167], v[196:199], v[50:53]
	v_mfma_f32_16x16x32_bf16 v[38:41], v[156:159], v[204:207], v[38:41]
	v_mfma_f32_16x16x32_bf16 v[34:37], v[164:167], v[204:207], v[34:37]
	v_mfma_f32_16x16x32_bf16 v[22:25], v[156:159], v[214:217], v[22:25]
	v_mfma_f32_16x16x32_bf16 v[18:21], v[164:167], v[214:217], v[18:21]
	v_mfma_f32_16x16x32_bf16 v[46:49], v[168:171], v[184:187], v[46:49]
	v_mfma_f32_16x16x32_bf16 v[42:45], v[176:179], v[184:187], v[42:45]
	v_mfma_f32_16x16x32_bf16 v[30:33], v[168:171], v[192:195], v[30:33]
	v_mfma_f32_16x16x32_bf16 v[26:29], v[176:179], v[192:195], v[26:29]
	v_mfma_f32_16x16x32_bf16 v[14:17], v[168:171], v[200:203], v[14:17]
	v_mfma_f32_16x16x32_bf16 v[10:13], v[176:179], v[200:203], v[10:13]
	v_mfma_f32_16x16x32_bf16 v[6:9], v[168:171], v[210:213], v[6:9]
	v_mfma_f32_16x16x32_bf16 v[2:5], v[176:179], v[210:213], v[2:5]
	v_mfma_f32_16x16x32_bf16 v[46:49], v[172:175], v[188:191], v[46:49]
	v_mfma_f32_16x16x32_bf16 v[42:45], v[180:183], v[188:191], v[42:45]
	v_mfma_f32_16x16x32_bf16 v[30:33], v[172:175], v[196:199], v[30:33]
	v_mfma_f32_16x16x32_bf16 v[26:29], v[180:183], v[196:199], v[26:29]
	v_mfma_f32_16x16x32_bf16 v[14:17], v[172:175], v[204:207], v[14:17]
	v_mfma_f32_16x16x32_bf16 v[10:13], v[180:183], v[204:207], v[10:13]
	v_mfma_f32_16x16x32_bf16 v[6:9], v[172:175], v[214:217], v[6:9]
	v_mfma_f32_16x16x32_bf16 v[2:5], v[180:183], v[214:217], v[2:5]
	s_barrier
	s_setprio 0
	s_add_i32 s54, 0, 0x18000
	v_add_u32_e32 v151, s54, v146
	s_add_i32 s55, 0, 0x1c000
	ds_read_b128 v[152:155], v151
	ds_read_b128 v[156:159], v151 offset:1024
	ds_read_b128 v[160:163], v151 offset:2048
	ds_read_b128 v[164:167], v151 offset:3072
	v_add_u32_e32 v151, s55, v146
	ds_read_b128 v[168:171], v151
	ds_read_b128 v[172:175], v151 offset:1024
	ds_read_b128 v[176:179], v151 offset:2048
	ds_read_b128 v[180:183], v151 offset:3072
	s_add_u32 s26, s26, 0x160000
	s_addc_u32 s27, s27, 0
	s_mov_b32 m0, s35
	v_lshl_add_u64 v[226:227], s[26:27], 0, v[136:137]
	ds_read_b128 v[184:187], v150 offset:32768
	ds_read_b128 v[188:191], v150 offset:33792
	ds_read_b128 v[192:195], v150 offset:34816
	ds_read_b128 v[196:199], v150 offset:35840
	ds_read_b128 v[200:203], v150 offset:36864
	ds_read_b128 v[204:207], v150 offset:37888
	ds_read_b128 v[210:213], v150 offset:38912
	ds_read_b128 v[214:217], v150 offset:39936
	global_load_lds_dwordx4 v[226:227], off
	v_lshl_add_u64 v[226:227], s[26:27], 0, v[132:133]
	s_mov_b32 m0, s36
	s_nop 0
	global_load_lds_dwordx4 v[226:227], off
	s_waitcnt vmcnt(8)
	s_waitcnt lgkmcnt(0)
	s_setprio 1
	s_barrier
	v_mfma_f32_16x16x32_bf16 v[126:129], v[152:155], v[184:187], v[126:129]
	v_mfma_f32_16x16x32_bf16 v[122:125], v[160:163], v[184:187], v[122:125]
	v_mfma_f32_16x16x32_bf16 v[118:121], v[152:155], v[192:195], v[118:121]
	v_mfma_f32_16x16x32_bf16 v[114:117], v[160:163], v[192:195], v[114:117]
	v_mfma_f32_16x16x32_bf16 v[102:105], v[152:155], v[200:203], v[102:105]
	v_mfma_f32_16x16x32_bf16 v[98:101], v[160:163], v[200:203], v[98:101]
	v_mfma_f32_16x16x32_bf16 v[86:89], v[152:155], v[210:213], v[86:89]
	v_mfma_f32_16x16x32_bf16 v[82:85], v[160:163], v[210:213], v[82:85]
	v_mfma_f32_16x16x32_bf16 v[126:129], v[156:159], v[188:191], v[126:129]
	v_mfma_f32_16x16x32_bf16 v[122:125], v[164:167], v[188:191], v[122:125]
	v_mfma_f32_16x16x32_bf16 v[118:121], v[156:159], v[196:199], v[118:121]
	v_mfma_f32_16x16x32_bf16 v[114:117], v[164:167], v[196:199], v[114:117]
	v_mfma_f32_16x16x32_bf16 v[102:105], v[156:159], v[204:207], v[102:105]
	v_mfma_f32_16x16x32_bf16 v[98:101], v[164:167], v[204:207], v[98:101]
	v_mfma_f32_16x16x32_bf16 v[86:89], v[156:159], v[214:217], v[86:89]
	v_mfma_f32_16x16x32_bf16 v[82:85], v[164:167], v[214:217], v[82:85]
	v_mfma_f32_16x16x32_bf16 v[110:113], v[168:171], v[184:187], v[110:113]
	v_mfma_f32_16x16x32_bf16 v[106:109], v[176:179], v[184:187], v[106:109]
	v_mfma_f32_16x16x32_bf16 v[94:97], v[168:171], v[192:195], v[94:97]
	v_mfma_f32_16x16x32_bf16 v[90:93], v[176:179], v[192:195], v[90:93]
	v_mfma_f32_16x16x32_bf16 v[78:81], v[168:171], v[200:203], v[78:81]
	v_mfma_f32_16x16x32_bf16 v[74:77], v[176:179], v[200:203], v[74:77]
	v_mfma_f32_16x16x32_bf16 v[70:73], v[168:171], v[210:213], v[70:73]
	v_mfma_f32_16x16x32_bf16 v[66:69], v[176:179], v[210:213], v[66:69]
	v_mfma_f32_16x16x32_bf16 v[110:113], v[172:175], v[188:191], v[110:113]
	v_mfma_f32_16x16x32_bf16 v[106:109], v[180:183], v[188:191], v[106:109]
	v_mfma_f32_16x16x32_bf16 v[94:97], v[172:175], v[196:199], v[94:97]
	v_mfma_f32_16x16x32_bf16 v[90:93], v[180:183], v[196:199], v[90:93]
	v_mfma_f32_16x16x32_bf16 v[78:81], v[172:175], v[204:207], v[78:81]
	v_mfma_f32_16x16x32_bf16 v[74:77], v[180:183], v[204:207], v[74:77]
	v_mfma_f32_16x16x32_bf16 v[70:73], v[172:175], v[214:217], v[70:73]
	v_mfma_f32_16x16x32_bf16 v[66:69], v[180:183], v[214:217], v[66:69]
	s_barrier
; #define PG8_STAGE(bufoff, gbase, voff) do { _Pragma("unroll") for (int _i = 0; _i < 2; ++_i) \
;         __builtin_amdgcn_global_load_lds((const unsigned*)((const char*)(gbase) + (voff)[_i]), (PG8_LAS unsigned*)(lds + (bufoff) + ldsw + _i * 8192), 16, 0, 0); } while (0)
; #define PG8_LDA(dst, b, h) do { _Pragma("unroll") for (int m = 0; m < 4; ++m) _Pragma("unroll") for (int k = 0; k < 2; ++k) dst[m][k] = *(const PG8_LAS bf16x8*)(lds + PG8_SA(b, h) + aoff + m * 2048 + k * 1024); } while (0)
; #define PG8_MMA(ai, bj, At, Bt) do { __builtin_amdgcn_s_setprio(1); _Pragma("unroll") for (int m = 0; m < 4; ++m) _Pragma("unroll") for (int n = 0; n < 2; ++n) _Pragma("unroll") for (int k = 0; k < 2; ++k) \
;         acc[ai][bj][m][n] = __builtin_amdgcn_mfma_f32_16x16x32_bf16(Bt[n][k], At[m][k], acc[ai][bj][m][n], 0, 0, 0); __builtin_amdgcn_s_setprio(0); } while (0)
; #define PG8_WAIT_V(n) asm volatile("s_waitcnt vmcnt(" #n ")" ::: "memory")
; #define PG8_WAIT_L(n) asm volatile("s_waitcnt lgkmcnt(" #n ")" ::: "memory")
; #define PG8_BAR __builtin_amdgcn_s_barrier()
; #define PG8_SCHED __builtin_amdgcn_sched_barrier(0)
; template <class Epi, class Sched, bool ALIGN_EPI = false, bool SP2 = false>
; __device__ __forceinline__ void gemm_phase(PG8_LAS unsigned char* lds, const Gemm g, const Sched& S, const Epi& E) {
;     ...
;             PG8_LDA(At, 1, 1); PG8_STAGE(PG8_SB(1, 0), b3, voffB); PG8_STAGE(PG8_SB(1, 1), b3 + hstepB, voffB); PG8_STAGE(PG8_SA(1, 0), a3, voffA);
;             PG8_WAIT_V(8); PG8_WAIT_L(0); PG8_BAR; PG8_MMA(1, 0, At, B0); PG8_MMA(1, 1, At, B1); PG8_BAR; PG8_SCHED;
	s_setprio 0
	s_add_i32 s26, s54, s29
	v_lshl_add_u64 v[218:219], v[218:219], 0, s[8:9]
	s_mov_b32 m0, s26
	ds_read_b128 v[184:187], v150 offset:49152
	ds_read_b128 v[188:191], v150 offset:50176
	ds_read_b128 v[192:195], v150 offset:51200
	ds_read_b128 v[196:199], v150 offset:52224
	ds_read_b128 v[200:203], v150 offset:53248
	ds_read_b128 v[204:207], v150 offset:54272
	ds_read_b128 v[210:213], v150 offset:55296
	ds_read_b128 v[214:217], v150 offset:56320
	global_load_lds_dwordx4 v[218:219], off
	s_add_i32 m0, s26, 0x2000
	s_add_u32 s24, s24, 0x160080
	v_lshl_add_u64 v[218:219], v[220:221], 0, s[8:9]
	s_addc_u32 s25, s25, 0
	s_add_i32 s26, s55, s29
	global_load_lds_dwordx4 v[218:219], off
	v_lshl_add_u64 v[218:219], s[24:25], 0, v[134:135]
	s_mov_b32 m0, s26
	s_nop 0
	global_load_lds_dwordx4 v[218:219], off
	v_lshl_add_u64 v[218:219], s[24:25], 0, v[130:131]
	s_add_i32 m0, s26, 0x2000
	s_nop 0
	global_load_lds_dwordx4 v[218:219], off
	v_lshl_add_u64 v[218:219], v[222:223], 0, s[8:9]
	s_mov_b32 m0, s38
	s_nop 0
	global_load_lds_dwordx4 v[218:219], off
	v_lshl_add_u64 v[218:219], v[224:225], 0, s[8:9]
	s_mov_b32 m0, s39
	s_nop 0
	global_load_lds_dwordx4 v[218:219], off
	s_waitcnt vmcnt(8)
	s_waitcnt lgkmcnt(0)
	s_setprio 1
	s_barrier
	v_mfma_f32_16x16x32_bf16 v[62:65], v[152:155], v[184:187], v[62:65]
	v_mfma_f32_16x16x32_bf16 v[58:61], v[160:163], v[184:187], v[58:61]
	v_mfma_f32_16x16x32_bf16 v[54:57], v[152:155], v[192:195], v[54:57]
	v_mfma_f32_16x16x32_bf16 v[50:53], v[160:163], v[192:195], v[50:53]
	v_mfma_f32_16x16x32_bf16 v[38:41], v[152:155], v[200:203], v[38:41]
	v_mfma_f32_16x16x32_bf16 v[34:37], v[160:163], v[200:203], v[34:37]
	v_mfma_f32_16x16x32_bf16 v[22:25], v[152:155], v[210:213], v[22:25]
	v_mfma_f32_16x16x32_bf16 v[18:21], v[160:163], v[210:213], v[18:21]
	v_mfma_f32_16x16x32_bf16 v[62:65], v[156:159], v[188:191], v[62:65]
	v_mfma_f32_16x16x32_bf16 v[58:61], v[164:167], v[188:191], v[58:61]
	v_mfma_f32_16x16x32_bf16 v[54:57], v[156:159], v[196:199], v[54:57]
	v_mfma_f32_16x16x32_bf16 v[50:53], v[164:167], v[196:199], v[50:53]
	v_mfma_f32_16x16x32_bf16 v[38:41], v[156:159], v[204:207], v[38:41]
	v_mfma_f32_16x16x32_bf16 v[34:37], v[164:167], v[204:207], v[34:37]
	v_mfma_f32_16x16x32_bf16 v[22:25], v[156:159], v[214:217], v[22:25]
	v_mfma_f32_16x16x32_bf16 v[18:21], v[164:167], v[214:217], v[18:21]
	v_mfma_f32_16x16x32_bf16 v[46:49], v[168:171], v[184:187], v[46:49]
	v_mfma_f32_16x16x32_bf16 v[42:45], v[176:179], v[184:187], v[42:45]
	v_mfma_f32_16x16x32_bf16 v[30:33], v[168:171], v[192:195], v[30:33]
	v_mfma_f32_16x16x32_bf16 v[26:29], v[176:179], v[192:195], v[26:29]
	v_mfma_f32_16x16x32_bf16 v[14:17], v[168:171], v[200:203], v[14:17]
	v_mfma_f32_16x16x32_bf16 v[10:13], v[176:179], v[200:203], v[10:13]
	v_mfma_f32_16x16x32_bf16 v[6:9], v[168:171], v[210:213], v[6:9]
	v_mfma_f32_16x16x32_bf16 v[2:5], v[176:179], v[210:213], v[2:5]
	v_mfma_f32_16x16x32_bf16 v[46:49], v[172:175], v[188:191], v[46:49]
	v_mfma_f32_16x16x32_bf16 v[42:45], v[180:183], v[188:191], v[42:45]
	v_mfma_f32_16x16x32_bf16 v[30:33], v[172:175], v[196:199], v[30:33]
	v_mfma_f32_16x16x32_bf16 v[26:29], v[180:183], v[196:199], v[26:29]
	v_mfma_f32_16x16x32_bf16 v[14:17], v[172:175], v[204:207], v[14:17]
	v_mfma_f32_16x16x32_bf16 v[10:13], v[180:183], v[204:207], v[10:13]
	v_mfma_f32_16x16x32_bf16 v[6:9], v[172:175], v[214:217], v[6:9]
	v_mfma_f32_16x16x32_bf16 v[2:5], v[180:183], v[214:217], v[2:5]
	s_barrier
	s_setprio 0
	s_add_i32 s53, s53, 2
	s_add_u32 s22, s22, 0x100
	s_addc_u32 s23, s23, 0
	s_add_u32 s51, s51, 0x100
	s_addc_u32 s52, s52, 0
	s_cmpk_gt_u32 s53, 0x55
	s_cbranch_scc0 .LBB0_2487
	s_and_b64 vcc, exec, s[10:11]
	s_cbranch_vccz .LBB0_2490
	s_barrier

; #define PG8_STAGE(bufoff, gbase, voff) do { _Pragma("unroll") for (int _i = 0; _i < 2; ++_i) \
;         __builtin_amdgcn_global_load_lds((const unsigned*)((const char*)(gbase) + (voff)[_i]), (PG8_LAS unsigned*)(lds + (bufoff) + ldsw + _i * 8192), 16, 0, 0); } while (0)
; #define PG8_LDA(dst, b, h) do { _Pragma("unroll") for (int m = 0; m < 4; ++m) _Pragma("unroll") for (int k = 0; k < 2; ++k) dst[m][k] = *(const PG8_LAS bf16x8*)(lds + PG8_SA(b, h) + aoff + m * 2048 + k * 1024); } while (0)
; #define PG8_LDB(dst, b, h) do { _Pragma("unroll") for (int n = 0; n < 2; ++n) _Pragma("unroll") for (int k = 0; k < 2; ++k) dst[n][k] = *(const PG8_LAS bf16x8*)(lds + PG8_SB(b, h) + boff + n * 2048 + k * 1024); } while (0)
; #define PG8_MMA(ai, bj, At, Bt) do { __builtin_amdgcn_s_setprio(1); _Pragma("unroll") for (int m = 0; m < 4; ++m) _Pragma("unroll") for (int n = 0; n < 2; ++n) _Pragma("unroll") for (int k = 0; k < 2; ++k) \
;         acc[ai][bj][m][n] = __builtin_amdgcn_mfma_f32_16x16x32_bf16(Bt[n][k], At[m][k], acc[ai][bj][m][n], 0, 0, 0); __builtin_amdgcn_s_setprio(0); } while (0)
; #define PG8_WAIT_V(n) asm volatile("s_waitcnt vmcnt(" #n ")" ::: "memory")
; #define PG8_WAIT_L(n) asm volatile("s_waitcnt lgkmcnt(" #n ")" ::: "memory")
; #define PG8_BAR __builtin_amdgcn_s_barrier()
; #define PG8_SCHED __builtin_amdgcn_sched_barrier(0)
; template <class Epi, class Sched, bool ALIGN_EPI = false, bool SP2 = false>
; __device__ __forceinline__ void gemm_phase(PG8_LAS unsigned char* lds, const Gemm g, const Sched& S, const Epi& E) {
;     ...
;             PG8_LDB(B0, 0, 0); PG8_LDB(B1, 0, 1); PG8_SCHED; PG8_LDA(At, 0, 0); PG8_STAGE(PG8_SA(1, 1), a1 + hstepA, voffA);
;             PG8_WAIT_V(8); PG8_WAIT_L(0); PG8_BAR; PG8_MMA(0, 0, At, B0); PG8_MMA(0, 1, At, B1); PG8_BAR; PG8_SCHED;
;             PG8_LDA(At, 0, 1); PG8_STAGE(PG8_SB(0, 0), b2, voffB); PG8_STAGE(PG8_SB(0, 1), b2 + hstepB, voffB); PG8_STAGE(PG8_SA(0, 0), a2, voffA);
;             PG8_WAIT_V(8); PG8_WAIT_L(0); PG8_BAR; PG8_MMA(1, 0, At, B0); PG8_MMA(1, 1, At, B1); PG8_BAR; PG8_SCHED;
.LBB0_2615:
	ds_read_b128 v[130:133], v166
	ds_read_b128 v[134:137], v166 offset:1024
	ds_read_b128 v[138:141], v166 offset:2048
	ds_read_b128 v[142:145], v166 offset:3072
	ds_read_b128 v[170:173], v167
	ds_read_b128 v[174:177], v167 offset:1024
	ds_read_b128 v[178:181], v167 offset:2048
	ds_read_b128 v[182:185], v167 offset:3072
	s_add_u32 s24, s22, 0xfff80080
	s_addc_u32 s25, s23, -1
	s_cmp_eq_u32 s48, 28
	s_cselect_b32 s27, s15, s25
	s_cselect_b32 s26, s44, s24
	s_cselect_b32 s25, s13, s47
	s_cselect_b32 s24, s45, s46
	v_lshl_add_u64 v[162:163], s[22:23], 0, v[154:155]
	s_add_i32 m0, s21, 0xc000
	ds_read_b128 v[186:189], v168
	ds_read_b128 v[190:193], v168 offset:1024
	ds_read_b128 v[194:197], v168 offset:2048
	ds_read_b128 v[198:201], v168 offset:3072
	ds_read_b128 v[202:205], v168 offset:4096
	ds_read_b128 v[210:213], v168 offset:5120
	ds_read_b128 v[214:217], v168 offset:6144
	ds_read_b128 v[218:221], v168 offset:7168
	global_load_lds_dwordx4 v[162:163], off
	v_lshl_add_u64 v[162:163], s[22:23], 0, v[156:157]
	s_add_i32 m0, s21, 0xe000
	s_nop 0
	global_load_lds_dwordx4 v[162:163], off
	s_waitcnt vmcnt(8)
	s_waitcnt lgkmcnt(0)
	s_setprio 1
	s_barrier
	v_mfma_f32_16x16x32_bf16 v[126:129], v[130:133], v[186:189], v[126:129]
	v_mfma_f32_16x16x32_bf16 v[122:125], v[138:141], v[186:189], v[122:125]
	v_mfma_f32_16x16x32_bf16 v[118:121], v[130:133], v[194:197], v[118:121]
	v_mfma_f32_16x16x32_bf16 v[114:117], v[138:141], v[194:197], v[114:117]
	v_mfma_f32_16x16x32_bf16 v[110:113], v[130:133], v[202:205], v[110:113]
	v_mfma_f32_16x16x32_bf16 v[102:105], v[138:141], v[202:205], v[102:105]
	v_mfma_f32_16x16x32_bf16 v[94:97], v[130:133], v[214:217], v[94:97]
	v_mfma_f32_16x16x32_bf16 v[86:89], v[138:141], v[214:217], v[86:89]
	v_mfma_f32_16x16x32_bf16 v[126:129], v[134:137], v[190:193], v[126:129]
	v_mfma_f32_16x16x32_bf16 v[122:125], v[142:145], v[190:193], v[122:125]
	v_mfma_f32_16x16x32_bf16 v[118:121], v[134:137], v[198:201], v[118:121]
	v_mfma_f32_16x16x32_bf16 v[114:117], v[142:145], v[198:201], v[114:117]
	v_mfma_f32_16x16x32_bf16 v[110:113], v[134:137], v[210:213], v[110:113]
	v_mfma_f32_16x16x32_bf16 v[102:105], v[142:145], v[210:213], v[102:105]
	v_mfma_f32_16x16x32_bf16 v[94:97], v[134:137], v[218:221], v[94:97]
	v_mfma_f32_16x16x32_bf16 v[86:89], v[142:145], v[218:221], v[86:89]
	v_mfma_f32_16x16x32_bf16 v[106:109], v[170:173], v[186:189], v[106:109]
	v_mfma_f32_16x16x32_bf16 v[98:101], v[178:181], v[186:189], v[98:101]
	v_mfma_f32_16x16x32_bf16 v[90:93], v[170:173], v[194:197], v[90:93]
	v_mfma_f32_16x16x32_bf16 v[82:85], v[178:181], v[194:197], v[82:85]
	v_mfma_f32_16x16x32_bf16 v[78:81], v[170:173], v[202:205], v[78:81]
	v_mfma_f32_16x16x32_bf16 v[74:77], v[178:181], v[202:205], v[74:77]
	v_mfma_f32_16x16x32_bf16 v[70:73], v[170:173], v[214:217], v[70:73]
	v_mfma_f32_16x16x32_bf16 v[66:69], v[178:181], v[214:217], v[66:69]
	v_mfma_f32_16x16x32_bf16 v[106:109], v[174:177], v[190:193], v[106:109]
	v_mfma_f32_16x16x32_bf16 v[98:101], v[182:185], v[190:193], v[98:101]
	v_mfma_f32_16x16x32_bf16 v[90:93], v[174:177], v[198:201], v[90:93]
	v_mfma_f32_16x16x32_bf16 v[82:85], v[182:185], v[198:201], v[82:85]
	v_mfma_f32_16x16x32_bf16 v[78:81], v[174:177], v[210:213], v[78:81]
	v_mfma_f32_16x16x32_bf16 v[74:77], v[182:185], v[210:213], v[74:77]
	v_mfma_f32_16x16x32_bf16 v[70:73], v[174:177], v[218:221], v[70:73]
	v_mfma_f32_16x16x32_bf16 v[66:69], v[182:185], v[218:221], v[66:69]
	s_barrier
	s_setprio 0
	s_add_i32 s49, s40, s29
	v_lshl_add_u64 v[162:163], s[24:25], 0, v[150:151]
	s_mov_b32 m0, s49
	ds_read_b128 v[186:189], v168 offset:16384
	ds_read_b128 v[190:193], v168 offset:17408
	ds_read_b128 v[194:197], v168 offset:18432
	ds_read_b128 v[198:201], v168 offset:19456
	ds_read_b128 v[202:205], v168 offset:20480
	ds_read_b128 v[210:213], v168 offset:21504
	ds_read_b128 v[214:217], v168 offset:22528
	ds_read_b128 v[218:221], v168 offset:23552
	global_load_lds_dwordx4 v[162:163], off
	s_add_i32 m0, s49, 0x2000
	s_add_u32 s50, s24, 0x80000
	v_lshl_add_u64 v[206:207], s[24:25], 0, v[146:147]
	s_addc_u32 s51, s25, 0
	s_add_i32 s49, s41, s29
	global_load_lds_dwordx4 v[206:207], off
	v_lshl_add_u64 v[222:223], s[50:51], 0, v[150:151]
	s_mov_b32 m0, s49
	v_lshl_add_u64 v[224:225], s[26:27], 0, v[148:149]
	global_load_lds_dwordx4 v[222:223], off
	v_lshl_add_u64 v[222:223], s[50:51], 0, v[146:147]
	s_add_i32 m0, s49, 0x2000
	s_nop 0
	global_load_lds_dwordx4 v[222:223], off
	v_lshl_add_u64 v[222:223], s[26:27], 0, v[152:153]
	s_mov_b32 m0, s21
	s_nop 0
	global_load_lds_dwordx4 v[222:223], off
	s_mov_b32 m0, s33
	s_nop 0
	global_load_lds_dwordx4 v[224:225], off
	s_waitcnt vmcnt(8)
	s_waitcnt lgkmcnt(0)
	s_setprio 1
	s_barrier
; #define PG8_STAGE(bufoff, gbase, voff) do { _Pragma("unroll") for (int _i = 0; _i < 2; ++_i) \
;         __builtin_amdgcn_global_load_lds((const unsigned*)((const char*)(gbase) + (voff)[_i]), (PG8_LAS unsigned*)(lds + (bufoff) + ldsw + _i * 8192), 16, 0, 0); } while (0)
; #define PG8_LDA(dst, b, h) do { _Pragma("unroll") for (int m = 0; m < 4; ++m) _Pragma("unroll") for (int k = 0; k < 2; ++k) dst[m][k] = *(const PG8_LAS bf16x8*)(lds + PG8_SA(b, h) + aoff + m * 2048 + k * 1024); } while (0)
; #define PG8_LDB(dst, b, h) do { _Pragma("unroll") for (int n = 0; n < 2; ++n) _Pragma("unroll") for (int k = 0; k < 2; ++k) dst[n][k] = *(const PG8_LAS bf16x8*)(lds + PG8_SB(b, h) + boff + n * 2048 + k * 1024); } while (0)
; #define PG8_MMA(ai, bj, At, Bt) do { __builtin_amdgcn_s_setprio(1); _Pragma("unroll") for (int m = 0; m < 4; ++m) _Pragma("unroll") for (int n = 0; n < 2; ++n) _Pragma("unroll") for (int k = 0; k < 2; ++k) \
;         acc[ai][bj][m][n] = __builtin_amdgcn_mfma_f32_16x16x32_bf16(Bt[n][k], At[m][k], acc[ai][bj][m][n], 0, 0, 0); __builtin_amdgcn_s_setprio(0); } while (0)
; #define PG8_WAIT_V(n) asm volatile("s_waitcnt vmcnt(" #n ")" ::: "memory")
; #define PG8_WAIT_L(n) asm volatile("s_waitcnt lgkmcnt(" #n ")" ::: "memory")
; #define PG8_BAR __builtin_amdgcn_s_barrier()
; #define PG8_SCHED __builtin_amdgcn_sched_barrier(0)
; template <class Epi, class Sched, bool ALIGN_EPI = false, bool SP2 = false>
; __device__ __forceinline__ void gemm_phase(PG8_LAS unsigned char* lds, const Gemm g, const Sched& S, const Epi& E) {
;     ...
;             PG8_WAIT_V(8); PG8_WAIT_L(0); PG8_BAR; PG8_MMA(1, 0, At, B0); PG8_MMA(1, 1, At, B1); PG8_BAR; PG8_SCHED;
;             PG8_LDB(B0, 1, 0); PG8_LDB(B1, 1, 1); PG8_SCHED; PG8_LDA(At, 1, 0); PG8_STAGE(PG8_SA(0, 1), a2 + hstepA, voffA);
;             PG8_WAIT_V(8); PG8_WAIT_L(0); PG8_BAR; PG8_MMA(0, 0, At, B0); PG8_MMA(0, 1, At, B1); PG8_BAR; PG8_SCHED;
	v_mfma_f32_16x16x32_bf16 v[62:65], v[130:133], v[186:189], v[62:65]
	v_mfma_f32_16x16x32_bf16 v[58:61], v[138:141], v[186:189], v[58:61]
	v_mfma_f32_16x16x32_bf16 v[54:57], v[130:133], v[194:197], v[54:57]
	v_mfma_f32_16x16x32_bf16 v[46:49], v[138:141], v[194:197], v[46:49]
	v_mfma_f32_16x16x32_bf16 v[38:41], v[130:133], v[202:205], v[38:41]
	v_mfma_f32_16x16x32_bf16 v[30:33], v[138:141], v[202:205], v[30:33]
	v_mfma_f32_16x16x32_bf16 v[22:25], v[130:133], v[214:217], v[22:25]
	v_mfma_f32_16x16x32_bf16 v[14:17], v[138:141], v[214:217], v[14:17]
	v_mfma_f32_16x16x32_bf16 v[62:65], v[134:137], v[190:193], v[62:65]
	v_mfma_f32_16x16x32_bf16 v[58:61], v[142:145], v[190:193], v[58:61]
	v_mfma_f32_16x16x32_bf16 v[54:57], v[134:137], v[198:201], v[54:57]
	v_mfma_f32_16x16x32_bf16 v[46:49], v[142:145], v[198:201], v[46:49]
	v_mfma_f32_16x16x32_bf16 v[38:41], v[134:137], v[210:213], v[38:41]
	v_mfma_f32_16x16x32_bf16 v[30:33], v[142:145], v[210:213], v[30:33]
	v_mfma_f32_16x16x32_bf16 v[22:25], v[134:137], v[218:221], v[22:25]
	v_mfma_f32_16x16x32_bf16 v[14:17], v[142:145], v[218:221], v[14:17]
	v_mfma_f32_16x16x32_bf16 v[50:53], v[170:173], v[186:189], v[50:53]
	v_mfma_f32_16x16x32_bf16 v[42:45], v[178:181], v[186:189], v[42:45]
	v_mfma_f32_16x16x32_bf16 v[34:37], v[170:173], v[194:197], v[34:37]
	v_mfma_f32_16x16x32_bf16 v[26:29], v[178:181], v[194:197], v[26:29]
	v_mfma_f32_16x16x32_bf16 v[18:21], v[170:173], v[202:205], v[18:21]
	v_mfma_f32_16x16x32_bf16 v[10:13], v[178:181], v[202:205], v[10:13]
	v_mfma_f32_16x16x32_bf16 v[6:9], v[170:173], v[214:217], v[6:9]
	v_mfma_f32_16x16x32_bf16 v[2:5], v[178:181], v[214:217], v[2:5]
	v_mfma_f32_16x16x32_bf16 v[50:53], v[174:177], v[190:193], v[50:53]
	v_mfma_f32_16x16x32_bf16 v[42:45], v[182:185], v[190:193], v[42:45]
	v_mfma_f32_16x16x32_bf16 v[34:37], v[174:177], v[198:201], v[34:37]
	v_mfma_f32_16x16x32_bf16 v[26:29], v[182:185], v[198:201], v[26:29]
	v_mfma_f32_16x16x32_bf16 v[18:21], v[174:177], v[210:213], v[18:21]
	v_mfma_f32_16x16x32_bf16 v[10:13], v[182:185], v[210:213], v[10:13]
	v_mfma_f32_16x16x32_bf16 v[6:9], v[174:177], v[218:221], v[6:9]
	v_mfma_f32_16x16x32_bf16 v[2:5], v[182:185], v[218:221], v[2:5]
	s_barrier
	s_setprio 0
	s_add_i32 s49, 0, 0x18000
	s_add_i32 s50, 0, 0x1c000
	v_add_u32_e32 v142, s49, v164
	v_add_u32_e32 v169, s50, v164
	ds_read_b128 v[130:133], v142
	ds_read_b128 v[134:137], v142 offset:1024
	ds_read_b128 v[138:141], v142 offset:2048
	ds_read_b128 v[142:145], v142 offset:3072
	ds_read_b128 v[170:173], v169
	ds_read_b128 v[174:177], v169 offset:1024
	ds_read_b128 v[178:181], v169 offset:2048
	ds_read_b128 v[182:185], v169 offset:3072
	s_add_u32 s26, s26, 0x80000
	s_addc_u32 s27, s27, 0
	s_mov_b32 m0, s34
	v_lshl_add_u64 v[226:227], s[26:27], 0, v[152:153]
	ds_read_b128 v[186:189], v168 offset:32768
	ds_read_b128 v[190:193], v168 offset:33792
	ds_read_b128 v[194:197], v168 offset:34816
	ds_read_b128 v[198:201], v168 offset:35840
	ds_read_b128 v[202:205], v168 offset:36864
	ds_read_b128 v[210:213], v168 offset:37888
	ds_read_b128 v[214:217], v168 offset:38912
	ds_read_b128 v[218:221], v168 offset:39936
	global_load_lds_dwordx4 v[226:227], off
	v_lshl_add_u64 v[226:227], s[26:27], 0, v[148:149]
	s_mov_b32 m0, s35
	s_nop 0
	global_load_lds_dwordx4 v[226:227], off
	s_waitcnt vmcnt(8)
	s_waitcnt lgkmcnt(0)
	s_setprio 1
	s_barrier
	v_mfma_f32_16x16x32_bf16 v[126:129], v[130:133], v[186:189], v[126:129]
	v_mfma_f32_16x16x32_bf16 v[122:125], v[138:141], v[186:189], v[122:125]
	v_mfma_f32_16x16x32_bf16 v[118:121], v[130:133], v[194:197], v[118:121]
	v_mfma_f32_16x16x32_bf16 v[114:117], v[138:141], v[194:197], v[114:117]
	v_mfma_f32_16x16x32_bf16 v[110:113], v[130:133], v[202:205], v[110:113]
	v_mfma_f32_16x16x32_bf16 v[102:105], v[138:141], v[202:205], v[102:105]
	v_mfma_f32_16x16x32_bf16 v[94:97], v[130:133], v[214:217], v[94:97]
	v_mfma_f32_16x16x32_bf16 v[86:89], v[138:141], v[214:217], v[86:89]
	v_mfma_f32_16x16x32_bf16 v[126:129], v[134:137], v[190:193], v[126:129]
	v_mfma_f32_16x16x32_bf16 v[122:125], v[142:145], v[190:193], v[122:125]
	v_mfma_f32_16x16x32_bf16 v[118:121], v[134:137], v[198:201], v[118:121]
	v_mfma_f32_16x16x32_bf16 v[114:117], v[142:145], v[198:201], v[114:117]
	v_mfma_f32_16x16x32_bf16 v[110:113], v[134:137], v[210:213], v[110:113]
	v_mfma_f32_16x16x32_bf16 v[102:105], v[142:145], v[210:213], v[102:105]
	v_mfma_f32_16x16x32_bf16 v[94:97], v[134:137], v[218:221], v[94:97]
	v_mfma_f32_16x16x32_bf16 v[86:89], v[142:145], v[218:221], v[86:89]
	v_mfma_f32_16x16x32_bf16 v[106:109], v[170:173], v[186:189], v[106:109]
	v_mfma_f32_16x16x32_bf16 v[98:101], v[178:181], v[186:189], v[98:101]
	v_mfma_f32_16x16x32_bf16 v[90:93], v[170:173], v[194:197], v[90:93]
	v_mfma_f32_16x16x32_bf16 v[82:85], v[178:181], v[194:197], v[82:85]
	v_mfma_f32_16x16x32_bf16 v[78:81], v[170:173], v[202:205], v[78:81]
	v_mfma_f32_16x16x32_bf16 v[74:77], v[178:181], v[202:205], v[74:77]
	v_mfma_f32_16x16x32_bf16 v[70:73], v[170:173], v[214:217], v[70:73]
	v_mfma_f32_16x16x32_bf16 v[66:69], v[178:181], v[214:217], v[66:69]
	v_mfma_f32_16x16x32_bf16 v[106:109], v[174:177], v[190:193], v[106:109]
	v_mfma_f32_16x16x32_bf16 v[98:101], v[182:185], v[190:193], v[98:101]
	v_mfma_f32_16x16x32_bf16 v[90:93], v[174:177], v[198:201], v[90:93]
	v_mfma_f32_16x16x32_bf16 v[82:85], v[182:185], v[198:201], v[82:85]
	v_mfma_f32_16x16x32_bf16 v[78:81], v[174:177], v[210:213], v[78:81]
	v_mfma_f32_16x16x32_bf16 v[74:77], v[182:185], v[210:213], v[74:77]
	v_mfma_f32_16x16x32_bf16 v[70:73], v[174:177], v[218:221], v[70:73]
	v_mfma_f32_16x16x32_bf16 v[66:69], v[182:185], v[218:221], v[66:69]
	s_barrier
; #define PG8_STAGE(bufoff, gbase, voff) do { _Pragma("unroll") for (int _i = 0; _i < 2; ++_i) \
;         __builtin_amdgcn_global_load_lds((const unsigned*)((const char*)(gbase) + (voff)[_i]), (PG8_LAS unsigned*)(lds + (bufoff) + ldsw + _i * 8192), 16, 0, 0); } while (0)
; #define PG8_LDA(dst, b, h) do { _Pragma("unroll") for (int m = 0; m < 4; ++m) _Pragma("unroll") for (int k = 0; k < 2; ++k) dst[m][k] = *(const PG8_LAS bf16x8*)(lds + PG8_SA(b, h) + aoff + m * 2048 + k * 1024); } while (0)
; #define PG8_MMA(ai, bj, At, Bt) do { __builtin_amdgcn_s_setprio(1); _Pragma("unroll") for (int m = 0; m < 4; ++m) _Pragma("unroll") for (int n = 0; n < 2; ++n) _Pragma("unroll") for (int k = 0; k < 2; ++k) \
;         acc[ai][bj][m][n] = __builtin_amdgcn_mfma_f32_16x16x32_bf16(Bt[n][k], At[m][k], acc[ai][bj][m][n], 0, 0, 0); __builtin_amdgcn_s_setprio(0); } while (0)
; #define PG8_WAIT_V(n) asm volatile("s_waitcnt vmcnt(" #n ")" ::: "memory")
; #define PG8_WAIT_L(n) asm volatile("s_waitcnt lgkmcnt(" #n ")" ::: "memory")
; #define PG8_BAR __builtin_amdgcn_s_barrier()
; #define PG8_SCHED __builtin_amdgcn_sched_barrier(0)
; template <class Epi, class Sched, bool ALIGN_EPI = false, bool SP2 = false>
; __device__ __forceinline__ void gemm_phase(PG8_LAS unsigned char* lds, const Gemm g, const Sched& S, const Epi& E) {
;     ...
;             PG8_LDA(At, 1, 1); PG8_STAGE(PG8_SB(1, 0), b3, voffB); PG8_STAGE(PG8_SB(1, 1), b3 + hstepB, voffB); PG8_STAGE(PG8_SA(1, 0), a3, voffA);
;             PG8_WAIT_V(8); PG8_WAIT_L(0); PG8_BAR; PG8_MMA(1, 0, At, B0); PG8_MMA(1, 1, At, B1); PG8_BAR; PG8_SCHED;
	s_setprio 0
	s_add_i32 s26, s49, s29
	v_lshl_add_u64 v[162:163], v[162:163], 0, s[8:9]
	s_mov_b32 m0, s26
	ds_read_b128 v[186:189], v168 offset:49152
	ds_read_b128 v[190:193], v168 offset:50176
	ds_read_b128 v[194:197], v168 offset:51200
	ds_read_b128 v[198:201], v168 offset:52224
	ds_read_b128 v[202:205], v168 offset:53248
	ds_read_b128 v[210:213], v168 offset:54272
	ds_read_b128 v[214:217], v168 offset:55296
	ds_read_b128 v[218:221], v168 offset:56320
	global_load_lds_dwordx4 v[162:163], off
	s_add_i32 m0, s26, 0x2000
	s_add_u32 s24, s24, 0x80080
	v_lshl_add_u64 v[162:163], v[206:207], 0, s[8:9]
	s_addc_u32 s25, s25, 0
	s_add_i32 s26, s50, s29
	global_load_lds_dwordx4 v[162:163], off
	v_lshl_add_u64 v[162:163], s[24:25], 0, v[150:151]
	s_mov_b32 m0, s26
	s_nop 0
	global_load_lds_dwordx4 v[162:163], off
	v_lshl_add_u64 v[162:163], s[24:25], 0, v[146:147]
	s_add_i32 m0, s26, 0x2000
	s_nop 0
	global_load_lds_dwordx4 v[162:163], off
	v_lshl_add_u64 v[162:163], v[222:223], 0, s[8:9]
	s_mov_b32 m0, s37
	s_nop 0
	global_load_lds_dwordx4 v[162:163], off
	v_lshl_add_u64 v[162:163], v[224:225], 0, s[8:9]
	s_mov_b32 m0, s38
	s_nop 0
	global_load_lds_dwordx4 v[162:163], off
	s_waitcnt vmcnt(8)
	s_waitcnt lgkmcnt(0)
	s_setprio 1
	s_barrier
	v_mfma_f32_16x16x32_bf16 v[62:65], v[130:133], v[186:189], v[62:65]
	v_mfma_f32_16x16x32_bf16 v[58:61], v[138:141], v[186:189], v[58:61]
	v_mfma_f32_16x16x32_bf16 v[54:57], v[130:133], v[194:197], v[54:57]
	v_mfma_f32_16x16x32_bf16 v[46:49], v[138:141], v[194:197], v[46:49]
	v_mfma_f32_16x16x32_bf16 v[38:41], v[130:133], v[202:205], v[38:41]
	v_mfma_f32_16x16x32_bf16 v[30:33], v[138:141], v[202:205], v[30:33]
	v_mfma_f32_16x16x32_bf16 v[22:25], v[130:133], v[214:217], v[22:25]
	v_mfma_f32_16x16x32_bf16 v[14:17], v[138:141], v[214:217], v[14:17]
	v_mfma_f32_16x16x32_bf16 v[62:65], v[134:137], v[190:193], v[62:65]
	v_mfma_f32_16x16x32_bf16 v[58:61], v[142:145], v[190:193], v[58:61]
	v_mfma_f32_16x16x32_bf16 v[54:57], v[134:137], v[198:201], v[54:57]
	v_mfma_f32_16x16x32_bf16 v[46:49], v[142:145], v[198:201], v[46:49]
	v_mfma_f32_16x16x32_bf16 v[38:41], v[134:137], v[210:213], v[38:41]
	v_mfma_f32_16x16x32_bf16 v[30:33], v[142:145], v[210:213], v[30:33]
	v_mfma_f32_16x16x32_bf16 v[22:25], v[134:137], v[218:221], v[22:25]
	v_mfma_f32_16x16x32_bf16 v[14:17], v[142:145], v[218:221], v[14:17]
	v_mfma_f32_16x16x32_bf16 v[50:53], v[170:173], v[186:189], v[50:53]
	v_mfma_f32_16x16x32_bf16 v[42:45], v[178:181], v[186:189], v[42:45]
	v_mfma_f32_16x16x32_bf16 v[34:37], v[170:173], v[194:197], v[34:37]
	v_mfma_f32_16x16x32_bf16 v[26:29], v[178:181], v[194:197], v[26:29]
	v_mfma_f32_16x16x32_bf16 v[18:21], v[170:173], v[202:205], v[18:21]
	v_mfma_f32_16x16x32_bf16 v[10:13], v[178:181], v[202:205], v[10:13]
	v_mfma_f32_16x16x32_bf16 v[6:9], v[170:173], v[214:217], v[6:9]
	v_mfma_f32_16x16x32_bf16 v[2:5], v[178:181], v[214:217], v[2:5]
	v_mfma_f32_16x16x32_bf16 v[50:53], v[174:177], v[190:193], v[50:53]
	v_mfma_f32_16x16x32_bf16 v[42:45], v[182:185], v[190:193], v[42:45]
	v_mfma_f32_16x16x32_bf16 v[34:37], v[174:177], v[198:201], v[34:37]
	v_mfma_f32_16x16x32_bf16 v[26:29], v[182:185], v[198:201], v[26:29]
	v_mfma_f32_16x16x32_bf16 v[18:21], v[174:177], v[210:213], v[18:21]
	v_mfma_f32_16x16x32_bf16 v[10:13], v[182:185], v[210:213], v[10:13]
	v_mfma_f32_16x16x32_bf16 v[6:9], v[174:177], v[218:221], v[6:9]
	v_mfma_f32_16x16x32_bf16 v[2:5], v[182:185], v[218:221], v[2:5]
	s_barrier
	s_setprio 0
	s_add_i32 s48, s48, 2
	s_add_u32 s22, s22, 0x100
	s_addc_u32 s23, s23, 0
	s_add_u32 s46, s46, 0x100
	s_addc_u32 s47, s47, 0
	s_cmp_gt_u32 s48, 29
	s_cbranch_scc0 .LBB0_2615
	s_and_b64 vcc, exec, s[10:11]
	s_cbranch_vccz .LBB0_2618
	s_barrier

; #define PG8_STAGE(bufoff, gbase, voff) do { _Pragma("unroll") for (int _i = 0; _i < 2; ++_i) \
;         __builtin_amdgcn_global_load_lds((const unsigned*)((const char*)(gbase) + (voff)[_i]), (PG8_LAS unsigned*)(lds + (bufoff) + ldsw + _i * 8192), 16, 0, 0); } while (0)
; #define PG8_LDA(dst, b, h) do { _Pragma("unroll") for (int m = 0; m < 4; ++m) _Pragma("unroll") for (int k = 0; k < 2; ++k) dst[m][k] = *(const PG8_LAS bf16x8*)(lds + PG8_SA(b, h) + aoff + m * 2048 + k * 1024); } while (0)
; #define PG8_LDB(dst, b, h) do { _Pragma("unroll") for (int n = 0; n < 2; ++n) _Pragma("unroll") for (int k = 0; k < 2; ++k) dst[n][k] = *(const PG8_LAS bf16x8*)(lds + PG8_SB(b, h) + boff + n * 2048 + k * 1024); } while (0)
; #define PG8_MMA(ai, bj, At, Bt) do { __builtin_amdgcn_s_setprio(1); _Pragma("unroll") for (int m = 0; m < 4; ++m) _Pragma("unroll") for (int n = 0; n < 2; ++n) _Pragma("unroll") for (int k = 0; k < 2; ++k) \
;         acc[ai][bj][m][n] = __builtin_amdgcn_mfma_f32_16x16x32_bf16(Bt[n][k], At[m][k], acc[ai][bj][m][n], 0, 0, 0); __builtin_amdgcn_s_setprio(0); } while (0)
; #define PG8_WAIT_V(n) asm volatile("s_waitcnt vmcnt(" #n ")" ::: "memory")
; #define PG8_WAIT_L(n) asm volatile("s_waitcnt lgkmcnt(" #n ")" ::: "memory")
; #define PG8_BAR __builtin_amdgcn_s_barrier()
; #define PG8_SCHED __builtin_amdgcn_sched_barrier(0)
; template <class Epi, class Sched, bool ALIGN_EPI = false, bool SP2 = false>
; __device__ __forceinline__ void gemm_phase(PG8_LAS unsigned char* lds, const Gemm g, const Sched& S, const Epi& E) {
;     ...
;             PG8_LDB(B0, 0, 0); PG8_LDB(B1, 0, 1); PG8_SCHED; PG8_LDA(At, 0, 0); PG8_STAGE(PG8_SA(1, 1), a1 + hstepA, voffA);
;             PG8_WAIT_V(8); PG8_WAIT_L(0); PG8_BAR; PG8_MMA(0, 0, At, B0); PG8_MMA(0, 1, At, B1); PG8_BAR; PG8_SCHED;
;             PG8_LDA(At, 0, 1); PG8_STAGE(PG8_SB(0, 0), b2, voffB); PG8_STAGE(PG8_SB(0, 1), b2 + hstepB, voffB); PG8_STAGE(PG8_SA(0, 0), a2, voffA);
;             PG8_WAIT_V(8); PG8_WAIT_L(0); PG8_BAR; PG8_MMA(1, 0, At, B0); PG8_MMA(1, 1, At, B1); PG8_BAR; PG8_SCHED;
.LBB0_3372:
	ds_read_b128 v[130:133], v164
	ds_read_b128 v[134:137], v164 offset:1024
	ds_read_b128 v[138:141], v164 offset:2048
	ds_read_b128 v[142:145], v164 offset:3072
	ds_read_b128 v[168:171], v165
	ds_read_b128 v[172:175], v165 offset:1024
	ds_read_b128 v[176:179], v165 offset:2048
	ds_read_b128 v[180:183], v165 offset:3072
	s_add_u32 s34, s30, 0xfff80080
	s_addc_u32 s35, s31, -1
	s_cmp_eq_u32 s59, 28
	s_cselect_b32 s37, s23, s35
	s_cselect_b32 s36, s55, s34
	s_cselect_b32 s35, s21, s58
	s_cselect_b32 s34, s56, s57
	v_lshl_add_u64 v[218:219], s[30:31], 0, v[154:155]
	s_add_i32 m0, s29, 0xc000
	ds_read_b128 v[184:187], v166
	ds_read_b128 v[188:191], v166 offset:1024
	ds_read_b128 v[192:195], v166 offset:2048
	ds_read_b128 v[196:199], v166 offset:3072
	ds_read_b128 v[200:203], v166 offset:4096
	ds_read_b128 v[204:207], v166 offset:5120
	ds_read_b128 v[210:213], v166 offset:6144
	ds_read_b128 v[214:217], v166 offset:7168
	global_load_lds_dwordx4 v[218:219], off
	v_lshl_add_u64 v[218:219], s[30:31], 0, v[156:157]
	s_add_i32 m0, s29, 0xe000
	s_nop 0
	global_load_lds_dwordx4 v[218:219], off
	s_waitcnt vmcnt(8)
	s_waitcnt lgkmcnt(0)
	s_setprio 1
	s_barrier
	v_mfma_f32_16x16x32_bf16 v[126:129], v[130:133], v[184:187], v[126:129]
	v_mfma_f32_16x16x32_bf16 v[122:125], v[138:141], v[184:187], v[122:125]
	v_mfma_f32_16x16x32_bf16 v[118:121], v[130:133], v[192:195], v[118:121]
	v_mfma_f32_16x16x32_bf16 v[114:117], v[138:141], v[192:195], v[114:117]
	v_mfma_f32_16x16x32_bf16 v[110:113], v[130:133], v[200:203], v[110:113]
	v_mfma_f32_16x16x32_bf16 v[102:105], v[138:141], v[200:203], v[102:105]
	v_mfma_f32_16x16x32_bf16 v[94:97], v[130:133], v[210:213], v[94:97]
	v_mfma_f32_16x16x32_bf16 v[86:89], v[138:141], v[210:213], v[86:89]
	v_mfma_f32_16x16x32_bf16 v[126:129], v[134:137], v[188:191], v[126:129]
	v_mfma_f32_16x16x32_bf16 v[122:125], v[142:145], v[188:191], v[122:125]
	v_mfma_f32_16x16x32_bf16 v[118:121], v[134:137], v[196:199], v[118:121]
	v_mfma_f32_16x16x32_bf16 v[114:117], v[142:145], v[196:199], v[114:117]
	v_mfma_f32_16x16x32_bf16 v[110:113], v[134:137], v[204:207], v[110:113]
	v_mfma_f32_16x16x32_bf16 v[102:105], v[142:145], v[204:207], v[102:105]
	v_mfma_f32_16x16x32_bf16 v[94:97], v[134:137], v[214:217], v[94:97]
	v_mfma_f32_16x16x32_bf16 v[86:89], v[142:145], v[214:217], v[86:89]
	v_mfma_f32_16x16x32_bf16 v[106:109], v[168:171], v[184:187], v[106:109]
	v_mfma_f32_16x16x32_bf16 v[98:101], v[176:179], v[184:187], v[98:101]
	v_mfma_f32_16x16x32_bf16 v[90:93], v[168:171], v[192:195], v[90:93]
	v_mfma_f32_16x16x32_bf16 v[82:85], v[176:179], v[192:195], v[82:85]
	v_mfma_f32_16x16x32_bf16 v[78:81], v[168:171], v[200:203], v[78:81]
	v_mfma_f32_16x16x32_bf16 v[74:77], v[176:179], v[200:203], v[74:77]
	v_mfma_f32_16x16x32_bf16 v[70:73], v[168:171], v[210:213], v[70:73]
	v_mfma_f32_16x16x32_bf16 v[66:69], v[176:179], v[210:213], v[66:69]
	v_mfma_f32_16x16x32_bf16 v[106:109], v[172:175], v[188:191], v[106:109]
	v_mfma_f32_16x16x32_bf16 v[98:101], v[180:183], v[188:191], v[98:101]
	v_mfma_f32_16x16x32_bf16 v[90:93], v[172:175], v[196:199], v[90:93]
	v_mfma_f32_16x16x32_bf16 v[82:85], v[180:183], v[196:199], v[82:85]
	v_mfma_f32_16x16x32_bf16 v[78:81], v[172:175], v[204:207], v[78:81]
	v_mfma_f32_16x16x32_bf16 v[74:77], v[180:183], v[204:207], v[74:77]
	v_mfma_f32_16x16x32_bf16 v[70:73], v[172:175], v[214:217], v[70:73]
	v_mfma_f32_16x16x32_bf16 v[66:69], v[180:183], v[214:217], v[66:69]
	s_barrier
	s_setprio 0
	s_add_i32 s60, s48, s38
	v_lshl_add_u64 v[218:219], s[34:35], 0, v[150:151]
	s_mov_b32 m0, s60
	ds_read_b128 v[184:187], v166 offset:16384
	ds_read_b128 v[188:191], v166 offset:17408
	ds_read_b128 v[192:195], v166 offset:18432
	ds_read_b128 v[196:199], v166 offset:19456
	ds_read_b128 v[200:203], v166 offset:20480
	ds_read_b128 v[204:207], v166 offset:21504
	ds_read_b128 v[210:213], v166 offset:22528
	ds_read_b128 v[214:217], v166 offset:23552
	global_load_lds_dwordx4 v[218:219], off
	s_add_i32 m0, s60, 0x2000
	s_add_u32 s60, s34, 0x80000
	v_lshl_add_u64 v[220:221], s[34:35], 0, v[146:147]
	s_addc_u32 s61, s35, 0
	s_add_i32 s62, s49, s38
	global_load_lds_dwordx4 v[220:221], off
	v_lshl_add_u64 v[222:223], s[60:61], 0, v[150:151]
	s_mov_b32 m0, s62
	v_lshl_add_u64 v[224:225], s[36:37], 0, v[148:149]
	global_load_lds_dwordx4 v[222:223], off
	v_lshl_add_u64 v[222:223], s[60:61], 0, v[146:147]
	s_add_i32 m0, s62, 0x2000
	s_nop 0
	global_load_lds_dwordx4 v[222:223], off
	v_lshl_add_u64 v[222:223], s[36:37], 0, v[152:153]
	s_mov_b32 m0, s29
	s_nop 0
	global_load_lds_dwordx4 v[222:223], off
	s_mov_b32 m0, s41
	s_nop 0
	global_load_lds_dwordx4 v[224:225], off
	s_waitcnt vmcnt(8)
	s_waitcnt lgkmcnt(0)
	s_setprio 1
	s_barrier
; #define PG8_STAGE(bufoff, gbase, voff) do { _Pragma("unroll") for (int _i = 0; _i < 2; ++_i) \
;         __builtin_amdgcn_global_load_lds((const unsigned*)((const char*)(gbase) + (voff)[_i]), (PG8_LAS unsigned*)(lds + (bufoff) + ldsw + _i * 8192), 16, 0, 0); } while (0)
; #define PG8_LDA(dst, b, h) do { _Pragma("unroll") for (int m = 0; m < 4; ++m) _Pragma("unroll") for (int k = 0; k < 2; ++k) dst[m][k] = *(const PG8_LAS bf16x8*)(lds + PG8_SA(b, h) + aoff + m * 2048 + k * 1024); } while (0)
; #define PG8_LDB(dst, b, h) do { _Pragma("unroll") for (int n = 0; n < 2; ++n) _Pragma("unroll") for (int k = 0; k < 2; ++k) dst[n][k] = *(const PG8_LAS bf16x8*)(lds + PG8_SB(b, h) + boff + n * 2048 + k * 1024); } while (0)
; #define PG8_MMA(ai, bj, At, Bt) do { __builtin_amdgcn_s_setprio(1); _Pragma("unroll") for (int m = 0; m < 4; ++m) _Pragma("unroll") for (int n = 0; n < 2; ++n) _Pragma("unroll") for (int k = 0; k < 2; ++k) \
;         acc[ai][bj][m][n] = __builtin_amdgcn_mfma_f32_16x16x32_bf16(Bt[n][k], At[m][k], acc[ai][bj][m][n], 0, 0, 0); __builtin_amdgcn_s_setprio(0); } while (0)
; #define PG8_WAIT_V(n) asm volatile("s_waitcnt vmcnt(" #n ")" ::: "memory")
; template <class Epi, class Sched, bool ALIGN_EPI = false, bool SP2 = false>
; __device__ __forceinline__ void gemm_phase(PG8_LAS unsigned char* lds, const Gemm g, const Sched& S, const Epi& E) {
;     ...
;             PG8_LDB(B0, 0, 0); PG8_LDB(B1, 0, 1); PG8_SCHED; PG8_LDA(At, 0, 0); PG8_STAGE(PG8_SA(1, 1), a1 + hstepA, voffA);
;             PG8_WAIT_V(8); PG8_WAIT_L(0); PG8_BAR; PG8_MMA(0, 0, At, B0); PG8_MMA(0, 1, At, B1); PG8_BAR; PG8_SCHED;
;             PG8_LDA(At, 0, 1); PG8_STAGE(PG8_SB(0, 0), b2, voffB); PG8_STAGE(PG8_SB(0, 1), b2 + hstepB, voffB); PG8_STAGE(PG8_SA(0, 0), a2, voffA);
;             PG8_WAIT_V(8); PG8_WAIT_L(0); PG8_BAR; PG8_MMA(1, 0, At, B0); PG8_MMA(1, 1, At, B1); PG8_BAR; PG8_SCHED;
;             PG8_LDB(B0, 1, 0); PG8_LDB(B1, 1, 1); PG8_SCHED; PG8_LDA(At, 1, 0); PG8_STAGE(PG8_SA(0, 1), a2 + hstepA, voffA);
;             PG8_WAIT_V(8); PG8_WAIT_L(0); PG8_BAR; PG8_MMA(0, 0, At, B0); PG8_MMA(0, 1, At, B1); PG8_BAR; PG8_SCHED;
;             PG8_LDA(At, 1, 1); PG8_STAGE(PG8_SB(1, 0), b3, voffB); PG8_STAGE(PG8_SB(1, 1), b3 + hstepB, voffB); PG8_STAGE(PG8_SA(1, 0), a3, voffA);
;             PG8_WAIT_V(8); PG8_WAIT_L(0); PG8_BAR; PG8_MMA(1, 0, At, B0); PG8_MMA(1, 1, At, B1); PG8_BAR; PG8_SCHED;
	v_mfma_f32_16x16x32_bf16 v[62:65], v[130:133], v[184:187], v[62:65]
	v_mfma_f32_16x16x32_bf16 v[58:61], v[138:141], v[184:187], v[58:61]
	v_mfma_f32_16x16x32_bf16 v[54:57], v[130:133], v[192:195], v[54:57]
	v_mfma_f32_16x16x32_bf16 v[46:49], v[138:141], v[192:195], v[46:49]
	v_mfma_f32_16x16x32_bf16 v[38:41], v[130:133], v[200:203], v[38:41]
	v_mfma_f32_16x16x32_bf16 v[30:33], v[138:141], v[200:203], v[30:33]
	v_mfma_f32_16x16x32_bf16 v[22:25], v[130:133], v[210:213], v[22:25]
	v_mfma_f32_16x16x32_bf16 v[14:17], v[138:141], v[210:213], v[14:17]
	v_mfma_f32_16x16x32_bf16 v[62:65], v[134:137], v[188:191], v[62:65]
	v_mfma_f32_16x16x32_bf16 v[58:61], v[142:145], v[188:191], v[58:61]
	v_mfma_f32_16x16x32_bf16 v[54:57], v[134:137], v[196:199], v[54:57]
	v_mfma_f32_16x16x32_bf16 v[46:49], v[142:145], v[196:199], v[46:49]
	v_mfma_f32_16x16x32_bf16 v[38:41], v[134:137], v[204:207], v[38:41]
	v_mfma_f32_16x16x32_bf16 v[30:33], v[142:145], v[204:207], v[30:33]
	v_mfma_f32_16x16x32_bf16 v[22:25], v[134:137], v[214:217], v[22:25]
	v_mfma_f32_16x16x32_bf16 v[14:17], v[142:145], v[214:217], v[14:17]
	v_mfma_f32_16x16x32_bf16 v[50:53], v[168:171], v[184:187], v[50:53]
	v_mfma_f32_16x16x32_bf16 v[42:45], v[176:179], v[184:187], v[42:45]
	v_mfma_f32_16x16x32_bf16 v[34:37], v[168:171], v[192:195], v[34:37]
	v_mfma_f32_16x16x32_bf16 v[26:29], v[176:179], v[192:195], v[26:29]
	v_mfma_f32_16x16x32_bf16 v[18:21], v[168:171], v[200:203], v[18:21]
	v_mfma_f32_16x16x32_bf16 v[10:13], v[176:179], v[200:203], v[10:13]
	v_mfma_f32_16x16x32_bf16 v[6:9], v[168:171], v[210:213], v[6:9]
	v_mfma_f32_16x16x32_bf16 v[2:5], v[176:179], v[210:213], v[2:5]
	v_mfma_f32_16x16x32_bf16 v[50:53], v[172:175], v[188:191], v[50:53]
	v_mfma_f32_16x16x32_bf16 v[42:45], v[180:183], v[188:191], v[42:45]
	v_mfma_f32_16x16x32_bf16 v[34:37], v[172:175], v[196:199], v[34:37]
	v_mfma_f32_16x16x32_bf16 v[26:29], v[180:183], v[196:199], v[26:29]
	v_mfma_f32_16x16x32_bf16 v[18:21], v[172:175], v[204:207], v[18:21]
	v_mfma_f32_16x16x32_bf16 v[10:13], v[180:183], v[204:207], v[10:13]
	v_mfma_f32_16x16x32_bf16 v[6:9], v[172:175], v[214:217], v[6:9]
	v_mfma_f32_16x16x32_bf16 v[2:5], v[180:183], v[214:217], v[2:5]
	s_barrier
	s_setprio 0
	s_add_i32 s60, 0, 0x18000
	s_add_i32 s61, 0, 0x1c000
	v_add_u32_e32 v142, s60, v162
	v_add_u32_e32 v167, s61, v162
	ds_read_b128 v[130:133], v142
	ds_read_b128 v[134:137], v142 offset:1024
	ds_read_b128 v[138:141], v142 offset:2048
	ds_read_b128 v[142:145], v142 offset:3072
	ds_read_b128 v[168:171], v167
	ds_read_b128 v[172:175], v167 offset:1024
	ds_read_b128 v[176:179], v167 offset:2048
	ds_read_b128 v[180:183], v167 offset:3072
	s_add_u32 s36, s36, 0x80000
	s_addc_u32 s37, s37, 0
	s_mov_b32 m0, s42
	v_lshl_add_u64 v[226:227], s[36:37], 0, v[152:153]
	ds_read_b128 v[184:187], v166 offset:32768
	ds_read_b128 v[188:191], v166 offset:33792
	ds_read_b128 v[192:195], v166 offset:34816
	ds_read_b128 v[196:199], v166 offset:35840
	ds_read_b128 v[200:203], v166 offset:36864
	ds_read_b128 v[204:207], v166 offset:37888
	ds_read_b128 v[210:213], v166 offset:38912
	ds_read_b128 v[214:217], v166 offset:39936
	global_load_lds_dwordx4 v[226:227], off
	v_lshl_add_u64 v[226:227], s[36:37], 0, v[148:149]
	s_mov_b32 m0, s43
	s_nop 0
	global_load_lds_dwordx4 v[226:227], off
	s_waitcnt vmcnt(8)
	s_waitcnt lgkmcnt(0)
	s_setprio 1
	s_barrier
	v_mfma_f32_16x16x32_bf16 v[126:129], v[130:133], v[184:187], v[126:129]
	v_mfma_f32_16x16x32_bf16 v[122:125], v[138:141], v[184:187], v[122:125]
	v_mfma_f32_16x16x32_bf16 v[118:121], v[130:133], v[192:195], v[118:121]
	v_mfma_f32_16x16x32_bf16 v[114:117], v[138:141], v[192:195], v[114:117]
	v_mfma_f32_16x16x32_bf16 v[110:113], v[130:133], v[200:203], v[110:113]
	v_mfma_f32_16x16x32_bf16 v[102:105], v[138:141], v[200:203], v[102:105]
	v_mfma_f32_16x16x32_bf16 v[94:97], v[130:133], v[210:213], v[94:97]
	v_mfma_f32_16x16x32_bf16 v[86:89], v[138:141], v[210:213], v[86:89]
	v_mfma_f32_16x16x32_bf16 v[126:129], v[134:137], v[188:191], v[126:129]
	v_mfma_f32_16x16x32_bf16 v[122:125], v[142:145], v[188:191], v[122:125]
	v_mfma_f32_16x16x32_bf16 v[118:121], v[134:137], v[196:199], v[118:121]
	v_mfma_f32_16x16x32_bf16 v[114:117], v[142:145], v[196:199], v[114:117]
	v_mfma_f32_16x16x32_bf16 v[110:113], v[134:137], v[204:207], v[110:113]
	v_mfma_f32_16x16x32_bf16 v[102:105], v[142:145], v[204:207], v[102:105]
	v_mfma_f32_16x16x32_bf16 v[94:97], v[134:137], v[214:217], v[94:97]
	v_mfma_f32_16x16x32_bf16 v[86:89], v[142:145], v[214:217], v[86:89]
	v_mfma_f32_16x16x32_bf16 v[106:109], v[168:171], v[184:187], v[106:109]
	v_mfma_f32_16x16x32_bf16 v[98:101], v[176:179], v[184:187], v[98:101]
	v_mfma_f32_16x16x32_bf16 v[90:93], v[168:171], v[192:195], v[90:93]
	v_mfma_f32_16x16x32_bf16 v[82:85], v[176:179], v[192:195], v[82:85]
	v_mfma_f32_16x16x32_bf16 v[78:81], v[168:171], v[200:203], v[78:81]
	v_mfma_f32_16x16x32_bf16 v[74:77], v[176:179], v[200:203], v[74:77]
	v_mfma_f32_16x16x32_bf16 v[70:73], v[168:171], v[210:213], v[70:73]
	v_mfma_f32_16x16x32_bf16 v[66:69], v[176:179], v[210:213], v[66:69]
	v_mfma_f32_16x16x32_bf16 v[106:109], v[172:175], v[188:191], v[106:109]
	v_mfma_f32_16x16x32_bf16 v[98:101], v[180:183], v[188:191], v[98:101]
	v_mfma_f32_16x16x32_bf16 v[90:93], v[172:175], v[196:199], v[90:93]
	v_mfma_f32_16x16x32_bf16 v[82:85], v[180:183], v[196:199], v[82:85]
	v_mfma_f32_16x16x32_bf16 v[78:81], v[172:175], v[204:207], v[78:81]
	v_mfma_f32_16x16x32_bf16 v[74:77], v[180:183], v[204:207], v[74:77]
	v_mfma_f32_16x16x32_bf16 v[70:73], v[172:175], v[214:217], v[70:73]
	v_mfma_f32_16x16x32_bf16 v[66:69], v[180:183], v[214:217], v[66:69]
	s_barrier
; #define PG8_STAGE(bufoff, gbase, voff) do { _Pragma("unroll") for (int _i = 0; _i < 2; ++_i) \
;         __builtin_amdgcn_global_load_lds((const unsigned*)((const char*)(gbase) + (voff)[_i]), (PG8_LAS unsigned*)(lds + (bufoff) + ldsw + _i * 8192), 16, 0, 0); } while (0)
; #define PG8_LDA(dst, b, h) do { _Pragma("unroll") for (int m = 0; m < 4; ++m) _Pragma("unroll") for (int k = 0; k < 2; ++k) dst[m][k] = *(const PG8_LAS bf16x8*)(lds + PG8_SA(b, h) + aoff + m * 2048 + k * 1024); } while (0)
; #define PG8_MMA(ai, bj, At, Bt) do { __builtin_amdgcn_s_setprio(1); _Pragma("unroll") for (int m = 0; m < 4; ++m) _Pragma("unroll") for (int n = 0; n < 2; ++n) _Pragma("unroll") for (int k = 0; k < 2; ++k) \
;         acc[ai][bj][m][n] = __builtin_amdgcn_mfma_f32_16x16x32_bf16(Bt[n][k], At[m][k], acc[ai][bj][m][n], 0, 0, 0); __builtin_amdgcn_s_setprio(0); } while (0)
; #define PG8_WAIT_V(n) asm volatile("s_waitcnt vmcnt(" #n ")" ::: "memory")
; #define PG8_WAIT_L(n) asm volatile("s_waitcnt lgkmcnt(" #n ")" ::: "memory")
; #define PG8_BAR __builtin_amdgcn_s_barrier()
; #define PG8_SCHED __builtin_amdgcn_sched_barrier(0)
; template <class Epi, class Sched, bool ALIGN_EPI = false, bool SP2 = false>
; __device__ __forceinline__ void gemm_phase(PG8_LAS unsigned char* lds, const Gemm g, const Sched& S, const Epi& E) {
;     ...
;         for (int t = 0; t < nt; t += 2) {
;             const bool last = (t == nt - 2);
;             const char* a1 = cA + (size_t)(t + 1) * kstep;
;             const char* a2 = last ? nA : cA + (size_t)(t + 2) * kstep; const char* b2 = last ? nB : cB + (size_t)(t + 2) * kstep;
;     ...
;             PG8_LDA(At, 1, 1); PG8_STAGE(PG8_SB(1, 0), b3, voffB); PG8_STAGE(PG8_SB(1, 1), b3 + hstepB, voffB); PG8_STAGE(PG8_SA(1, 0), a3, voffA);
;             PG8_WAIT_V(8); PG8_WAIT_L(0); PG8_BAR; PG8_MMA(1, 0, At, B0); PG8_MMA(1, 1, At, B1); PG8_BAR; PG8_SCHED;
	s_setprio 0
	s_add_i32 s36, s60, s38
	v_lshl_add_u64 v[218:219], v[218:219], 0, s[10:11]
	s_mov_b32 m0, s36
	ds_read_b128 v[184:187], v166 offset:49152
	ds_read_b128 v[188:191], v166 offset:50176
	ds_read_b128 v[192:195], v166 offset:51200
	ds_read_b128 v[196:199], v166 offset:52224
	ds_read_b128 v[200:203], v166 offset:53248
	ds_read_b128 v[204:207], v166 offset:54272
	ds_read_b128 v[210:213], v166 offset:55296
	ds_read_b128 v[214:217], v166 offset:56320
	global_load_lds_dwordx4 v[218:219], off
	s_add_i32 m0, s36, 0x2000
	s_add_u32 s34, s34, 0x80080
	v_lshl_add_u64 v[218:219], v[220:221], 0, s[10:11]
	s_addc_u32 s35, s35, 0
	s_add_i32 s36, s61, s38
	global_load_lds_dwordx4 v[218:219], off
	v_lshl_add_u64 v[218:219], s[34:35], 0, v[150:151]
	s_mov_b32 m0, s36
	s_nop 0
	global_load_lds_dwordx4 v[218:219], off
	v_lshl_add_u64 v[218:219], s[34:35], 0, v[146:147]
	s_add_i32 m0, s36, 0x2000
	s_nop 0
	global_load_lds_dwordx4 v[218:219], off
	v_lshl_add_u64 v[218:219], v[222:223], 0, s[10:11]
	s_mov_b32 m0, s45
	s_nop 0
	global_load_lds_dwordx4 v[218:219], off
	v_lshl_add_u64 v[218:219], v[224:225], 0, s[10:11]
	s_mov_b32 m0, s46
	s_nop 0
	global_load_lds_dwordx4 v[218:219], off
	s_waitcnt vmcnt(8)
	s_waitcnt lgkmcnt(0)
	s_setprio 1
	s_barrier
	v_mfma_f32_16x16x32_bf16 v[62:65], v[130:133], v[184:187], v[62:65]
	v_mfma_f32_16x16x32_bf16 v[58:61], v[138:141], v[184:187], v[58:61]
	v_mfma_f32_16x16x32_bf16 v[54:57], v[130:133], v[192:195], v[54:57]
	v_mfma_f32_16x16x32_bf16 v[46:49], v[138:141], v[192:195], v[46:49]
	v_mfma_f32_16x16x32_bf16 v[38:41], v[130:133], v[200:203], v[38:41]
	v_mfma_f32_16x16x32_bf16 v[30:33], v[138:141], v[200:203], v[30:33]
	v_mfma_f32_16x16x32_bf16 v[22:25], v[130:133], v[210:213], v[22:25]
	v_mfma_f32_16x16x32_bf16 v[14:17], v[138:141], v[210:213], v[14:17]
	v_mfma_f32_16x16x32_bf16 v[62:65], v[134:137], v[188:191], v[62:65]
	v_mfma_f32_16x16x32_bf16 v[58:61], v[142:145], v[188:191], v[58:61]
	v_mfma_f32_16x16x32_bf16 v[54:57], v[134:137], v[196:199], v[54:57]
	v_mfma_f32_16x16x32_bf16 v[46:49], v[142:145], v[196:199], v[46:49]
	v_mfma_f32_16x16x32_bf16 v[38:41], v[134:137], v[204:207], v[38:41]
	v_mfma_f32_16x16x32_bf16 v[30:33], v[142:145], v[204:207], v[30:33]
	v_mfma_f32_16x16x32_bf16 v[22:25], v[134:137], v[214:217], v[22:25]
	v_mfma_f32_16x16x32_bf16 v[14:17], v[142:145], v[214:217], v[14:17]
	v_mfma_f32_16x16x32_bf16 v[50:53], v[168:171], v[184:187], v[50:53]
	v_mfma_f32_16x16x32_bf16 v[42:45], v[176:179], v[184:187], v[42:45]
	v_mfma_f32_16x16x32_bf16 v[34:37], v[168:171], v[192:195], v[34:37]
	v_mfma_f32_16x16x32_bf16 v[26:29], v[176:179], v[192:195], v[26:29]
	v_mfma_f32_16x16x32_bf16 v[18:21], v[168:171], v[200:203], v[18:21]
	v_mfma_f32_16x16x32_bf16 v[10:13], v[176:179], v[200:203], v[10:13]
	v_mfma_f32_16x16x32_bf16 v[6:9], v[168:171], v[210:213], v[6:9]
	v_mfma_f32_16x16x32_bf16 v[2:5], v[176:179], v[210:213], v[2:5]
	v_mfma_f32_16x16x32_bf16 v[50:53], v[172:175], v[188:191], v[50:53]
	v_mfma_f32_16x16x32_bf16 v[42:45], v[180:183], v[188:191], v[42:45]
	v_mfma_f32_16x16x32_bf16 v[34:37], v[172:175], v[196:199], v[34:37]
	v_mfma_f32_16x16x32_bf16 v[26:29], v[180:183], v[196:199], v[26:29]
	v_mfma_f32_16x16x32_bf16 v[18:21], v[172:175], v[204:207], v[18:21]
	v_mfma_f32_16x16x32_bf16 v[10:13], v[180:183], v[204:207], v[10:13]
	v_mfma_f32_16x16x32_bf16 v[6:9], v[172:175], v[214:217], v[6:9]
	v_mfma_f32_16x16x32_bf16 v[2:5], v[180:183], v[214:217], v[2:5]
	s_barrier
	s_setprio 0
	s_add_i32 s59, s59, 2
	s_add_u32 s30, s30, 0x100
	s_addc_u32 s31, s31, 0
	s_add_u32 s57, s57, 0x100
	s_addc_u32 s58, s58, 0
	s_cmp_gt_u32 s59, 29
	s_cbranch_scc0 .LBB0_3372
	s_and_b64 vcc, exec, s[12:13]
	s_cbranch_vccz .LBB0_3375
	s_barrier

; #define PG8_STAGE(bufoff, gbase, voff) do { _Pragma("unroll") for (int _i = 0; _i < 2; ++_i) \
;         __builtin_amdgcn_global_load_lds((const unsigned*)((const char*)(gbase) + (voff)[_i]), (PG8_LAS unsigned*)(lds + (bufoff) + ldsw + _i * 8192), 16, 0, 0); } while (0)
; #define PG8_LDA(dst, b, h) do { _Pragma("unroll") for (int m = 0; m < 4; ++m) _Pragma("unroll") for (int k = 0; k < 2; ++k) dst[m][k] = *(const PG8_LAS bf16x8*)(lds + PG8_SA(b, h) + aoff + m * 2048 + k * 1024); } while (0)
; #define PG8_LDB(dst, b, h) do { _Pragma("unroll") for (int n = 0; n < 2; ++n) _Pragma("unroll") for (int k = 0; k < 2; ++k) dst[n][k] = *(const PG8_LAS bf16x8*)(lds + PG8_SB(b, h) + boff + n * 2048 + k * 1024); } while (0)
; #define PG8_MMA(ai, bj, At, Bt) do { __builtin_amdgcn_s_setprio(1); _Pragma("unroll") for (int m = 0; m < 4; ++m) _Pragma("unroll") for (int n = 0; n < 2; ++n) _Pragma("unroll") for (int k = 0; k < 2; ++k) \
;         acc[ai][bj][m][n] = __builtin_amdgcn_mfma_f32_16x16x32_bf16(Bt[n][k], At[m][k], acc[ai][bj][m][n], 0, 0, 0); __builtin_amdgcn_s_setprio(0); } while (0)
; #define PG8_WAIT_V(n) asm volatile("s_waitcnt vmcnt(" #n ")" ::: "memory")
; #define PG8_WAIT_L(n) asm volatile("s_waitcnt lgkmcnt(" #n ")" ::: "memory")
; #define PG8_BAR __builtin_amdgcn_s_barrier()
; #define PG8_SCHED __builtin_amdgcn_sched_barrier(0)
; template <class Epi, class Sched, bool ALIGN_EPI = false, bool SP2 = false>
; __device__ __forceinline__ void gemm_phase(PG8_LAS unsigned char* lds, const Gemm g, const Sched& S, const Epi& E) {
;     ...
;             PG8_LDB(B0, 0, 0); PG8_LDB(B1, 0, 1); PG8_SCHED; PG8_LDA(At, 0, 0); PG8_STAGE(PG8_SA(1, 1), a1 + hstepA, voffA);
;             PG8_WAIT_V(8); PG8_WAIT_L(0); PG8_BAR; PG8_MMA(0, 0, At, B0); PG8_MMA(0, 1, At, B1); PG8_BAR; PG8_SCHED;
;             PG8_LDA(At, 0, 1); PG8_STAGE(PG8_SB(0, 0), b2, voffB); PG8_STAGE(PG8_SB(0, 1), b2 + hstepB, voffB); PG8_STAGE(PG8_SA(0, 0), a2, voffA);
;             PG8_WAIT_V(8); PG8_WAIT_L(0); PG8_BAR; PG8_MMA(1, 0, At, B0); PG8_MMA(1, 1, At, B1); PG8_BAR; PG8_SCHED;
.LBB0_3500:
	ds_read_b128 v[154:157], v150
	ds_read_b128 v[158:161], v150 offset:1024
	ds_read_b128 v[162:165], v150 offset:2048
	ds_read_b128 v[166:169], v150 offset:3072
	ds_read_b128 v[170:173], v151
	ds_read_b128 v[174:177], v151 offset:1024
	ds_read_b128 v[178:181], v151 offset:2048
	ds_read_b128 v[182:185], v151 offset:3072
	s_add_u32 s22, s20, 0xfff80080
	s_addc_u32 s23, s21, -1
	s_cmp_eq_u32 s48, 28
	s_cselect_b32 s25, s13, s23
	s_cselect_b32 s24, s44, s22
	s_cselect_b32 s23, s11, s47
	s_cselect_b32 s22, s45, s46
	v_lshl_add_u64 v[146:147], s[20:21], 0, v[138:139]
	s_add_i32 m0, s19, 0xc000
	ds_read_b128 v[186:189], v152
	ds_read_b128 v[190:193], v152 offset:1024
	ds_read_b128 v[194:197], v152 offset:2048
	ds_read_b128 v[198:201], v152 offset:3072
	ds_read_b128 v[202:205], v152 offset:4096
	ds_read_b128 v[210:213], v152 offset:5120
	ds_read_b128 v[214:217], v152 offset:6144
	ds_read_b128 v[218:221], v152 offset:7168
	global_load_lds_dwordx4 v[146:147], off
	v_lshl_add_u64 v[146:147], s[20:21], 0, v[140:141]
	s_add_i32 m0, s19, 0xe000
	s_nop 0
	global_load_lds_dwordx4 v[146:147], off
	s_waitcnt vmcnt(8)
	s_waitcnt lgkmcnt(0)
	s_setprio 1
	s_barrier
	v_mfma_f32_16x16x32_bf16 v[126:129], v[154:157], v[186:189], v[126:129]
	v_mfma_f32_16x16x32_bf16 v[122:125], v[162:165], v[186:189], v[122:125]
	v_mfma_f32_16x16x32_bf16 v[110:113], v[154:157], v[194:197], v[110:113]
	v_mfma_f32_16x16x32_bf16 v[106:109], v[162:165], v[194:197], v[106:109]
	v_mfma_f32_16x16x32_bf16 v[94:97], v[154:157], v[202:205], v[94:97]
	v_mfma_f32_16x16x32_bf16 v[90:93], v[162:165], v[202:205], v[90:93]
	v_mfma_f32_16x16x32_bf16 v[78:81], v[154:157], v[214:217], v[78:81]
	v_mfma_f32_16x16x32_bf16 v[74:77], v[162:165], v[214:217], v[74:77]
	v_mfma_f32_16x16x32_bf16 v[126:129], v[158:161], v[190:193], v[126:129]
	v_mfma_f32_16x16x32_bf16 v[122:125], v[166:169], v[190:193], v[122:125]
	v_mfma_f32_16x16x32_bf16 v[110:113], v[158:161], v[198:201], v[110:113]
	v_mfma_f32_16x16x32_bf16 v[106:109], v[166:169], v[198:201], v[106:109]
	v_mfma_f32_16x16x32_bf16 v[94:97], v[158:161], v[210:213], v[94:97]
	v_mfma_f32_16x16x32_bf16 v[90:93], v[166:169], v[210:213], v[90:93]
	v_mfma_f32_16x16x32_bf16 v[78:81], v[158:161], v[218:221], v[78:81]
	v_mfma_f32_16x16x32_bf16 v[74:77], v[166:169], v[218:221], v[74:77]
	v_mfma_f32_16x16x32_bf16 v[118:121], v[170:173], v[186:189], v[118:121]
	v_mfma_f32_16x16x32_bf16 v[114:117], v[178:181], v[186:189], v[114:117]
	v_mfma_f32_16x16x32_bf16 v[102:105], v[170:173], v[194:197], v[102:105]
	v_mfma_f32_16x16x32_bf16 v[98:101], v[178:181], v[194:197], v[98:101]
	v_mfma_f32_16x16x32_bf16 v[86:89], v[170:173], v[202:205], v[86:89]
	v_mfma_f32_16x16x32_bf16 v[82:85], v[178:181], v[202:205], v[82:85]
	v_mfma_f32_16x16x32_bf16 v[70:73], v[170:173], v[214:217], v[70:73]
	v_mfma_f32_16x16x32_bf16 v[66:69], v[178:181], v[214:217], v[66:69]
	v_mfma_f32_16x16x32_bf16 v[118:121], v[174:177], v[190:193], v[118:121]
	v_mfma_f32_16x16x32_bf16 v[114:117], v[182:185], v[190:193], v[114:117]
	v_mfma_f32_16x16x32_bf16 v[102:105], v[174:177], v[198:201], v[102:105]
	v_mfma_f32_16x16x32_bf16 v[98:101], v[182:185], v[198:201], v[98:101]
	v_mfma_f32_16x16x32_bf16 v[86:89], v[174:177], v[210:213], v[86:89]
	v_mfma_f32_16x16x32_bf16 v[82:85], v[182:185], v[210:213], v[82:85]
	v_mfma_f32_16x16x32_bf16 v[70:73], v[174:177], v[218:221], v[70:73]
	v_mfma_f32_16x16x32_bf16 v[66:69], v[182:185], v[218:221], v[66:69]
	s_barrier
	s_setprio 0
	s_add_i32 s49, s40, s29
	v_lshl_add_u64 v[146:147], s[22:23], 0, v[134:135]
	s_mov_b32 m0, s49
	ds_read_b128 v[186:189], v152 offset:16384
	ds_read_b128 v[190:193], v152 offset:17408
	ds_read_b128 v[194:197], v152 offset:18432
	ds_read_b128 v[198:201], v152 offset:19456
	ds_read_b128 v[202:205], v152 offset:20480
	ds_read_b128 v[210:213], v152 offset:21504
	ds_read_b128 v[214:217], v152 offset:22528
	ds_read_b128 v[218:221], v152 offset:23552
	global_load_lds_dwordx4 v[146:147], off
	s_add_i32 m0, s49, 0x2000
	s_add_u32 s50, s22, 0x80000
	v_lshl_add_u64 v[206:207], s[22:23], 0, v[130:131]
	s_addc_u32 s51, s23, 0
	s_add_i32 s49, s41, s29
	global_load_lds_dwordx4 v[206:207], off
	v_lshl_add_u64 v[222:223], s[50:51], 0, v[134:135]
	s_mov_b32 m0, s49
	v_lshl_add_u64 v[224:225], s[24:25], 0, v[132:133]
	global_load_lds_dwordx4 v[222:223], off
	v_lshl_add_u64 v[222:223], s[50:51], 0, v[130:131]
	s_add_i32 m0, s49, 0x2000
	s_nop 0
	global_load_lds_dwordx4 v[222:223], off
	v_lshl_add_u64 v[222:223], s[24:25], 0, v[136:137]
	s_mov_b32 m0, s19
	s_nop 0
	global_load_lds_dwordx4 v[222:223], off
	s_mov_b32 m0, s33
	s_nop 0
	global_load_lds_dwordx4 v[224:225], off
	s_waitcnt vmcnt(8)
	s_waitcnt lgkmcnt(0)
	s_setprio 1
	s_barrier
; #define PG8_STAGE(bufoff, gbase, voff) do { _Pragma("unroll") for (int _i = 0; _i < 2; ++_i) \
;         __builtin_amdgcn_global_load_lds((const unsigned*)((const char*)(gbase) + (voff)[_i]), (PG8_LAS unsigned*)(lds + (bufoff) + ldsw + _i * 8192), 16, 0, 0); } while (0)
; #define PG8_LDA(dst, b, h) do { _Pragma("unroll") for (int m = 0; m < 4; ++m) _Pragma("unroll") for (int k = 0; k < 2; ++k) dst[m][k] = *(const PG8_LAS bf16x8*)(lds + PG8_SA(b, h) + aoff + m * 2048 + k * 1024); } while (0)
; #define PG8_LDB(dst, b, h) do { _Pragma("unroll") for (int n = 0; n < 2; ++n) _Pragma("unroll") for (int k = 0; k < 2; ++k) dst[n][k] = *(const PG8_LAS bf16x8*)(lds + PG8_SB(b, h) + boff + n * 2048 + k * 1024); } while (0)
; #define PG8_MMA(ai, bj, At, Bt) do { __builtin_amdgcn_s_setprio(1); _Pragma("unroll") for (int m = 0; m < 4; ++m) _Pragma("unroll") for (int n = 0; n < 2; ++n) _Pragma("unroll") for (int k = 0; k < 2; ++k) \
;         acc[ai][bj][m][n] = __builtin_amdgcn_mfma_f32_16x16x32_bf16(Bt[n][k], At[m][k], acc[ai][bj][m][n], 0, 0, 0); __builtin_amdgcn_s_setprio(0); } while (0)
; #define PG8_WAIT_V(n) asm volatile("s_waitcnt vmcnt(" #n ")" ::: "memory")
; #define PG8_WAIT_L(n) asm volatile("s_waitcnt lgkmcnt(" #n ")" ::: "memory")
; #define PG8_BAR __builtin_amdgcn_s_barrier()
; #define PG8_SCHED __builtin_amdgcn_sched_barrier(0)
; template <class Epi, class Sched, bool ALIGN_EPI = false, bool SP2 = false>
; __device__ __forceinline__ void gemm_phase(PG8_LAS unsigned char* lds, const Gemm g, const Sched& S, const Epi& E) {
;     ...
;             PG8_LDA(At, 0, 1); PG8_STAGE(PG8_SB(0, 0), b2, voffB); PG8_STAGE(PG8_SB(0, 1), b2 + hstepB, voffB); PG8_STAGE(PG8_SA(0, 0), a2, voffA);
;             PG8_WAIT_V(8); PG8_WAIT_L(0); PG8_BAR; PG8_MMA(1, 0, At, B0); PG8_MMA(1, 1, At, B1); PG8_BAR; PG8_SCHED;
;             PG8_LDB(B0, 1, 0); PG8_LDB(B1, 1, 1); PG8_SCHED; PG8_LDA(At, 1, 0); PG8_STAGE(PG8_SA(0, 1), a2 + hstepA, voffA);
;             PG8_WAIT_V(8); PG8_WAIT_L(0); PG8_BAR; PG8_MMA(0, 0, At, B0); PG8_MMA(0, 1, At, B1); PG8_BAR; PG8_SCHED;
	v_mfma_f32_16x16x32_bf16 v[62:65], v[154:157], v[186:189], v[62:65]
	v_mfma_f32_16x16x32_bf16 v[58:61], v[162:165], v[186:189], v[58:61]
	v_mfma_f32_16x16x32_bf16 v[46:49], v[154:157], v[194:197], v[46:49]
	v_mfma_f32_16x16x32_bf16 v[42:45], v[162:165], v[194:197], v[42:45]
	v_mfma_f32_16x16x32_bf16 v[30:33], v[154:157], v[202:205], v[30:33]
	v_mfma_f32_16x16x32_bf16 v[26:29], v[162:165], v[202:205], v[26:29]
	v_mfma_f32_16x16x32_bf16 v[14:17], v[154:157], v[214:217], v[14:17]
	v_mfma_f32_16x16x32_bf16 v[10:13], v[162:165], v[214:217], v[10:13]
	v_mfma_f32_16x16x32_bf16 v[62:65], v[158:161], v[190:193], v[62:65]
	v_mfma_f32_16x16x32_bf16 v[58:61], v[166:169], v[190:193], v[58:61]
	v_mfma_f32_16x16x32_bf16 v[46:49], v[158:161], v[198:201], v[46:49]
	v_mfma_f32_16x16x32_bf16 v[42:45], v[166:169], v[198:201], v[42:45]
	v_mfma_f32_16x16x32_bf16 v[30:33], v[158:161], v[210:213], v[30:33]
	v_mfma_f32_16x16x32_bf16 v[26:29], v[166:169], v[210:213], v[26:29]
	v_mfma_f32_16x16x32_bf16 v[14:17], v[158:161], v[218:221], v[14:17]
	v_mfma_f32_16x16x32_bf16 v[10:13], v[166:169], v[218:221], v[10:13]
	v_mfma_f32_16x16x32_bf16 v[54:57], v[170:173], v[186:189], v[54:57]
	v_mfma_f32_16x16x32_bf16 v[50:53], v[178:181], v[186:189], v[50:53]
	v_mfma_f32_16x16x32_bf16 v[38:41], v[170:173], v[194:197], v[38:41]
	v_mfma_f32_16x16x32_bf16 v[34:37], v[178:181], v[194:197], v[34:37]
	v_mfma_f32_16x16x32_bf16 v[22:25], v[170:173], v[202:205], v[22:25]
	v_mfma_f32_16x16x32_bf16 v[18:21], v[178:181], v[202:205], v[18:21]
	v_mfma_f32_16x16x32_bf16 v[6:9], v[170:173], v[214:217], v[6:9]
	v_mfma_f32_16x16x32_bf16 v[2:5], v[178:181], v[214:217], v[2:5]
	v_mfma_f32_16x16x32_bf16 v[54:57], v[174:177], v[190:193], v[54:57]
	v_mfma_f32_16x16x32_bf16 v[50:53], v[182:185], v[190:193], v[50:53]
	v_mfma_f32_16x16x32_bf16 v[38:41], v[174:177], v[198:201], v[38:41]
	v_mfma_f32_16x16x32_bf16 v[34:37], v[182:185], v[198:201], v[34:37]
	v_mfma_f32_16x16x32_bf16 v[22:25], v[174:177], v[210:213], v[22:25]
	v_mfma_f32_16x16x32_bf16 v[18:21], v[182:185], v[210:213], v[18:21]
	v_mfma_f32_16x16x32_bf16 v[6:9], v[174:177], v[218:221], v[6:9]
	v_mfma_f32_16x16x32_bf16 v[2:5], v[182:185], v[218:221], v[2:5]
	s_barrier
	s_setprio 0
	s_add_i32 s49, 0, 0x18000
	v_add_u32_e32 v153, s49, v148
	s_add_i32 s50, 0, 0x1c000
	ds_read_b128 v[154:157], v153
	ds_read_b128 v[158:161], v153 offset:1024
	ds_read_b128 v[162:165], v153 offset:2048
	ds_read_b128 v[166:169], v153 offset:3072
	v_add_u32_e32 v153, s50, v148
	ds_read_b128 v[170:173], v153
	ds_read_b128 v[174:177], v153 offset:1024
	ds_read_b128 v[178:181], v153 offset:2048
	ds_read_b128 v[182:185], v153 offset:3072
	s_add_u32 s24, s24, 0x80000
	s_addc_u32 s25, s25, 0
	s_mov_b32 m0, s34
	v_lshl_add_u64 v[226:227], s[24:25], 0, v[136:137]
	ds_read_b128 v[186:189], v152 offset:32768
	ds_read_b128 v[190:193], v152 offset:33792
	ds_read_b128 v[194:197], v152 offset:34816
	ds_read_b128 v[198:201], v152 offset:35840
	ds_read_b128 v[202:205], v152 offset:36864
	ds_read_b128 v[210:213], v152 offset:37888
	ds_read_b128 v[214:217], v152 offset:38912
	ds_read_b128 v[218:221], v152 offset:39936
	global_load_lds_dwordx4 v[226:227], off
	v_lshl_add_u64 v[226:227], s[24:25], 0, v[132:133]
	s_mov_b32 m0, s35
	s_nop 0
	global_load_lds_dwordx4 v[226:227], off
	s_waitcnt vmcnt(8)
	s_waitcnt lgkmcnt(0)
	s_setprio 1
	s_barrier
	v_mfma_f32_16x16x32_bf16 v[126:129], v[154:157], v[186:189], v[126:129]
	v_mfma_f32_16x16x32_bf16 v[122:125], v[162:165], v[186:189], v[122:125]
	v_mfma_f32_16x16x32_bf16 v[110:113], v[154:157], v[194:197], v[110:113]
	v_mfma_f32_16x16x32_bf16 v[106:109], v[162:165], v[194:197], v[106:109]
	v_mfma_f32_16x16x32_bf16 v[94:97], v[154:157], v[202:205], v[94:97]
	v_mfma_f32_16x16x32_bf16 v[90:93], v[162:165], v[202:205], v[90:93]
	v_mfma_f32_16x16x32_bf16 v[78:81], v[154:157], v[214:217], v[78:81]
	v_mfma_f32_16x16x32_bf16 v[74:77], v[162:165], v[214:217], v[74:77]
	v_mfma_f32_16x16x32_bf16 v[126:129], v[158:161], v[190:193], v[126:129]
	v_mfma_f32_16x16x32_bf16 v[122:125], v[166:169], v[190:193], v[122:125]
	v_mfma_f32_16x16x32_bf16 v[110:113], v[158:161], v[198:201], v[110:113]
	v_mfma_f32_16x16x32_bf16 v[106:109], v[166:169], v[198:201], v[106:109]
	v_mfma_f32_16x16x32_bf16 v[94:97], v[158:161], v[210:213], v[94:97]
	v_mfma_f32_16x16x32_bf16 v[90:93], v[166:169], v[210:213], v[90:93]
	v_mfma_f32_16x16x32_bf16 v[78:81], v[158:161], v[218:221], v[78:81]
	v_mfma_f32_16x16x32_bf16 v[74:77], v[166:169], v[218:221], v[74:77]
	v_mfma_f32_16x16x32_bf16 v[118:121], v[170:173], v[186:189], v[118:121]
	v_mfma_f32_16x16x32_bf16 v[114:117], v[178:181], v[186:189], v[114:117]
	v_mfma_f32_16x16x32_bf16 v[102:105], v[170:173], v[194:197], v[102:105]
	v_mfma_f32_16x16x32_bf16 v[98:101], v[178:181], v[194:197], v[98:101]
	v_mfma_f32_16x16x32_bf16 v[86:89], v[170:173], v[202:205], v[86:89]
	v_mfma_f32_16x16x32_bf16 v[82:85], v[178:181], v[202:205], v[82:85]
	v_mfma_f32_16x16x32_bf16 v[70:73], v[170:173], v[214:217], v[70:73]
	v_mfma_f32_16x16x32_bf16 v[66:69], v[178:181], v[214:217], v[66:69]
	v_mfma_f32_16x16x32_bf16 v[118:121], v[174:177], v[190:193], v[118:121]
	v_mfma_f32_16x16x32_bf16 v[114:117], v[182:185], v[190:193], v[114:117]
	v_mfma_f32_16x16x32_bf16 v[102:105], v[174:177], v[198:201], v[102:105]
	v_mfma_f32_16x16x32_bf16 v[98:101], v[182:185], v[198:201], v[98:101]
	v_mfma_f32_16x16x32_bf16 v[86:89], v[174:177], v[210:213], v[86:89]
	v_mfma_f32_16x16x32_bf16 v[82:85], v[182:185], v[210:213], v[82:85]
	v_mfma_f32_16x16x32_bf16 v[70:73], v[174:177], v[218:221], v[70:73]
	v_mfma_f32_16x16x32_bf16 v[66:69], v[182:185], v[218:221], v[66:69]
	s_barrier
; #define PG8_STAGE(bufoff, gbase, voff) do { _Pragma("unroll") for (int _i = 0; _i < 2; ++_i) \
;         __builtin_amdgcn_global_load_lds((const unsigned*)((const char*)(gbase) + (voff)[_i]), (PG8_LAS unsigned*)(lds + (bufoff) + ldsw + _i * 8192), 16, 0, 0); } while (0)
; #define PG8_LDA(dst, b, h) do { _Pragma("unroll") for (int m = 0; m < 4; ++m) _Pragma("unroll") for (int k = 0; k < 2; ++k) dst[m][k] = *(const PG8_LAS bf16x8*)(lds + PG8_SA(b, h) + aoff + m * 2048 + k * 1024); } while (0)
; #define PG8_MMA(ai, bj, At, Bt) do { __builtin_amdgcn_s_setprio(1); _Pragma("unroll") for (int m = 0; m < 4; ++m) _Pragma("unroll") for (int n = 0; n < 2; ++n) _Pragma("unroll") for (int k = 0; k < 2; ++k) \
;         acc[ai][bj][m][n] = __builtin_amdgcn_mfma_f32_16x16x32_bf16(Bt[n][k], At[m][k], acc[ai][bj][m][n], 0, 0, 0); __builtin_amdgcn_s_setprio(0); } while (0)
; #define PG8_WAIT_V(n) asm volatile("s_waitcnt vmcnt(" #n ")" ::: "memory")
; #define PG8_WAIT_L(n) asm volatile("s_waitcnt lgkmcnt(" #n ")" ::: "memory")
; #define PG8_BAR __builtin_amdgcn_s_barrier()
; #define PG8_SCHED __builtin_amdgcn_sched_barrier(0)
; template <class Epi, class Sched, bool ALIGN_EPI = false, bool SP2 = false>
; __device__ __forceinline__ void gemm_phase(PG8_LAS unsigned char* lds, const Gemm g, const Sched& S, const Epi& E) {
;     ...
;         for (int t = 0; t < nt; t += 2) {
;             const bool last = (t == nt - 2);
;             const char* a1 = cA + (size_t)(t + 1) * kstep;
;             const char* a2 = last ? nA : cA + (size_t)(t + 2) * kstep; const char* b2 = last ? nB : cB + (size_t)(t + 2) * kstep;
;     ...
;             PG8_LDA(At, 1, 1); PG8_STAGE(PG8_SB(1, 0), b3, voffB); PG8_STAGE(PG8_SB(1, 1), b3 + hstepB, voffB); PG8_STAGE(PG8_SA(1, 0), a3, voffA);
;             PG8_WAIT_V(8); PG8_WAIT_L(0); PG8_BAR; PG8_MMA(1, 0, At, B0); PG8_MMA(1, 1, At, B1); PG8_BAR; PG8_SCHED;
	s_setprio 0
	s_add_i32 s24, s49, s29
	v_lshl_add_u64 v[146:147], v[146:147], 0, s[6:7]
	s_mov_b32 m0, s24
	ds_read_b128 v[186:189], v152 offset:49152
	ds_read_b128 v[190:193], v152 offset:50176
	ds_read_b128 v[194:197], v152 offset:51200
	ds_read_b128 v[198:201], v152 offset:52224
	ds_read_b128 v[202:205], v152 offset:53248
	ds_read_b128 v[210:213], v152 offset:54272
	ds_read_b128 v[214:217], v152 offset:55296
	ds_read_b128 v[218:221], v152 offset:56320
	global_load_lds_dwordx4 v[146:147], off
	s_add_i32 m0, s24, 0x2000
	s_add_u32 s22, s22, 0x80080
	v_lshl_add_u64 v[146:147], v[206:207], 0, s[6:7]
	s_addc_u32 s23, s23, 0
	s_add_i32 s24, s50, s29
	global_load_lds_dwordx4 v[146:147], off
	v_lshl_add_u64 v[146:147], s[22:23], 0, v[134:135]
	s_mov_b32 m0, s24
	s_nop 0
	global_load_lds_dwordx4 v[146:147], off
	v_lshl_add_u64 v[146:147], s[22:23], 0, v[130:131]
	s_add_i32 m0, s24, 0x2000
	s_nop 0
	global_load_lds_dwordx4 v[146:147], off
	v_lshl_add_u64 v[146:147], v[222:223], 0, s[6:7]
	s_mov_b32 m0, s37
	s_nop 0
	global_load_lds_dwordx4 v[146:147], off
	v_lshl_add_u64 v[146:147], v[224:225], 0, s[6:7]
	s_mov_b32 m0, s38
	s_nop 0
	global_load_lds_dwordx4 v[146:147], off
	s_waitcnt vmcnt(8)
	s_waitcnt lgkmcnt(0)
	s_setprio 1
	s_barrier
	v_mfma_f32_16x16x32_bf16 v[62:65], v[154:157], v[186:189], v[62:65]
	v_mfma_f32_16x16x32_bf16 v[58:61], v[162:165], v[186:189], v[58:61]
	v_mfma_f32_16x16x32_bf16 v[46:49], v[154:157], v[194:197], v[46:49]
	v_mfma_f32_16x16x32_bf16 v[42:45], v[162:165], v[194:197], v[42:45]
	v_mfma_f32_16x16x32_bf16 v[30:33], v[154:157], v[202:205], v[30:33]
	v_mfma_f32_16x16x32_bf16 v[26:29], v[162:165], v[202:205], v[26:29]
	v_mfma_f32_16x16x32_bf16 v[14:17], v[154:157], v[214:217], v[14:17]
	v_mfma_f32_16x16x32_bf16 v[10:13], v[162:165], v[214:217], v[10:13]
	v_mfma_f32_16x16x32_bf16 v[62:65], v[158:161], v[190:193], v[62:65]
	v_mfma_f32_16x16x32_bf16 v[58:61], v[166:169], v[190:193], v[58:61]
	v_mfma_f32_16x16x32_bf16 v[46:49], v[158:161], v[198:201], v[46:49]
	v_mfma_f32_16x16x32_bf16 v[42:45], v[166:169], v[198:201], v[42:45]
	v_mfma_f32_16x16x32_bf16 v[30:33], v[158:161], v[210:213], v[30:33]
	v_mfma_f32_16x16x32_bf16 v[26:29], v[166:169], v[210:213], v[26:29]
	v_mfma_f32_16x16x32_bf16 v[14:17], v[158:161], v[218:221], v[14:17]
	v_mfma_f32_16x16x32_bf16 v[10:13], v[166:169], v[218:221], v[10:13]
	v_mfma_f32_16x16x32_bf16 v[54:57], v[170:173], v[186:189], v[54:57]
	v_mfma_f32_16x16x32_bf16 v[50:53], v[178:181], v[186:189], v[50:53]
	v_mfma_f32_16x16x32_bf16 v[38:41], v[170:173], v[194:197], v[38:41]
	v_mfma_f32_16x16x32_bf16 v[34:37], v[178:181], v[194:197], v[34:37]
	v_mfma_f32_16x16x32_bf16 v[22:25], v[170:173], v[202:205], v[22:25]
	v_mfma_f32_16x16x32_bf16 v[18:21], v[178:181], v[202:205], v[18:21]
	v_mfma_f32_16x16x32_bf16 v[6:9], v[170:173], v[214:217], v[6:9]
	v_mfma_f32_16x16x32_bf16 v[2:5], v[178:181], v[214:217], v[2:5]
	v_mfma_f32_16x16x32_bf16 v[54:57], v[174:177], v[190:193], v[54:57]
	v_mfma_f32_16x16x32_bf16 v[50:53], v[182:185], v[190:193], v[50:53]
	v_mfma_f32_16x16x32_bf16 v[38:41], v[174:177], v[198:201], v[38:41]
	v_mfma_f32_16x16x32_bf16 v[34:37], v[182:185], v[198:201], v[34:37]
	v_mfma_f32_16x16x32_bf16 v[22:25], v[174:177], v[210:213], v[22:25]
	v_mfma_f32_16x16x32_bf16 v[18:21], v[182:185], v[210:213], v[18:21]
	v_mfma_f32_16x16x32_bf16 v[6:9], v[174:177], v[218:221], v[6:9]
	v_mfma_f32_16x16x32_bf16 v[2:5], v[182:185], v[218:221], v[2:5]
	s_barrier
	s_setprio 0
	s_add_i32 s48, s48, 2
	s_add_u32 s20, s20, 0x100
	s_addc_u32 s21, s21, 0
	s_add_u32 s46, s46, 0x100
	s_addc_u32 s47, s47, 0
	s_cmp_gt_u32 s48, 29
	s_cbranch_scc0 .LBB0_3500
	s_and_b64 vcc, exec, s[8:9]
	s_cbranch_vccz .LBB0_3503
	s_barrier

; #define PG8_STAGE(bufoff, gbase, voff) do { _Pragma("unroll") for (int _i = 0; _i < 2; ++_i) \
;         __builtin_amdgcn_global_load_lds((const unsigned*)((const char*)(gbase) + (voff)[_i]), (PG8_LAS unsigned*)(lds + (bufoff) + ldsw + _i * 8192), 16, 0, 0); } while (0)
; #define PG8_LDA(dst, b, h) do { _Pragma("unroll") for (int m = 0; m < 4; ++m) _Pragma("unroll") for (int k = 0; k < 2; ++k) dst[m][k] = *(const PG8_LAS bf16x8*)(lds + PG8_SA(b, h) + aoff + m * 2048 + k * 1024); } while (0)
; #define PG8_LDB(dst, b, h) do { _Pragma("unroll") for (int n = 0; n < 2; ++n) _Pragma("unroll") for (int k = 0; k < 2; ++k) dst[n][k] = *(const PG8_LAS bf16x8*)(lds + PG8_SB(b, h) + boff + n * 2048 + k * 1024); } while (0)
; #define PG8_MMA(ai, bj, At, Bt) do { __builtin_amdgcn_s_setprio(1); _Pragma("unroll") for (int m = 0; m < 4; ++m) _Pragma("unroll") for (int n = 0; n < 2; ++n) _Pragma("unroll") for (int k = 0; k < 2; ++k) \
;         acc[ai][bj][m][n] = __builtin_amdgcn_mfma_f32_16x16x32_bf16(Bt[n][k], At[m][k], acc[ai][bj][m][n], 0, 0, 0); __builtin_amdgcn_s_setprio(0); } while (0)
; #define PG8_WAIT_V(n) asm volatile("s_waitcnt vmcnt(" #n ")" ::: "memory")
; #define PG8_WAIT_L(n) asm volatile("s_waitcnt lgkmcnt(" #n ")" ::: "memory")
; #define PG8_BAR __builtin_amdgcn_s_barrier()
; #define PG8_SCHED __builtin_amdgcn_sched_barrier(0)
; template <class Epi, class Sched, bool ALIGN_EPI = false, bool SP2 = false>
; __device__ __forceinline__ void gemm_phase(PG8_LAS unsigned char* lds, const Gemm g, const Sched& S, const Epi& E) {
;     ...
;             PG8_LDB(B0, 0, 0); PG8_LDB(B1, 0, 1); PG8_SCHED; PG8_LDA(At, 0, 0); PG8_STAGE(PG8_SA(1, 1), a1 + hstepA, voffA);
;             PG8_WAIT_V(8); PG8_WAIT_L(0); PG8_BAR; PG8_MMA(0, 0, At, B0); PG8_MMA(0, 1, At, B1); PG8_BAR; PG8_SCHED;
;             PG8_LDA(At, 0, 1); PG8_STAGE(PG8_SB(0, 0), b2, voffB); PG8_STAGE(PG8_SB(0, 1), b2 + hstepB, voffB); PG8_STAGE(PG8_SA(0, 0), a2, voffA);
;             PG8_WAIT_V(8); PG8_WAIT_L(0); PG8_BAR; PG8_MMA(1, 0, At, B0); PG8_MMA(1, 1, At, B1); PG8_BAR; PG8_SCHED;
.LBB0_3571:
	ds_read_b128 v[152:155], v148
	ds_read_b128 v[156:159], v148 offset:1024
	ds_read_b128 v[160:163], v148 offset:2048
	ds_read_b128 v[164:167], v148 offset:3072
	ds_read_b128 v[168:171], v149
	ds_read_b128 v[172:175], v149 offset:1024
	ds_read_b128 v[176:179], v149 offset:2048
	ds_read_b128 v[180:183], v149 offset:3072
	s_add_u32 s24, s22, 0xffea0080
	s_addc_u32 s25, s23, -1
	s_cmpk_eq_i32 s55, 0x54
	s_cselect_b32 s27, s7, s25
	s_cselect_b32 s26, s6, s24
	s_cselect_b32 s25, s21, s54
	s_cselect_b32 s24, s20, s53
	v_lshl_add_u64 v[218:219], s[22:23], 0, v[138:139]
	s_add_i32 m0, s35, 0xc000
	ds_read_b128 v[184:187], v150
	ds_read_b128 v[188:191], v150 offset:1024
	ds_read_b128 v[192:195], v150 offset:2048
	ds_read_b128 v[196:199], v150 offset:3072
	ds_read_b128 v[200:203], v150 offset:4096
	ds_read_b128 v[204:207], v150 offset:5120
	ds_read_b128 v[210:213], v150 offset:6144
	ds_read_b128 v[214:217], v150 offset:7168
	global_load_lds_dwordx4 v[218:219], off
	v_lshl_add_u64 v[218:219], s[22:23], 0, v[140:141]
	s_add_i32 m0, s35, 0xe000
	s_nop 0
	global_load_lds_dwordx4 v[218:219], off
	s_waitcnt vmcnt(8)
	s_waitcnt lgkmcnt(0)
	s_setprio 1
	s_barrier
	v_mfma_f32_16x16x32_bf16 v[126:129], v[152:155], v[184:187], v[126:129]
	v_mfma_f32_16x16x32_bf16 v[122:125], v[160:163], v[184:187], v[122:125]
	v_mfma_f32_16x16x32_bf16 v[118:121], v[152:155], v[192:195], v[118:121]
	v_mfma_f32_16x16x32_bf16 v[114:117], v[160:163], v[192:195], v[114:117]
	v_mfma_f32_16x16x32_bf16 v[102:105], v[152:155], v[200:203], v[102:105]
	v_mfma_f32_16x16x32_bf16 v[98:101], v[160:163], v[200:203], v[98:101]
	v_mfma_f32_16x16x32_bf16 v[86:89], v[152:155], v[210:213], v[86:89]
	v_mfma_f32_16x16x32_bf16 v[82:85], v[160:163], v[210:213], v[82:85]
	v_mfma_f32_16x16x32_bf16 v[126:129], v[156:159], v[188:191], v[126:129]
	v_mfma_f32_16x16x32_bf16 v[122:125], v[164:167], v[188:191], v[122:125]
	v_mfma_f32_16x16x32_bf16 v[118:121], v[156:159], v[196:199], v[118:121]
	v_mfma_f32_16x16x32_bf16 v[114:117], v[164:167], v[196:199], v[114:117]
	v_mfma_f32_16x16x32_bf16 v[102:105], v[156:159], v[204:207], v[102:105]
	v_mfma_f32_16x16x32_bf16 v[98:101], v[164:167], v[204:207], v[98:101]
	v_mfma_f32_16x16x32_bf16 v[86:89], v[156:159], v[214:217], v[86:89]
	v_mfma_f32_16x16x32_bf16 v[82:85], v[164:167], v[214:217], v[82:85]
	v_mfma_f32_16x16x32_bf16 v[110:113], v[168:171], v[184:187], v[110:113]
	v_mfma_f32_16x16x32_bf16 v[106:109], v[176:179], v[184:187], v[106:109]
	v_mfma_f32_16x16x32_bf16 v[94:97], v[168:171], v[192:195], v[94:97]
	v_mfma_f32_16x16x32_bf16 v[90:93], v[176:179], v[192:195], v[90:93]
	v_mfma_f32_16x16x32_bf16 v[78:81], v[168:171], v[200:203], v[78:81]
	v_mfma_f32_16x16x32_bf16 v[74:77], v[176:179], v[200:203], v[74:77]
	v_mfma_f32_16x16x32_bf16 v[70:73], v[168:171], v[210:213], v[70:73]
	v_mfma_f32_16x16x32_bf16 v[66:69], v[176:179], v[210:213], v[66:69]
	v_mfma_f32_16x16x32_bf16 v[110:113], v[172:175], v[188:191], v[110:113]
	v_mfma_f32_16x16x32_bf16 v[106:109], v[180:183], v[188:191], v[106:109]
	v_mfma_f32_16x16x32_bf16 v[94:97], v[172:175], v[196:199], v[94:97]
	v_mfma_f32_16x16x32_bf16 v[90:93], v[180:183], v[196:199], v[90:93]
	v_mfma_f32_16x16x32_bf16 v[78:81], v[172:175], v[204:207], v[78:81]
	v_mfma_f32_16x16x32_bf16 v[74:77], v[180:183], v[204:207], v[74:77]
	v_mfma_f32_16x16x32_bf16 v[70:73], v[172:175], v[214:217], v[70:73]
	v_mfma_f32_16x16x32_bf16 v[66:69], v[180:183], v[214:217], v[66:69]
	s_barrier
	s_setprio 0
	s_add_i32 s56, s43, s31
	v_lshl_add_u64 v[218:219], s[24:25], 0, v[134:135]
	s_mov_b32 m0, s56
	ds_read_b128 v[184:187], v150 offset:16384
	ds_read_b128 v[188:191], v150 offset:17408
	ds_read_b128 v[192:195], v150 offset:18432
	ds_read_b128 v[196:199], v150 offset:19456
	ds_read_b128 v[200:203], v150 offset:20480
	ds_read_b128 v[204:207], v150 offset:21504
	ds_read_b128 v[210:213], v150 offset:22528
	ds_read_b128 v[214:217], v150 offset:23552
	global_load_lds_dwordx4 v[218:219], off
	s_add_i32 m0, s56, 0x2000
	s_add_u32 s56, s24, 0x160000
	v_lshl_add_u64 v[220:221], s[24:25], 0, v[130:131]
	s_addc_u32 s57, s25, 0
	s_add_i32 s58, s44, s31
	global_load_lds_dwordx4 v[220:221], off
	v_lshl_add_u64 v[222:223], s[56:57], 0, v[134:135]
	s_mov_b32 m0, s58
	v_lshl_add_u64 v[224:225], s[26:27], 0, v[132:133]
	global_load_lds_dwordx4 v[222:223], off
	v_lshl_add_u64 v[222:223], s[56:57], 0, v[130:131]
	s_add_i32 m0, s58, 0x2000
	s_nop 0
	global_load_lds_dwordx4 v[222:223], off
	v_lshl_add_u64 v[222:223], s[26:27], 0, v[136:137]
	s_mov_b32 m0, s35
	s_nop 0
	global_load_lds_dwordx4 v[222:223], off
	s_mov_b32 m0, s36
	s_nop 0
	global_load_lds_dwordx4 v[224:225], off
	s_waitcnt vmcnt(8)
	s_waitcnt lgkmcnt(0)
	s_setprio 1
	s_barrier
; #define PG8_STAGE(bufoff, gbase, voff) do { _Pragma("unroll") for (int _i = 0; _i < 2; ++_i) \
;         __builtin_amdgcn_global_load_lds((const unsigned*)((const char*)(gbase) + (voff)[_i]), (PG8_LAS unsigned*)(lds + (bufoff) + ldsw + _i * 8192), 16, 0, 0); } while (0)
; #define PG8_LDA(dst, b, h) do { _Pragma("unroll") for (int m = 0; m < 4; ++m) _Pragma("unroll") for (int k = 0; k < 2; ++k) dst[m][k] = *(const PG8_LAS bf16x8*)(lds + PG8_SA(b, h) + aoff + m * 2048 + k * 1024); } while (0)
; #define PG8_LDB(dst, b, h) do { _Pragma("unroll") for (int n = 0; n < 2; ++n) _Pragma("unroll") for (int k = 0; k < 2; ++k) dst[n][k] = *(const PG8_LAS bf16x8*)(lds + PG8_SB(b, h) + boff + n * 2048 + k * 1024); } while (0)
; #define PG8_MMA(ai, bj, At, Bt) do { __builtin_amdgcn_s_setprio(1); _Pragma("unroll") for (int m = 0; m < 4; ++m) _Pragma("unroll") for (int n = 0; n < 2; ++n) _Pragma("unroll") for (int k = 0; k < 2; ++k) \
;         acc[ai][bj][m][n] = __builtin_amdgcn_mfma_f32_16x16x32_bf16(Bt[n][k], At[m][k], acc[ai][bj][m][n], 0, 0, 0); __builtin_amdgcn_s_setprio(0); } while (0)
; #define PG8_WAIT_V(n) asm volatile("s_waitcnt vmcnt(" #n ")" ::: "memory")
; #define PG8_WAIT_L(n) asm volatile("s_waitcnt lgkmcnt(" #n ")" ::: "memory")
; #define PG8_BAR __builtin_amdgcn_s_barrier()
; #define PG8_SCHED __builtin_amdgcn_sched_barrier(0)
; template <class Epi, class Sched, bool ALIGN_EPI = false, bool SP2 = false>
; __device__ __forceinline__ void gemm_phase(PG8_LAS unsigned char* lds, const Gemm g, const Sched& S, const Epi& E) {
;     ...
;             PG8_LDA(At, 0, 1); PG8_STAGE(PG8_SB(0, 0), b2, voffB); PG8_STAGE(PG8_SB(0, 1), b2 + hstepB, voffB); PG8_STAGE(PG8_SA(0, 0), a2, voffA);
;             PG8_WAIT_V(8); PG8_WAIT_L(0); PG8_BAR; PG8_MMA(1, 0, At, B0); PG8_MMA(1, 1, At, B1); PG8_BAR; PG8_SCHED;
;             PG8_LDB(B0, 1, 0); PG8_LDB(B1, 1, 1); PG8_SCHED; PG8_LDA(At, 1, 0); PG8_STAGE(PG8_SA(0, 1), a2 + hstepA, voffA);
;             PG8_WAIT_V(8); PG8_WAIT_L(0); PG8_BAR; PG8_MMA(0, 0, At, B0); PG8_MMA(0, 1, At, B1); PG8_BAR; PG8_SCHED;
	v_mfma_f32_16x16x32_bf16 v[62:65], v[152:155], v[184:187], v[62:65]
	v_mfma_f32_16x16x32_bf16 v[58:61], v[160:163], v[184:187], v[58:61]
	v_mfma_f32_16x16x32_bf16 v[54:57], v[152:155], v[192:195], v[54:57]
	v_mfma_f32_16x16x32_bf16 v[50:53], v[160:163], v[192:195], v[50:53]
	v_mfma_f32_16x16x32_bf16 v[38:41], v[152:155], v[200:203], v[38:41]
	v_mfma_f32_16x16x32_bf16 v[34:37], v[160:163], v[200:203], v[34:37]
	v_mfma_f32_16x16x32_bf16 v[22:25], v[152:155], v[210:213], v[22:25]
	v_mfma_f32_16x16x32_bf16 v[18:21], v[160:163], v[210:213], v[18:21]
	v_mfma_f32_16x16x32_bf16 v[62:65], v[156:159], v[188:191], v[62:65]
	v_mfma_f32_16x16x32_bf16 v[58:61], v[164:167], v[188:191], v[58:61]
	v_mfma_f32_16x16x32_bf16 v[54:57], v[156:159], v[196:199], v[54:57]
	v_mfma_f32_16x16x32_bf16 v[50:53], v[164:167], v[196:199], v[50:53]
	v_mfma_f32_16x16x32_bf16 v[38:41], v[156:159], v[204:207], v[38:41]
	v_mfma_f32_16x16x32_bf16 v[34:37], v[164:167], v[204:207], v[34:37]
	v_mfma_f32_16x16x32_bf16 v[22:25], v[156:159], v[214:217], v[22:25]
	v_mfma_f32_16x16x32_bf16 v[18:21], v[164:167], v[214:217], v[18:21]
	v_mfma_f32_16x16x32_bf16 v[46:49], v[168:171], v[184:187], v[46:49]
	v_mfma_f32_16x16x32_bf16 v[42:45], v[176:179], v[184:187], v[42:45]
	v_mfma_f32_16x16x32_bf16 v[30:33], v[168:171], v[192:195], v[30:33]
	v_mfma_f32_16x16x32_bf16 v[26:29], v[176:179], v[192:195], v[26:29]
	v_mfma_f32_16x16x32_bf16 v[14:17], v[168:171], v[200:203], v[14:17]
	v_mfma_f32_16x16x32_bf16 v[10:13], v[176:179], v[200:203], v[10:13]
	v_mfma_f32_16x16x32_bf16 v[6:9], v[168:171], v[210:213], v[6:9]
	v_mfma_f32_16x16x32_bf16 v[2:5], v[176:179], v[210:213], v[2:5]
	v_mfma_f32_16x16x32_bf16 v[46:49], v[172:175], v[188:191], v[46:49]
	v_mfma_f32_16x16x32_bf16 v[42:45], v[180:183], v[188:191], v[42:45]
	v_mfma_f32_16x16x32_bf16 v[30:33], v[172:175], v[196:199], v[30:33]
	v_mfma_f32_16x16x32_bf16 v[26:29], v[180:183], v[196:199], v[26:29]
	v_mfma_f32_16x16x32_bf16 v[14:17], v[172:175], v[204:207], v[14:17]
	v_mfma_f32_16x16x32_bf16 v[10:13], v[180:183], v[204:207], v[10:13]
	v_mfma_f32_16x16x32_bf16 v[6:9], v[172:175], v[214:217], v[6:9]
	v_mfma_f32_16x16x32_bf16 v[2:5], v[180:183], v[214:217], v[2:5]
	s_barrier
	s_setprio 0
	s_add_i32 s56, 0, 0x18000
	v_add_u32_e32 v151, s56, v146
	s_add_i32 s57, 0, 0x1c000
	ds_read_b128 v[152:155], v151
	ds_read_b128 v[156:159], v151 offset:1024
	ds_read_b128 v[160:163], v151 offset:2048
	ds_read_b128 v[164:167], v151 offset:3072
	v_add_u32_e32 v151, s57, v146
	ds_read_b128 v[168:171], v151
	ds_read_b128 v[172:175], v151 offset:1024
	ds_read_b128 v[176:179], v151 offset:2048
	ds_read_b128 v[180:183], v151 offset:3072
	s_add_u32 s26, s26, 0x160000
	s_addc_u32 s27, s27, 0
	s_mov_b32 m0, s37
	v_lshl_add_u64 v[226:227], s[26:27], 0, v[136:137]
	ds_read_b128 v[184:187], v150 offset:32768
	ds_read_b128 v[188:191], v150 offset:33792
	ds_read_b128 v[192:195], v150 offset:34816
	ds_read_b128 v[196:199], v150 offset:35840
	ds_read_b128 v[200:203], v150 offset:36864
	ds_read_b128 v[204:207], v150 offset:37888
	ds_read_b128 v[210:213], v150 offset:38912
	ds_read_b128 v[214:217], v150 offset:39936
	global_load_lds_dwordx4 v[226:227], off
	v_lshl_add_u64 v[226:227], s[26:27], 0, v[132:133]
	s_mov_b32 m0, s38
	s_nop 0
	global_load_lds_dwordx4 v[226:227], off
	s_waitcnt vmcnt(8)
	s_waitcnt lgkmcnt(0)
	s_setprio 1
	s_barrier
	v_mfma_f32_16x16x32_bf16 v[126:129], v[152:155], v[184:187], v[126:129]
	v_mfma_f32_16x16x32_bf16 v[122:125], v[160:163], v[184:187], v[122:125]
	v_mfma_f32_16x16x32_bf16 v[118:121], v[152:155], v[192:195], v[118:121]
	v_mfma_f32_16x16x32_bf16 v[114:117], v[160:163], v[192:195], v[114:117]
	v_mfma_f32_16x16x32_bf16 v[102:105], v[152:155], v[200:203], v[102:105]
	v_mfma_f32_16x16x32_bf16 v[98:101], v[160:163], v[200:203], v[98:101]
	v_mfma_f32_16x16x32_bf16 v[86:89], v[152:155], v[210:213], v[86:89]
	v_mfma_f32_16x16x32_bf16 v[82:85], v[160:163], v[210:213], v[82:85]
	v_mfma_f32_16x16x32_bf16 v[126:129], v[156:159], v[188:191], v[126:129]
	v_mfma_f32_16x16x32_bf16 v[122:125], v[164:167], v[188:191], v[122:125]
	v_mfma_f32_16x16x32_bf16 v[118:121], v[156:159], v[196:199], v[118:121]
	v_mfma_f32_16x16x32_bf16 v[114:117], v[164:167], v[196:199], v[114:117]
	v_mfma_f32_16x16x32_bf16 v[102:105], v[156:159], v[204:207], v[102:105]
	v_mfma_f32_16x16x32_bf16 v[98:101], v[164:167], v[204:207], v[98:101]
	v_mfma_f32_16x16x32_bf16 v[86:89], v[156:159], v[214:217], v[86:89]
	v_mfma_f32_16x16x32_bf16 v[82:85], v[164:167], v[214:217], v[82:85]
	v_mfma_f32_16x16x32_bf16 v[110:113], v[168:171], v[184:187], v[110:113]
	v_mfma_f32_16x16x32_bf16 v[106:109], v[176:179], v[184:187], v[106:109]
	v_mfma_f32_16x16x32_bf16 v[94:97], v[168:171], v[192:195], v[94:97]
	v_mfma_f32_16x16x32_bf16 v[90:93], v[176:179], v[192:195], v[90:93]
	v_mfma_f32_16x16x32_bf16 v[78:81], v[168:171], v[200:203], v[78:81]
	v_mfma_f32_16x16x32_bf16 v[74:77], v[176:179], v[200:203], v[74:77]
	v_mfma_f32_16x16x32_bf16 v[70:73], v[168:171], v[210:213], v[70:73]
	v_mfma_f32_16x16x32_bf16 v[66:69], v[176:179], v[210:213], v[66:69]
	v_mfma_f32_16x16x32_bf16 v[110:113], v[172:175], v[188:191], v[110:113]
	v_mfma_f32_16x16x32_bf16 v[106:109], v[180:183], v[188:191], v[106:109]
	v_mfma_f32_16x16x32_bf16 v[94:97], v[172:175], v[196:199], v[94:97]
	v_mfma_f32_16x16x32_bf16 v[90:93], v[180:183], v[196:199], v[90:93]
	v_mfma_f32_16x16x32_bf16 v[78:81], v[172:175], v[204:207], v[78:81]
	v_mfma_f32_16x16x32_bf16 v[74:77], v[180:183], v[204:207], v[74:77]
	v_mfma_f32_16x16x32_bf16 v[70:73], v[172:175], v[214:217], v[70:73]
	v_mfma_f32_16x16x32_bf16 v[66:69], v[180:183], v[214:217], v[66:69]
	s_barrier
; #define PG8_STAGE(bufoff, gbase, voff) do { _Pragma("unroll") for (int _i = 0; _i < 2; ++_i) \
;         __builtin_amdgcn_global_load_lds((const unsigned*)((const char*)(gbase) + (voff)[_i]), (PG8_LAS unsigned*)(lds + (bufoff) + ldsw + _i * 8192), 16, 0, 0); } while (0)
; #define PG8_LDA(dst, b, h) do { _Pragma("unroll") for (int m = 0; m < 4; ++m) _Pragma("unroll") for (int k = 0; k < 2; ++k) dst[m][k] = *(const PG8_LAS bf16x8*)(lds + PG8_SA(b, h) + aoff + m * 2048 + k * 1024); } while (0)
; #define PG8_MMA(ai, bj, At, Bt) do { __builtin_amdgcn_s_setprio(1); _Pragma("unroll") for (int m = 0; m < 4; ++m) _Pragma("unroll") for (int n = 0; n < 2; ++n) _Pragma("unroll") for (int k = 0; k < 2; ++k) \
;         acc[ai][bj][m][n] = __builtin_amdgcn_mfma_f32_16x16x32_bf16(Bt[n][k], At[m][k], acc[ai][bj][m][n], 0, 0, 0); __builtin_amdgcn_s_setprio(0); } while (0)
; #define PG8_WAIT_V(n) asm volatile("s_waitcnt vmcnt(" #n ")" ::: "memory")
; #define PG8_WAIT_L(n) asm volatile("s_waitcnt lgkmcnt(" #n ")" ::: "memory")
; #define PG8_BAR __builtin_amdgcn_s_barrier()
; #define PG8_SCHED __builtin_amdgcn_sched_barrier(0)
; template <class Epi, class Sched, bool ALIGN_EPI = false, bool SP2 = false>
; __device__ __forceinline__ void gemm_phase(PG8_LAS unsigned char* lds, const Gemm g, const Sched& S, const Epi& E) {
;     ...
;         for (int t = 0; t < nt; t += 2) {
;             const bool last = (t == nt - 2);
;             const char* a1 = cA + (size_t)(t + 1) * kstep;
;             const char* a2 = last ? nA : cA + (size_t)(t + 2) * kstep; const char* b2 = last ? nB : cB + (size_t)(t + 2) * kstep;
;     ...
;             PG8_LDA(At, 1, 1); PG8_STAGE(PG8_SB(1, 0), b3, voffB); PG8_STAGE(PG8_SB(1, 1), b3 + hstepB, voffB); PG8_STAGE(PG8_SA(1, 0), a3, voffA);
;             PG8_WAIT_V(8); PG8_WAIT_L(0); PG8_BAR; PG8_MMA(1, 0, At, B0); PG8_MMA(1, 1, At, B1); PG8_BAR; PG8_SCHED;
	s_setprio 0
	s_add_i32 s26, s56, s31
	v_lshl_add_u64 v[218:219], v[218:219], 0, s[8:9]
	s_mov_b32 m0, s26
	ds_read_b128 v[184:187], v150 offset:49152
	ds_read_b128 v[188:191], v150 offset:50176
	ds_read_b128 v[192:195], v150 offset:51200
	ds_read_b128 v[196:199], v150 offset:52224
	ds_read_b128 v[200:203], v150 offset:53248
	ds_read_b128 v[204:207], v150 offset:54272
	ds_read_b128 v[210:213], v150 offset:55296
	ds_read_b128 v[214:217], v150 offset:56320
	global_load_lds_dwordx4 v[218:219], off
	s_add_i32 m0, s26, 0x2000
	s_add_u32 s24, s24, 0x160080
	v_lshl_add_u64 v[218:219], v[220:221], 0, s[8:9]
	s_addc_u32 s25, s25, 0
	s_add_i32 s26, s57, s31
	global_load_lds_dwordx4 v[218:219], off
	v_lshl_add_u64 v[218:219], s[24:25], 0, v[134:135]
	s_mov_b32 m0, s26
	s_nop 0
	global_load_lds_dwordx4 v[218:219], off
	v_lshl_add_u64 v[218:219], s[24:25], 0, v[130:131]
	s_add_i32 m0, s26, 0x2000
	s_nop 0
	global_load_lds_dwordx4 v[218:219], off
	v_lshl_add_u64 v[218:219], v[222:223], 0, s[8:9]
	s_mov_b32 m0, s40
	s_nop 0
	global_load_lds_dwordx4 v[218:219], off
	v_lshl_add_u64 v[218:219], v[224:225], 0, s[8:9]
	s_mov_b32 m0, s41
	s_nop 0
	global_load_lds_dwordx4 v[218:219], off
	s_waitcnt vmcnt(8)
	s_waitcnt lgkmcnt(0)
	s_setprio 1
	s_barrier
	v_mfma_f32_16x16x32_bf16 v[62:65], v[152:155], v[184:187], v[62:65]
	v_mfma_f32_16x16x32_bf16 v[58:61], v[160:163], v[184:187], v[58:61]
	v_mfma_f32_16x16x32_bf16 v[54:57], v[152:155], v[192:195], v[54:57]
	v_mfma_f32_16x16x32_bf16 v[50:53], v[160:163], v[192:195], v[50:53]
	v_mfma_f32_16x16x32_bf16 v[38:41], v[152:155], v[200:203], v[38:41]
	v_mfma_f32_16x16x32_bf16 v[34:37], v[160:163], v[200:203], v[34:37]
	v_mfma_f32_16x16x32_bf16 v[22:25], v[152:155], v[210:213], v[22:25]
	v_mfma_f32_16x16x32_bf16 v[18:21], v[160:163], v[210:213], v[18:21]
	v_mfma_f32_16x16x32_bf16 v[62:65], v[156:159], v[188:191], v[62:65]
	v_mfma_f32_16x16x32_bf16 v[58:61], v[164:167], v[188:191], v[58:61]
	v_mfma_f32_16x16x32_bf16 v[54:57], v[156:159], v[196:199], v[54:57]
	v_mfma_f32_16x16x32_bf16 v[50:53], v[164:167], v[196:199], v[50:53]
	v_mfma_f32_16x16x32_bf16 v[38:41], v[156:159], v[204:207], v[38:41]
	v_mfma_f32_16x16x32_bf16 v[34:37], v[164:167], v[204:207], v[34:37]
	v_mfma_f32_16x16x32_bf16 v[22:25], v[156:159], v[214:217], v[22:25]
	v_mfma_f32_16x16x32_bf16 v[18:21], v[164:167], v[214:217], v[18:21]
	v_mfma_f32_16x16x32_bf16 v[46:49], v[168:171], v[184:187], v[46:49]
	v_mfma_f32_16x16x32_bf16 v[42:45], v[176:179], v[184:187], v[42:45]
	v_mfma_f32_16x16x32_bf16 v[30:33], v[168:171], v[192:195], v[30:33]
	v_mfma_f32_16x16x32_bf16 v[26:29], v[176:179], v[192:195], v[26:29]
	v_mfma_f32_16x16x32_bf16 v[14:17], v[168:171], v[200:203], v[14:17]
	v_mfma_f32_16x16x32_bf16 v[10:13], v[176:179], v[200:203], v[10:13]
	v_mfma_f32_16x16x32_bf16 v[6:9], v[168:171], v[210:213], v[6:9]
	v_mfma_f32_16x16x32_bf16 v[2:5], v[176:179], v[210:213], v[2:5]
	v_mfma_f32_16x16x32_bf16 v[46:49], v[172:175], v[188:191], v[46:49]
	v_mfma_f32_16x16x32_bf16 v[42:45], v[180:183], v[188:191], v[42:45]
	v_mfma_f32_16x16x32_bf16 v[30:33], v[172:175], v[196:199], v[30:33]
	v_mfma_f32_16x16x32_bf16 v[26:29], v[180:183], v[196:199], v[26:29]
	v_mfma_f32_16x16x32_bf16 v[14:17], v[172:175], v[204:207], v[14:17]
	v_mfma_f32_16x16x32_bf16 v[10:13], v[180:183], v[204:207], v[10:13]
	v_mfma_f32_16x16x32_bf16 v[6:9], v[172:175], v[214:217], v[6:9]
	v_mfma_f32_16x16x32_bf16 v[2:5], v[180:183], v[214:217], v[2:5]
	s_barrier
	s_setprio 0
	s_add_i32 s55, s55, 2
	s_add_u32 s22, s22, 0x100
	s_addc_u32 s23, s23, 0
	s_add_u32 s53, s53, 0x100
	s_addc_u32 s54, s54, 0
	s_cmpk_gt_u32 s55, 0x55
	s_cbranch_scc0 .LBB0_3571
	s_and_b64 vcc, exec, s[10:11]
	s_cbranch_vccz .LBB0_3574
	s_barrier
